# v66 + s_nop before each second LDS-DMA removed by ordering the m0 write above the address VALU
# baseline (speedup 1.0000x reference)
; #define PG8_STAGE(bufoff, gbase, voff) do { _Pragma("unroll") for (int _i = 0; _i < 2; ++_i) \
;         __builtin_amdgcn_global_load_lds((const unsigned*)((const char*)(gbase) + (voff)[_i]), (LAS unsigned*)(lds + (bufoff) + ldsw + _i * 8192), 16, 0, 0); } while (0)
; #define PG8_LDA(dst, b, h) do { _Pragma("unroll") for (int m = 0; m < 4; ++m) _Pragma("unroll") for (int k = 0; k < 2; ++k) dst[m][k] = *(const LAS bf16x8*)(lds + PG8_SA(b, h) + aoff + m * 2048 + k * 1024); } while (0)
; #define PG8_LDB(dst, b, h) do { _Pragma("unroll") for (int n = 0; n < 2; ++n) _Pragma("unroll") for (int k = 0; k < 2; ++k) dst[n][k] = *(const LAS bf16x8*)(lds + PG8_SB(b, h) + boff + n * 2048 + k * 1024); } while (0)
; #define PG8_MMA(ai, bj, At, Bt) do { __builtin_amdgcn_s_setprio(1); _Pragma("unroll") for (int m = 0; m < 4; ++m) _Pragma("unroll") for (int n = 0; n < 2; ++n) _Pragma("unroll") for (int k = 0; k < 2; ++k) \
;         acc[ai][bj][m][n] = __builtin_amdgcn_mfma_f32_16x16x32_bf16(Bt[n][k], At[m][k], acc[ai][bj][m][n], 0, 0, 0); __builtin_amdgcn_s_setprio(0); } while (0)
; #define PG8_WAIT_V(n) asm volatile("s_waitcnt vmcnt(" #n ")" ::: "memory")
; #define PG8_WAIT_L(n) asm volatile("s_waitcnt lgkmcnt(" #n ")" ::: "memory")
; #define PG8_BAR __builtin_amdgcn_s_barrier()
; #define PG8_SCHED __builtin_amdgcn_sched_barrier(0)
; template <class Epi>
; DI void gemm_phase(LAS unsigned char* lds, const Gemm g, const StaticOrder S, const Epi E) {
;     ...
;             const bool last = (t == nt - 2);
;             const char* a1 = cA + (size_t)(t + 1) * kstep;
;             const char* a2 = last ? nA : cA + (size_t)(t + 2) * kstep; const char* b2 = last ? nB : cB + (size_t)(t + 2) * kstep;
;             const char* a3 = a2 + kstep; const char* b3 = b2 + kstep;
;             PG8_LDB(B0, 0, 0); PG8_SCHED; PG8_LDA(At, 0, 0); PG8_STAGE(PG8_SA(1, 1), a1 + hstep, voffA);
;             PG8_WAIT_L(8); PG8_BAR; PG8_WAIT_L(0); PG8_MMA(0, 0, At, B0); PG8_BAR; PG8_SCHED;
;             PG8_LDB(B1, 0, 1); PG8_STAGE(PG8_SB(0, 0), b2, voffB);
;             PG8_BAR; PG8_WAIT_L(0); PG8_MMA(0, 1, At, B1); PG8_BAR;
;             PG8_LDA(At, 0, 1); PG8_STAGE(PG8_SA(0, 0), a2, voffA);
;             PG8_BAR; PG8_WAIT_L(0); PG8_MMA(1, 0, At, B0); PG8_BAR; PG8_SCHED;
;             PG8_STAGE(PG8_SB(0, 1), b2 + hstep, voffB);
;             PG8_WAIT_V(6); PG8_BAR; PG8_MMA(1, 1, At, B1); PG8_BAR;
.LBB0_107:
	ds_read_b128 v[152:155], v149
	ds_read_b128 v[156:159], v149 offset:1024
	ds_read_b128 v[160:163], v149 offset:2048
	ds_read_b128 v[164:167], v149 offset:3072
	s_add_u32 s14, s76, 0xfffc0080
	s_addc_u32 s15, s77, -1
	s_cmp_eq_u32 s97, 12
	s_cselect_b32 s81, s11, s15
	s_cselect_b32 s80, s93, s14
	s_cselect_b32 s79, s9, s96
	s_cselect_b32 s78, s94, s95
	v_lshl_add_u64 v[144:145], s[76:77], 0, v[136:137]
	s_add_i32 m0, s29, 0xc000
	ds_read_b128 v[168:171], v150
	ds_read_b128 v[176:179], v150 offset:2048
	ds_read_b128 v[184:187], v150 offset:4096
	ds_read_b128 v[192:195], v150 offset:6144
	global_load_lds_dwordx4 v[144:145], off
	s_add_i32 m0, s29, 0xe000
	v_lshl_add_u64 v[144:145], s[76:77], 0, v[138:139]
	global_load_lds_dwordx4 v[144:145], off
	s_waitcnt lgkmcnt(4)
	s_setprio 1
	s_barrier
	ds_read_b128 v[172:175], v150 offset:1024
	ds_read_b128 v[180:183], v150 offset:3072
	ds_read_b128 v[188:191], v150 offset:5120
	ds_read_b128 v[196:199], v150 offset:7168
	s_waitcnt lgkmcnt(4)
	v_mfma_f32_16x16x32_bf16 v[124:127], v[152:155], v[168:171], v[124:127]
	v_mfma_f32_16x16x32_bf16 v[116:119], v[160:163], v[168:171], v[116:119]
	v_mfma_f32_16x16x32_bf16 v[108:111], v[152:155], v[176:179], v[108:111]
	v_mfma_f32_16x16x32_bf16 v[100:103], v[160:163], v[176:179], v[100:103]
	v_mfma_f32_16x16x32_bf16 v[92:95], v[152:155], v[184:187], v[92:95]
	v_mfma_f32_16x16x32_bf16 v[84:87], v[160:163], v[184:187], v[84:87]
	v_mfma_f32_16x16x32_bf16 v[76:79], v[152:155], v[192:195], v[76:79]
	v_mfma_f32_16x16x32_bf16 v[68:71], v[160:163], v[192:195], v[68:71]
	s_waitcnt lgkmcnt(3)
	v_mfma_f32_16x16x32_bf16 v[124:127], v[156:159], v[172:175], v[124:127]
	v_mfma_f32_16x16x32_bf16 v[116:119], v[164:167], v[172:175], v[116:119]
	s_waitcnt lgkmcnt(2)
	v_mfma_f32_16x16x32_bf16 v[108:111], v[156:159], v[180:183], v[108:111]
	v_mfma_f32_16x16x32_bf16 v[100:103], v[164:167], v[180:183], v[100:103]
	s_waitcnt lgkmcnt(1)
	v_mfma_f32_16x16x32_bf16 v[92:95], v[156:159], v[188:191], v[92:95]
	v_mfma_f32_16x16x32_bf16 v[84:87], v[164:167], v[188:191], v[84:87]
	s_waitcnt lgkmcnt(0)
	s_setprio 2
	s_barrier
	v_mfma_f32_16x16x32_bf16 v[76:79], v[156:159], v[196:199], v[76:79]
	v_mfma_f32_16x16x32_bf16 v[68:71], v[164:167], v[196:199], v[68:71]
	s_setprio 0
	s_add_i32 s14, s89, s7
	v_lshl_add_u64 v[144:145], s[78:79], 0, v[132:133]
	s_mov_b32 m0, s14
	ds_read_b128 v[200:203], v151
	ds_read_b128 v[204:207], v151 offset:1024
	ds_read_b128 v[208:211], v151 offset:2048
	ds_read_b128 v[212:215], v151 offset:3072
	global_load_lds_dwordx4 v[144:145], off
	s_add_i32 m0, s14, 0x2000
	v_lshl_add_u64 v[216:217], s[78:79], 0, v[128:129]
	global_load_lds_dwordx4 v[216:217], off
	s_setprio 1
	s_barrier
	s_waitcnt lgkmcnt(0)
	v_mfma_f32_16x16x32_bf16 v[120:123], v[200:203], v[168:171], v[120:123]
	v_mfma_f32_16x16x32_bf16 v[112:115], v[208:211], v[168:171], v[112:115]
	v_mfma_f32_16x16x32_bf16 v[104:107], v[200:203], v[176:179], v[104:107]
	v_mfma_f32_16x16x32_bf16 v[96:99], v[208:211], v[176:179], v[96:99]
	v_mfma_f32_16x16x32_bf16 v[88:91], v[200:203], v[184:187], v[88:91]
	v_mfma_f32_16x16x32_bf16 v[80:83], v[208:211], v[184:187], v[80:83]
	v_mfma_f32_16x16x32_bf16 v[72:75], v[200:203], v[192:195], v[72:75]
	v_mfma_f32_16x16x32_bf16 v[64:67], v[208:211], v[192:195], v[64:67]
	v_mfma_f32_16x16x32_bf16 v[120:123], v[204:207], v[172:175], v[120:123]
	v_mfma_f32_16x16x32_bf16 v[112:115], v[212:215], v[172:175], v[112:115]
	v_mfma_f32_16x16x32_bf16 v[104:107], v[204:207], v[180:183], v[104:107]
	v_mfma_f32_16x16x32_bf16 v[96:99], v[212:215], v[180:183], v[96:99]
	v_mfma_f32_16x16x32_bf16 v[88:91], v[204:207], v[188:191], v[88:91]
	v_mfma_f32_16x16x32_bf16 v[80:83], v[212:215], v[188:191], v[80:83]
	s_setprio 2
	s_barrier
	v_mfma_f32_16x16x32_bf16 v[72:75], v[204:207], v[196:199], v[72:75]
	v_mfma_f32_16x16x32_bf16 v[64:67], v[212:215], v[196:199], v[64:67]
	s_setprio 0
	s_mov_b32 m0, s29
	v_lshl_add_u64 v[218:219], s[80:81], 0, v[134:135]
	ds_read_b128 v[168:171], v150 offset:16384
	ds_read_b128 v[176:179], v150 offset:18432
	ds_read_b128 v[184:187], v150 offset:20480
	ds_read_b128 v[192:195], v150 offset:22528
	global_load_lds_dwordx4 v[218:219], off
	s_mov_b32 m0, s59
	v_lshl_add_u64 v[220:221], s[80:81], 0, v[130:131]
	global_load_lds_dwordx4 v[220:221], off
	s_setprio 1
	s_barrier
	ds_read_b128 v[172:175], v150 offset:17408
	ds_read_b128 v[180:183], v150 offset:19456
	ds_read_b128 v[188:191], v150 offset:21504
	ds_read_b128 v[196:199], v150 offset:23552
	s_waitcnt lgkmcnt(4)
	v_mfma_f32_16x16x32_bf16 v[60:63], v[152:155], v[168:171], v[60:63]
	v_mfma_f32_16x16x32_bf16 v[52:55], v[160:163], v[168:171], v[52:55]
	v_mfma_f32_16x16x32_bf16 v[44:47], v[152:155], v[176:179], v[44:47]
	v_mfma_f32_16x16x32_bf16 v[36:39], v[160:163], v[176:179], v[36:39]
	v_mfma_f32_16x16x32_bf16 v[28:31], v[152:155], v[184:187], v[28:31]
	v_mfma_f32_16x16x32_bf16 v[20:23], v[160:163], v[184:187], v[20:23]
	v_mfma_f32_16x16x32_bf16 v[12:15], v[152:155], v[192:195], v[12:15]
	v_mfma_f32_16x16x32_bf16 v[4:7], v[160:163], v[192:195], v[4:7]
	s_waitcnt lgkmcnt(3)
	v_mfma_f32_16x16x32_bf16 v[60:63], v[156:159], v[172:175], v[60:63]
	v_mfma_f32_16x16x32_bf16 v[52:55], v[164:167], v[172:175], v[52:55]
	s_waitcnt lgkmcnt(2)
	v_mfma_f32_16x16x32_bf16 v[44:47], v[156:159], v[180:183], v[44:47]
	v_mfma_f32_16x16x32_bf16 v[36:39], v[164:167], v[180:183], v[36:39]
	s_waitcnt lgkmcnt(1)
	v_mfma_f32_16x16x32_bf16 v[28:31], v[156:159], v[188:191], v[28:31]
	v_mfma_f32_16x16x32_bf16 v[20:23], v[164:167], v[188:191], v[20:23]
	s_waitcnt lgkmcnt(0)
	s_setprio 2
	s_barrier
; #define PG8_STAGE(bufoff, gbase, voff) do { _Pragma("unroll") for (int _i = 0; _i < 2; ++_i) \
;         __builtin_amdgcn_global_load_lds((const unsigned*)((const char*)(gbase) + (voff)[_i]), (LAS unsigned*)(lds + (bufoff) + ldsw + _i * 8192), 16, 0, 0); } while (0)
; #define PG8_LDA(dst, b, h) do { _Pragma("unroll") for (int m = 0; m < 4; ++m) _Pragma("unroll") for (int k = 0; k < 2; ++k) dst[m][k] = *(const LAS bf16x8*)(lds + PG8_SA(b, h) + aoff + m * 2048 + k * 1024); } while (0)
; #define PG8_LDB(dst, b, h) do { _Pragma("unroll") for (int n = 0; n < 2; ++n) _Pragma("unroll") for (int k = 0; k < 2; ++k) dst[n][k] = *(const LAS bf16x8*)(lds + PG8_SB(b, h) + boff + n * 2048 + k * 1024); } while (0)
; #define PG8_MMA(ai, bj, At, Bt) do { __builtin_amdgcn_s_setprio(1); _Pragma("unroll") for (int m = 0; m < 4; ++m) _Pragma("unroll") for (int n = 0; n < 2; ++n) _Pragma("unroll") for (int k = 0; k < 2; ++k) \
;         acc[ai][bj][m][n] = __builtin_amdgcn_mfma_f32_16x16x32_bf16(Bt[n][k], At[m][k], acc[ai][bj][m][n], 0, 0, 0); __builtin_amdgcn_s_setprio(0); } while (0)
; #define PG8_WAIT_V(n) asm volatile("s_waitcnt vmcnt(" #n ")" ::: "memory")
; #define PG8_WAIT_L(n) asm volatile("s_waitcnt lgkmcnt(" #n ")" ::: "memory")
; #define PG8_BAR __builtin_amdgcn_s_barrier()
; #define PG8_SCHED __builtin_amdgcn_sched_barrier(0)
; #define PG8_LDA(dst, b, h) do { _Pragma("unroll") for (int m = 0; m < 4; ++m) _Pragma("unroll") for (int k = 0; k < 2; ++k) dst[m][k] = *(const LAS bf16x8*)(lds + PG8_SA(b, h) + aoff + m * 2048 + k * 1024); } while (0)
; template <class Epi>
; DI void gemm_phase(LAS unsigned char* lds, const Gemm g, const StaticOrder S, const Epi E) {
;     ...
;             PG8_BAR; PG8_WAIT_L(0); PG8_MMA(1, 0, At, B0); PG8_BAR; PG8_SCHED;
;             PG8_STAGE(PG8_SB(0, 1), b2 + hstep, voffB);
;             PG8_WAIT_V(6); PG8_BAR; PG8_MMA(1, 1, At, B1); PG8_BAR;
;             PG8_LDB(B0, 1, 0); PG8_SCHED; PG8_LDA(At, 1, 0); PG8_STAGE(PG8_SA(0, 1), a2 + hstep, voffA);
;             PG8_WAIT_L(8); PG8_BAR; PG8_WAIT_L(0); PG8_MMA(0, 0, At, B0); PG8_BAR; PG8_SCHED;
;             PG8_LDB(B1, 1, 1); PG8_STAGE(PG8_SB(1, 0), b3, voffB);
;             PG8_BAR; PG8_WAIT_L(0); PG8_MMA(0, 1, At, B1); PG8_BAR;
;             PG8_LDA(At, 1, 1); PG8_STAGE(PG8_SA(1, 0), a3, voffA);
;             PG8_BAR; PG8_WAIT_L(0); PG8_MMA(1, 0, At, B0); PG8_BAR; PG8_SCHED;
	v_mfma_f32_16x16x32_bf16 v[12:15], v[156:159], v[196:199], v[12:15]
	v_mfma_f32_16x16x32_bf16 v[4:7], v[164:167], v[196:199], v[4:7]
	s_setprio 0
	s_add_u32 s14, s78, 0x40000
	s_addc_u32 s15, s79, 0
	s_add_i32 s35, s90, s7
	s_mov_b32 m0, s35
	v_lshl_add_u64 v[152:153], s[14:15], 0, v[132:133]
	global_load_lds_dwordx4 v[152:153], off
	s_add_i32 m0, s35, 0x2000
	v_lshl_add_u64 v[152:153], s[14:15], 0, v[128:129]
	global_load_lds_dwordx4 v[152:153], off
	s_waitcnt vmcnt(6)
	s_setprio 1
	s_barrier
	v_mfma_f32_16x16x32_bf16 v[56:59], v[200:203], v[168:171], v[56:59]
	v_mfma_f32_16x16x32_bf16 v[48:51], v[208:211], v[168:171], v[48:51]
	v_mfma_f32_16x16x32_bf16 v[40:43], v[200:203], v[176:179], v[40:43]
	v_mfma_f32_16x16x32_bf16 v[32:35], v[208:211], v[176:179], v[32:35]
	v_mfma_f32_16x16x32_bf16 v[24:27], v[200:203], v[184:187], v[24:27]
	v_mfma_f32_16x16x32_bf16 v[16:19], v[208:211], v[184:187], v[16:19]
	v_mfma_f32_16x16x32_bf16 v[8:11], v[200:203], v[192:195], v[8:11]
	v_mfma_f32_16x16x32_bf16 v[0:3], v[208:211], v[192:195], v[0:3]
	v_mfma_f32_16x16x32_bf16 v[56:59], v[204:207], v[172:175], v[56:59]
	v_mfma_f32_16x16x32_bf16 v[48:51], v[212:215], v[172:175], v[48:51]
	v_mfma_f32_16x16x32_bf16 v[40:43], v[204:207], v[180:183], v[40:43]
	v_mfma_f32_16x16x32_bf16 v[32:35], v[212:215], v[180:183], v[32:35]
	v_mfma_f32_16x16x32_bf16 v[24:27], v[204:207], v[188:191], v[24:27]
	v_mfma_f32_16x16x32_bf16 v[16:19], v[212:215], v[188:191], v[16:19]
	s_setprio 2
	s_barrier
	v_mfma_f32_16x16x32_bf16 v[8:11], v[204:207], v[196:199], v[8:11]
	v_mfma_f32_16x16x32_bf16 v[0:3], v[212:215], v[196:199], v[0:3]
	s_setprio 0
	s_add_i32 s35, 0, 0x18000
	v_add_u32_e32 v164, s35, v147
	ds_read_b128 v[152:155], v164
	ds_read_b128 v[156:159], v164 offset:1024
	ds_read_b128 v[160:163], v164 offset:2048
	ds_read_b128 v[164:167], v164 offset:3072
	s_add_u32 s14, s80, 0x40000
	s_addc_u32 s15, s81, 0
	s_mov_b32 m0, s82
	v_lshl_add_u64 v[200:201], s[14:15], 0, v[134:135]
	ds_read_b128 v[168:171], v150 offset:32768
	ds_read_b128 v[176:179], v150 offset:34816
	ds_read_b128 v[184:187], v150 offset:36864
	ds_read_b128 v[192:195], v150 offset:38912
	global_load_lds_dwordx4 v[200:201], off
	s_mov_b32 m0, s83
	v_lshl_add_u64 v[200:201], s[14:15], 0, v[130:131]
	global_load_lds_dwordx4 v[200:201], off
	s_waitcnt lgkmcnt(4)
	s_setprio 1
	s_barrier
	ds_read_b128 v[172:175], v150 offset:33792
	ds_read_b128 v[180:183], v150 offset:35840
	ds_read_b128 v[188:191], v150 offset:37888
	ds_read_b128 v[196:199], v150 offset:39936
	s_waitcnt lgkmcnt(4)
	v_mfma_f32_16x16x32_bf16 v[124:127], v[152:155], v[168:171], v[124:127]
	v_mfma_f32_16x16x32_bf16 v[116:119], v[160:163], v[168:171], v[116:119]
	v_mfma_f32_16x16x32_bf16 v[108:111], v[152:155], v[176:179], v[108:111]
	v_mfma_f32_16x16x32_bf16 v[100:103], v[160:163], v[176:179], v[100:103]
	v_mfma_f32_16x16x32_bf16 v[92:95], v[152:155], v[184:187], v[92:95]
	v_mfma_f32_16x16x32_bf16 v[84:87], v[160:163], v[184:187], v[84:87]
	v_mfma_f32_16x16x32_bf16 v[76:79], v[152:155], v[192:195], v[76:79]
	v_mfma_f32_16x16x32_bf16 v[68:71], v[160:163], v[192:195], v[68:71]
	s_waitcnt lgkmcnt(3)
	v_mfma_f32_16x16x32_bf16 v[124:127], v[156:159], v[172:175], v[124:127]
	v_mfma_f32_16x16x32_bf16 v[116:119], v[164:167], v[172:175], v[116:119]
	s_waitcnt lgkmcnt(2)
	v_mfma_f32_16x16x32_bf16 v[108:111], v[156:159], v[180:183], v[108:111]
	v_mfma_f32_16x16x32_bf16 v[100:103], v[164:167], v[180:183], v[100:103]
	s_waitcnt lgkmcnt(1)
	v_mfma_f32_16x16x32_bf16 v[92:95], v[156:159], v[188:191], v[92:95]
	v_mfma_f32_16x16x32_bf16 v[84:87], v[164:167], v[188:191], v[84:87]
	s_waitcnt lgkmcnt(0)
	s_setprio 2
	s_barrier
	v_mfma_f32_16x16x32_bf16 v[76:79], v[156:159], v[196:199], v[76:79]
	v_mfma_f32_16x16x32_bf16 v[68:71], v[164:167], v[196:199], v[68:71]
	s_setprio 0
	s_add_i32 s80, 0, 0x1c000
	s_add_i32 s14, s35, s7
	v_add_u32_e32 v212, s80, v147
	v_lshl_add_u64 v[144:145], v[144:145], 0, s[4:5]
	s_mov_b32 m0, s14
	ds_read_b128 v[200:203], v212
	ds_read_b128 v[204:207], v212 offset:1024
	ds_read_b128 v[208:211], v212 offset:2048
	ds_read_b128 v[212:215], v212 offset:3072
	global_load_lds_dwordx4 v[144:145], off
	s_add_i32 m0, s14, 0x2000
	v_lshl_add_u64 v[144:145], v[216:217], 0, s[4:5]
	global_load_lds_dwordx4 v[144:145], off
	s_setprio 1
	s_barrier
	s_waitcnt lgkmcnt(0)
	v_mfma_f32_16x16x32_bf16 v[120:123], v[200:203], v[168:171], v[120:123]
	v_mfma_f32_16x16x32_bf16 v[112:115], v[208:211], v[168:171], v[112:115]
	v_mfma_f32_16x16x32_bf16 v[104:107], v[200:203], v[176:179], v[104:107]
	v_mfma_f32_16x16x32_bf16 v[96:99], v[208:211], v[176:179], v[96:99]
	v_mfma_f32_16x16x32_bf16 v[88:91], v[200:203], v[184:187], v[88:91]
	v_mfma_f32_16x16x32_bf16 v[80:83], v[208:211], v[184:187], v[80:83]
	v_mfma_f32_16x16x32_bf16 v[72:75], v[200:203], v[192:195], v[72:75]
	v_mfma_f32_16x16x32_bf16 v[64:67], v[208:211], v[192:195], v[64:67]
	v_mfma_f32_16x16x32_bf16 v[120:123], v[204:207], v[172:175], v[120:123]
	v_mfma_f32_16x16x32_bf16 v[112:115], v[212:215], v[172:175], v[112:115]
	v_mfma_f32_16x16x32_bf16 v[104:107], v[204:207], v[180:183], v[104:107]
	v_mfma_f32_16x16x32_bf16 v[96:99], v[212:215], v[180:183], v[96:99]
	v_mfma_f32_16x16x32_bf16 v[88:91], v[204:207], v[188:191], v[88:91]
	v_mfma_f32_16x16x32_bf16 v[80:83], v[212:215], v[188:191], v[80:83]
	s_setprio 2
	s_barrier
	v_mfma_f32_16x16x32_bf16 v[72:75], v[204:207], v[196:199], v[72:75]
	v_mfma_f32_16x16x32_bf16 v[64:67], v[212:215], v[196:199], v[64:67]
	s_setprio 0
	s_mov_b32 m0, s85
	v_lshl_add_u64 v[144:145], v[218:219], 0, s[4:5]
	ds_read_b128 v[168:171], v150 offset:49152
	ds_read_b128 v[176:179], v150 offset:51200
	ds_read_b128 v[184:187], v150 offset:53248
	ds_read_b128 v[192:195], v150 offset:55296
	global_load_lds_dwordx4 v[144:145], off
	s_mov_b32 m0, s86
	v_lshl_add_u64 v[144:145], v[220:221], 0, s[4:5]
	global_load_lds_dwordx4 v[144:145], off
	s_setprio 1
	s_barrier
; DI unsigned pk_bf16(float lo, float hi) { f32x2 v = {lo, hi}; return __builtin_bit_cast(unsigned, __builtin_convertvector(v, bf16v2)); }
; DI float fast_silu(float x) { return x * fast_sigmoid(x); }
; #define PG8_STAGE(bufoff, gbase, voff) do { _Pragma("unroll") for (int _i = 0; _i < 2; ++_i) \
;         __builtin_amdgcn_global_load_lds((const unsigned*)((const char*)(gbase) + (voff)[_i]), (LAS unsigned*)(lds + (bufoff) + ldsw + _i * 8192), 16, 0, 0); } while (0)
; #define PG8_LDA(dst, b, h) do { _Pragma("unroll") for (int m = 0; m < 4; ++m) _Pragma("unroll") for (int k = 0; k < 2; ++k) dst[m][k] = *(const LAS bf16x8*)(lds + PG8_SA(b, h) + aoff + m * 2048 + k * 1024); } while (0)
; #define PG8_MMA(ai, bj, At, Bt) do { __builtin_amdgcn_s_setprio(1); _Pragma("unroll") for (int m = 0; m < 4; ++m) _Pragma("unroll") for (int n = 0; n < 2; ++n) _Pragma("unroll") for (int k = 0; k < 2; ++k) \
;         acc[ai][bj][m][n] = __builtin_amdgcn_mfma_f32_16x16x32_bf16(Bt[n][k], At[m][k], acc[ai][bj][m][n], 0, 0, 0); __builtin_amdgcn_s_setprio(0); } while (0)
; #define PG8_WAIT_V(n) asm volatile("s_waitcnt vmcnt(" #n ")" ::: "memory")
; template <class Epi>
; DI void gemm_phase(LAS unsigned char* lds, const Gemm g, const StaticOrder S, const Epi E) {
;     ...
;             PG8_LDA(At, 1, 1); PG8_STAGE(PG8_SA(1, 0), a3, voffA);
;             PG8_BAR; PG8_WAIT_L(0); PG8_MMA(1, 0, At, B0); PG8_BAR; PG8_SCHED;
;             PG8_STAGE(PG8_SB(1, 1), b3 + hstep, voffB);
;             PG8_WAIT_V(6); PG8_BAR; PG8_MMA(1, 1, At, B1); PG8_BAR;
;     DI void operator()(AccRef acc, const Unit& u, int wr, int wc, int fr, int fq) const {
;     ...
; #pragma unroll
;         for (int ai = 0; ai < 2; ++ai)
; #pragma unroll
;             for (int m = 0; m < 4; ++m) {
;                 const int row = row0 + ai * 128 + m * 16;
;                 const float r = RS ? rsc.r[ai][m] : 1.0f;
;                 const f32x4 a0 = acc[ai][0][m][0] * r, a1 = acc[ai][0][m][1] * r, b0 = acc[ai][1][m][0] * r, b1 = acc[ai][1][m][1] * r;
;                 u32x4 w;
;                 w.x = pk_bf16(fast_silu(a0[0]) * b0[0], fast_silu(a0[1]) * b0[1]); w.y = pk_bf16(fast_silu(a0[2]) * b0[2], fast_silu(a0[3]) * b0[3]);
;                 w.z = pk_bf16(fast_silu(a1[0]) * b1[0], fast_silu(a1[1]) * b1[1]); w.w = pk_bf16(fast_silu(a1[2]) * b1[2], fast_silu(a1[3]) * b1[3]);
;                 *(u32x4*)(G + (size_t)row * DFF + col) = w;
	ds_read_b128 v[172:175], v150 offset:50176
	ds_read_b128 v[180:183], v150 offset:52224
	ds_read_b128 v[188:191], v150 offset:54272
	ds_read_b128 v[196:199], v150 offset:56320
	s_waitcnt lgkmcnt(4)
	v_mfma_f32_16x16x32_bf16 v[60:63], v[152:155], v[168:171], v[60:63]
	v_mfma_f32_16x16x32_bf16 v[52:55], v[160:163], v[168:171], v[52:55]
	v_mfma_f32_16x16x32_bf16 v[44:47], v[152:155], v[176:179], v[44:47]
	v_mfma_f32_16x16x32_bf16 v[36:39], v[160:163], v[176:179], v[36:39]
	v_mfma_f32_16x16x32_bf16 v[28:31], v[152:155], v[184:187], v[28:31]
	v_mfma_f32_16x16x32_bf16 v[20:23], v[160:163], v[184:187], v[20:23]
	v_mfma_f32_16x16x32_bf16 v[12:15], v[152:155], v[192:195], v[12:15]
	v_mfma_f32_16x16x32_bf16 v[4:7], v[160:163], v[192:195], v[4:7]
	s_waitcnt lgkmcnt(3)
	v_mfma_f32_16x16x32_bf16 v[60:63], v[156:159], v[172:175], v[60:63]
	v_mfma_f32_16x16x32_bf16 v[52:55], v[164:167], v[172:175], v[52:55]
	s_waitcnt lgkmcnt(2)
	v_mfma_f32_16x16x32_bf16 v[44:47], v[156:159], v[180:183], v[44:47]
	v_mfma_f32_16x16x32_bf16 v[36:39], v[164:167], v[180:183], v[36:39]
	s_waitcnt lgkmcnt(1)
	v_mfma_f32_16x16x32_bf16 v[28:31], v[156:159], v[188:191], v[28:31]
	v_mfma_f32_16x16x32_bf16 v[20:23], v[164:167], v[188:191], v[20:23]
	s_waitcnt lgkmcnt(0)
	s_setprio 2
	s_barrier
	v_mfma_f32_16x16x32_bf16 v[12:15], v[156:159], v[196:199], v[12:15]
	v_mfma_f32_16x16x32_bf16 v[4:7], v[164:167], v[196:199], v[4:7]
	s_setprio 0
	s_add_u32 s14, s78, 0x40080
	s_addc_u32 s15, s79, 0
	s_add_i32 s35, s80, s7
	s_mov_b32 m0, s35
	v_lshl_add_u64 v[144:145], s[14:15], 0, v[132:133]
	global_load_lds_dwordx4 v[144:145], off
	s_add_i32 m0, s35, 0x2000
	v_lshl_add_u64 v[144:145], s[14:15], 0, v[128:129]
	global_load_lds_dwordx4 v[144:145], off
	s_waitcnt vmcnt(6)
	s_setprio 1
	s_barrier
	v_mfma_f32_16x16x32_bf16 v[56:59], v[200:203], v[168:171], v[56:59]
	v_mfma_f32_16x16x32_bf16 v[48:51], v[208:211], v[168:171], v[48:51]
	v_mfma_f32_16x16x32_bf16 v[40:43], v[200:203], v[176:179], v[40:43]
	v_mfma_f32_16x16x32_bf16 v[32:35], v[208:211], v[176:179], v[32:35]
	v_mfma_f32_16x16x32_bf16 v[24:27], v[200:203], v[184:187], v[24:27]
	v_mfma_f32_16x16x32_bf16 v[16:19], v[208:211], v[184:187], v[16:19]
	v_mfma_f32_16x16x32_bf16 v[8:11], v[200:203], v[192:195], v[8:11]
	v_mfma_f32_16x16x32_bf16 v[0:3], v[208:211], v[192:195], v[0:3]
	v_mfma_f32_16x16x32_bf16 v[56:59], v[204:207], v[172:175], v[56:59]
	v_mfma_f32_16x16x32_bf16 v[48:51], v[212:215], v[172:175], v[48:51]
	v_mfma_f32_16x16x32_bf16 v[40:43], v[204:207], v[180:183], v[40:43]
	v_mfma_f32_16x16x32_bf16 v[32:35], v[212:215], v[180:183], v[32:35]
	v_mfma_f32_16x16x32_bf16 v[24:27], v[204:207], v[188:191], v[24:27]
	v_mfma_f32_16x16x32_bf16 v[16:19], v[212:215], v[188:191], v[16:19]
	s_setprio 2
	s_barrier
	v_mfma_f32_16x16x32_bf16 v[8:11], v[204:207], v[196:199], v[8:11]
	v_mfma_f32_16x16x32_bf16 v[0:3], v[212:215], v[196:199], v[0:3]
	s_setprio 0
	s_add_i32 s97, s97, 2
	s_add_u32 s76, s76, 0x100
	s_addc_u32 s77, s77, 0
	s_add_u32 s95, s95, 0x100
	s_addc_u32 s96, s96, 0
	s_cmp_gt_u32 s97, 13
	s_cbranch_scc0 .LBB0_107
	v_mul_f32_e32 v153, 0xbfb8aa3b, v124
	v_exp_f32_e32 v153, v153
	v_mul_f32_e32 v154, 0xbfb8aa3b, v125
	v_exp_f32_e32 v155, v154
	v_lshl_or_b32 v144, s92, 7, v148
	v_add_f32_e32 v153, 1.0, v153
	v_rcp_f32_e32 v154, v153
	v_add_f32_e32 v153, 1.0, v155
	v_mul_f32_e32 v155, 0xbfb8aa3b, v126
	v_exp_f32_e32 v156, v155
	v_mul_f32_e32 v155, 0xbfb8aa3b, v127
	v_exp_f32_e32 v157, v155
	v_rcp_f32_e32 v155, v153
	v_add_f32_e32 v153, 1.0, v156
	v_rcp_f32_e32 v156, v153
	v_add_f32_e32 v153, 1.0, v157
	v_rcp_f32_e32 v157, v153
	v_pk_mul_f32 v[124:125], v[124:125], v[154:155]
	v_ashrrev_i32_e32 v145, 31, v144
	v_pk_mul_f32 v[120:121], v[124:125], v[120:121]
	v_pk_mul_f32 v[124:125], v[126:127], v[156:157]
	v_cvt_pk_bf16_f32 v120, v120, v121
	v_mul_f32_e32 v121, 0xbfb8aa3b, v116
	v_pk_mul_f32 v[122:123], v[124:125], v[122:123]
	v_exp_f32_e32 v124, v121
	v_mul_f32_e32 v121, 0xbfb8aa3b, v117
	v_exp_f32_e32 v125, v121
	v_cvt_pk_bf16_f32 v121, v122, v123
	v_add_f32_e32 v122, 1.0, v124
	v_mul_f32_e32 v124, 0xbfb8aa3b, v118
	v_add_f32_e32 v123, 1.0, v125
	v_mul_f32_e32 v125, 0xbfb8aa3b, v119
	v_exp_f32_e32 v124, v124
	v_exp_f32_e32 v125, v125
	v_rcp_f32_e32 v122, v122
	v_rcp_f32_e32 v123, v123
	v_add_f32_e32 v124, 1.0, v124
	v_add_f32_e32 v125, 1.0, v125
	v_rcp_f32_e32 v124, v124
	v_rcp_f32_e32 v125, v125
	v_pk_mul_f32 v[116:117], v[116:117], v[122:123]
	v_lshl_add_u32 v152, s28, 8, v146
	v_pk_mul_f32 v[112:113], v[116:117], v[112:113]
	v_lshl_add_u64 v[144:145], v[144:145], 1, s[54:55]
	v_cvt_pk_bf16_f32 v122, v112, v113
	v_pk_mul_f32 v[112:113], v[118:119], v[124:125]
	v_or_b32_e32 v116, 16, v152
	v_pk_mul_f32 v[112:113], v[112:113], v[114:115]
	v_mul_f32_e32 v114, 0xbfb8aa3b, v110
	v_cvt_pk_bf16_f32 v123, v112, v113
	v_mad_i64_i32 v[112:113], s[14:15], v152, s91, v[144:145]
	global_store_dwordx4 v[112:113], v[120:123], off
	v_mul_f32_e32 v112, 0xbfb8aa3b, v108
	v_mul_f32_e32 v113, 0xbfb8aa3b, v109
	v_exp_f32_e32 v112, v112
	v_exp_f32_e32 v113, v113
	v_mul_f32_e32 v115, 0xbfb8aa3b, v111
	v_exp_f32_e32 v114, v114
	v_exp_f32_e32 v115, v115
	v_add_f32_e32 v112, 1.0, v112
	v_add_f32_e32 v113, 1.0, v113
	v_rcp_f32_e32 v112, v112
	v_rcp_f32_e32 v113, v113
	v_add_f32_e32 v114, 1.0, v114
	v_add_f32_e32 v115, 1.0, v115
	v_rcp_f32_e32 v114, v114
	v_rcp_f32_e32 v115, v115
	v_pk_mul_f32 v[108:109], v[108:109], v[112:113]
	s_and_b64 vcc, exec, s[0:1]
	v_pk_mul_f32 v[104:105], v[108:109], v[104:105]
	v_pk_mul_f32 v[108:109], v[110:111], v[114:115]
	v_cvt_pk_bf16_f32 v104, v104, v105
	v_mul_f32_e32 v105, 0xbfb8aa3b, v100
	v_pk_mul_f32 v[106:107], v[108:109], v[106:107]
; DI unsigned pk_bf16(float lo, float hi) { f32x2 v = {lo, hi}; return __builtin_bit_cast(unsigned, __builtin_convertvector(v, bf16v2)); }
; DI float fast_silu(float x) { return x * fast_sigmoid(x); }
;     DI void operator()(AccRef acc, const Unit& u, int wr, int wc, int fr, int fq) const {
;     ...
; #pragma unroll
;         for (int ai = 0; ai < 2; ++ai)
; #pragma unroll
;             for (int m = 0; m < 4; ++m) {
;                 const int row = row0 + ai * 128 + m * 16;
;                 const float r = RS ? rsc.r[ai][m] : 1.0f;
;                 const f32x4 a0 = acc[ai][0][m][0] * r, a1 = acc[ai][0][m][1] * r, b0 = acc[ai][1][m][0] * r, b1 = acc[ai][1][m][1] * r;
;                 u32x4 w;
;                 w.x = pk_bf16(fast_silu(a0[0]) * b0[0], fast_silu(a0[1]) * b0[1]); w.y = pk_bf16(fast_silu(a0[2]) * b0[2], fast_silu(a0[3]) * b0[3]);
;                 w.z = pk_bf16(fast_silu(a1[0]) * b1[0], fast_silu(a1[1]) * b1[1]); w.w = pk_bf16(fast_silu(a1[2]) * b1[2], fast_silu(a1[3]) * b1[3]);
;                 *(u32x4*)(G + (size_t)row * DFF + col) = w;
	v_exp_f32_e32 v108, v105
	v_mul_f32_e32 v105, 0xbfb8aa3b, v101
	v_exp_f32_e32 v109, v105
	v_cvt_pk_bf16_f32 v105, v106, v107
	v_add_f32_e32 v106, 1.0, v108
	v_mul_f32_e32 v108, 0xbfb8aa3b, v102
	v_add_f32_e32 v107, 1.0, v109
	v_mul_f32_e32 v109, 0xbfb8aa3b, v103
	v_exp_f32_e32 v108, v108
	v_exp_f32_e32 v109, v109
	v_rcp_f32_e32 v106, v106
	v_rcp_f32_e32 v107, v107
	v_add_f32_e32 v108, 1.0, v108
	v_add_f32_e32 v109, 1.0, v109
	v_rcp_f32_e32 v108, v108
	v_rcp_f32_e32 v109, v109
	v_pk_mul_f32 v[100:101], v[100:101], v[106:107]
	s_mov_b32 s92, s8
	v_pk_mul_f32 v[96:97], v[100:101], v[96:97]
	v_or_b32_e32 v100, 32, v152
	v_cvt_pk_bf16_f32 v106, v96, v97
	v_pk_mul_f32 v[96:97], v[102:103], v[108:109]
	s_mov_b32 s28, s10
	v_pk_mul_f32 v[96:97], v[96:97], v[98:99]
	v_mul_f32_e32 v98, 0xbfb8aa3b, v94
	v_cvt_pk_bf16_f32 v107, v96, v97
	v_mad_i64_i32 v[96:97], s[14:15], v116, s91, v[144:145]
	global_store_dwordx4 v[96:97], v[104:107], off
	v_mul_f32_e32 v96, 0xbfb8aa3b, v92
	v_mul_f32_e32 v97, 0xbfb8aa3b, v93
	v_exp_f32_e32 v96, v96
	v_exp_f32_e32 v97, v97
	v_mul_f32_e32 v99, 0xbfb8aa3b, v95
	v_exp_f32_e32 v98, v98
	v_exp_f32_e32 v99, v99
	v_add_f32_e32 v96, 1.0, v96
	v_add_f32_e32 v97, 1.0, v97
	v_rcp_f32_e32 v96, v96
	v_rcp_f32_e32 v97, v97
	v_add_f32_e32 v98, 1.0, v98
	v_add_f32_e32 v99, 1.0, v99
	v_rcp_f32_e32 v98, v98
	v_rcp_f32_e32 v99, v99
	v_pk_mul_f32 v[92:93], v[92:93], v[96:97]
	s_mov_b64 s[78:79], s[26:27]
	v_pk_mul_f32 v[88:89], v[92:93], v[88:89]
	v_pk_mul_f32 v[92:93], v[94:95], v[98:99]
	v_cvt_pk_bf16_f32 v88, v88, v89
	v_mul_f32_e32 v89, 0xbfb8aa3b, v84
	v_pk_mul_f32 v[90:91], v[92:93], v[90:91]
	v_exp_f32_e32 v92, v89
	v_mul_f32_e32 v89, 0xbfb8aa3b, v85
	v_exp_f32_e32 v93, v89
	v_cvt_pk_bf16_f32 v89, v90, v91
	v_add_f32_e32 v90, 1.0, v92
	v_mul_f32_e32 v92, 0xbfb8aa3b, v86
	v_add_f32_e32 v91, 1.0, v93
	v_mul_f32_e32 v93, 0xbfb8aa3b, v87
	v_exp_f32_e32 v92, v92
	v_exp_f32_e32 v93, v93
	v_rcp_f32_e32 v90, v90
	v_rcp_f32_e32 v91, v91
	v_add_f32_e32 v92, 1.0, v92
	v_add_f32_e32 v93, 1.0, v93
	v_rcp_f32_e32 v92, v92
	v_rcp_f32_e32 v93, v93
	v_pk_mul_f32 v[84:85], v[84:85], v[90:91]
	s_mov_b64 s[76:77], s[24:25]
	v_pk_mul_f32 v[80:81], v[84:85], v[80:81]
	v_or_b32_e32 v84, 48, v152
	v_cvt_pk_bf16_f32 v90, v80, v81
	v_pk_mul_f32 v[80:81], v[86:87], v[92:93]
	s_nop 0
	v_pk_mul_f32 v[80:81], v[80:81], v[82:83]
	v_mul_f32_e32 v82, 0xbfb8aa3b, v78
	v_cvt_pk_bf16_f32 v91, v80, v81
	v_mad_i64_i32 v[80:81], s[14:15], v100, s91, v[144:145]
	global_store_dwordx4 v[80:81], v[88:91], off
	v_mul_f32_e32 v80, 0xbfb8aa3b, v76
	v_mul_f32_e32 v81, 0xbfb8aa3b, v77
	v_exp_f32_e32 v80, v80
	v_exp_f32_e32 v81, v81
	v_mul_f32_e32 v83, 0xbfb8aa3b, v79
	v_exp_f32_e32 v82, v82
	v_exp_f32_e32 v83, v83
	v_add_f32_e32 v80, 1.0, v80
	v_add_f32_e32 v81, 1.0, v81
	v_rcp_f32_e32 v80, v80
	v_rcp_f32_e32 v81, v81
	v_add_f32_e32 v82, 1.0, v82
	v_add_f32_e32 v83, 1.0, v83
	v_rcp_f32_e32 v82, v82
	v_rcp_f32_e32 v83, v83
	v_pk_mul_f32 v[76:77], v[76:77], v[80:81]
	s_nop 0
	v_pk_mul_f32 v[72:73], v[76:77], v[72:73]
	v_pk_mul_f32 v[76:77], v[78:79], v[82:83]
	v_cvt_pk_bf16_f32 v72, v72, v73
	v_mul_f32_e32 v73, 0xbfb8aa3b, v68
	v_pk_mul_f32 v[74:75], v[76:77], v[74:75]
	v_exp_f32_e32 v76, v73
	v_mul_f32_e32 v73, 0xbfb8aa3b, v69
	v_exp_f32_e32 v77, v73
	v_cvt_pk_bf16_f32 v73, v74, v75
	v_add_f32_e32 v74, 1.0, v76
	v_mul_f32_e32 v76, 0xbfb8aa3b, v70
	v_add_f32_e32 v75, 1.0, v77
	v_mul_f32_e32 v77, 0xbfb8aa3b, v71
	v_exp_f32_e32 v76, v76
	v_exp_f32_e32 v77, v77
	v_rcp_f32_e32 v74, v74
	v_rcp_f32_e32 v75, v75
	v_add_f32_e32 v76, 1.0, v76
	v_add_f32_e32 v77, 1.0, v77
	v_rcp_f32_e32 v76, v76
	v_rcp_f32_e32 v77, v77
	v_pk_mul_f32 v[68:69], v[68:69], v[74:75]
	s_nop 0
	v_pk_mul_f32 v[64:65], v[68:69], v[64:65]
	v_add_u32_e32 v68, 0x80, v152
	v_cvt_pk_bf16_f32 v74, v64, v65
	v_pk_mul_f32 v[64:65], v[70:71], v[76:77]
	s_nop 0
	v_pk_mul_f32 v[64:65], v[64:65], v[66:67]
	v_mul_f32_e32 v66, 0xbfb8aa3b, v62
	v_cvt_pk_bf16_f32 v75, v64, v65
	v_mad_i64_i32 v[64:65], s[14:15], v84, s91, v[144:145]
	global_store_dwordx4 v[64:65], v[72:75], off
	v_mul_f32_e32 v64, 0xbfb8aa3b, v60
	v_mul_f32_e32 v65, 0xbfb8aa3b, v61
	v_exp_f32_e32 v64, v64
	v_exp_f32_e32 v65, v65
	v_mul_f32_e32 v67, 0xbfb8aa3b, v63
	v_exp_f32_e32 v66, v66
	v_exp_f32_e32 v67, v67
	v_add_f32_e32 v64, 1.0, v64
	v_add_f32_e32 v65, 1.0, v65
	v_rcp_f32_e32 v64, v64
	v_rcp_f32_e32 v65, v65
	v_add_f32_e32 v66, 1.0, v66
	v_add_f32_e32 v67, 1.0, v67
	v_rcp_f32_e32 v66, v66
	v_rcp_f32_e32 v67, v67
	v_pk_mul_f32 v[60:61], v[60:61], v[64:65]
	s_nop 0
	v_pk_mul_f32 v[56:57], v[60:61], v[56:57]
	v_pk_mul_f32 v[60:61], v[62:63], v[66:67]
	v_cvt_pk_bf16_f32 v56, v56, v57
	v_mul_f32_e32 v57, 0xbfb8aa3b, v52
	v_pk_mul_f32 v[58:59], v[60:61], v[58:59]
	v_exp_f32_e32 v60, v57
	v_mul_f32_e32 v57, 0xbfb8aa3b, v53
	v_exp_f32_e32 v61, v57
	v_cvt_pk_bf16_f32 v57, v58, v59
	v_add_f32_e32 v58, 1.0, v60
	v_mul_f32_e32 v60, 0xbfb8aa3b, v54
	v_add_f32_e32 v59, 1.0, v61
	v_mul_f32_e32 v61, 0xbfb8aa3b, v55
	v_exp_f32_e32 v60, v60
	v_exp_f32_e32 v61, v61
	v_rcp_f32_e32 v58, v58
	v_rcp_f32_e32 v59, v59
	v_add_f32_e32 v60, 1.0, v60
	v_add_f32_e32 v61, 1.0, v61
	v_rcp_f32_e32 v60, v60
; DI unsigned pk_bf16(float lo, float hi) { f32x2 v = {lo, hi}; return __builtin_bit_cast(unsigned, __builtin_convertvector(v, bf16v2)); }
; DI float fast_silu(float x) { return x * fast_sigmoid(x); }
; #define PG8_WAIT_V(n) asm volatile("s_waitcnt vmcnt(" #n ")" ::: "memory")
; #define PG8_BAR __builtin_amdgcn_s_barrier()
; #define PG8_WAIT_V(n) asm volatile("s_waitcnt vmcnt(" #n ")" ::: "memory")
; #define PG8_BAR __builtin_amdgcn_s_barrier()
; template <class Epi>
; DI void gemm_phase(LAS unsigned char* lds, const Gemm g, const StaticOrder S, const Epi E) {
;     ...
;         E(acc, cur, wr, wc, fr, fq);
;         if (!has_next) break;
; #pragma unroll
;         for (int a = 0; a < 2; ++a)
; #pragma unroll
;             for (int b = 0; b < 2; ++b)
; #pragma unroll
;                 for (int m = 0; m < 4; ++m)
; #pragma unroll
;                     for (int n = 0; n < 2; ++n) acc[a][b][m][n] = (f32x4){0.f, 0.f, 0.f, 0.f};
;         cur = nxt; cA = nA; cB = nB; ++ui;
;     }
;     PG8_WAIT_V(0);
;     if (wr == 0) PG8_BAR;
;     PG8_BAR;
;     DI void operator()(AccRef acc, const Unit& u, int wr, int wc, int fr, int fq) const {
;     ...
; #pragma unroll
;         for (int ai = 0; ai < 2; ++ai)
; #pragma unroll
;             for (int m = 0; m < 4; ++m) {
;                 const int row = row0 + ai * 128 + m * 16;
;                 const float r = RS ? rsc.r[ai][m] : 1.0f;
;                 const f32x4 a0 = acc[ai][0][m][0] * r, a1 = acc[ai][0][m][1] * r, b0 = acc[ai][1][m][0] * r, b1 = acc[ai][1][m][1] * r;
;                 u32x4 w;
;                 w.x = pk_bf16(fast_silu(a0[0]) * b0[0], fast_silu(a0[1]) * b0[1]); w.y = pk_bf16(fast_silu(a0[2]) * b0[2], fast_silu(a0[3]) * b0[3]);
;                 w.z = pk_bf16(fast_silu(a1[0]) * b1[0], fast_silu(a1[1]) * b1[1]); w.w = pk_bf16(fast_silu(a1[2]) * b1[2], fast_silu(a1[3]) * b1[3]);
;                 *(u32x4*)(G + (size_t)row * DFF + col) = w;
	v_rcp_f32_e32 v61, v61
	v_pk_mul_f32 v[52:53], v[52:53], v[58:59]
	s_nop 0
	v_pk_mul_f32 v[48:49], v[52:53], v[48:49]
	v_add_u32_e32 v52, 0x90, v152
	v_cvt_pk_bf16_f32 v58, v48, v49
	v_pk_mul_f32 v[48:49], v[54:55], v[60:61]
	s_nop 0
	v_pk_mul_f32 v[48:49], v[48:49], v[50:51]
	v_mul_f32_e32 v50, 0xbfb8aa3b, v46
	v_cvt_pk_bf16_f32 v59, v48, v49
	v_mad_i64_i32 v[48:49], s[14:15], v68, s91, v[144:145]
	global_store_dwordx4 v[48:49], v[56:59], off
	v_mul_f32_e32 v48, 0xbfb8aa3b, v44
	v_mul_f32_e32 v49, 0xbfb8aa3b, v45
	v_exp_f32_e32 v48, v48
	v_exp_f32_e32 v49, v49
	v_mul_f32_e32 v51, 0xbfb8aa3b, v47
	v_exp_f32_e32 v50, v50
	v_exp_f32_e32 v51, v51
	v_add_f32_e32 v48, 1.0, v48
	v_add_f32_e32 v49, 1.0, v49
	v_rcp_f32_e32 v48, v48
	v_rcp_f32_e32 v49, v49
	v_add_f32_e32 v50, 1.0, v50
	v_add_f32_e32 v51, 1.0, v51
	v_rcp_f32_e32 v50, v50
	v_rcp_f32_e32 v51, v51
	v_pk_mul_f32 v[44:45], v[44:45], v[48:49]
	s_nop 0
	v_pk_mul_f32 v[40:41], v[44:45], v[40:41]
	v_pk_mul_f32 v[44:45], v[46:47], v[50:51]
	v_cvt_pk_bf16_f32 v40, v40, v41
	v_mul_f32_e32 v41, 0xbfb8aa3b, v36
	v_pk_mul_f32 v[42:43], v[44:45], v[42:43]
	v_exp_f32_e32 v44, v41
	v_mul_f32_e32 v41, 0xbfb8aa3b, v37
	v_exp_f32_e32 v45, v41
	v_cvt_pk_bf16_f32 v41, v42, v43
	v_add_f32_e32 v42, 1.0, v44
	v_mul_f32_e32 v44, 0xbfb8aa3b, v38
	v_add_f32_e32 v43, 1.0, v45
	v_mul_f32_e32 v45, 0xbfb8aa3b, v39
	v_exp_f32_e32 v44, v44
	v_exp_f32_e32 v45, v45
	v_rcp_f32_e32 v42, v42
	v_rcp_f32_e32 v43, v43
	v_add_f32_e32 v44, 1.0, v44
	v_add_f32_e32 v45, 1.0, v45
	v_rcp_f32_e32 v44, v44
	v_rcp_f32_e32 v45, v45
	v_pk_mul_f32 v[36:37], v[36:37], v[42:43]
	s_nop 0
	v_pk_mul_f32 v[32:33], v[36:37], v[32:33]
	v_add_u32_e32 v36, 0xa0, v152
	v_cvt_pk_bf16_f32 v42, v32, v33
	v_pk_mul_f32 v[32:33], v[38:39], v[44:45]
	s_nop 0
	v_pk_mul_f32 v[32:33], v[32:33], v[34:35]
	v_mul_f32_e32 v34, 0xbfb8aa3b, v30
	v_cvt_pk_bf16_f32 v43, v32, v33
	v_mad_i64_i32 v[32:33], s[14:15], v52, s91, v[144:145]
	global_store_dwordx4 v[32:33], v[40:43], off
	v_mul_f32_e32 v32, 0xbfb8aa3b, v28
	v_mul_f32_e32 v33, 0xbfb8aa3b, v29
	v_exp_f32_e32 v32, v32
	v_exp_f32_e32 v33, v33
	v_mul_f32_e32 v35, 0xbfb8aa3b, v31
	v_exp_f32_e32 v34, v34
	v_exp_f32_e32 v35, v35
	v_add_f32_e32 v32, 1.0, v32
	v_add_f32_e32 v33, 1.0, v33
	v_rcp_f32_e32 v32, v32
	v_rcp_f32_e32 v33, v33
	v_add_f32_e32 v34, 1.0, v34
	v_add_f32_e32 v35, 1.0, v35
	v_rcp_f32_e32 v34, v34
	v_rcp_f32_e32 v35, v35
	v_pk_mul_f32 v[28:29], v[28:29], v[32:33]
	s_nop 0
	v_pk_mul_f32 v[24:25], v[28:29], v[24:25]
	v_pk_mul_f32 v[28:29], v[30:31], v[34:35]
	v_cvt_pk_bf16_f32 v24, v24, v25
	v_mul_f32_e32 v25, 0xbfb8aa3b, v20
	v_pk_mul_f32 v[26:27], v[28:29], v[26:27]
	v_exp_f32_e32 v28, v25
	v_mul_f32_e32 v25, 0xbfb8aa3b, v21
	v_exp_f32_e32 v29, v25
	v_cvt_pk_bf16_f32 v25, v26, v27
	v_add_f32_e32 v26, 1.0, v28
	v_mul_f32_e32 v28, 0xbfb8aa3b, v22
	v_add_f32_e32 v27, 1.0, v29
	v_mul_f32_e32 v29, 0xbfb8aa3b, v23
	v_exp_f32_e32 v28, v28
	v_exp_f32_e32 v29, v29
	v_rcp_f32_e32 v26, v26
	v_rcp_f32_e32 v27, v27
	v_add_f32_e32 v28, 1.0, v28
	v_add_f32_e32 v29, 1.0, v29
	v_rcp_f32_e32 v28, v28
	v_rcp_f32_e32 v29, v29
	v_pk_mul_f32 v[20:21], v[20:21], v[26:27]
	s_nop 0
	v_pk_mul_f32 v[16:17], v[20:21], v[16:17]
	v_add_u32_e32 v20, 0xb0, v152
	v_cvt_pk_bf16_f32 v26, v16, v17
	v_pk_mul_f32 v[16:17], v[22:23], v[28:29]
	s_nop 0
	v_pk_mul_f32 v[16:17], v[16:17], v[18:19]
	v_mul_f32_e32 v18, 0xbfb8aa3b, v14
	v_cvt_pk_bf16_f32 v27, v16, v17
	v_mad_i64_i32 v[16:17], s[14:15], v36, s91, v[144:145]
	global_store_dwordx4 v[16:17], v[24:27], off
	v_mul_f32_e32 v16, 0xbfb8aa3b, v12
	v_mul_f32_e32 v17, 0xbfb8aa3b, v13
	v_exp_f32_e32 v16, v16
	v_exp_f32_e32 v17, v17
	v_mul_f32_e32 v19, 0xbfb8aa3b, v15
	v_exp_f32_e32 v18, v18
	v_exp_f32_e32 v19, v19
	v_add_f32_e32 v16, 1.0, v16
	v_add_f32_e32 v17, 1.0, v17
	v_rcp_f32_e32 v16, v16
	v_rcp_f32_e32 v17, v17
	v_add_f32_e32 v18, 1.0, v18
	v_add_f32_e32 v19, 1.0, v19
	v_rcp_f32_e32 v18, v18
	v_rcp_f32_e32 v19, v19
	v_pk_mul_f32 v[12:13], v[12:13], v[16:17]
	s_nop 0
	v_pk_mul_f32 v[8:9], v[12:13], v[8:9]
	v_pk_mul_f32 v[12:13], v[14:15], v[18:19]
	v_cvt_pk_bf16_f32 v8, v8, v9
	v_mul_f32_e32 v9, 0xbfb8aa3b, v4
	v_pk_mul_f32 v[10:11], v[12:13], v[10:11]
	v_exp_f32_e32 v12, v9
	v_mul_f32_e32 v9, 0xbfb8aa3b, v5
	v_exp_f32_e32 v13, v9
	v_cvt_pk_bf16_f32 v9, v10, v11
	v_add_f32_e32 v10, 1.0, v12
	v_mul_f32_e32 v12, 0xbfb8aa3b, v6
	v_add_f32_e32 v11, 1.0, v13
	v_mul_f32_e32 v13, 0xbfb8aa3b, v7
	v_exp_f32_e32 v12, v12
	v_exp_f32_e32 v13, v13
	v_rcp_f32_e32 v10, v10
	v_rcp_f32_e32 v11, v11
	v_add_f32_e32 v12, 1.0, v12
	v_add_f32_e32 v13, 1.0, v13
	v_rcp_f32_e32 v12, v12
	v_rcp_f32_e32 v13, v13
	v_pk_mul_f32 v[4:5], v[4:5], v[10:11]
	s_nop 0
	v_pk_mul_f32 v[0:1], v[4:5], v[0:1]
	s_nop 0
	v_cvt_pk_bf16_f32 v10, v0, v1
	v_pk_mul_f32 v[0:1], v[6:7], v[12:13]
	s_nop 0
	v_pk_mul_f32 v[0:1], v[0:1], v[2:3]
	s_nop 0
	v_cvt_pk_bf16_f32 v11, v0, v1
	v_mad_i64_i32 v[0:1], s[14:15], v20, s91, v[144:145]
	global_store_dwordx4 v[0:1], v[8:11], off
	s_cbranch_vccz .LBB0_104
	s_waitcnt vmcnt(0)
	v_readlane_b32 s92, v243, 8
	s_cmpk_gt_u32 s6, 0xff
	v_readlane_b32 s93, v243, 9
	s_cbranch_scc1 .LBB0_111
	s_barrier

; #define PG8_STAGE(bufoff, gbase, voff) do { _Pragma("unroll") for (int _i = 0; _i < 2; ++_i) \
;         __builtin_amdgcn_global_load_lds((const unsigned*)((const char*)(gbase) + (voff)[_i]), (LAS unsigned*)(lds + (bufoff) + ldsw + _i * 8192), 16, 0, 0); } while (0)
; #define PG8_LDA(dst, b, h) do { _Pragma("unroll") for (int m = 0; m < 4; ++m) _Pragma("unroll") for (int k = 0; k < 2; ++k) dst[m][k] = *(const LAS bf16x8*)(lds + PG8_SA(b, h) + aoff + m * 2048 + k * 1024); } while (0)
; #define PG8_LDB(dst, b, h) do { _Pragma("unroll") for (int n = 0; n < 2; ++n) _Pragma("unroll") for (int k = 0; k < 2; ++k) dst[n][k] = *(const LAS bf16x8*)(lds + PG8_SB(b, h) + boff + n * 2048 + k * 1024); } while (0)
; #define PG8_MMA(ai, bj, At, Bt) do { __builtin_amdgcn_s_setprio(1); _Pragma("unroll") for (int m = 0; m < 4; ++m) _Pragma("unroll") for (int n = 0; n < 2; ++n) _Pragma("unroll") for (int k = 0; k < 2; ++k) \
;         acc[ai][bj][m][n] = __builtin_amdgcn_mfma_f32_16x16x32_bf16(Bt[n][k], At[m][k], acc[ai][bj][m][n], 0, 0, 0); __builtin_amdgcn_s_setprio(0); } while (0)
; #define PG8_WAIT_V(n) asm volatile("s_waitcnt vmcnt(" #n ")" ::: "memory")
; #define PG8_WAIT_L(n) asm volatile("s_waitcnt lgkmcnt(" #n ")" ::: "memory")
; #define PG8_BAR __builtin_amdgcn_s_barrier()
; #define PG8_SCHED __builtin_amdgcn_sched_barrier(0)
; #define PG8_WAIT_V(n) asm volatile("s_waitcnt vmcnt(" #n ")" ::: "memory")
; template <class Epi>
; DI void gemm_phase(LAS unsigned char* lds, const Gemm g, const StaticOrder S, const Epi E) {
;     ...
;             PG8_LDB(B0, 0, 0); PG8_SCHED; PG8_LDA(At, 0, 0); PG8_STAGE(PG8_SA(1, 1), a1 + hstep, voffA);
;             PG8_WAIT_L(8); PG8_BAR; PG8_WAIT_L(0); PG8_MMA(0, 0, At, B0); PG8_BAR; PG8_SCHED;
;             PG8_LDB(B1, 0, 1); PG8_STAGE(PG8_SB(0, 0), b2, voffB);
;             PG8_BAR; PG8_WAIT_L(0); PG8_MMA(0, 1, At, B1); PG8_BAR;
;             PG8_LDA(At, 0, 1); PG8_STAGE(PG8_SA(0, 0), a2, voffA);
;             PG8_BAR; PG8_WAIT_L(0); PG8_MMA(1, 0, At, B0); PG8_BAR; PG8_SCHED;
;             PG8_STAGE(PG8_SB(0, 1), b2 + hstep, voffB);
;             PG8_WAIT_V(6); PG8_BAR; PG8_MMA(1, 1, At, B1); PG8_BAR;
;             PG8_LDB(B0, 1, 0); PG8_SCHED; PG8_LDA(At, 1, 0); PG8_STAGE(PG8_SA(0, 1), a2 + hstep, voffA);
;             PG8_WAIT_L(8); PG8_BAR; PG8_WAIT_L(0); PG8_MMA(0, 0, At, B0); PG8_BAR; PG8_SCHED;
.LBB0_186:
	ds_read_b128 v[128:131], v207
	ds_read_b128 v[132:135], v207 offset:1024
	ds_read_b128 v[136:139], v207 offset:2048
	ds_read_b128 v[140:143], v207 offset:3072
	s_add_u32 s76, s28, 0x100
	s_addc_u32 s77, s29, 0
	s_cmp_eq_u32 s97, 40
	s_cselect_b32 s81, s9, s77
	s_cselect_b32 s80, s8, s76
	s_cselect_b32 s79, s11, s7
	s_cselect_b32 s78, s10, s6
	v_lshl_add_u64 v[192:193], s[28:29], 0, v[184:185]
	s_add_i32 m0, s82, 0xc000
	ds_read_b128 v[144:147], v208
	ds_read_b128 v[152:155], v208 offset:2048
	ds_read_b128 v[160:163], v208 offset:4096
	ds_read_b128 v[168:171], v208 offset:6144
	global_load_lds_dwordx4 v[192:193], off
	s_add_i32 m0, s82, 0xe000
	v_lshl_add_u64 v[192:193], s[28:29], 0, v[186:187]
	global_load_lds_dwordx4 v[192:193], off
	s_waitcnt lgkmcnt(4)
	s_setprio 1
	s_barrier
	ds_read_b128 v[148:151], v208 offset:1024
	ds_read_b128 v[156:159], v208 offset:3072
	ds_read_b128 v[164:167], v208 offset:5120
	ds_read_b128 v[172:175], v208 offset:7168
	s_waitcnt lgkmcnt(4)
	v_mfma_f32_16x16x32_bf16 v[124:127], v[128:131], v[144:147], v[124:127]
	v_mfma_f32_16x16x32_bf16 v[120:123], v[136:139], v[144:147], v[120:123]
	v_mfma_f32_16x16x32_bf16 v[108:111], v[128:131], v[152:155], v[108:111]
	v_mfma_f32_16x16x32_bf16 v[104:107], v[136:139], v[152:155], v[104:107]
	v_mfma_f32_16x16x32_bf16 v[92:95], v[128:131], v[160:163], v[92:95]
	v_mfma_f32_16x16x32_bf16 v[88:91], v[136:139], v[160:163], v[88:91]
	v_mfma_f32_16x16x32_bf16 v[76:79], v[128:131], v[168:171], v[76:79]
	v_mfma_f32_16x16x32_bf16 v[72:75], v[136:139], v[168:171], v[72:75]
	s_waitcnt lgkmcnt(3)
	v_mfma_f32_16x16x32_bf16 v[124:127], v[132:135], v[148:151], v[124:127]
	v_mfma_f32_16x16x32_bf16 v[120:123], v[140:143], v[148:151], v[120:123]
	s_waitcnt lgkmcnt(2)
	v_mfma_f32_16x16x32_bf16 v[108:111], v[132:135], v[156:159], v[108:111]
	v_mfma_f32_16x16x32_bf16 v[104:107], v[140:143], v[156:159], v[104:107]
	s_waitcnt lgkmcnt(1)
	v_mfma_f32_16x16x32_bf16 v[92:95], v[132:135], v[164:167], v[92:95]
	v_mfma_f32_16x16x32_bf16 v[88:91], v[140:143], v[164:167], v[88:91]
	s_waitcnt lgkmcnt(0)
	s_setprio 2
	s_barrier
	v_mfma_f32_16x16x32_bf16 v[76:79], v[132:135], v[172:175], v[76:79]
	v_mfma_f32_16x16x32_bf16 v[72:75], v[140:143], v[172:175], v[72:75]
	s_setprio 0
	s_add_i32 s14, s91, s59
	v_lshl_add_u64 v[216:217], s[78:79], 0, v[178:179]
	s_mov_b32 m0, s14
	ds_read_b128 v[192:195], v209
	ds_read_b128 v[196:199], v209 offset:1024
	ds_read_b128 v[200:203], v209 offset:2048
	ds_read_b128 v[212:215], v209 offset:3072
	global_load_lds_dwordx4 v[216:217], off
	s_add_i32 m0, s14, 0x2000
	v_lshl_add_u64 v[218:219], s[78:79], 0, v[182:183]
	global_load_lds_dwordx4 v[218:219], off
	s_setprio 1
	s_barrier
	s_waitcnt lgkmcnt(0)
	v_mfma_f32_16x16x32_bf16 v[116:119], v[192:195], v[144:147], v[116:119]
	v_mfma_f32_16x16x32_bf16 v[112:115], v[200:203], v[144:147], v[112:115]
	v_mfma_f32_16x16x32_bf16 v[100:103], v[192:195], v[152:155], v[100:103]
	v_mfma_f32_16x16x32_bf16 v[96:99], v[200:203], v[152:155], v[96:99]
	v_mfma_f32_16x16x32_bf16 v[84:87], v[192:195], v[160:163], v[84:87]
	v_mfma_f32_16x16x32_bf16 v[80:83], v[200:203], v[160:163], v[80:83]
	v_mfma_f32_16x16x32_bf16 v[68:71], v[192:195], v[168:171], v[68:71]
	v_mfma_f32_16x16x32_bf16 v[64:67], v[200:203], v[168:171], v[64:67]
	v_mfma_f32_16x16x32_bf16 v[116:119], v[196:199], v[148:151], v[116:119]
	v_mfma_f32_16x16x32_bf16 v[112:115], v[212:215], v[148:151], v[112:115]
	v_mfma_f32_16x16x32_bf16 v[100:103], v[196:199], v[156:159], v[100:103]
	v_mfma_f32_16x16x32_bf16 v[96:99], v[212:215], v[156:159], v[96:99]
	v_mfma_f32_16x16x32_bf16 v[84:87], v[196:199], v[164:167], v[84:87]
	v_mfma_f32_16x16x32_bf16 v[80:83], v[212:215], v[164:167], v[80:83]
	s_setprio 2
	s_barrier
	v_mfma_f32_16x16x32_bf16 v[68:71], v[196:199], v[172:175], v[68:71]
	v_mfma_f32_16x16x32_bf16 v[64:67], v[212:215], v[172:175], v[64:67]
	s_setprio 0
	s_mov_b32 m0, s82
	v_lshl_add_u64 v[220:221], s[80:81], 0, v[176:177]
	ds_read_b128 v[144:147], v208 offset:16384
	ds_read_b128 v[152:155], v208 offset:18432
	ds_read_b128 v[160:163], v208 offset:20480
	ds_read_b128 v[168:171], v208 offset:22528
	global_load_lds_dwordx4 v[220:221], off
	s_mov_b32 m0, s83
	v_lshl_add_u64 v[224:225], s[80:81], 0, v[180:181]
	global_load_lds_dwordx4 v[224:225], off
	s_setprio 1
	s_barrier
	ds_read_b128 v[148:151], v208 offset:17408
	ds_read_b128 v[156:159], v208 offset:19456
	ds_read_b128 v[164:167], v208 offset:21504
	ds_read_b128 v[172:175], v208 offset:23552
	s_waitcnt lgkmcnt(4)
	v_mfma_f32_16x16x32_bf16 v[60:63], v[128:131], v[144:147], v[60:63]
	v_mfma_f32_16x16x32_bf16 v[56:59], v[136:139], v[144:147], v[56:59]
	v_mfma_f32_16x16x32_bf16 v[44:47], v[128:131], v[152:155], v[44:47]
	v_mfma_f32_16x16x32_bf16 v[40:43], v[136:139], v[152:155], v[40:43]
	v_mfma_f32_16x16x32_bf16 v[28:31], v[128:131], v[160:163], v[28:31]
	v_mfma_f32_16x16x32_bf16 v[24:27], v[136:139], v[160:163], v[24:27]
	v_mfma_f32_16x16x32_bf16 v[12:15], v[128:131], v[168:171], v[12:15]
	v_mfma_f32_16x16x32_bf16 v[8:11], v[136:139], v[168:171], v[8:11]
	s_waitcnt lgkmcnt(3)
	v_mfma_f32_16x16x32_bf16 v[60:63], v[132:135], v[148:151], v[60:63]
	v_mfma_f32_16x16x32_bf16 v[56:59], v[140:143], v[148:151], v[56:59]
	s_waitcnt lgkmcnt(2)
	v_mfma_f32_16x16x32_bf16 v[44:47], v[132:135], v[156:159], v[44:47]
	v_mfma_f32_16x16x32_bf16 v[40:43], v[140:143], v[156:159], v[40:43]
	s_waitcnt lgkmcnt(1)
	v_mfma_f32_16x16x32_bf16 v[28:31], v[132:135], v[164:167], v[28:31]
	v_mfma_f32_16x16x32_bf16 v[24:27], v[140:143], v[164:167], v[24:27]
	s_waitcnt lgkmcnt(0)
	s_setprio 2
	s_barrier
; #define PG8_STAGE(bufoff, gbase, voff) do { _Pragma("unroll") for (int _i = 0; _i < 2; ++_i) \
;         __builtin_amdgcn_global_load_lds((const unsigned*)((const char*)(gbase) + (voff)[_i]), (LAS unsigned*)(lds + (bufoff) + ldsw + _i * 8192), 16, 0, 0); } while (0)
; #define PG8_LDA(dst, b, h) do { _Pragma("unroll") for (int m = 0; m < 4; ++m) _Pragma("unroll") for (int k = 0; k < 2; ++k) dst[m][k] = *(const LAS bf16x8*)(lds + PG8_SA(b, h) + aoff + m * 2048 + k * 1024); } while (0)
; #define PG8_LDB(dst, b, h) do { _Pragma("unroll") for (int n = 0; n < 2; ++n) _Pragma("unroll") for (int k = 0; k < 2; ++k) dst[n][k] = *(const LAS bf16x8*)(lds + PG8_SB(b, h) + boff + n * 2048 + k * 1024); } while (0)
; #define PG8_MMA(ai, bj, At, Bt) do { __builtin_amdgcn_s_setprio(1); _Pragma("unroll") for (int m = 0; m < 4; ++m) _Pragma("unroll") for (int n = 0; n < 2; ++n) _Pragma("unroll") for (int k = 0; k < 2; ++k) \
;         acc[ai][bj][m][n] = __builtin_amdgcn_mfma_f32_16x16x32_bf16(Bt[n][k], At[m][k], acc[ai][bj][m][n], 0, 0, 0); __builtin_amdgcn_s_setprio(0); } while (0)
; #define PG8_WAIT_V(n) asm volatile("s_waitcnt vmcnt(" #n ")" ::: "memory")
; #define PG8_WAIT_L(n) asm volatile("s_waitcnt lgkmcnt(" #n ")" ::: "memory")
; #define PG8_BAR __builtin_amdgcn_s_barrier()
; #define PG8_SCHED __builtin_amdgcn_sched_barrier(0)
; #define PG8_LDA(dst, b, h) do { _Pragma("unroll") for (int m = 0; m < 4; ++m) _Pragma("unroll") for (int k = 0; k < 2; ++k) dst[m][k] = *(const LAS bf16x8*)(lds + PG8_SA(b, h) + aoff + m * 2048 + k * 1024); } while (0)
; template <class Epi>
; DI void gemm_phase(LAS unsigned char* lds, const Gemm g, const StaticOrder S, const Epi E) {
;     ...
;             PG8_BAR; PG8_WAIT_L(0); PG8_MMA(1, 0, At, B0); PG8_BAR; PG8_SCHED;
;             PG8_STAGE(PG8_SB(0, 1), b2 + hstep, voffB);
;             PG8_WAIT_V(6); PG8_BAR; PG8_MMA(1, 1, At, B1); PG8_BAR;
;             PG8_LDB(B0, 1, 0); PG8_SCHED; PG8_LDA(At, 1, 0); PG8_STAGE(PG8_SA(0, 1), a2 + hstep, voffA);
;             PG8_WAIT_L(8); PG8_BAR; PG8_WAIT_L(0); PG8_MMA(0, 0, At, B0); PG8_BAR; PG8_SCHED;
;             PG8_LDB(B1, 1, 1); PG8_STAGE(PG8_SB(1, 0), b3, voffB);
;             PG8_BAR; PG8_WAIT_L(0); PG8_MMA(0, 1, At, B1); PG8_BAR;
;             PG8_LDA(At, 1, 1); PG8_STAGE(PG8_SA(1, 0), a3, voffA);
;             PG8_BAR; PG8_WAIT_L(0); PG8_MMA(1, 0, At, B0); PG8_BAR; PG8_SCHED;
	v_mfma_f32_16x16x32_bf16 v[12:15], v[132:135], v[172:175], v[12:15]
	v_mfma_f32_16x16x32_bf16 v[8:11], v[140:143], v[172:175], v[8:11]
	s_setprio 0
	s_add_u32 s14, s78, 0xb0000
	s_addc_u32 s15, s79, 0
	s_add_i32 s28, s92, s59
	s_mov_b32 m0, s28
	v_lshl_add_u64 v[128:129], s[14:15], 0, v[178:179]
	global_load_lds_dwordx4 v[128:129], off
	s_add_i32 m0, s28, 0x2000
	v_lshl_add_u64 v[128:129], s[14:15], 0, v[182:183]
	global_load_lds_dwordx4 v[128:129], off
	s_waitcnt vmcnt(6)
	s_setprio 1
	s_barrier
	v_mfma_f32_16x16x32_bf16 v[52:55], v[192:195], v[144:147], v[52:55]
	v_mfma_f32_16x16x32_bf16 v[48:51], v[200:203], v[144:147], v[48:51]
	v_mfma_f32_16x16x32_bf16 v[36:39], v[192:195], v[152:155], v[36:39]
	v_mfma_f32_16x16x32_bf16 v[32:35], v[200:203], v[152:155], v[32:35]
	v_mfma_f32_16x16x32_bf16 v[20:23], v[192:195], v[160:163], v[20:23]
	v_mfma_f32_16x16x32_bf16 v[16:19], v[200:203], v[160:163], v[16:19]
	v_mfma_f32_16x16x32_bf16 v[4:7], v[192:195], v[168:171], v[4:7]
	v_mfma_f32_16x16x32_bf16 v[0:3], v[200:203], v[168:171], v[0:3]
	v_mfma_f32_16x16x32_bf16 v[52:55], v[196:199], v[148:151], v[52:55]
	v_mfma_f32_16x16x32_bf16 v[48:51], v[212:215], v[148:151], v[48:51]
	v_mfma_f32_16x16x32_bf16 v[36:39], v[196:199], v[156:159], v[36:39]
	v_mfma_f32_16x16x32_bf16 v[32:35], v[212:215], v[156:159], v[32:35]
	v_mfma_f32_16x16x32_bf16 v[20:23], v[196:199], v[164:167], v[20:23]
	v_mfma_f32_16x16x32_bf16 v[16:19], v[212:215], v[164:167], v[16:19]
	s_setprio 2
	s_barrier
	v_mfma_f32_16x16x32_bf16 v[4:7], v[196:199], v[172:175], v[4:7]
	v_mfma_f32_16x16x32_bf16 v[0:3], v[212:215], v[172:175], v[0:3]
	s_setprio 0
	s_add_i32 s28, 0, 0x18000
	v_add_u32_e32 v140, s28, v205
	ds_read_b128 v[128:131], v140
	ds_read_b128 v[132:135], v140 offset:1024
	ds_read_b128 v[136:139], v140 offset:2048
	ds_read_b128 v[140:143], v140 offset:3072
	s_add_u32 s14, s80, 0xb0000
	s_addc_u32 s15, s81, 0
	s_mov_b32 m0, s84
	v_lshl_add_u64 v[192:193], s[14:15], 0, v[176:177]
	ds_read_b128 v[144:147], v208 offset:32768
	ds_read_b128 v[152:155], v208 offset:34816
	ds_read_b128 v[160:163], v208 offset:36864
	ds_read_b128 v[168:171], v208 offset:38912
	global_load_lds_dwordx4 v[192:193], off
	s_mov_b32 m0, s85
	v_lshl_add_u64 v[192:193], s[14:15], 0, v[180:181]
	global_load_lds_dwordx4 v[192:193], off
	s_waitcnt lgkmcnt(4)
	s_setprio 1
	s_barrier
	ds_read_b128 v[148:151], v208 offset:33792
	ds_read_b128 v[156:159], v208 offset:35840
	ds_read_b128 v[164:167], v208 offset:37888
	ds_read_b128 v[172:175], v208 offset:39936
	s_waitcnt lgkmcnt(4)
	v_mfma_f32_16x16x32_bf16 v[124:127], v[128:131], v[144:147], v[124:127]
	v_mfma_f32_16x16x32_bf16 v[120:123], v[136:139], v[144:147], v[120:123]
	v_mfma_f32_16x16x32_bf16 v[108:111], v[128:131], v[152:155], v[108:111]
	v_mfma_f32_16x16x32_bf16 v[104:107], v[136:139], v[152:155], v[104:107]
	v_mfma_f32_16x16x32_bf16 v[92:95], v[128:131], v[160:163], v[92:95]
	v_mfma_f32_16x16x32_bf16 v[88:91], v[136:139], v[160:163], v[88:91]
	v_mfma_f32_16x16x32_bf16 v[76:79], v[128:131], v[168:171], v[76:79]
	v_mfma_f32_16x16x32_bf16 v[72:75], v[136:139], v[168:171], v[72:75]
	s_waitcnt lgkmcnt(3)
	v_mfma_f32_16x16x32_bf16 v[124:127], v[132:135], v[148:151], v[124:127]
	v_mfma_f32_16x16x32_bf16 v[120:123], v[140:143], v[148:151], v[120:123]
	s_waitcnt lgkmcnt(2)
	v_mfma_f32_16x16x32_bf16 v[108:111], v[132:135], v[156:159], v[108:111]
	v_mfma_f32_16x16x32_bf16 v[104:107], v[140:143], v[156:159], v[104:107]
	s_waitcnt lgkmcnt(1)
	v_mfma_f32_16x16x32_bf16 v[92:95], v[132:135], v[164:167], v[92:95]
	v_mfma_f32_16x16x32_bf16 v[88:91], v[140:143], v[164:167], v[88:91]
	s_waitcnt lgkmcnt(0)
	s_setprio 2
	s_barrier
	v_mfma_f32_16x16x32_bf16 v[76:79], v[132:135], v[172:175], v[76:79]
	v_mfma_f32_16x16x32_bf16 v[72:75], v[140:143], v[172:175], v[72:75]
	s_setprio 0
	s_add_i32 s29, 0, 0x1c000
	s_add_i32 s14, s28, s59
	v_add_u32_e32 v211, s29, v205
	v_lshl_add_u64 v[216:217], v[216:217], 0, s[24:25]
	s_mov_b32 m0, s14
	ds_read_b128 v[192:195], v211
	ds_read_b128 v[196:199], v211 offset:1024
	ds_read_b128 v[200:203], v211 offset:2048
	ds_read_b128 v[212:215], v211 offset:3072
	global_load_lds_dwordx4 v[216:217], off
	s_add_i32 m0, s14, 0x2000
	v_lshl_add_u64 v[216:217], v[218:219], 0, s[24:25]
	global_load_lds_dwordx4 v[216:217], off
	s_setprio 1
	s_barrier
	s_waitcnt lgkmcnt(0)
	v_mfma_f32_16x16x32_bf16 v[116:119], v[192:195], v[144:147], v[116:119]
	v_mfma_f32_16x16x32_bf16 v[112:115], v[200:203], v[144:147], v[112:115]
	v_mfma_f32_16x16x32_bf16 v[100:103], v[192:195], v[152:155], v[100:103]
	v_mfma_f32_16x16x32_bf16 v[96:99], v[200:203], v[152:155], v[96:99]
	v_mfma_f32_16x16x32_bf16 v[84:87], v[192:195], v[160:163], v[84:87]
	v_mfma_f32_16x16x32_bf16 v[80:83], v[200:203], v[160:163], v[80:83]
	v_mfma_f32_16x16x32_bf16 v[68:71], v[192:195], v[168:171], v[68:71]
	v_mfma_f32_16x16x32_bf16 v[64:67], v[200:203], v[168:171], v[64:67]
	v_mfma_f32_16x16x32_bf16 v[116:119], v[196:199], v[148:151], v[116:119]
	v_mfma_f32_16x16x32_bf16 v[112:115], v[212:215], v[148:151], v[112:115]
	v_mfma_f32_16x16x32_bf16 v[100:103], v[196:199], v[156:159], v[100:103]
	v_mfma_f32_16x16x32_bf16 v[96:99], v[212:215], v[156:159], v[96:99]
	v_mfma_f32_16x16x32_bf16 v[84:87], v[196:199], v[164:167], v[84:87]
	v_mfma_f32_16x16x32_bf16 v[80:83], v[212:215], v[164:167], v[80:83]
	s_setprio 2
	s_barrier
	v_mfma_f32_16x16x32_bf16 v[68:71], v[196:199], v[172:175], v[68:71]
	v_mfma_f32_16x16x32_bf16 v[64:67], v[212:215], v[172:175], v[64:67]
	s_setprio 0
	s_mov_b32 m0, s87
	v_lshl_add_u64 v[216:217], v[220:221], 0, s[24:25]
	ds_read_b128 v[144:147], v208 offset:49152
	ds_read_b128 v[152:155], v208 offset:51200
	ds_read_b128 v[160:163], v208 offset:53248
	ds_read_b128 v[168:171], v208 offset:55296
	global_load_lds_dwordx4 v[216:217], off
	s_mov_b32 m0, s88
	v_lshl_add_u64 v[216:217], v[224:225], 0, s[24:25]
	global_load_lds_dwordx4 v[216:217], off
	s_setprio 1
	s_barrier
; #define PG8_STAGE(bufoff, gbase, voff) do { _Pragma("unroll") for (int _i = 0; _i < 2; ++_i) \
;         __builtin_amdgcn_global_load_lds((const unsigned*)((const char*)(gbase) + (voff)[_i]), (LAS unsigned*)(lds + (bufoff) + ldsw + _i * 8192), 16, 0, 0); } while (0)
; #define PG8_LDA(dst, b, h) do { _Pragma("unroll") for (int m = 0; m < 4; ++m) _Pragma("unroll") for (int k = 0; k < 2; ++k) dst[m][k] = *(const LAS bf16x8*)(lds + PG8_SA(b, h) + aoff + m * 2048 + k * 1024); } while (0)
; #define PG8_LDB(dst, b, h) do { _Pragma("unroll") for (int n = 0; n < 2; ++n) _Pragma("unroll") for (int k = 0; k < 2; ++k) dst[n][k] = *(const LAS bf16x8*)(lds + PG8_SB(b, h) + boff + n * 2048 + k * 1024); } while (0)
; #define PG8_MMA(ai, bj, At, Bt) do { __builtin_amdgcn_s_setprio(1); _Pragma("unroll") for (int m = 0; m < 4; ++m) _Pragma("unroll") for (int n = 0; n < 2; ++n) _Pragma("unroll") for (int k = 0; k < 2; ++k) \
;         acc[ai][bj][m][n] = __builtin_amdgcn_mfma_f32_16x16x32_bf16(Bt[n][k], At[m][k], acc[ai][bj][m][n], 0, 0, 0); __builtin_amdgcn_s_setprio(0); } while (0)
; #define PG8_WAIT_V(n) asm volatile("s_waitcnt vmcnt(" #n ")" ::: "memory")
; #define PG8_WAIT_L(n) asm volatile("s_waitcnt lgkmcnt(" #n ")" ::: "memory")
; #define PG8_BAR __builtin_amdgcn_s_barrier()
; #define PG8_SCHED __builtin_amdgcn_sched_barrier(0)
; #define PG8_STAGE(bufoff, gbase, voff) do { _Pragma("unroll") for (int _i = 0; _i < 2; ++_i) \
;         __builtin_amdgcn_global_load_lds((const unsigned*)((const char*)(gbase) + (voff)[_i]), (LAS unsigned*)(lds + (bufoff) + ldsw + _i * 8192), 16, 0, 0); } while (0)
; #define PG8_WAIT_V(n) asm volatile("s_waitcnt vmcnt(" #n ")" ::: "memory")
; template <class Epi>
; DI void gemm_phase(LAS unsigned char* lds, const Gemm g, const StaticOrder S, const Epi E) {
;     ...
;         for (int t = 0; t < nt; t += 2) {
;     ...
;             PG8_WAIT_L(8); PG8_BAR; PG8_WAIT_L(0); PG8_MMA(0, 0, At, B0); PG8_BAR; PG8_SCHED;
;             PG8_LDB(B1, 1, 1); PG8_STAGE(PG8_SB(1, 0), b3, voffB);
;             PG8_BAR; PG8_WAIT_L(0); PG8_MMA(0, 1, At, B1); PG8_BAR;
;             PG8_LDA(At, 1, 1); PG8_STAGE(PG8_SA(1, 0), a3, voffA);
;             PG8_BAR; PG8_WAIT_L(0); PG8_MMA(1, 0, At, B0); PG8_BAR; PG8_SCHED;
;             PG8_STAGE(PG8_SB(1, 1), b3 + hstep, voffB);
;             PG8_WAIT_V(6); PG8_BAR; PG8_MMA(1, 1, At, B1); PG8_BAR;
	ds_read_b128 v[148:151], v208 offset:50176
	ds_read_b128 v[156:159], v208 offset:52224
	ds_read_b128 v[164:167], v208 offset:54272
	ds_read_b128 v[172:175], v208 offset:56320
	s_waitcnt lgkmcnt(4)
	v_mfma_f32_16x16x32_bf16 v[60:63], v[128:131], v[144:147], v[60:63]
	v_mfma_f32_16x16x32_bf16 v[56:59], v[136:139], v[144:147], v[56:59]
	v_mfma_f32_16x16x32_bf16 v[44:47], v[128:131], v[152:155], v[44:47]
	v_mfma_f32_16x16x32_bf16 v[40:43], v[136:139], v[152:155], v[40:43]
	v_mfma_f32_16x16x32_bf16 v[28:31], v[128:131], v[160:163], v[28:31]
	v_mfma_f32_16x16x32_bf16 v[24:27], v[136:139], v[160:163], v[24:27]
	v_mfma_f32_16x16x32_bf16 v[12:15], v[128:131], v[168:171], v[12:15]
	v_mfma_f32_16x16x32_bf16 v[8:11], v[136:139], v[168:171], v[8:11]
	s_waitcnt lgkmcnt(3)
	v_mfma_f32_16x16x32_bf16 v[60:63], v[132:135], v[148:151], v[60:63]
	v_mfma_f32_16x16x32_bf16 v[56:59], v[140:143], v[148:151], v[56:59]
	s_waitcnt lgkmcnt(2)
	v_mfma_f32_16x16x32_bf16 v[44:47], v[132:135], v[156:159], v[44:47]
	v_mfma_f32_16x16x32_bf16 v[40:43], v[140:143], v[156:159], v[40:43]
	s_waitcnt lgkmcnt(1)
	v_mfma_f32_16x16x32_bf16 v[28:31], v[132:135], v[164:167], v[28:31]
	v_mfma_f32_16x16x32_bf16 v[24:27], v[140:143], v[164:167], v[24:27]
	s_waitcnt lgkmcnt(0)
	s_setprio 2
	s_barrier
	v_mfma_f32_16x16x32_bf16 v[12:15], v[132:135], v[172:175], v[12:15]
	v_mfma_f32_16x16x32_bf16 v[8:11], v[140:143], v[172:175], v[8:11]
	s_setprio 0
	s_add_u32 s14, s78, 0xb0080
	s_addc_u32 s15, s79, 0
	s_add_i32 s28, s29, s59
	s_mov_b32 m0, s28
	v_lshl_add_u64 v[128:129], s[14:15], 0, v[178:179]
	global_load_lds_dwordx4 v[128:129], off
	s_add_i32 m0, s28, 0x2000
	v_lshl_add_u64 v[128:129], s[14:15], 0, v[182:183]
	global_load_lds_dwordx4 v[128:129], off
	s_waitcnt vmcnt(6)
	s_setprio 1
	s_barrier
	v_mfma_f32_16x16x32_bf16 v[52:55], v[192:195], v[144:147], v[52:55]
	v_mfma_f32_16x16x32_bf16 v[48:51], v[200:203], v[144:147], v[48:51]
	v_mfma_f32_16x16x32_bf16 v[36:39], v[192:195], v[152:155], v[36:39]
	v_mfma_f32_16x16x32_bf16 v[32:35], v[200:203], v[152:155], v[32:35]
	v_mfma_f32_16x16x32_bf16 v[20:23], v[192:195], v[160:163], v[20:23]
	v_mfma_f32_16x16x32_bf16 v[16:19], v[200:203], v[160:163], v[16:19]
	v_mfma_f32_16x16x32_bf16 v[4:7], v[192:195], v[168:171], v[4:7]
	v_mfma_f32_16x16x32_bf16 v[0:3], v[200:203], v[168:171], v[0:3]
	v_mfma_f32_16x16x32_bf16 v[52:55], v[196:199], v[148:151], v[52:55]
	v_mfma_f32_16x16x32_bf16 v[48:51], v[212:215], v[148:151], v[48:51]
	v_mfma_f32_16x16x32_bf16 v[36:39], v[196:199], v[156:159], v[36:39]
	v_mfma_f32_16x16x32_bf16 v[32:35], v[212:215], v[156:159], v[32:35]
	v_mfma_f32_16x16x32_bf16 v[20:23], v[196:199], v[164:167], v[20:23]
	v_mfma_f32_16x16x32_bf16 v[16:19], v[212:215], v[164:167], v[16:19]
	s_setprio 2
	s_barrier
	v_mfma_f32_16x16x32_bf16 v[4:7], v[196:199], v[172:175], v[4:7]
	v_mfma_f32_16x16x32_bf16 v[0:3], v[212:215], v[172:175], v[0:3]
	s_setprio 0
	s_add_i32 s97, s97, 2
	s_add_u32 s6, s6, 0x100
	s_addc_u32 s7, s7, 0
	s_cmp_gt_u32 s97, 41
	s_mov_b64 s[28:29], s[76:77]
	s_cbranch_scc0 .LBB0_186
; DI unsigned pk_bf16(float lo, float hi) { f32x2 v = {lo, hi}; return __builtin_bit_cast(unsigned, __builtin_convertvector(v, bf16v2)); }
; DI f32x4 bf_lo4(u32x4 w) { f32x4 r; r[0] = bf_lo(w.x); r[1] = bf_hi(w.x); r[2] = bf_lo(w.y); r[3] = bf_hi(w.y); return r; }
; DI f32x4 bf_hi4(u32x4 w) { f32x4 r; r[0] = bf_lo(w.z); r[1] = bf_hi(w.z); r[2] = bf_lo(w.w); r[3] = bf_hi(w.w); return r; }
;     DI void operator()(AccRef acc, const Unit& u, int wr, int wc, int fr, int fq) const {
;         const float scale = HALFSTEP ? 0.5f : 1.0f;
;         const int row0 = u.pm * 256 + wr * 64 + fr, col0 = u.pn * 256 + wc * 32 + 8 * fq;
; #pragma unroll
;         for (int ai = 0; ai < 2; ++ai) {
;             f32x4 bv[4][2][2];
; #pragma unroll
;             for (int m = 0; m < 4; ++m)
; #pragma unroll
;                 for (int bj = 0; bj < 2; ++bj) {
;                     const size_t o = (size_t)(row0 + ai * 128 + m * 16) * DM + col0 + bj * 128;
;                     if (BASEF32) { bv[m][bj][0] = *(const f32x4*)(basef + o); bv[m][bj][1] = *(const f32x4*)(basef + o + 4); }
;                     else { const u32x4 h = *(const u32x4*)(xnb + o); bv[m][bj][0] = bf_lo4(h); bv[m][bj][1] = bf_hi4(h); }
;                 }
; #pragma unroll
;             for (int m = 0; m < 4; ++m) {
;                 const int row = row0 + ai * 128 + m * 16;
;                 float q = 0.f;
; #pragma unroll
;                 for (int bj = 0; bj < 2; ++bj) {
;                     const size_t o = (size_t)row * DM + col0 + bj * 128;
;                     const f32x4 r0 = bv[m][bj][0] + scale * acc[ai][bj][m][0], r1 = bv[m][bj][1] + scale * acc[ai][bj][m][1];
;                     u32x4 w; w.x = pk_bf16(r0[0], r0[1]); w.y = pk_bf16(r0[2], r0[3]); w.z = pk_bf16(r1[0], r1[1]); w.w = pk_bf16(r1[2], r1[3]);
;                     *(u32x4*)(xnb + o) = w;
;                     if (STATS) q += r0[0] * r0[0] + r0[1] * r0[1] + r0[2] * r0[2] + r0[3] * r0[3] + r1[0] * r1[0] + r1[1] * r1[1] + r1[2] * r1[2] + r1[3] * r1[3];
;                 }
;                 if (STATS) { q += __shfl_xor(q, 16); q += __shfl_xor(q, 32); if (fq == 0) atomicAdd(ss + row, q); }
;             }
	v_lshl_add_u32 v194, s96, 8, v204
	v_lshl_or_b32 v192, s95, 8, v206
	v_ashrrev_i32_e32 v193, 31, v192
	v_ashrrev_i32_e32 v195, 31, v194
	v_lshl_add_u64 v[196:197], v[192:193], 2, s[52:53]
	v_lshlrev_b64 v[128:129], 12, v[194:195]
	v_lshl_add_u64 v[128:129], v[196:197], 0, v[128:129]
	global_load_dwordx4 v[214:217], v[128:129], off
	global_load_dwordx4 v[218:221], v[128:129], off offset:16
	global_load_dwordx4 v[224:227], v[128:129], off offset:512
	global_load_dwordx4 v[228:231], v[128:129], off offset:528
	v_or_b32_e32 v202, 16, v194
	v_or_b32_e32 v200, 32, v194
	v_or_b32_e32 v198, 48, v194
	v_ashrrev_i32_e32 v203, 31, v202
	v_ashrrev_i32_e32 v201, 31, v200
	v_ashrrev_i32_e32 v199, 31, v198
	v_lshlrev_b64 v[128:129], 12, v[202:203]
	v_lshlrev_b64 v[130:131], 12, v[200:201]
	v_lshlrev_b64 v[132:133], 12, v[198:199]
	v_lshl_add_u64 v[128:129], v[196:197], 0, v[128:129]
	v_lshl_add_u64 v[130:131], v[196:197], 0, v[130:131]
	v_lshl_add_u64 v[132:133], v[196:197], 0, v[132:133]
	global_load_dwordx4 v[168:171], v[128:129], off offset:16
	global_load_dwordx4 v[172:175], v[128:129], off
	global_load_dwordx4 v[160:163], v[128:129], off offset:528
	global_load_dwordx4 v[164:167], v[128:129], off offset:512
	global_load_dwordx4 v[152:155], v[130:131], off offset:16
	global_load_dwordx4 v[156:159], v[130:131], off
	global_load_dwordx4 v[144:147], v[130:131], off offset:528
	global_load_dwordx4 v[148:151], v[130:131], off offset:512
	global_load_dwordx4 v[136:139], v[132:133], off offset:16
	global_load_dwordx4 v[140:143], v[132:133], off
	s_nop 0
	global_load_dwordx4 v[128:131], v[132:133], off offset:528
	s_nop 0
	global_load_dwordx4 v[132:135], v[132:133], off offset:512
	v_and_b32_e32 v212, 64, v210
	v_xor_b32_e32 v211, 16, v210
	v_add_u32_e32 v212, 64, v212
	v_xor_b32_e32 v213, 32, v210
	v_cmp_lt_i32_e32 vcc, v211, v212
	v_lshlrev_b64 v[232:233], 11, v[194:195]
	s_waitcnt vmcnt(0)
	v_pk_fma_f32 v[124:125], v[124:125], 0.5, v[214:215] op_sel_hi:[1,0,1]
	v_cndmask_b32_e32 v211, v210, v211, vcc
	v_cmp_lt_i32_e32 vcc, v213, v212
	v_pk_fma_f32 v[116:117], v[116:117], 0.5, v[224:225] op_sel_hi:[1,0,1]
	v_lshlrev_b32_e32 v212, 2, v211
	v_cndmask_b32_e32 v213, v210, v213, vcc
	v_lshlrev_b32_e32 v211, 2, v213
	v_pk_fma_f32 v[126:127], v[126:127], 0.5, v[216:217] op_sel_hi:[1,0,1]
	v_pk_fma_f32 v[216:217], v[112:113], 0.5, v[228:229] op_sel_hi:[1,0,1]
	v_cvt_pk_bf16_f32 v112, v124, v125
	v_mul_f32_e32 v125, v125, v125
	v_mul_f32_e32 v213, v117, v117
	v_pk_fma_f32 v[118:119], v[118:119], 0.5, v[226:227] op_sel_hi:[1,0,1]
	v_fmac_f32_e32 v125, v124, v124
	v_fmac_f32_e32 v213, v116, v116
	v_fmac_f32_e32 v125, v126, v126
	v_fmac_f32_e32 v213, v118, v118
	v_pk_fma_f32 v[120:121], v[120:121], 0.5, v[218:219] op_sel_hi:[1,0,1]
	v_fmac_f32_e32 v125, v127, v127
	v_fmac_f32_e32 v213, v119, v119
	v_fmac_f32_e32 v125, v120, v120
	v_fmac_f32_e32 v213, v216, v216
	v_pk_fma_f32 v[122:123], v[122:123], 0.5, v[220:221] op_sel_hi:[1,0,1]
	v_pk_fma_f32 v[214:215], v[114:115], 0.5, v[230:231] op_sel_hi:[1,0,1]
	v_fmac_f32_e32 v125, v121, v121
	v_fmac_f32_e32 v213, v217, v217
	v_fmac_f32_e32 v125, v122, v122
	v_fmac_f32_e32 v213, v214, v214
	v_fmac_f32_e32 v125, v123, v123
	v_fmac_f32_e32 v213, v215, v215
	v_cvt_pk_bf16_f32 v115, v122, v123
	v_add_f32_e32 v122, v125, v213
	ds_bpermute_b32 v123, v212, v122
	v_cvt_pk_bf16_f32 v114, v120, v121
	v_lshl_add_u64 v[120:121], s[56:57], 0, v[232:233]
	v_cvt_pk_bf16_f32 v113, v126, v127
	v_lshl_add_u64 v[120:121], v[192:193], 1, v[120:121]
	global_store_dwordx4 v[120:121], v[112:115], off
	s_waitcnt lgkmcnt(0)
	s_nop 0
	v_add_f32_e32 v112, v122, v123
	ds_bpermute_b32 v113, v211, v112
	v_cvt_pk_bf16_f32 v114, v116, v117
	v_cvt_pk_bf16_f32 v115, v118, v119
	v_cvt_pk_bf16_f32 v116, v216, v217
	v_cvt_pk_bf16_f32 v117, v214, v215
	global_store_dwordx4 v[120:121], v[114:117], off offset:256
	s_and_saveexec_b64 s[6:7], s[0:1]
	s_cbranch_execz .LBB0_189
	v_lshl_add_u64 v[114:115], v[194:195], 2, s[60:61]
	s_waitcnt lgkmcnt(0)
	v_add_f32_e32 v112, v112, v113
	global_atomic_add_f32 v[114:115], v112, off

; #define PG8_STAGE(bufoff, gbase, voff) do { _Pragma("unroll") for (int _i = 0; _i < 2; ++_i) \
;         __builtin_amdgcn_global_load_lds((const unsigned*)((const char*)(gbase) + (voff)[_i]), (LAS unsigned*)(lds + (bufoff) + ldsw + _i * 8192), 16, 0, 0); } while (0)
; #define PG8_LDA(dst, b, h) do { _Pragma("unroll") for (int m = 0; m < 4; ++m) _Pragma("unroll") for (int k = 0; k < 2; ++k) dst[m][k] = *(const LAS bf16x8*)(lds + PG8_SA(b, h) + aoff + m * 2048 + k * 1024); } while (0)
; #define PG8_LDB(dst, b, h) do { _Pragma("unroll") for (int n = 0; n < 2; ++n) _Pragma("unroll") for (int k = 0; k < 2; ++k) dst[n][k] = *(const LAS bf16x8*)(lds + PG8_SB(b, h) + boff + n * 2048 + k * 1024); } while (0)
; #define PG8_MMA(ai, bj, At, Bt) do { __builtin_amdgcn_s_setprio(1); _Pragma("unroll") for (int m = 0; m < 4; ++m) _Pragma("unroll") for (int n = 0; n < 2; ++n) _Pragma("unroll") for (int k = 0; k < 2; ++k) \
;         acc[ai][bj][m][n] = __builtin_amdgcn_mfma_f32_16x16x32_bf16(Bt[n][k], At[m][k], acc[ai][bj][m][n], 0, 0, 0); __builtin_amdgcn_s_setprio(0); } while (0)
; #define PG8_WAIT_V(n) asm volatile("s_waitcnt vmcnt(" #n ")" ::: "memory")
; #define PG8_WAIT_L(n) asm volatile("s_waitcnt lgkmcnt(" #n ")" ::: "memory")
; #define PG8_BAR __builtin_amdgcn_s_barrier()
; #define PG8_SCHED __builtin_amdgcn_sched_barrier(0)
; #define PG8_WAIT_V(n) asm volatile("s_waitcnt vmcnt(" #n ")" ::: "memory")
; template <class Epi>
; DI void gemm_phase(LAS unsigned char* lds, const Gemm g, const StaticOrder S, const Epi E) {
;     ...
;             PG8_LDB(B0, 0, 0); PG8_SCHED; PG8_LDA(At, 0, 0); PG8_STAGE(PG8_SA(1, 1), a1 + hstep, voffA);
;             PG8_WAIT_L(8); PG8_BAR; PG8_WAIT_L(0); PG8_MMA(0, 0, At, B0); PG8_BAR; PG8_SCHED;
;             PG8_LDB(B1, 0, 1); PG8_STAGE(PG8_SB(0, 0), b2, voffB);
;             PG8_BAR; PG8_WAIT_L(0); PG8_MMA(0, 1, At, B1); PG8_BAR;
;             PG8_LDA(At, 0, 1); PG8_STAGE(PG8_SA(0, 0), a2, voffA);
;             PG8_BAR; PG8_WAIT_L(0); PG8_MMA(1, 0, At, B0); PG8_BAR; PG8_SCHED;
;             PG8_STAGE(PG8_SB(0, 1), b2 + hstep, voffB);
;             PG8_WAIT_V(6); PG8_BAR; PG8_MMA(1, 1, At, B1); PG8_BAR;
;             PG8_LDB(B0, 1, 0); PG8_SCHED; PG8_LDA(At, 1, 0); PG8_STAGE(PG8_SA(0, 1), a2 + hstep, voffA);
;             PG8_WAIT_L(8); PG8_BAR; PG8_WAIT_L(0); PG8_MMA(0, 0, At, B0); PG8_BAR; PG8_SCHED;
.LBB0_274:
	ds_read_b128 v[100:103], v227
	ds_read_b128 v[134:137], v227 offset:1024
	ds_read_b128 v[138:141], v227 offset:2048
	ds_read_b128 v[142:145], v227 offset:3072
	s_add_u32 s14, s8, 0xfffc0080
	s_addc_u32 s15, s9, -1
	s_cmp_eq_u32 s95, 12
	s_cselect_b32 s77, s1, s15
	s_cselect_b32 s76, s6, s14
	s_cselect_b32 s53, s7, s94
	s_cselect_b32 s52, s21, s23
	v_lshl_add_u64 v[104:105], s[8:9], 0, v[212:213]
	s_add_i32 m0, s78, 0xc000
	ds_read_b128 v[146:149], v228
	ds_read_b128 v[154:157], v228 offset:2048
	ds_read_b128 v[162:165], v228 offset:4096
	ds_read_b128 v[170:173], v228 offset:6144
	global_load_lds_dwordx4 v[104:105], off
	s_add_i32 m0, s78, 0xe000
	v_lshl_add_u64 v[104:105], s[8:9], 0, v[214:215]
	global_load_lds_dwordx4 v[104:105], off
	s_waitcnt lgkmcnt(4)
	s_setprio 1
	s_barrier
	ds_read_b128 v[150:153], v228 offset:1024
	ds_read_b128 v[158:161], v228 offset:3072
	ds_read_b128 v[166:169], v228 offset:5120
	ds_read_b128 v[174:177], v228 offset:7168
	s_waitcnt lgkmcnt(4)
	v_mfma_f32_16x16x32_bf16 v[130:133], v[100:103], v[146:149], v[130:133]
	v_mfma_f32_16x16x32_bf16 v[126:129], v[138:141], v[146:149], v[126:129]
	v_mfma_f32_16x16x32_bf16 v[114:117], v[100:103], v[154:157], v[114:117]
	v_mfma_f32_16x16x32_bf16 v[110:113], v[138:141], v[154:157], v[110:113]
	v_mfma_f32_16x16x32_bf16 v[92:95], v[100:103], v[162:165], v[92:95]
	v_mfma_f32_16x16x32_bf16 v[88:91], v[138:141], v[162:165], v[88:91]
	v_mfma_f32_16x16x32_bf16 v[76:79], v[100:103], v[170:173], v[76:79]
	v_mfma_f32_16x16x32_bf16 v[72:75], v[138:141], v[170:173], v[72:75]
	s_waitcnt lgkmcnt(3)
	v_mfma_f32_16x16x32_bf16 v[130:133], v[134:137], v[150:153], v[130:133]
	v_mfma_f32_16x16x32_bf16 v[126:129], v[142:145], v[150:153], v[126:129]
	s_waitcnt lgkmcnt(2)
	v_mfma_f32_16x16x32_bf16 v[114:117], v[134:137], v[158:161], v[114:117]
	v_mfma_f32_16x16x32_bf16 v[110:113], v[142:145], v[158:161], v[110:113]
	s_waitcnt lgkmcnt(1)
	v_mfma_f32_16x16x32_bf16 v[92:95], v[134:137], v[166:169], v[92:95]
	v_mfma_f32_16x16x32_bf16 v[88:91], v[142:145], v[166:169], v[88:91]
	s_waitcnt lgkmcnt(0)
	s_setprio 2
	s_barrier
	v_mfma_f32_16x16x32_bf16 v[76:79], v[134:137], v[174:177], v[76:79]
	v_mfma_f32_16x16x32_bf16 v[72:75], v[142:145], v[174:177], v[72:75]
	s_setprio 0
	s_add_i32 s14, s87, s59
	v_lshl_add_u64 v[194:195], s[52:53], 0, v[200:201]
	s_mov_b32 m0, s14
	ds_read_b128 v[178:181], v229
	ds_read_b128 v[182:185], v229 offset:1024
	ds_read_b128 v[186:189], v229 offset:2048
	ds_read_b128 v[190:193], v229 offset:3072
	global_load_lds_dwordx4 v[194:195], off
	s_add_i32 m0, s14, 0x2000
	v_lshl_add_u64 v[196:197], s[52:53], 0, v[204:205]
	global_load_lds_dwordx4 v[196:197], off
	s_setprio 1
	s_barrier
	s_waitcnt lgkmcnt(0)
	v_mfma_f32_16x16x32_bf16 v[122:125], v[178:181], v[146:149], v[122:125]
	v_mfma_f32_16x16x32_bf16 v[118:121], v[186:189], v[146:149], v[118:121]
	v_mfma_f32_16x16x32_bf16 v[104:107], v[178:181], v[154:157], v[106:109]
	v_mfma_f32_16x16x32_bf16 v[96:99], v[186:189], v[154:157], v[96:99]
	v_mfma_f32_16x16x32_bf16 v[84:87], v[178:181], v[162:165], v[84:87]
	v_mfma_f32_16x16x32_bf16 v[80:83], v[186:189], v[162:165], v[80:83]
	v_mfma_f32_16x16x32_bf16 v[68:71], v[178:181], v[170:173], v[68:71]
	v_mfma_f32_16x16x32_bf16 v[64:67], v[186:189], v[170:173], v[64:67]
	v_mfma_f32_16x16x32_bf16 v[122:125], v[182:185], v[150:153], v[122:125]
	v_mfma_f32_16x16x32_bf16 v[118:121], v[190:193], v[150:153], v[118:121]
	v_mfma_f32_16x16x32_bf16 v[104:107], v[182:185], v[158:161], v[104:107]
	v_mfma_f32_16x16x32_bf16 v[96:99], v[190:193], v[158:161], v[96:99]
	v_mfma_f32_16x16x32_bf16 v[84:87], v[182:185], v[166:169], v[84:87]
	v_mfma_f32_16x16x32_bf16 v[80:83], v[190:193], v[166:169], v[80:83]
	s_setprio 2
	s_barrier
	v_mfma_f32_16x16x32_bf16 v[68:71], v[182:185], v[174:177], v[68:71]
	v_mfma_f32_16x16x32_bf16 v[64:67], v[190:193], v[174:177], v[64:67]
	s_setprio 0
	s_mov_b32 m0, s78
	v_lshl_add_u64 v[220:221], s[76:77], 0, v[198:199]
	ds_read_b128 v[146:149], v228 offset:16384
	ds_read_b128 v[154:157], v228 offset:18432
	ds_read_b128 v[162:165], v228 offset:20480
	ds_read_b128 v[170:173], v228 offset:22528
	global_load_lds_dwordx4 v[220:221], off
	s_mov_b32 m0, s79
	v_lshl_add_u64 v[232:233], s[76:77], 0, v[202:203]
	global_load_lds_dwordx4 v[232:233], off
	s_setprio 1
	s_barrier
	ds_read_b128 v[150:153], v228 offset:17408
	ds_read_b128 v[158:161], v228 offset:19456
	ds_read_b128 v[166:169], v228 offset:21504
	ds_read_b128 v[174:177], v228 offset:23552
	s_waitcnt lgkmcnt(4)
	v_mfma_f32_16x16x32_bf16 v[60:63], v[100:103], v[146:149], v[60:63]
	v_mfma_f32_16x16x32_bf16 v[56:59], v[138:141], v[146:149], v[56:59]
	v_mfma_f32_16x16x32_bf16 v[44:47], v[100:103], v[154:157], v[44:47]
	v_mfma_f32_16x16x32_bf16 v[40:43], v[138:141], v[154:157], v[40:43]
	v_mfma_f32_16x16x32_bf16 v[28:31], v[100:103], v[162:165], v[28:31]
	v_mfma_f32_16x16x32_bf16 v[24:27], v[138:141], v[162:165], v[24:27]
	v_mfma_f32_16x16x32_bf16 v[12:15], v[100:103], v[170:173], v[12:15]
	v_mfma_f32_16x16x32_bf16 v[8:11], v[138:141], v[170:173], v[8:11]
	s_waitcnt lgkmcnt(3)
	v_mfma_f32_16x16x32_bf16 v[60:63], v[134:137], v[150:153], v[60:63]
	v_mfma_f32_16x16x32_bf16 v[56:59], v[142:145], v[150:153], v[56:59]
	s_waitcnt lgkmcnt(2)
	v_mfma_f32_16x16x32_bf16 v[44:47], v[134:137], v[158:161], v[44:47]
	v_mfma_f32_16x16x32_bf16 v[40:43], v[142:145], v[158:161], v[40:43]
	s_waitcnt lgkmcnt(1)
	v_mfma_f32_16x16x32_bf16 v[28:31], v[134:137], v[166:169], v[28:31]
	v_mfma_f32_16x16x32_bf16 v[24:27], v[142:145], v[166:169], v[24:27]
	s_waitcnt lgkmcnt(0)
	s_setprio 2
	s_barrier
; #define PG8_STAGE(bufoff, gbase, voff) do { _Pragma("unroll") for (int _i = 0; _i < 2; ++_i) \
;         __builtin_amdgcn_global_load_lds((const unsigned*)((const char*)(gbase) + (voff)[_i]), (LAS unsigned*)(lds + (bufoff) + ldsw + _i * 8192), 16, 0, 0); } while (0)
; #define PG8_LDA(dst, b, h) do { _Pragma("unroll") for (int m = 0; m < 4; ++m) _Pragma("unroll") for (int k = 0; k < 2; ++k) dst[m][k] = *(const LAS bf16x8*)(lds + PG8_SA(b, h) + aoff + m * 2048 + k * 1024); } while (0)
; #define PG8_LDB(dst, b, h) do { _Pragma("unroll") for (int n = 0; n < 2; ++n) _Pragma("unroll") for (int k = 0; k < 2; ++k) dst[n][k] = *(const LAS bf16x8*)(lds + PG8_SB(b, h) + boff + n * 2048 + k * 1024); } while (0)
; #define PG8_MMA(ai, bj, At, Bt) do { __builtin_amdgcn_s_setprio(1); _Pragma("unroll") for (int m = 0; m < 4; ++m) _Pragma("unroll") for (int n = 0; n < 2; ++n) _Pragma("unroll") for (int k = 0; k < 2; ++k) \
;         acc[ai][bj][m][n] = __builtin_amdgcn_mfma_f32_16x16x32_bf16(Bt[n][k], At[m][k], acc[ai][bj][m][n], 0, 0, 0); __builtin_amdgcn_s_setprio(0); } while (0)
; #define PG8_WAIT_V(n) asm volatile("s_waitcnt vmcnt(" #n ")" ::: "memory")
; #define PG8_WAIT_L(n) asm volatile("s_waitcnt lgkmcnt(" #n ")" ::: "memory")
; #define PG8_BAR __builtin_amdgcn_s_barrier()
; #define PG8_SCHED __builtin_amdgcn_sched_barrier(0)
; #define PG8_LDA(dst, b, h) do { _Pragma("unroll") for (int m = 0; m < 4; ++m) _Pragma("unroll") for (int k = 0; k < 2; ++k) dst[m][k] = *(const LAS bf16x8*)(lds + PG8_SA(b, h) + aoff + m * 2048 + k * 1024); } while (0)
; template <class Epi>
; DI void gemm_phase(LAS unsigned char* lds, const Gemm g, const StaticOrder S, const Epi E) {
;     ...
;             PG8_BAR; PG8_WAIT_L(0); PG8_MMA(1, 0, At, B0); PG8_BAR; PG8_SCHED;
;             PG8_STAGE(PG8_SB(0, 1), b2 + hstep, voffB);
;             PG8_WAIT_V(6); PG8_BAR; PG8_MMA(1, 1, At, B1); PG8_BAR;
;             PG8_LDB(B0, 1, 0); PG8_SCHED; PG8_LDA(At, 1, 0); PG8_STAGE(PG8_SA(0, 1), a2 + hstep, voffA);
;             PG8_WAIT_L(8); PG8_BAR; PG8_WAIT_L(0); PG8_MMA(0, 0, At, B0); PG8_BAR; PG8_SCHED;
;             PG8_LDB(B1, 1, 1); PG8_STAGE(PG8_SB(1, 0), b3, voffB);
;             PG8_BAR; PG8_WAIT_L(0); PG8_MMA(0, 1, At, B1); PG8_BAR;
;             PG8_LDA(At, 1, 1); PG8_STAGE(PG8_SA(1, 0), a3, voffA);
;             PG8_BAR; PG8_WAIT_L(0); PG8_MMA(1, 0, At, B0); PG8_BAR; PG8_SCHED;
	v_mfma_f32_16x16x32_bf16 v[12:15], v[134:137], v[174:177], v[12:15]
	v_mfma_f32_16x16x32_bf16 v[8:11], v[142:145], v[174:177], v[8:11]
	s_setprio 0
	s_add_u32 s14, s52, 0x40000
	s_addc_u32 s15, s53, 0
	s_add_i32 s35, s90, s59
	s_mov_b32 m0, s35
	v_lshl_add_u64 v[100:101], s[14:15], 0, v[200:201]
	global_load_lds_dwordx4 v[100:101], off
	s_add_i32 m0, s35, 0x2000
	v_lshl_add_u64 v[100:101], s[14:15], 0, v[204:205]
	global_load_lds_dwordx4 v[100:101], off
	s_waitcnt vmcnt(6)
	s_setprio 1
	s_barrier
	v_mfma_f32_16x16x32_bf16 v[52:55], v[178:181], v[146:149], v[52:55]
	v_mfma_f32_16x16x32_bf16 v[48:51], v[186:189], v[146:149], v[48:51]
	v_mfma_f32_16x16x32_bf16 v[36:39], v[178:181], v[154:157], v[36:39]
	v_mfma_f32_16x16x32_bf16 v[32:35], v[186:189], v[154:157], v[32:35]
	v_mfma_f32_16x16x32_bf16 v[20:23], v[178:181], v[162:165], v[20:23]
	v_mfma_f32_16x16x32_bf16 v[16:19], v[186:189], v[162:165], v[16:19]
	v_mfma_f32_16x16x32_bf16 v[4:7], v[178:181], v[170:173], v[4:7]
	v_mfma_f32_16x16x32_bf16 v[0:3], v[186:189], v[170:173], v[0:3]
	v_mfma_f32_16x16x32_bf16 v[52:55], v[182:185], v[150:153], v[52:55]
	v_mfma_f32_16x16x32_bf16 v[48:51], v[190:193], v[150:153], v[48:51]
	v_mfma_f32_16x16x32_bf16 v[36:39], v[182:185], v[158:161], v[36:39]
	v_mfma_f32_16x16x32_bf16 v[32:35], v[190:193], v[158:161], v[32:35]
	v_mfma_f32_16x16x32_bf16 v[20:23], v[182:185], v[166:169], v[20:23]
	v_mfma_f32_16x16x32_bf16 v[16:19], v[190:193], v[166:169], v[16:19]
	s_setprio 2
	s_barrier
	v_mfma_f32_16x16x32_bf16 v[4:7], v[182:185], v[174:177], v[4:7]
	v_mfma_f32_16x16x32_bf16 v[0:3], v[190:193], v[174:177], v[0:3]
	s_setprio 0
	s_add_i32 s35, 0, 0x18000
	v_add_u32_e32 v108, s35, v225
	ds_read_b128 v[100:103], v108
	ds_read_b128 v[134:137], v108 offset:1024
	ds_read_b128 v[138:141], v108 offset:2048
	ds_read_b128 v[142:145], v108 offset:3072
	s_add_u32 s14, s76, 0x40000
	s_addc_u32 s15, s77, 0
	s_mov_b32 m0, s80
	v_lshl_add_u64 v[108:109], s[14:15], 0, v[198:199]
	ds_read_b128 v[146:149], v228 offset:32768
	ds_read_b128 v[154:157], v228 offset:34816
	ds_read_b128 v[162:165], v228 offset:36864
	ds_read_b128 v[170:173], v228 offset:38912
	global_load_lds_dwordx4 v[108:109], off
	s_mov_b32 m0, s81
	v_lshl_add_u64 v[108:109], s[14:15], 0, v[202:203]
	global_load_lds_dwordx4 v[108:109], off
	s_waitcnt lgkmcnt(4)
	s_setprio 1
	s_barrier
	ds_read_b128 v[150:153], v228 offset:33792
	ds_read_b128 v[158:161], v228 offset:35840
	ds_read_b128 v[166:169], v228 offset:37888
	ds_read_b128 v[174:177], v228 offset:39936
	s_waitcnt lgkmcnt(4)
	v_mfma_f32_16x16x32_bf16 v[130:133], v[100:103], v[146:149], v[130:133]
	v_mfma_f32_16x16x32_bf16 v[126:129], v[138:141], v[146:149], v[126:129]
	v_mfma_f32_16x16x32_bf16 v[114:117], v[100:103], v[154:157], v[114:117]
	v_mfma_f32_16x16x32_bf16 v[108:111], v[138:141], v[154:157], v[110:113]
	v_mfma_f32_16x16x32_bf16 v[92:95], v[100:103], v[162:165], v[92:95]
	v_mfma_f32_16x16x32_bf16 v[88:91], v[138:141], v[162:165], v[88:91]
	v_mfma_f32_16x16x32_bf16 v[76:79], v[100:103], v[170:173], v[76:79]
	v_mfma_f32_16x16x32_bf16 v[72:75], v[138:141], v[170:173], v[72:75]
	s_waitcnt lgkmcnt(3)
	v_mfma_f32_16x16x32_bf16 v[130:133], v[134:137], v[150:153], v[130:133]
	v_mfma_f32_16x16x32_bf16 v[126:129], v[142:145], v[150:153], v[126:129]
	s_waitcnt lgkmcnt(2)
	v_mfma_f32_16x16x32_bf16 v[114:117], v[134:137], v[158:161], v[114:117]
	v_mfma_f32_16x16x32_bf16 v[110:113], v[142:145], v[158:161], v[108:111]
	s_waitcnt lgkmcnt(1)
	v_mfma_f32_16x16x32_bf16 v[92:95], v[134:137], v[166:169], v[92:95]
	v_mfma_f32_16x16x32_bf16 v[88:91], v[142:145], v[166:169], v[88:91]
	s_waitcnt lgkmcnt(0)
	s_setprio 2
	s_barrier
	v_mfma_f32_16x16x32_bf16 v[76:79], v[134:137], v[174:177], v[76:79]
	v_mfma_f32_16x16x32_bf16 v[72:75], v[142:145], v[174:177], v[72:75]
	s_setprio 0
	s_add_i32 s76, 0, 0x1c000
	v_add_u32_e32 v108, s76, v225
	s_add_i32 s14, s35, s59
	ds_read_b128 v[178:181], v108
	ds_read_b128 v[182:185], v108 offset:1024
	ds_read_b128 v[186:189], v108 offset:2048
	ds_read_b128 v[190:193], v108 offset:3072
	s_mov_b32 m0, s14
	v_lshl_add_u64 v[108:109], v[194:195], 0, s[18:19]
	global_load_lds_dwordx4 v[108:109], off
	s_add_i32 m0, s14, 0x2000
	v_lshl_add_u64 v[108:109], v[196:197], 0, s[18:19]
	global_load_lds_dwordx4 v[108:109], off
	s_setprio 1
	s_barrier
	s_waitcnt lgkmcnt(0)
	v_mfma_f32_16x16x32_bf16 v[122:125], v[178:181], v[146:149], v[122:125]
	v_mfma_f32_16x16x32_bf16 v[118:121], v[186:189], v[146:149], v[118:121]
	v_mfma_f32_16x16x32_bf16 v[104:107], v[178:181], v[154:157], v[104:107]
	v_mfma_f32_16x16x32_bf16 v[96:99], v[186:189], v[154:157], v[96:99]
	v_mfma_f32_16x16x32_bf16 v[84:87], v[178:181], v[162:165], v[84:87]
	v_mfma_f32_16x16x32_bf16 v[80:83], v[186:189], v[162:165], v[80:83]
	v_mfma_f32_16x16x32_bf16 v[68:71], v[178:181], v[170:173], v[68:71]
	v_mfma_f32_16x16x32_bf16 v[64:67], v[186:189], v[170:173], v[64:67]
	v_mfma_f32_16x16x32_bf16 v[122:125], v[182:185], v[150:153], v[122:125]
	v_mfma_f32_16x16x32_bf16 v[118:121], v[190:193], v[150:153], v[118:121]
	v_mfma_f32_16x16x32_bf16 v[106:109], v[182:185], v[158:161], v[104:107]
	v_mfma_f32_16x16x32_bf16 v[96:99], v[190:193], v[158:161], v[96:99]
	v_mfma_f32_16x16x32_bf16 v[84:87], v[182:185], v[166:169], v[84:87]
	v_mfma_f32_16x16x32_bf16 v[80:83], v[190:193], v[166:169], v[80:83]
	s_setprio 2
	s_barrier
	v_mfma_f32_16x16x32_bf16 v[68:71], v[182:185], v[174:177], v[68:71]
	v_mfma_f32_16x16x32_bf16 v[64:67], v[190:193], v[174:177], v[64:67]
	s_setprio 0
	s_mov_b32 m0, s83
	v_lshl_add_u64 v[104:105], v[220:221], 0, s[18:19]
	ds_read_b128 v[146:149], v228 offset:49152
	ds_read_b128 v[154:157], v228 offset:51200
	ds_read_b128 v[162:165], v228 offset:53248
	ds_read_b128 v[170:173], v228 offset:55296
	global_load_lds_dwordx4 v[104:105], off
	s_mov_b32 m0, s84
	v_lshl_add_u64 v[104:105], v[232:233], 0, s[18:19]
	global_load_lds_dwordx4 v[104:105], off
	s_setprio 1
	s_barrier
; #define PG8_STAGE(bufoff, gbase, voff) do { _Pragma("unroll") for (int _i = 0; _i < 2; ++_i) \
;         __builtin_amdgcn_global_load_lds((const unsigned*)((const char*)(gbase) + (voff)[_i]), (LAS unsigned*)(lds + (bufoff) + ldsw + _i * 8192), 16, 0, 0); } while (0)
; #define PG8_LDA(dst, b, h) do { _Pragma("unroll") for (int m = 0; m < 4; ++m) _Pragma("unroll") for (int k = 0; k < 2; ++k) dst[m][k] = *(const LAS bf16x8*)(lds + PG8_SA(b, h) + aoff + m * 2048 + k * 1024); } while (0)
; #define PG8_WAIT_V(n) asm volatile("s_waitcnt vmcnt(" #n ")" ::: "memory")
; template <class Epi>
; DI void gemm_phase(LAS unsigned char* lds, const Gemm g, const StaticOrder S, const Epi E) {
;     ...
;             PG8_WAIT_L(8); PG8_BAR; PG8_WAIT_L(0); PG8_MMA(0, 0, At, B0); PG8_BAR; PG8_SCHED;
;             PG8_LDB(B1, 1, 1); PG8_STAGE(PG8_SB(1, 0), b3, voffB);
;             PG8_BAR; PG8_WAIT_L(0); PG8_MMA(0, 1, At, B1); PG8_BAR;
;             PG8_LDA(At, 1, 1); PG8_STAGE(PG8_SA(1, 0), a3, voffA);
;             PG8_BAR; PG8_WAIT_L(0); PG8_MMA(1, 0, At, B0); PG8_BAR; PG8_SCHED;
;             PG8_STAGE(PG8_SB(1, 1), b3 + hstep, voffB);
;             PG8_WAIT_V(6); PG8_BAR; PG8_MMA(1, 1, At, B1); PG8_BAR;
;     DI void operator()(AccRef acc, const Unit& u, int wr, int wc, int fr, int fq) const {
;         const int X = u.pn >> 2, h = u.pn & 3, isk = wc >> 1, i0 = (wc & 1) * 32 + 8 * fq;
;         bf16_t* dst = (X ? qkoB : qkoA) + h * 256 + isk * 128 + i0;
;         const float qs0 = isk ? 1.0f : 0.08838834764831845f;
;         const int row0 = u.pm * 256 + wr * 64 + fr;
;         const RowScales rsc = load_rowscales(ss, row0);
; #pragma unroll
;         for (int ai = 0; ai < 2; ++ai) {
;             f32x4 cs[4][2], sn[4][2];
;             if (X == 0) {
; #pragma unroll
;                 for (int m = 0; m < 4; ++m) {
;                     const int pos = (row0 + ai * 128 + m * 16) & (SEQ - 1);
;                     cs[m][0] = *(const f32x4*)(cosT + pos * 64 + i0); cs[m][1] = *(const f32x4*)(cosT + pos * 64 + i0 + 4);
;                     sn[m][0] = *(const f32x4*)(sinT + pos * 64 + i0); sn[m][1] = *(const f32x4*)(sinT + pos * 64 + i0 + 4);
;                 }
;             } else {
; #pragma unroll
;                 for (int m = 0; m < 4; ++m) { cs[m][0] = cs[m][1] = (f32x4){1.f, 1.f, 1.f, 1.f}; sn[m][0] = sn[m][1] = (f32x4){0.f, 0.f, 0.f, 0.f}; }
;             }
	ds_read_b128 v[150:153], v228 offset:50176
	ds_read_b128 v[158:161], v228 offset:52224
	ds_read_b128 v[166:169], v228 offset:54272
	ds_read_b128 v[174:177], v228 offset:56320
	s_waitcnt lgkmcnt(4)
	v_mfma_f32_16x16x32_bf16 v[60:63], v[100:103], v[146:149], v[60:63]
	v_mfma_f32_16x16x32_bf16 v[56:59], v[138:141], v[146:149], v[56:59]
	v_mfma_f32_16x16x32_bf16 v[44:47], v[100:103], v[154:157], v[44:47]
	v_mfma_f32_16x16x32_bf16 v[40:43], v[138:141], v[154:157], v[40:43]
	v_mfma_f32_16x16x32_bf16 v[28:31], v[100:103], v[162:165], v[28:31]
	v_mfma_f32_16x16x32_bf16 v[24:27], v[138:141], v[162:165], v[24:27]
	v_mfma_f32_16x16x32_bf16 v[12:15], v[100:103], v[170:173], v[12:15]
	v_mfma_f32_16x16x32_bf16 v[8:11], v[138:141], v[170:173], v[8:11]
	s_waitcnt lgkmcnt(3)
	v_mfma_f32_16x16x32_bf16 v[60:63], v[134:137], v[150:153], v[60:63]
	v_mfma_f32_16x16x32_bf16 v[56:59], v[142:145], v[150:153], v[56:59]
	s_waitcnt lgkmcnt(2)
	v_mfma_f32_16x16x32_bf16 v[44:47], v[134:137], v[158:161], v[44:47]
	v_mfma_f32_16x16x32_bf16 v[40:43], v[142:145], v[158:161], v[40:43]
	s_waitcnt lgkmcnt(1)
	v_mfma_f32_16x16x32_bf16 v[28:31], v[134:137], v[166:169], v[28:31]
	v_mfma_f32_16x16x32_bf16 v[24:27], v[142:145], v[166:169], v[24:27]
	s_waitcnt lgkmcnt(0)
	s_setprio 2
	s_barrier
	v_mfma_f32_16x16x32_bf16 v[12:15], v[134:137], v[174:177], v[12:15]
	v_mfma_f32_16x16x32_bf16 v[8:11], v[142:145], v[174:177], v[8:11]
	s_setprio 0
	s_add_u32 s14, s52, 0x40080
	s_addc_u32 s15, s53, 0
	s_add_i32 s35, s76, s59
	s_mov_b32 m0, s35
	v_lshl_add_u64 v[100:101], s[14:15], 0, v[200:201]
	global_load_lds_dwordx4 v[100:101], off
	s_add_i32 m0, s35, 0x2000
	v_lshl_add_u64 v[100:101], s[14:15], 0, v[204:205]
	global_load_lds_dwordx4 v[100:101], off
	s_waitcnt vmcnt(6)
	s_setprio 1
	s_barrier
	v_mfma_f32_16x16x32_bf16 v[52:55], v[178:181], v[146:149], v[52:55]
	v_mfma_f32_16x16x32_bf16 v[48:51], v[186:189], v[146:149], v[48:51]
	v_mfma_f32_16x16x32_bf16 v[36:39], v[178:181], v[154:157], v[36:39]
	v_mfma_f32_16x16x32_bf16 v[32:35], v[186:189], v[154:157], v[32:35]
	v_mfma_f32_16x16x32_bf16 v[20:23], v[178:181], v[162:165], v[20:23]
	v_mfma_f32_16x16x32_bf16 v[16:19], v[186:189], v[162:165], v[16:19]
	v_mfma_f32_16x16x32_bf16 v[4:7], v[178:181], v[170:173], v[4:7]
	v_mfma_f32_16x16x32_bf16 v[0:3], v[186:189], v[170:173], v[0:3]
	v_mfma_f32_16x16x32_bf16 v[52:55], v[182:185], v[150:153], v[52:55]
	v_mfma_f32_16x16x32_bf16 v[48:51], v[190:193], v[150:153], v[48:51]
	v_mfma_f32_16x16x32_bf16 v[36:39], v[182:185], v[158:161], v[36:39]
	v_mfma_f32_16x16x32_bf16 v[32:35], v[190:193], v[158:161], v[32:35]
	v_mfma_f32_16x16x32_bf16 v[20:23], v[182:185], v[166:169], v[20:23]
	v_mfma_f32_16x16x32_bf16 v[16:19], v[190:193], v[166:169], v[16:19]
	s_setprio 2
	s_barrier
	v_mfma_f32_16x16x32_bf16 v[4:7], v[182:185], v[174:177], v[4:7]
	v_mfma_f32_16x16x32_bf16 v[0:3], v[190:193], v[174:177], v[0:3]
	s_setprio 0
	s_add_i32 s95, s95, 2
	s_add_u32 s8, s8, 0x100
	s_addc_u32 s9, s9, 0
	s_add_u32 s23, s23, 0x100
	s_addc_u32 s94, s94, 0
	s_cmp_gt_u32 s95, 13
	s_cbranch_scc0 .LBB0_274
	v_lshl_add_u32 v102, s0, 8, v224
	v_ashrrev_i32_e32 v103, 31, v102
	v_lshl_add_u64 v[134:135], v[102:103], 2, s[60:61]
	global_load_dword v237, v[134:135], off
	global_load_dword v236, v[134:135], off offset:64
	global_load_dword v105, v[134:135], off offset:128
	global_load_dword v101, v[134:135], off offset:192
	global_load_dword v231, v[134:135], off offset:512
	global_load_dword v232, v[134:135], off offset:576
	global_load_dword v233, v[134:135], off offset:640
	global_load_dword v234, v[134:135], off offset:704
	s_cmp_lt_u32 s93, 4
	s_cselect_b64 s[0:1], -1, 0
	s_cmp_gt_u32 s93, 3
	v_lshlrev_b32_e32 v235, 6, v102
	v_mov_b32_e32 v100, 1.0
	v_mov_b32_e32 v104, 0
	v_mov_b32_e32 v134, 0
	v_mov_b32_e32 v135, 0
	v_mov_b32_e32 v136, 0
	v_mov_b32_e32 v137, 0
	v_mov_b32_e32 v142, 0
	v_mov_b32_e32 v143, 0
	v_mov_b32_e32 v144, 0
	v_mov_b32_e32 v145, 0
	v_mov_b32_e32 v146, 0
	v_mov_b32_e32 v147, 0
	v_mov_b32_e32 v148, 0
	v_mov_b32_e32 v149, 0
	v_mov_b32_e32 v154, 0
	v_mov_b32_e32 v155, 0
	v_mov_b32_e32 v156, 0
	v_mov_b32_e32 v157, 0
	v_mov_b32_e32 v162, 0
	v_mov_b32_e32 v163, 0
	v_mov_b32_e32 v164, 0
	v_mov_b32_e32 v165, 0
	v_mov_b32_e32 v174, 0
	v_mov_b32_e32 v175, 0
	v_mov_b32_e32 v176, 0
	v_mov_b32_e32 v177, 0
	v_mov_b32_e32 v182, 0
	v_mov_b32_e32 v183, 0
	v_mov_b32_e32 v184, 0
	v_mov_b32_e32 v185, 0
	v_mov_b32_e32 v194, 0
	v_mov_b32_e32 v195, 0
	v_mov_b32_e32 v196, 0
	v_mov_b32_e32 v197, 0
	v_mov_b32_e32 v138, 1.0
	v_mov_b32_e32 v139, 1.0
	v_mov_b32_e32 v140, 1.0
	v_mov_b32_e32 v141, 1.0
	v_mov_b32_e32 v190, 1.0
	v_mov_b32_e32 v191, 1.0
	v_mov_b32_e32 v192, 1.0
	v_mov_b32_e32 v193, 1.0
	v_mov_b32_e32 v186, 1.0
	v_mov_b32_e32 v187, 1.0
	v_mov_b32_e32 v188, 1.0
	v_mov_b32_e32 v189, 1.0
	v_mov_b32_e32 v178, 1.0
	v_mov_b32_e32 v179, 1.0
	v_mov_b32_e32 v180, 1.0
	v_mov_b32_e32 v181, 1.0
	v_mov_b32_e32 v170, 1.0
	v_mov_b32_e32 v171, 1.0
	v_mov_b32_e32 v172, 1.0
	v_mov_b32_e32 v173, 1.0
	v_mov_b32_e32 v166, 1.0
	v_mov_b32_e32 v167, 1.0
	v_mov_b32_e32 v168, 1.0
	v_mov_b32_e32 v169, 1.0
	v_mov_b32_e32 v158, 1.0
	v_mov_b32_e32 v159, 1.0
	v_mov_b32_e32 v160, 1.0
	v_mov_b32_e32 v161, 1.0
	v_mov_b32_e32 v150, 1.0
	v_mov_b32_e32 v151, 1.0
	v_mov_b32_e32 v152, 1.0
	v_mov_b32_e32 v153, 1.0
	s_cbranch_scc1 .LBB0_277
	v_lshlrev_b32_e32 v134, 2, v235
	v_and_b32_e32 v134, 0x1fcf00, v134
	v_mov_b32_e32 v135, v207
	v_lshl_add_u64 v[136:137], v[208:209], 0, v[134:135]
	global_load_dwordx4 v[190:193], v[136:137], off
	global_load_dwordx4 v[186:189], v[136:137], off offset:16
	v_lshl_add_u64 v[136:137], v[210:211], 0, v[134:135]
	global_load_dwordx4 v[182:185], v[136:137], off offset:16
	global_load_dwordx4 v[194:197], v[136:137], off
	v_or_b32_e32 v136, 0x1000, v134
	v_mov_b32_e32 v137, v207
	v_lshl_add_u64 v[138:139], v[208:209], 0, v[136:137]
	v_lshl_add_u64 v[136:137], v[210:211], 0, v[136:137]
	global_load_dwordx4 v[178:181], v[138:139], off
	global_load_dwordx4 v[170:173], v[138:139], off offset:16
	global_load_dwordx4 v[162:165], v[136:137], off offset:16
	global_load_dwordx4 v[174:177], v[136:137], off
	v_or_b32_e32 v136, 0x2000, v134
	v_mov_b32_e32 v137, v207
	v_lshl_add_u64 v[138:139], v[208:209], 0, v[136:137]
	v_lshl_add_u64 v[136:137], v[210:211], 0, v[136:137]
	v_or_b32_e32 v134, 0x3000, v134
	global_load_dwordx4 v[166:169], v[138:139], off
	global_load_dwordx4 v[158:161], v[138:139], off offset:16
	global_load_dwordx4 v[146:149], v[136:137], off offset:16
	global_load_dwordx4 v[154:157], v[136:137], off
	v_lshl_add_u64 v[136:137], v[208:209], 0, v[134:135]
	v_lshl_add_u64 v[142:143], v[210:211], 0, v[134:135]
	global_load_dwordx4 v[138:141], v[136:137], off offset:16
	global_load_dwordx4 v[150:153], v[136:137], off
	s_nop 0
	global_load_dwordx4 v[134:137], v[142:143], off offset:16
	s_nop 0
	global_load_dwordx4 v[142:145], v[142:143], off

; #define PG8_STAGE(bufoff, gbase, voff) do { _Pragma("unroll") for (int _i = 0; _i < 2; ++_i) \
;         __builtin_amdgcn_global_load_lds((const unsigned*)((const char*)(gbase) + (voff)[_i]), (LAS unsigned*)(lds + (bufoff) + ldsw + _i * 8192), 16, 0, 0); } while (0)
; #define PG8_LDA(dst, b, h) do { _Pragma("unroll") for (int m = 0; m < 4; ++m) _Pragma("unroll") for (int k = 0; k < 2; ++k) dst[m][k] = *(const LAS bf16x8*)(lds + PG8_SA(b, h) + aoff + m * 2048 + k * 1024); } while (0)
; #define PG8_LDB(dst, b, h) do { _Pragma("unroll") for (int n = 0; n < 2; ++n) _Pragma("unroll") for (int k = 0; k < 2; ++k) dst[n][k] = *(const LAS bf16x8*)(lds + PG8_SB(b, h) + boff + n * 2048 + k * 1024); } while (0)
; #define PG8_MMA(ai, bj, At, Bt) do { __builtin_amdgcn_s_setprio(1); _Pragma("unroll") for (int m = 0; m < 4; ++m) _Pragma("unroll") for (int n = 0; n < 2; ++n) _Pragma("unroll") for (int k = 0; k < 2; ++k) \
;         acc[ai][bj][m][n] = __builtin_amdgcn_mfma_f32_16x16x32_bf16(Bt[n][k], At[m][k], acc[ai][bj][m][n], 0, 0, 0); __builtin_amdgcn_s_setprio(0); } while (0)
; #define PG8_WAIT_V(n) asm volatile("s_waitcnt vmcnt(" #n ")" ::: "memory")
; #define PG8_WAIT_L(n) asm volatile("s_waitcnt lgkmcnt(" #n ")" ::: "memory")
; #define PG8_BAR __builtin_amdgcn_s_barrier()
; #define PG8_SCHED __builtin_amdgcn_sched_barrier(0)
; #define PG8_WAIT_V(n) asm volatile("s_waitcnt vmcnt(" #n ")" ::: "memory")
; template <class Epi>
; DI void gemm_phase(LAS unsigned char* lds, const Gemm g, const StaticOrder S, const Epi E) {
;     ...
;             PG8_LDB(B0, 0, 0); PG8_SCHED; PG8_LDA(At, 0, 0); PG8_STAGE(PG8_SA(1, 1), a1 + hstep, voffA);
;             PG8_WAIT_L(8); PG8_BAR; PG8_WAIT_L(0); PG8_MMA(0, 0, At, B0); PG8_BAR; PG8_SCHED;
;             PG8_LDB(B1, 0, 1); PG8_STAGE(PG8_SB(0, 0), b2, voffB);
;             PG8_BAR; PG8_WAIT_L(0); PG8_MMA(0, 1, At, B1); PG8_BAR;
;             PG8_LDA(At, 0, 1); PG8_STAGE(PG8_SA(0, 0), a2, voffA);
;             PG8_BAR; PG8_WAIT_L(0); PG8_MMA(1, 0, At, B0); PG8_BAR; PG8_SCHED;
;             PG8_STAGE(PG8_SB(0, 1), b2 + hstep, voffB);
;             PG8_WAIT_V(6); PG8_BAR; PG8_MMA(1, 1, At, B1); PG8_BAR;
;             PG8_LDB(B0, 1, 0); PG8_SCHED; PG8_LDA(At, 1, 0); PG8_STAGE(PG8_SA(0, 1), a2 + hstep, voffA);
;             PG8_WAIT_L(8); PG8_BAR; PG8_WAIT_L(0); PG8_MMA(0, 0, At, B0); PG8_BAR; PG8_SCHED;
.LBB0_298:
	ds_read_b128 v[128:131], v168
	ds_read_b128 v[132:135], v168 offset:1024
	ds_read_b128 v[154:157], v168 offset:2048
	ds_read_b128 v[158:161], v168 offset:3072
	s_add_u32 s5, s8, 0xfffc0080
	s_addc_u32 s14, s9, -1
	s_cmp_eq_u32 s4, 12
	s_cselect_b32 s81, s6, s14
	s_cselect_b32 s80, s7, s5
	s_cselect_b32 s79, s21, vcc_hi
	s_cselect_b32 s78, s23, vcc_lo
	v_lshl_add_u64 v[162:163], s[8:9], 0, v[146:147]
	s_add_i32 m0, s58, 0xc000
	ds_read_b128 v[172:175], v169
	ds_read_b128 v[180:183], v169 offset:2048
	ds_read_b128 v[188:191], v169 offset:4096
	ds_read_b128 v[196:199], v169 offset:6144
	global_load_lds_dwordx4 v[162:163], off
	s_add_i32 m0, s58, 0xe000
	v_lshl_add_u64 v[162:163], s[8:9], 0, v[148:149]
	global_load_lds_dwordx4 v[162:163], off
	s_waitcnt lgkmcnt(4)
	s_setprio 1
	s_barrier
	ds_read_b128 v[176:179], v169 offset:1024
	ds_read_b128 v[184:187], v169 offset:3072
	ds_read_b128 v[192:195], v169 offset:5120
	ds_read_b128 v[200:203], v169 offset:7168
	s_waitcnt lgkmcnt(4)
	v_mfma_f32_16x16x32_bf16 v[124:127], v[128:131], v[172:175], v[124:127]
	v_mfma_f32_16x16x32_bf16 v[120:123], v[154:157], v[172:175], v[120:123]
	v_mfma_f32_16x16x32_bf16 v[112:115], v[128:131], v[180:183], v[112:115]
	v_mfma_f32_16x16x32_bf16 v[104:107], v[154:157], v[180:183], v[104:107]
	v_mfma_f32_16x16x32_bf16 v[96:99], v[128:131], v[188:191], v[96:99]
	v_mfma_f32_16x16x32_bf16 v[88:91], v[154:157], v[188:191], v[88:91]
	v_mfma_f32_16x16x32_bf16 v[80:83], v[128:131], v[196:199], v[80:83]
	v_mfma_f32_16x16x32_bf16 v[72:75], v[154:157], v[196:199], v[72:75]
	s_waitcnt lgkmcnt(3)
	v_mfma_f32_16x16x32_bf16 v[124:127], v[132:135], v[176:179], v[124:127]
	v_mfma_f32_16x16x32_bf16 v[120:123], v[158:161], v[176:179], v[120:123]
	s_waitcnt lgkmcnt(2)
	v_mfma_f32_16x16x32_bf16 v[112:115], v[132:135], v[184:187], v[112:115]
	v_mfma_f32_16x16x32_bf16 v[104:107], v[158:161], v[184:187], v[104:107]
	s_waitcnt lgkmcnt(1)
	v_mfma_f32_16x16x32_bf16 v[96:99], v[132:135], v[192:195], v[96:99]
	v_mfma_f32_16x16x32_bf16 v[88:91], v[158:161], v[192:195], v[88:91]
	s_waitcnt lgkmcnt(0)
	s_setprio 2
	s_barrier
	v_mfma_f32_16x16x32_bf16 v[80:83], v[132:135], v[200:203], v[80:83]
	v_mfma_f32_16x16x32_bf16 v[72:75], v[158:161], v[200:203], v[72:75]
	s_setprio 0
	s_add_i32 s5, s94, s19
	v_lshl_add_u64 v[162:163], s[78:79], 0, v[138:139]
	s_mov_b32 m0, s5
	ds_read_b128 v[204:207], v170
	ds_read_b128 v[208:211], v170 offset:1024
	ds_read_b128 v[212:215], v170 offset:2048
	ds_read_b128 v[216:219], v170 offset:3072
	global_load_lds_dwordx4 v[162:163], off
	s_add_i32 m0, s5, 0x2000
	v_lshl_add_u64 v[220:221], s[78:79], 0, v[142:143]
	global_load_lds_dwordx4 v[220:221], off
	s_setprio 1
	s_barrier
	s_waitcnt lgkmcnt(0)
	v_mfma_f32_16x16x32_bf16 v[116:119], v[204:207], v[172:175], v[116:119]
	v_mfma_f32_16x16x32_bf16 v[108:111], v[212:215], v[172:175], v[108:111]
	v_mfma_f32_16x16x32_bf16 v[100:103], v[204:207], v[180:183], v[100:103]
	v_mfma_f32_16x16x32_bf16 v[92:95], v[212:215], v[180:183], v[92:95]
	v_mfma_f32_16x16x32_bf16 v[84:87], v[204:207], v[188:191], v[84:87]
	v_mfma_f32_16x16x32_bf16 v[76:79], v[212:215], v[188:191], v[76:79]
	v_mfma_f32_16x16x32_bf16 v[68:71], v[204:207], v[196:199], v[68:71]
	v_mfma_f32_16x16x32_bf16 v[64:67], v[212:215], v[196:199], v[64:67]
	v_mfma_f32_16x16x32_bf16 v[116:119], v[208:211], v[176:179], v[116:119]
	v_mfma_f32_16x16x32_bf16 v[108:111], v[216:219], v[176:179], v[108:111]
	v_mfma_f32_16x16x32_bf16 v[100:103], v[208:211], v[184:187], v[100:103]
	v_mfma_f32_16x16x32_bf16 v[92:95], v[216:219], v[184:187], v[92:95]
	v_mfma_f32_16x16x32_bf16 v[84:87], v[208:211], v[192:195], v[84:87]
	v_mfma_f32_16x16x32_bf16 v[76:79], v[216:219], v[192:195], v[76:79]
	s_setprio 2
	s_barrier
	v_mfma_f32_16x16x32_bf16 v[68:71], v[208:211], v[200:203], v[68:71]
	v_mfma_f32_16x16x32_bf16 v[64:67], v[216:219], v[200:203], v[64:67]
	s_setprio 0
	s_mov_b32 m0, s58
	v_lshl_add_u64 v[224:225], s[80:81], 0, v[136:137]
	ds_read_b128 v[172:175], v169 offset:16384
	ds_read_b128 v[180:183], v169 offset:18432
	ds_read_b128 v[188:191], v169 offset:20480
	ds_read_b128 v[196:199], v169 offset:22528
	global_load_lds_dwordx4 v[224:225], off
	s_mov_b32 m0, s59
	v_lshl_add_u64 v[226:227], s[80:81], 0, v[140:141]
	global_load_lds_dwordx4 v[226:227], off
	s_setprio 1
	s_barrier
	ds_read_b128 v[176:179], v169 offset:17408
	ds_read_b128 v[184:187], v169 offset:19456
	ds_read_b128 v[192:195], v169 offset:21504
	ds_read_b128 v[200:203], v169 offset:23552
	s_waitcnt lgkmcnt(4)
	v_mfma_f32_16x16x32_bf16 v[60:63], v[128:131], v[172:175], v[60:63]
	v_mfma_f32_16x16x32_bf16 v[56:59], v[154:157], v[172:175], v[56:59]
	v_mfma_f32_16x16x32_bf16 v[48:51], v[128:131], v[180:183], v[48:51]
	v_mfma_f32_16x16x32_bf16 v[40:43], v[154:157], v[180:183], v[40:43]
	v_mfma_f32_16x16x32_bf16 v[32:35], v[128:131], v[188:191], v[32:35]
	v_mfma_f32_16x16x32_bf16 v[24:27], v[154:157], v[188:191], v[24:27]
	v_mfma_f32_16x16x32_bf16 v[16:19], v[128:131], v[196:199], v[16:19]
	v_mfma_f32_16x16x32_bf16 v[8:11], v[154:157], v[196:199], v[8:11]
	s_waitcnt lgkmcnt(3)
	v_mfma_f32_16x16x32_bf16 v[60:63], v[132:135], v[176:179], v[60:63]
	v_mfma_f32_16x16x32_bf16 v[56:59], v[158:161], v[176:179], v[56:59]
	s_waitcnt lgkmcnt(2)
	v_mfma_f32_16x16x32_bf16 v[48:51], v[132:135], v[184:187], v[48:51]
	v_mfma_f32_16x16x32_bf16 v[40:43], v[158:161], v[184:187], v[40:43]
	s_waitcnt lgkmcnt(1)
	v_mfma_f32_16x16x32_bf16 v[32:35], v[132:135], v[192:195], v[32:35]
	v_mfma_f32_16x16x32_bf16 v[24:27], v[158:161], v[192:195], v[24:27]
	s_waitcnt lgkmcnt(0)
	s_setprio 2
	s_barrier
; #define PG8_STAGE(bufoff, gbase, voff) do { _Pragma("unroll") for (int _i = 0; _i < 2; ++_i) \
;         __builtin_amdgcn_global_load_lds((const unsigned*)((const char*)(gbase) + (voff)[_i]), (LAS unsigned*)(lds + (bufoff) + ldsw + _i * 8192), 16, 0, 0); } while (0)
; #define PG8_LDA(dst, b, h) do { _Pragma("unroll") for (int m = 0; m < 4; ++m) _Pragma("unroll") for (int k = 0; k < 2; ++k) dst[m][k] = *(const LAS bf16x8*)(lds + PG8_SA(b, h) + aoff + m * 2048 + k * 1024); } while (0)
; #define PG8_LDB(dst, b, h) do { _Pragma("unroll") for (int n = 0; n < 2; ++n) _Pragma("unroll") for (int k = 0; k < 2; ++k) dst[n][k] = *(const LAS bf16x8*)(lds + PG8_SB(b, h) + boff + n * 2048 + k * 1024); } while (0)
; #define PG8_MMA(ai, bj, At, Bt) do { __builtin_amdgcn_s_setprio(1); _Pragma("unroll") for (int m = 0; m < 4; ++m) _Pragma("unroll") for (int n = 0; n < 2; ++n) _Pragma("unroll") for (int k = 0; k < 2; ++k) \
;         acc[ai][bj][m][n] = __builtin_amdgcn_mfma_f32_16x16x32_bf16(Bt[n][k], At[m][k], acc[ai][bj][m][n], 0, 0, 0); __builtin_amdgcn_s_setprio(0); } while (0)
; #define PG8_WAIT_V(n) asm volatile("s_waitcnt vmcnt(" #n ")" ::: "memory")
; #define PG8_WAIT_L(n) asm volatile("s_waitcnt lgkmcnt(" #n ")" ::: "memory")
; #define PG8_BAR __builtin_amdgcn_s_barrier()
; #define PG8_SCHED __builtin_amdgcn_sched_barrier(0)
; #define PG8_LDA(dst, b, h) do { _Pragma("unroll") for (int m = 0; m < 4; ++m) _Pragma("unroll") for (int k = 0; k < 2; ++k) dst[m][k] = *(const LAS bf16x8*)(lds + PG8_SA(b, h) + aoff + m * 2048 + k * 1024); } while (0)
; template <class Epi>
; DI void gemm_phase(LAS unsigned char* lds, const Gemm g, const StaticOrder S, const Epi E) {
;     ...
;             PG8_BAR; PG8_WAIT_L(0); PG8_MMA(1, 0, At, B0); PG8_BAR; PG8_SCHED;
;             PG8_STAGE(PG8_SB(0, 1), b2 + hstep, voffB);
;             PG8_WAIT_V(6); PG8_BAR; PG8_MMA(1, 1, At, B1); PG8_BAR;
;             PG8_LDB(B0, 1, 0); PG8_SCHED; PG8_LDA(At, 1, 0); PG8_STAGE(PG8_SA(0, 1), a2 + hstep, voffA);
;             PG8_WAIT_L(8); PG8_BAR; PG8_WAIT_L(0); PG8_MMA(0, 0, At, B0); PG8_BAR; PG8_SCHED;
;             PG8_LDB(B1, 1, 1); PG8_STAGE(PG8_SB(1, 0), b3, voffB);
;             PG8_BAR; PG8_WAIT_L(0); PG8_MMA(0, 1, At, B1); PG8_BAR;
;             PG8_LDA(At, 1, 1); PG8_STAGE(PG8_SA(1, 0), a3, voffA);
;             PG8_BAR; PG8_WAIT_L(0); PG8_MMA(1, 0, At, B0); PG8_BAR; PG8_SCHED;
	v_mfma_f32_16x16x32_bf16 v[16:19], v[132:135], v[200:203], v[16:19]
	v_mfma_f32_16x16x32_bf16 v[8:11], v[158:161], v[200:203], v[8:11]
	s_setprio 0
	s_add_u32 s14, s78, 0x40000
	s_addc_u32 s15, s79, 0
	s_add_i32 s5, s95, s19
	s_mov_b32 m0, s5
	v_lshl_add_u64 v[128:129], s[14:15], 0, v[138:139]
	global_load_lds_dwordx4 v[128:129], off
	s_add_i32 m0, s5, 0x2000
	v_lshl_add_u64 v[128:129], s[14:15], 0, v[142:143]
	global_load_lds_dwordx4 v[128:129], off
	s_waitcnt vmcnt(6)
	s_setprio 1
	s_barrier
	v_mfma_f32_16x16x32_bf16 v[52:55], v[204:207], v[172:175], v[52:55]
	v_mfma_f32_16x16x32_bf16 v[44:47], v[212:215], v[172:175], v[44:47]
	v_mfma_f32_16x16x32_bf16 v[36:39], v[204:207], v[180:183], v[36:39]
	v_mfma_f32_16x16x32_bf16 v[28:31], v[212:215], v[180:183], v[28:31]
	v_mfma_f32_16x16x32_bf16 v[20:23], v[204:207], v[188:191], v[20:23]
	v_mfma_f32_16x16x32_bf16 v[12:15], v[212:215], v[188:191], v[12:15]
	v_mfma_f32_16x16x32_bf16 v[4:7], v[204:207], v[196:199], v[4:7]
	v_mfma_f32_16x16x32_bf16 v[0:3], v[212:215], v[196:199], v[0:3]
	v_mfma_f32_16x16x32_bf16 v[52:55], v[208:211], v[176:179], v[52:55]
	v_mfma_f32_16x16x32_bf16 v[44:47], v[216:219], v[176:179], v[44:47]
	v_mfma_f32_16x16x32_bf16 v[36:39], v[208:211], v[184:187], v[36:39]
	v_mfma_f32_16x16x32_bf16 v[28:31], v[216:219], v[184:187], v[28:31]
	v_mfma_f32_16x16x32_bf16 v[20:23], v[208:211], v[192:195], v[20:23]
	v_mfma_f32_16x16x32_bf16 v[12:15], v[216:219], v[192:195], v[12:15]
	s_setprio 2
	s_barrier
	v_mfma_f32_16x16x32_bf16 v[4:7], v[208:211], v[200:203], v[4:7]
	v_mfma_f32_16x16x32_bf16 v[0:3], v[216:219], v[200:203], v[0:3]
	s_setprio 0
	s_add_i32 s5, 0, 0x18000
	v_add_u32_e32 v158, s5, v165
	ds_read_b128 v[128:131], v158
	ds_read_b128 v[132:135], v158 offset:1024
	ds_read_b128 v[154:157], v158 offset:2048
	ds_read_b128 v[158:161], v158 offset:3072
	s_add_u32 s14, s80, 0x40000
	s_addc_u32 s15, s81, 0
	s_mov_b32 m0, s77
	v_lshl_add_u64 v[204:205], s[14:15], 0, v[136:137]
	ds_read_b128 v[172:175], v169 offset:32768
	ds_read_b128 v[180:183], v169 offset:34816
	ds_read_b128 v[188:191], v169 offset:36864
	ds_read_b128 v[196:199], v169 offset:38912
	global_load_lds_dwordx4 v[204:205], off
	s_mov_b32 m0, s82
	v_lshl_add_u64 v[204:205], s[14:15], 0, v[140:141]
	global_load_lds_dwordx4 v[204:205], off
	s_waitcnt lgkmcnt(4)
	s_setprio 1
	s_barrier
	ds_read_b128 v[176:179], v169 offset:33792
	ds_read_b128 v[184:187], v169 offset:35840
	ds_read_b128 v[192:195], v169 offset:37888
	ds_read_b128 v[200:203], v169 offset:39936
	s_waitcnt lgkmcnt(4)
	v_mfma_f32_16x16x32_bf16 v[124:127], v[128:131], v[172:175], v[124:127]
	v_mfma_f32_16x16x32_bf16 v[120:123], v[154:157], v[172:175], v[120:123]
	v_mfma_f32_16x16x32_bf16 v[112:115], v[128:131], v[180:183], v[112:115]
	v_mfma_f32_16x16x32_bf16 v[104:107], v[154:157], v[180:183], v[104:107]
	v_mfma_f32_16x16x32_bf16 v[96:99], v[128:131], v[188:191], v[96:99]
	v_mfma_f32_16x16x32_bf16 v[88:91], v[154:157], v[188:191], v[88:91]
	v_mfma_f32_16x16x32_bf16 v[80:83], v[128:131], v[196:199], v[80:83]
	v_mfma_f32_16x16x32_bf16 v[72:75], v[154:157], v[196:199], v[72:75]
	s_waitcnt lgkmcnt(3)
	v_mfma_f32_16x16x32_bf16 v[124:127], v[132:135], v[176:179], v[124:127]
	v_mfma_f32_16x16x32_bf16 v[120:123], v[158:161], v[176:179], v[120:123]
	s_waitcnt lgkmcnt(2)
	v_mfma_f32_16x16x32_bf16 v[112:115], v[132:135], v[184:187], v[112:115]
	v_mfma_f32_16x16x32_bf16 v[104:107], v[158:161], v[184:187], v[104:107]
	s_waitcnt lgkmcnt(1)
	v_mfma_f32_16x16x32_bf16 v[96:99], v[132:135], v[192:195], v[96:99]
	v_mfma_f32_16x16x32_bf16 v[88:91], v[158:161], v[192:195], v[88:91]
	s_waitcnt lgkmcnt(0)
	s_setprio 2
	s_barrier
	v_mfma_f32_16x16x32_bf16 v[80:83], v[132:135], v[200:203], v[80:83]
	v_mfma_f32_16x16x32_bf16 v[72:75], v[158:161], v[200:203], v[72:75]
	s_setprio 0
	s_add_i32 s35, 0, 0x1c000
	s_add_i32 s5, s5, s19
	v_add_u32_e32 v171, s35, v165
	v_lshl_add_u64 v[162:163], v[162:163], 0, s[10:11]
	s_mov_b32 m0, s5
	ds_read_b128 v[204:207], v171
	ds_read_b128 v[208:211], v171 offset:1024
	ds_read_b128 v[212:215], v171 offset:2048
	ds_read_b128 v[216:219], v171 offset:3072
	global_load_lds_dwordx4 v[162:163], off
	s_add_i32 m0, s5, 0x2000
	v_lshl_add_u64 v[162:163], v[220:221], 0, s[10:11]
	global_load_lds_dwordx4 v[162:163], off
	s_setprio 1
	s_barrier
	s_waitcnt lgkmcnt(0)
	v_mfma_f32_16x16x32_bf16 v[116:119], v[204:207], v[172:175], v[116:119]
	v_mfma_f32_16x16x32_bf16 v[108:111], v[212:215], v[172:175], v[108:111]
	v_mfma_f32_16x16x32_bf16 v[100:103], v[204:207], v[180:183], v[100:103]
	v_mfma_f32_16x16x32_bf16 v[92:95], v[212:215], v[180:183], v[92:95]
	v_mfma_f32_16x16x32_bf16 v[84:87], v[204:207], v[188:191], v[84:87]
	v_mfma_f32_16x16x32_bf16 v[76:79], v[212:215], v[188:191], v[76:79]
	v_mfma_f32_16x16x32_bf16 v[68:71], v[204:207], v[196:199], v[68:71]
	v_mfma_f32_16x16x32_bf16 v[64:67], v[212:215], v[196:199], v[64:67]
	v_mfma_f32_16x16x32_bf16 v[116:119], v[208:211], v[176:179], v[116:119]
	v_mfma_f32_16x16x32_bf16 v[108:111], v[216:219], v[176:179], v[108:111]
	v_mfma_f32_16x16x32_bf16 v[100:103], v[208:211], v[184:187], v[100:103]
	v_mfma_f32_16x16x32_bf16 v[92:95], v[216:219], v[184:187], v[92:95]
	v_mfma_f32_16x16x32_bf16 v[84:87], v[208:211], v[192:195], v[84:87]
	v_mfma_f32_16x16x32_bf16 v[76:79], v[216:219], v[192:195], v[76:79]
	s_setprio 2
	s_barrier
	v_mfma_f32_16x16x32_bf16 v[68:71], v[208:211], v[200:203], v[68:71]
	v_mfma_f32_16x16x32_bf16 v[64:67], v[216:219], v[200:203], v[64:67]
	s_setprio 0
	s_mov_b32 m0, s86
	v_lshl_add_u64 v[162:163], v[224:225], 0, s[10:11]
	ds_read_b128 v[172:175], v169 offset:49152
	ds_read_b128 v[180:183], v169 offset:51200
	ds_read_b128 v[188:191], v169 offset:53248
	ds_read_b128 v[196:199], v169 offset:55296
	global_load_lds_dwordx4 v[162:163], off
	s_mov_b32 m0, s87
	v_lshl_add_u64 v[162:163], v[226:227], 0, s[10:11]
	global_load_lds_dwordx4 v[162:163], off
	s_setprio 1
	s_barrier
; #define PG8_STAGE(bufoff, gbase, voff) do { _Pragma("unroll") for (int _i = 0; _i < 2; ++_i) \
;         __builtin_amdgcn_global_load_lds((const unsigned*)((const char*)(gbase) + (voff)[_i]), (LAS unsigned*)(lds + (bufoff) + ldsw + _i * 8192), 16, 0, 0); } while (0)
; #define PG8_LDA(dst, b, h) do { _Pragma("unroll") for (int m = 0; m < 4; ++m) _Pragma("unroll") for (int k = 0; k < 2; ++k) dst[m][k] = *(const LAS bf16x8*)(lds + PG8_SA(b, h) + aoff + m * 2048 + k * 1024); } while (0)
; #define PG8_LDB(dst, b, h) do { _Pragma("unroll") for (int n = 0; n < 2; ++n) _Pragma("unroll") for (int k = 0; k < 2; ++k) dst[n][k] = *(const LAS bf16x8*)(lds + PG8_SB(b, h) + boff + n * 2048 + k * 1024); } while (0)
; #define PG8_MMA(ai, bj, At, Bt) do { __builtin_amdgcn_s_setprio(1); _Pragma("unroll") for (int m = 0; m < 4; ++m) _Pragma("unroll") for (int n = 0; n < 2; ++n) _Pragma("unroll") for (int k = 0; k < 2; ++k) \
;         acc[ai][bj][m][n] = __builtin_amdgcn_mfma_f32_16x16x32_bf16(Bt[n][k], At[m][k], acc[ai][bj][m][n], 0, 0, 0); __builtin_amdgcn_s_setprio(0); } while (0)
; #define PG8_WAIT_V(n) asm volatile("s_waitcnt vmcnt(" #n ")" ::: "memory")
; template <class Epi>
; DI void gemm_phase(LAS unsigned char* lds, const Gemm g, const StaticOrder S, const Epi E) {
;     ...
;             PG8_WAIT_L(8); PG8_BAR; PG8_WAIT_L(0); PG8_MMA(0, 0, At, B0); PG8_BAR; PG8_SCHED;
;             PG8_LDB(B1, 1, 1); PG8_STAGE(PG8_SB(1, 0), b3, voffB);
;             PG8_BAR; PG8_WAIT_L(0); PG8_MMA(0, 1, At, B1); PG8_BAR;
;             PG8_LDA(At, 1, 1); PG8_STAGE(PG8_SA(1, 0), a3, voffA);
;             PG8_BAR; PG8_WAIT_L(0); PG8_MMA(1, 0, At, B0); PG8_BAR; PG8_SCHED;
;             PG8_STAGE(PG8_SB(1, 1), b3 + hstep, voffB);
;             PG8_WAIT_V(6); PG8_BAR; PG8_MMA(1, 1, At, B1); PG8_BAR;
;     DI void operator()(AccRef acc, const Unit& u, int wr, int wc, int fr, int fq) const {
;         f32x4 ts[2][2];
; #pragma unroll
;         for (int bj = 0; bj < 2; ++bj) { const int tok = u.pn * 256 + bj * 128 + wc * 32 + 8 * fq; ts[bj][0] = *(const f32x4*)(ss + tok); ts[bj][1] = *(const f32x4*)(ss + tok + 4); }
; #pragma unroll
;         for (int bj = 0; bj < 2; ++bj)
; #pragma unroll
;             for (int n = 0; n < 2; ++n)
; #pragma unroll
;                 for (int e = 0; e < 4; ++e) ts[bj][n][e] = rsqrtf(ts[bj][n][e] * (1.0f / 1024.0f) + 1e-6f);
	ds_read_b128 v[176:179], v169 offset:50176
	ds_read_b128 v[184:187], v169 offset:52224
	ds_read_b128 v[192:195], v169 offset:54272
	ds_read_b128 v[200:203], v169 offset:56320
	s_waitcnt lgkmcnt(4)
	v_mfma_f32_16x16x32_bf16 v[60:63], v[128:131], v[172:175], v[60:63]
	v_mfma_f32_16x16x32_bf16 v[56:59], v[154:157], v[172:175], v[56:59]
	v_mfma_f32_16x16x32_bf16 v[48:51], v[128:131], v[180:183], v[48:51]
	v_mfma_f32_16x16x32_bf16 v[40:43], v[154:157], v[180:183], v[40:43]
	v_mfma_f32_16x16x32_bf16 v[32:35], v[128:131], v[188:191], v[32:35]
	v_mfma_f32_16x16x32_bf16 v[24:27], v[154:157], v[188:191], v[24:27]
	v_mfma_f32_16x16x32_bf16 v[16:19], v[128:131], v[196:199], v[16:19]
	v_mfma_f32_16x16x32_bf16 v[8:11], v[154:157], v[196:199], v[8:11]
	s_waitcnt lgkmcnt(3)
	v_mfma_f32_16x16x32_bf16 v[60:63], v[132:135], v[176:179], v[60:63]
	v_mfma_f32_16x16x32_bf16 v[56:59], v[158:161], v[176:179], v[56:59]
	s_waitcnt lgkmcnt(2)
	v_mfma_f32_16x16x32_bf16 v[48:51], v[132:135], v[184:187], v[48:51]
	v_mfma_f32_16x16x32_bf16 v[40:43], v[158:161], v[184:187], v[40:43]
	s_waitcnt lgkmcnt(1)
	v_mfma_f32_16x16x32_bf16 v[32:35], v[132:135], v[192:195], v[32:35]
	v_mfma_f32_16x16x32_bf16 v[24:27], v[158:161], v[192:195], v[24:27]
	s_waitcnt lgkmcnt(0)
	s_setprio 2
	s_barrier
	v_mfma_f32_16x16x32_bf16 v[16:19], v[132:135], v[200:203], v[16:19]
	v_mfma_f32_16x16x32_bf16 v[8:11], v[158:161], v[200:203], v[8:11]
	s_setprio 0
	s_add_u32 s14, s78, 0x40080
	s_addc_u32 s15, s79, 0
	s_add_i32 s5, s35, s19
	s_mov_b32 m0, s5
	v_lshl_add_u64 v[128:129], s[14:15], 0, v[138:139]
	global_load_lds_dwordx4 v[128:129], off
	s_add_i32 m0, s5, 0x2000
	v_lshl_add_u64 v[128:129], s[14:15], 0, v[142:143]
	global_load_lds_dwordx4 v[128:129], off
	s_waitcnt vmcnt(6)
	s_setprio 1
	s_barrier
	v_mfma_f32_16x16x32_bf16 v[52:55], v[204:207], v[172:175], v[52:55]
	v_mfma_f32_16x16x32_bf16 v[44:47], v[212:215], v[172:175], v[44:47]
	v_mfma_f32_16x16x32_bf16 v[36:39], v[204:207], v[180:183], v[36:39]
	v_mfma_f32_16x16x32_bf16 v[28:31], v[212:215], v[180:183], v[28:31]
	v_mfma_f32_16x16x32_bf16 v[20:23], v[204:207], v[188:191], v[20:23]
	v_mfma_f32_16x16x32_bf16 v[12:15], v[212:215], v[188:191], v[12:15]
	v_mfma_f32_16x16x32_bf16 v[4:7], v[204:207], v[196:199], v[4:7]
	v_mfma_f32_16x16x32_bf16 v[0:3], v[212:215], v[196:199], v[0:3]
	v_mfma_f32_16x16x32_bf16 v[52:55], v[208:211], v[176:179], v[52:55]
	v_mfma_f32_16x16x32_bf16 v[44:47], v[216:219], v[176:179], v[44:47]
	v_mfma_f32_16x16x32_bf16 v[36:39], v[208:211], v[184:187], v[36:39]
	v_mfma_f32_16x16x32_bf16 v[28:31], v[216:219], v[184:187], v[28:31]
	v_mfma_f32_16x16x32_bf16 v[20:23], v[208:211], v[192:195], v[20:23]
	v_mfma_f32_16x16x32_bf16 v[12:15], v[216:219], v[192:195], v[12:15]
	s_setprio 2
	s_barrier
	v_mfma_f32_16x16x32_bf16 v[4:7], v[208:211], v[200:203], v[4:7]
	v_mfma_f32_16x16x32_bf16 v[0:3], v[216:219], v[200:203], v[0:3]
	s_setprio 0
	s_add_i32 s4, s4, 2
	s_add_u32 s8, s8, 0x100
	s_addc_u32 s9, s9, 0
	s_add_u32 vcc_lo, vcc_lo, 0x100
	s_addc_u32 vcc_hi, vcc_hi, 0
	s_cmp_gt_u32 s4, 13
	s_cbranch_scc0 .LBB0_298
	s_lshl_b32 s4, s97, 8
	v_or_b32_e32 v128, s4, v166
	v_ashrrev_i32_e32 v129, 31, v128
	v_lshl_add_u64 v[132:133], v[128:129], 2, s[60:61]
	global_load_dwordx4 v[158:161], v[132:133], off offset:16
	global_load_dwordx4 v[154:157], v[132:133], off
	global_load_dwordx4 v[128:131], v[132:133], off offset:528
	s_nop 0
	global_load_dwordx4 v[132:135], v[132:133], off offset:512
	s_mov_b32 s6, 0x358637bd
	v_mov_b64_e32 v[162:163], s[6:7]
	s_lshl_b32 s6, s76, 8
	s_add_i32 s6, s6, s84
	s_lshr_b32 s5, s97, 3
	s_and_b32 s7, s5, 0x1fffc
	s_bfe_u32 s5, s6, 0x20008
	s_or_b32 s4, s4, s85
	s_or_b32 s5, s5, s7
	s_cmpk_lt_u32 s6, 0x400
	s_mov_b32 s97, s20
	s_mov_b32 s76, s22
	s_mov_b64 s[78:79], s[28:29]
	s_waitcnt vmcnt(0)
	v_pk_fma_f32 v[158:159], v[158:159], s[16:17], v[162:163] op_sel_hi:[1,0,0]
	v_pk_fma_f32 v[154:155], v[154:155], s[16:17], v[162:163] op_sel_hi:[1,0,0]
	v_pk_fma_f32 v[156:157], v[156:157], s[16:17], v[162:163] op_sel_hi:[1,0,0]
	v_mul_f32_e32 v171, 0x4b800000, v154
	v_cmp_gt_f32_e64 s[8:9], s96, v154
	v_cmp_gt_f32_e32 vcc, s96, v155
	v_pk_fma_f32 v[160:161], v[160:161], s[16:17], v[162:163] op_sel_hi:[1,0,0]
	v_cndmask_b32_e64 v154, v154, v171, s[8:9]
	v_mul_f32_e32 v171, 0x4b800000, v155
	v_cndmask_b32_e32 v155, v155, v171, vcc
	v_rsq_f32_e32 v154, v154
	v_rsq_f32_e32 v155, v155
	v_mul_f32_e32 v171, 0x4b800000, v156
	v_pk_fma_f32 v[132:133], v[132:133], s[16:17], v[162:163] op_sel_hi:[1,0,0]
	v_pk_fma_f32 v[134:135], v[134:135], s[16:17], v[162:163] op_sel_hi:[1,0,0]
	v_pk_mul_f32 v[172:173], v[154:155], s[18:19] op_sel_hi:[1,0]
	v_pk_fma_f32 v[128:129], v[128:129], s[16:17], v[162:163] op_sel_hi:[1,0,0]
	v_cndmask_b32_e64 v154, v154, v172, s[8:9]
	v_cmp_gt_f32_e64 s[8:9], s96, v156
	v_cndmask_b32_e32 v155, v155, v173, vcc
	v_cmp_gt_f32_e32 vcc, s96, v157
	v_cndmask_b32_e64 v156, v156, v171, s[8:9]
	v_mul_f32_e32 v171, 0x4b800000, v157
	v_cndmask_b32_e32 v157, v157, v171, vcc
	v_rsq_f32_e32 v156, v156
	v_rsq_f32_e32 v157, v157
	v_mul_f32_e32 v171, 0x4b800000, v158
	v_pk_fma_f32 v[130:131], v[130:131], s[16:17], v[162:163] op_sel_hi:[1,0,0]
	v_pk_mul_f32 v[124:125], v[124:125], v[154:155]
	v_pk_mul_f32 v[172:173], v[156:157], s[18:19] op_sel_hi:[1,0]
	v_mul_f32_e32 v162, 0x4b800000, v130
	v_cndmask_b32_e64 v156, v156, v172, s[8:9]
	v_cmp_gt_f32_e64 s[8:9], s96, v158
	v_cndmask_b32_e32 v157, v157, v173, vcc
	v_cmp_gt_f32_e32 vcc, s96, v159
	v_cndmask_b32_e64 v158, v158, v171, s[8:9]
	v_mul_f32_e32 v171, 0x4b800000, v159
	v_cndmask_b32_e32 v159, v159, v171, vcc
	v_rsq_f32_e32 v158, v158
	v_rsq_f32_e32 v159, v159
; DI unsigned pk_bf16(float lo, float hi) { f32x2 v = {lo, hi}; return __builtin_bit_cast(unsigned, __builtin_convertvector(v, bf16v2)); }
;     DI void operator()(AccRef acc, const Unit& u, int wr, int wc, int fr, int fq) const {
;     ...
;                 for (int e = 0; e < 4; ++e) ts[bj][n][e] = rsqrtf(ts[bj][n][e] * (1.0f / 1024.0f) + 1e-6f);
; #pragma unroll
;         for (int ai = 0; ai < 2; ++ai)
; #pragma unroll
;             for (int m = 0; m < 4; ++m) {
;                 const int R = u.pm * 256 + ai * 128 + wr * 64 + m * 16 + fr, X = R >> 10, hv = R & 1023;
; #pragma unroll
;                 for (int bj = 0; bj < 2; ++bj) {
;                     const int tok = u.pn * 256 + bj * 128 + wc * 32 + 8 * fq, b = tok >> 13, s = tok & (SEQ - 1);
;                     bf16_t* dst = (X ? vtB : vtA) + ((size_t)(((b * 4 + (hv >> 8)) * 128 + (s >> 6)) * 256 + (hv & 255))) * 64 + (s & 63);
;                     const f32x4 v0 = acc[ai][bj][m][0] * ts[bj][0], v1 = acc[ai][bj][m][1] * ts[bj][1];
;                     u32x4 w; w.x = pk_bf16(v0[0], v0[1]); w.y = pk_bf16(v0[2], v0[3]); w.z = pk_bf16(v1[0], v1[1]); w.w = pk_bf16(v1[2], v1[3]);
;                     *(u32x4*)dst = w;
;                 }
	v_mul_f32_e32 v171, 0x4b800000, v160
	v_pk_mul_f32 v[126:127], v[126:127], v[156:157]
	v_pk_mul_f32 v[112:113], v[112:113], v[154:155]
	v_pk_mul_f32 v[172:173], v[158:159], s[18:19] op_sel_hi:[1,0]
	v_pk_mul_f32 v[96:97], v[96:97], v[154:155]
	v_cndmask_b32_e64 v158, v158, v172, s[8:9]
	v_cmp_gt_f32_e64 s[8:9], s96, v160
	v_cndmask_b32_e32 v159, v159, v173, vcc
	v_cmp_gt_f32_e32 vcc, s96, v161
	v_cndmask_b32_e64 v160, v160, v171, s[8:9]
	v_mul_f32_e32 v171, 0x4b800000, v161
	v_cndmask_b32_e32 v161, v161, v171, vcc
	v_rsq_f32_e32 v160, v160
	v_rsq_f32_e32 v161, v161
	v_mul_f32_e32 v171, 0x4b800000, v132
	v_pk_mul_f32 v[80:81], v[80:81], v[154:155]
	v_pk_mul_f32 v[62:63], v[62:63], v[156:157]
	v_pk_mul_f32 v[172:173], v[160:161], s[18:19] op_sel_hi:[1,0]
	v_pk_mul_f32 v[60:61], v[60:61], v[154:155]
	v_cndmask_b32_e64 v160, v160, v172, s[8:9]
	v_cmp_gt_f32_e64 s[8:9], s96, v132
	v_cndmask_b32_e32 v161, v161, v173, vcc
	v_cmp_gt_f32_e32 vcc, s96, v133
	v_cndmask_b32_e64 v132, v132, v171, s[8:9]
	v_mul_f32_e32 v171, 0x4b800000, v133
	v_cndmask_b32_e32 v133, v133, v171, vcc
	v_rsq_f32_e32 v132, v132
	v_rsq_f32_e32 v133, v133
	v_mul_f32_e32 v171, 0x4b800000, v134
	v_pk_mul_f32 v[48:49], v[48:49], v[154:155]
	v_pk_mul_f32 v[32:33], v[32:33], v[154:155]
	v_pk_mul_f32 v[172:173], v[132:133], s[18:19] op_sel_hi:[1,0]
	v_pk_mul_f32 v[16:17], v[16:17], v[154:155]
	v_cndmask_b32_e64 v132, v132, v172, s[8:9]
	v_cmp_gt_f32_e64 s[8:9], s96, v134
	v_cndmask_b32_e32 v133, v133, v173, vcc
	v_cmp_gt_f32_e32 vcc, s96, v135
	v_cndmask_b32_e64 v134, v134, v171, s[8:9]
	v_mul_f32_e32 v171, 0x4b800000, v135
	v_cndmask_b32_e32 v135, v135, v171, vcc
	v_rsq_f32_e32 v134, v134
	v_rsq_f32_e32 v135, v135
	v_mul_f32_e32 v171, 0x4b800000, v128
	v_pk_mul_f32 v[116:117], v[116:117], v[132:133]
	v_pk_mul_f32 v[100:101], v[100:101], v[132:133]
	v_pk_mul_f32 v[172:173], v[134:135], s[18:19] op_sel_hi:[1,0]
	v_pk_mul_f32 v[84:85], v[84:85], v[132:133]
	v_cndmask_b32_e64 v134, v134, v172, s[8:9]
	v_cmp_gt_f32_e64 s[8:9], s96, v128
	v_cndmask_b32_e32 v135, v135, v173, vcc
	v_cmp_gt_f32_e32 vcc, s96, v129
	v_cndmask_b32_e64 v128, v128, v171, s[8:9]
	v_mul_f32_e32 v171, 0x4b800000, v129
	v_cndmask_b32_e32 v129, v129, v171, vcc
	v_rsq_f32_e32 v128, v128
	v_rsq_f32_e32 v129, v129
	v_lshl_or_b32 v171, s5, 15, v167
	v_pk_mul_f32 v[118:119], v[118:119], v[134:135]
	v_pk_mul_f32 v[102:103], v[102:103], v[134:135]
	v_pk_mul_f32 v[172:173], v[128:129], s[18:19] op_sel_hi:[1,0]
	v_pk_mul_f32 v[86:87], v[86:87], v[134:135]
	v_cndmask_b32_e64 v128, v128, v172, s[8:9]
	v_cmp_gt_f32_e64 s[8:9], s96, v130
	v_cndmask_b32_e32 v129, v129, v173, vcc
	v_cmp_gt_f32_e32 vcc, s96, v131
	v_cndmask_b32_e64 v130, v130, v162, s[8:9]
	v_mul_f32_e32 v162, 0x4b800000, v131
	v_cndmask_b32_e32 v131, v131, v162, vcc
	v_rsq_f32_e32 v130, v130
	v_rsq_f32_e32 v131, v131
	v_pk_mul_f32 v[172:173], v[122:123], v[160:161]
	v_pk_mul_f32 v[122:123], v[120:121], v[158:159]
	v_cvt_pk_bf16_f32 v120, v124, v125
	v_pk_mul_f32 v[162:163], v[130:131], s[18:19] op_sel_hi:[1,0]
	v_cvt_pk_bf16_f32 v121, v126, v127
	v_cndmask_b32_e64 v130, v130, v162, s[8:9]
	s_cselect_b32 s9, s53, s91
	s_cselect_b32 s8, s52, s90
	s_lshl_b32 s4, s4, 2
	s_and_b32 s4, s4, 0x7d00
	v_or_b32_e32 v162, s4, v171
	v_cndmask_b32_e32 v131, v131, v163, vcc
	v_ashrrev_i32_e32 v163, 31, v162
	v_lshlrev_b64 v[162:163], 7, v[162:163]
	v_lshl_add_u64 v[162:163], s[8:9], 0, v[162:163]
	v_lshl_add_u64 v[162:163], v[162:163], 0, v[144:145]
	v_cvt_pk_bf16_f32 v122, v122, v123
	v_cvt_pk_bf16_f32 v123, v172, v173
	s_or_b32 s5, s4, 0x200
	global_store_dwordx4 v[162:163], v[120:123], off
	s_addk_i32 s6, 0x80
	v_pk_mul_f32 v[70:71], v[70:71], v[134:135]
	v_or_b32_e32 v120, s5, v171
	v_ashrrev_i32_e32 v121, 31, v120
	v_lshlrev_b64 v[120:121], 7, v[120:121]
	v_lshl_add_u64 v[120:121], s[8:9], 0, v[120:121]
	v_pk_mul_f32 v[122:123], v[110:111], v[130:131]
	v_pk_mul_f32 v[110:111], v[108:109], v[128:129]
	v_lshl_add_u64 v[120:121], v[120:121], 0, v[144:145]
	v_cvt_pk_bf16_f32 v108, v116, v117
	v_cvt_pk_bf16_f32 v109, v118, v119
	v_cvt_pk_bf16_f32 v110, v110, v111
	v_cvt_pk_bf16_f32 v111, v122, v123
	v_or_b32_e32 v116, 16, v171
	global_store_dwordx4 v[120:121], v[108:111], off
	v_pk_mul_f32 v[68:69], v[68:69], v[132:133]
	v_pk_mul_f32 v[54:55], v[54:55], v[134:135]
	v_or_b32_e32 v108, s4, v116
	v_ashrrev_i32_e32 v109, 31, v108
	v_lshlrev_b64 v[108:109], 7, v[108:109]
	v_lshl_add_u64 v[108:109], s[8:9], 0, v[108:109]
	v_pk_mul_f32 v[110:111], v[114:115], v[156:157]
	v_pk_mul_f32 v[114:115], v[106:107], v[160:161]
	v_pk_mul_f32 v[106:107], v[104:105], v[158:159]
	v_lshl_add_u64 v[108:109], v[108:109], 0, v[144:145]
	v_cvt_pk_bf16_f32 v104, v112, v113
	v_cvt_pk_bf16_f32 v105, v110, v111
	v_cvt_pk_bf16_f32 v106, v106, v107
	v_cvt_pk_bf16_f32 v107, v114, v115
	global_store_dwordx4 v[108:109], v[104:107], off
	v_pk_mul_f32 v[52:53], v[52:53], v[132:133]
	v_pk_mul_f32 v[38:39], v[38:39], v[134:135]
	v_or_b32_e32 v104, s5, v116
	v_ashrrev_i32_e32 v105, 31, v104
	v_lshlrev_b64 v[104:105], 7, v[104:105]
	v_lshl_add_u64 v[104:105], s[8:9], 0, v[104:105]
	v_pk_mul_f32 v[106:107], v[94:95], v[130:131]
	v_pk_mul_f32 v[94:95], v[92:93], v[128:129]
	v_lshl_add_u64 v[104:105], v[104:105], 0, v[144:145]
	v_cvt_pk_bf16_f32 v92, v100, v101
	v_cvt_pk_bf16_f32 v93, v102, v103
	v_cvt_pk_bf16_f32 v94, v94, v95
	v_cvt_pk_bf16_f32 v95, v106, v107
	v_or_b32_e32 v100, 32, v171
	global_store_dwordx4 v[104:105], v[92:95], off
	v_pk_mul_f32 v[36:37], v[36:37], v[132:133]
	v_pk_mul_f32 v[22:23], v[22:23], v[134:135]
	v_or_b32_e32 v92, s4, v100
	v_ashrrev_i32_e32 v93, 31, v92
	v_lshlrev_b64 v[92:93], 7, v[92:93]
; DI unsigned pk_bf16(float lo, float hi) { f32x2 v = {lo, hi}; return __builtin_bit_cast(unsigned, __builtin_convertvector(v, bf16v2)); }
; #define PG8_WAIT_V(n) asm volatile("s_waitcnt vmcnt(" #n ")" ::: "memory")
; #define PG8_BAR __builtin_amdgcn_s_barrier()
; #define PG8_WAIT_V(n) asm volatile("s_waitcnt vmcnt(" #n ")" ::: "memory")
; #define PG8_BAR __builtin_amdgcn_s_barrier()
; template <class Epi>
; DI void gemm_phase(LAS unsigned char* lds, const Gemm g, const StaticOrder S, const Epi E) {
;     ...
;     PG8_WAIT_V(0);
;     if (wr == 0) PG8_BAR;
;     PG8_BAR;
;     DI void operator()(AccRef acc, const Unit& u, int wr, int wc, int fr, int fq) const {
;     ...
;             for (int m = 0; m < 4; ++m) {
;                 const int R = u.pm * 256 + ai * 128 + wr * 64 + m * 16 + fr, X = R >> 10, hv = R & 1023;
; #pragma unroll
;                 for (int bj = 0; bj < 2; ++bj) {
;                     const int tok = u.pn * 256 + bj * 128 + wc * 32 + 8 * fq, b = tok >> 13, s = tok & (SEQ - 1);
;                     bf16_t* dst = (X ? vtB : vtA) + ((size_t)(((b * 4 + (hv >> 8)) * 128 + (s >> 6)) * 256 + (hv & 255))) * 64 + (s & 63);
;                     const f32x4 v0 = acc[ai][bj][m][0] * ts[bj][0], v1 = acc[ai][bj][m][1] * ts[bj][1];
;                     u32x4 w; w.x = pk_bf16(v0[0], v0[1]); w.y = pk_bf16(v0[2], v0[3]); w.z = pk_bf16(v1[0], v1[1]); w.w = pk_bf16(v1[2], v1[3]);
;                     *(u32x4*)dst = w;
;                 }
;             }
	v_lshl_add_u64 v[92:93], s[8:9], 0, v[92:93]
	v_pk_mul_f32 v[94:95], v[98:99], v[156:157]
	v_pk_mul_f32 v[98:99], v[90:91], v[160:161]
	v_pk_mul_f32 v[90:91], v[88:89], v[158:159]
	v_lshl_add_u64 v[92:93], v[92:93], 0, v[144:145]
	v_cvt_pk_bf16_f32 v88, v96, v97
	v_cvt_pk_bf16_f32 v89, v94, v95
	v_cvt_pk_bf16_f32 v90, v90, v91
	v_cvt_pk_bf16_f32 v91, v98, v99
	global_store_dwordx4 v[92:93], v[88:91], off
	v_pk_mul_f32 v[20:21], v[20:21], v[132:133]
	v_pk_mul_f32 v[6:7], v[6:7], v[134:135]
	v_or_b32_e32 v88, s5, v100
	v_ashrrev_i32_e32 v89, 31, v88
	v_lshlrev_b64 v[88:89], 7, v[88:89]
	v_lshl_add_u64 v[88:89], s[8:9], 0, v[88:89]
	v_pk_mul_f32 v[90:91], v[78:79], v[130:131]
	v_pk_mul_f32 v[78:79], v[76:77], v[128:129]
	v_lshl_add_u64 v[88:89], v[88:89], 0, v[144:145]
	v_cvt_pk_bf16_f32 v76, v84, v85
	v_cvt_pk_bf16_f32 v77, v86, v87
	v_cvt_pk_bf16_f32 v78, v78, v79
	v_cvt_pk_bf16_f32 v79, v90, v91
	v_or_b32_e32 v84, 48, v171
	global_store_dwordx4 v[88:89], v[76:79], off
	v_pk_mul_f32 v[4:5], v[4:5], v[132:133]
	s_nop 0
	v_or_b32_e32 v76, s4, v84
	v_ashrrev_i32_e32 v77, 31, v76
	v_lshlrev_b64 v[76:77], 7, v[76:77]
	v_lshl_add_u64 v[76:77], s[8:9], 0, v[76:77]
	v_pk_mul_f32 v[78:79], v[82:83], v[156:157]
	v_pk_mul_f32 v[82:83], v[74:75], v[160:161]
	v_pk_mul_f32 v[74:75], v[72:73], v[158:159]
	v_lshl_add_u64 v[76:77], v[76:77], 0, v[144:145]
	v_cvt_pk_bf16_f32 v72, v80, v81
	v_cvt_pk_bf16_f32 v73, v78, v79
	v_cvt_pk_bf16_f32 v74, v74, v75
	v_cvt_pk_bf16_f32 v75, v82, v83
	global_store_dwordx4 v[76:77], v[72:75], off
	s_nop 1
	v_or_b32_e32 v72, s5, v84
	v_ashrrev_i32_e32 v73, 31, v72
	v_lshlrev_b64 v[72:73], 7, v[72:73]
	v_lshl_add_u64 v[72:73], s[8:9], 0, v[72:73]
	s_bfe_u32 s8, s6, 0x20008
	s_or_b32 s7, s8, s7
	s_lshl_b32 s7, s7, 15
	s_and_b32 s8, s6, 0xc0
	v_pk_mul_f32 v[74:75], v[66:67], v[130:131]
	v_pk_mul_f32 v[66:67], v[64:65], v[128:129]
	s_or_b32 s7, s7, s8
	v_lshl_add_u64 v[72:73], v[72:73], 0, v[144:145]
	v_cvt_pk_bf16_f32 v64, v68, v69
	v_cvt_pk_bf16_f32 v65, v70, v71
	v_cvt_pk_bf16_f32 v66, v66, v67
	v_cvt_pk_bf16_f32 v67, v74, v75
	v_or_b32_e32 v68, s7, v164
	global_store_dwordx4 v[72:73], v[64:67], off
	s_cmpk_lt_u32 s6, 0x400
	s_cselect_b32 s9, s53, s91
	v_or_b32_e32 v64, s4, v68
	v_ashrrev_i32_e32 v65, 31, v64
	s_cselect_b32 s8, s52, s90
	v_lshlrev_b64 v[64:65], 7, v[64:65]
	v_lshl_add_u64 v[64:65], s[8:9], 0, v[64:65]
	v_pk_mul_f32 v[66:67], v[58:59], v[160:161]
	v_pk_mul_f32 v[58:59], v[56:57], v[158:159]
	v_lshl_add_u64 v[64:65], v[64:65], 0, v[144:145]
	v_cvt_pk_bf16_f32 v56, v60, v61
	v_cvt_pk_bf16_f32 v57, v62, v63
	v_cvt_pk_bf16_f32 v58, v58, v59
	v_cvt_pk_bf16_f32 v59, v66, v67
	global_store_dwordx4 v[64:65], v[56:59], off
	s_and_b64 vcc, exec, s[0:1]
	s_nop 0
	v_or_b32_e32 v56, s5, v68
	v_ashrrev_i32_e32 v57, 31, v56
	v_lshlrev_b64 v[56:57], 7, v[56:57]
	v_lshl_add_u64 v[56:57], s[8:9], 0, v[56:57]
	v_pk_mul_f32 v[58:59], v[46:47], v[130:131]
	v_pk_mul_f32 v[46:47], v[44:45], v[128:129]
	v_lshl_add_u64 v[56:57], v[56:57], 0, v[144:145]
	v_cvt_pk_bf16_f32 v44, v52, v53
	v_cvt_pk_bf16_f32 v45, v54, v55
	v_cvt_pk_bf16_f32 v46, v46, v47
	v_cvt_pk_bf16_f32 v47, v58, v59
	v_or_b32_e32 v52, 16, v68
	global_store_dwordx4 v[56:57], v[44:47], off
	s_nop 1
	v_or_b32_e32 v44, s4, v52
	v_ashrrev_i32_e32 v45, 31, v44
	v_lshlrev_b64 v[44:45], 7, v[44:45]
	v_lshl_add_u64 v[44:45], s[8:9], 0, v[44:45]
	v_pk_mul_f32 v[46:47], v[50:51], v[156:157]
	v_pk_mul_f32 v[50:51], v[42:43], v[160:161]
	v_pk_mul_f32 v[42:43], v[40:41], v[158:159]
	v_lshl_add_u64 v[44:45], v[44:45], 0, v[144:145]
	v_cvt_pk_bf16_f32 v40, v48, v49
	v_cvt_pk_bf16_f32 v41, v46, v47
	v_cvt_pk_bf16_f32 v42, v42, v43
	v_cvt_pk_bf16_f32 v43, v50, v51
	global_store_dwordx4 v[44:45], v[40:43], off
	s_nop 1
	v_or_b32_e32 v40, s5, v52
	v_ashrrev_i32_e32 v41, 31, v40
	v_lshlrev_b64 v[40:41], 7, v[40:41]
	v_lshl_add_u64 v[40:41], s[8:9], 0, v[40:41]
	v_pk_mul_f32 v[42:43], v[30:31], v[130:131]
	v_pk_mul_f32 v[30:31], v[28:29], v[128:129]
	v_lshl_add_u64 v[40:41], v[40:41], 0, v[144:145]
	v_cvt_pk_bf16_f32 v28, v36, v37
	v_cvt_pk_bf16_f32 v29, v38, v39
	v_cvt_pk_bf16_f32 v30, v30, v31
	v_cvt_pk_bf16_f32 v31, v42, v43
	v_or_b32_e32 v36, 32, v68
	global_store_dwordx4 v[40:41], v[28:31], off
	s_nop 1
	v_or_b32_e32 v28, s4, v36
	v_ashrrev_i32_e32 v29, 31, v28
	v_lshlrev_b64 v[28:29], 7, v[28:29]
	v_lshl_add_u64 v[28:29], s[8:9], 0, v[28:29]
	v_pk_mul_f32 v[30:31], v[34:35], v[156:157]
	v_pk_mul_f32 v[34:35], v[26:27], v[160:161]
	v_pk_mul_f32 v[26:27], v[24:25], v[158:159]
	v_lshl_add_u64 v[28:29], v[28:29], 0, v[144:145]
	v_cvt_pk_bf16_f32 v24, v32, v33
	v_cvt_pk_bf16_f32 v25, v30, v31
	v_cvt_pk_bf16_f32 v26, v26, v27
	v_cvt_pk_bf16_f32 v27, v34, v35
	global_store_dwordx4 v[28:29], v[24:27], off
	s_nop 1
	v_or_b32_e32 v24, s5, v36
	v_ashrrev_i32_e32 v25, 31, v24
	v_lshlrev_b64 v[24:25], 7, v[24:25]
	v_lshl_add_u64 v[24:25], s[8:9], 0, v[24:25]
	v_pk_mul_f32 v[26:27], v[14:15], v[130:131]
	v_pk_mul_f32 v[14:15], v[12:13], v[128:129]
	v_lshl_add_u64 v[24:25], v[24:25], 0, v[144:145]
	v_cvt_pk_bf16_f32 v12, v20, v21
	v_cvt_pk_bf16_f32 v13, v22, v23
	v_cvt_pk_bf16_f32 v14, v14, v15
	v_cvt_pk_bf16_f32 v15, v26, v27
	v_or_b32_e32 v20, 48, v68
	global_store_dwordx4 v[24:25], v[12:15], off
	s_nop 1
	v_or_b32_e32 v12, s4, v20
	v_ashrrev_i32_e32 v13, 31, v12
	v_lshlrev_b64 v[12:13], 7, v[12:13]
	v_lshl_add_u64 v[12:13], s[8:9], 0, v[12:13]
	v_pk_mul_f32 v[14:15], v[18:19], v[156:157]
	v_pk_mul_f32 v[18:19], v[10:11], v[160:161]
	v_pk_mul_f32 v[10:11], v[8:9], v[158:159]
	v_lshl_add_u64 v[12:13], v[12:13], 0, v[144:145]
	v_cvt_pk_bf16_f32 v8, v16, v17
	v_cvt_pk_bf16_f32 v9, v14, v15
	v_cvt_pk_bf16_f32 v10, v10, v11
	v_cvt_pk_bf16_f32 v11, v18, v19
	global_store_dwordx4 v[12:13], v[8:11], off
	s_nop 1
	v_or_b32_e32 v8, s5, v20
	v_ashrrev_i32_e32 v9, 31, v8
	v_lshlrev_b64 v[8:9], 7, v[8:9]
	v_lshl_add_u64 v[8:9], s[8:9], 0, v[8:9]
	v_pk_mul_f32 v[10:11], v[2:3], v[130:131]
	v_pk_mul_f32 v[2:3], v[0:1], v[128:129]
	v_lshl_add_u64 v[8:9], v[8:9], 0, v[144:145]
	v_cvt_pk_bf16_f32 v0, v4, v5
	v_cvt_pk_bf16_f32 v1, v6, v7
	v_cvt_pk_bf16_f32 v2, v2, v3
	v_cvt_pk_bf16_f32 v3, v10, v11
	s_mov_b64 s[8:9], s[24:25]
	global_store_dwordx4 v[8:9], v[0:3], off
	s_cbranch_vccz .LBB0_291
	s_waitcnt vmcnt(0)
	s_cmpk_gt_u32 s17, 0xff
	s_cbranch_scc1 .LBB0_302
	s_barrier

; #define PG8_STAGE(bufoff, gbase, voff) do { _Pragma("unroll") for (int _i = 0; _i < 2; ++_i) \
;         __builtin_amdgcn_global_load_lds((const unsigned*)((const char*)(gbase) + (voff)[_i]), (LAS unsigned*)(lds + (bufoff) + ldsw + _i * 8192), 16, 0, 0); } while (0)
; #define PG8_LDA(dst, b, h) do { _Pragma("unroll") for (int m = 0; m < 4; ++m) _Pragma("unroll") for (int k = 0; k < 2; ++k) dst[m][k] = *(const LAS bf16x8*)(lds + PG8_SA(b, h) + aoff + m * 2048 + k * 1024); } while (0)
; #define PG8_LDB(dst, b, h) do { _Pragma("unroll") for (int n = 0; n < 2; ++n) _Pragma("unroll") for (int k = 0; k < 2; ++k) dst[n][k] = *(const LAS bf16x8*)(lds + PG8_SB(b, h) + boff + n * 2048 + k * 1024); } while (0)
; #define PG8_MMA(ai, bj, At, Bt) do { __builtin_amdgcn_s_setprio(1); _Pragma("unroll") for (int m = 0; m < 4; ++m) _Pragma("unroll") for (int n = 0; n < 2; ++n) _Pragma("unroll") for (int k = 0; k < 2; ++k) \
;         acc[ai][bj][m][n] = __builtin_amdgcn_mfma_f32_16x16x32_bf16(Bt[n][k], At[m][k], acc[ai][bj][m][n], 0, 0, 0); __builtin_amdgcn_s_setprio(0); } while (0)
; #define PG8_WAIT_V(n) asm volatile("s_waitcnt vmcnt(" #n ")" ::: "memory")
; #define PG8_WAIT_L(n) asm volatile("s_waitcnt lgkmcnt(" #n ")" ::: "memory")
; #define PG8_BAR __builtin_amdgcn_s_barrier()
; #define PG8_SCHED __builtin_amdgcn_sched_barrier(0)
; #define PG8_BAR __builtin_amdgcn_s_barrier()
; template <class Epi0, class Epi1>
; DI void gemm_phase_dual(LAS unsigned char* lds, const Gemm g, const Gemm g1, const StaticOrder S, const Epi0 E0, const Epi1 E1) {
;     ...
;             PG8_LDB(B0, 0, 0); PG8_SCHED; PG8_LDA(At, 0, 0); PG8_STAGE(PG8_SA(1, 1), a1 + hstep, voffA);
;             PG8_WAIT_L(8); PG8_BAR; PG8_WAIT_L(0); PG8_MMA(0, 0, At, B0); PG8_BAR; PG8_SCHED;
;             PG8_LDB(B1, 0, 1); PG8_STAGE(PG8_SB(0, 0), b2, voffB);
;             PG8_BAR; PG8_WAIT_L(0); PG8_MMA(0, 1, At, B1); PG8_BAR;
;             PG8_LDA(At, 0, 1); PG8_STAGE(PG8_SA(0, 0), a2, voffA);
;             PG8_BAR; PG8_WAIT_L(0); PG8_MMA(1, 0, At, B0); PG8_BAR; PG8_SCHED;
;             PG8_STAGE(PG8_SB(0, 1), b2 + hstep, voffB);
;             PG8_WAIT_V(6); PG8_BAR; PG8_MMA(1, 1, At, B1); PG8_BAR;
;             PG8_LDB(B0, 1, 0); PG8_SCHED; PG8_LDA(At, 1, 0); PG8_STAGE(PG8_SA(0, 1), a2 + hstep, voffA);
;             PG8_WAIT_L(8); PG8_BAR; PG8_WAIT_L(0); PG8_MMA(0, 0, At, B0); PG8_BAR; PG8_SCHED;
.LBB0_632:
	ds_read_b128 v[128:131], v181
	ds_read_b128 v[132:135], v181 offset:1024
	ds_read_b128 v[136:139], v181 offset:2048
	ds_read_b128 v[140:143], v181 offset:3072
	s_add_u32 s12, s10, 0xfffc0080
	s_addc_u32 s13, s11, -1
	s_cmp_eq_u32 s19, 12
	s_cselect_b32 s15, s1, s13
	s_cselect_b32 s14, s6, s12
	s_cselect_b32 s13, s7, s18
	s_cselect_b32 s12, s16, s17
	v_lshl_add_u64 v[190:191], s[10:11], 0, v[168:169]
	s_add_i32 m0, s49, 0xc000
	ds_read_b128 v[144:147], v183
	ds_read_b128 v[152:155], v183 offset:2048
	ds_read_b128 v[194:197], v183 offset:4096
	ds_read_b128 v[202:205], v183 offset:6144
	global_load_lds_dwordx4 v[190:191], off
	s_add_i32 m0, s49, 0xe000
	v_lshl_add_u64 v[190:191], s[10:11], 0, v[170:171]
	global_load_lds_dwordx4 v[190:191], off
	s_waitcnt lgkmcnt(4)
	s_setprio 1
	s_barrier
	ds_read_b128 v[148:151], v183 offset:1024
	ds_read_b128 v[184:187], v183 offset:3072
	ds_read_b128 v[198:201], v183 offset:5120
	ds_read_b128 v[206:209], v183 offset:7168
	s_waitcnt lgkmcnt(4)
	v_mfma_f32_16x16x32_bf16 v[124:127], v[128:131], v[144:147], v[124:127]
	v_mfma_f32_16x16x32_bf16 v[120:123], v[136:139], v[144:147], v[120:123]
	v_mfma_f32_16x16x32_bf16 v[108:111], v[128:131], v[152:155], v[108:111]
	v_mfma_f32_16x16x32_bf16 v[104:107], v[136:139], v[152:155], v[104:107]
	v_mfma_f32_16x16x32_bf16 v[92:95], v[128:131], v[194:197], v[92:95]
	v_mfma_f32_16x16x32_bf16 v[88:91], v[136:139], v[194:197], v[88:91]
	v_mfma_f32_16x16x32_bf16 v[76:79], v[128:131], v[202:205], v[76:79]
	v_mfma_f32_16x16x32_bf16 v[72:75], v[136:139], v[202:205], v[72:75]
	s_waitcnt lgkmcnt(3)
	v_mfma_f32_16x16x32_bf16 v[124:127], v[132:135], v[148:151], v[124:127]
	v_mfma_f32_16x16x32_bf16 v[120:123], v[140:143], v[148:151], v[120:123]
	s_waitcnt lgkmcnt(2)
	v_mfma_f32_16x16x32_bf16 v[108:111], v[132:135], v[184:187], v[108:111]
	v_mfma_f32_16x16x32_bf16 v[104:107], v[140:143], v[184:187], v[104:107]
	s_waitcnt lgkmcnt(1)
	v_mfma_f32_16x16x32_bf16 v[92:95], v[132:135], v[198:201], v[92:95]
	v_mfma_f32_16x16x32_bf16 v[88:91], v[140:143], v[198:201], v[88:91]
	s_waitcnt lgkmcnt(0)
	s_setprio 2
	s_barrier
	v_mfma_f32_16x16x32_bf16 v[76:79], v[132:135], v[206:209], v[76:79]
	v_mfma_f32_16x16x32_bf16 v[72:75], v[140:143], v[206:209], v[72:75]
	s_setprio 0
	s_add_i32 s41, s78, s48
	v_lshl_add_u64 v[190:191], s[12:13], 0, v[158:159]
	s_mov_b32 m0, s41
	ds_read_b128 v[210:213], v189
	ds_read_b128 v[214:217], v189 offset:1024
	ds_read_b128 v[218:221], v189 offset:2048
	ds_read_b128 v[224:227], v189 offset:3072
	global_load_lds_dwordx4 v[190:191], off
	s_add_i32 m0, s41, 0x2000
	v_lshl_add_u64 v[228:229], s[12:13], 0, v[162:163]
	global_load_lds_dwordx4 v[228:229], off
	s_setprio 1
	s_barrier
	s_waitcnt lgkmcnt(0)
	v_mfma_f32_16x16x32_bf16 v[116:119], v[210:213], v[144:147], v[116:119]
	v_mfma_f32_16x16x32_bf16 v[112:115], v[218:221], v[144:147], v[112:115]
	v_mfma_f32_16x16x32_bf16 v[100:103], v[210:213], v[152:155], v[100:103]
	v_mfma_f32_16x16x32_bf16 v[96:99], v[218:221], v[152:155], v[96:99]
	v_mfma_f32_16x16x32_bf16 v[84:87], v[210:213], v[194:197], v[84:87]
	v_mfma_f32_16x16x32_bf16 v[80:83], v[218:221], v[194:197], v[80:83]
	v_mfma_f32_16x16x32_bf16 v[68:71], v[210:213], v[202:205], v[68:71]
	v_mfma_f32_16x16x32_bf16 v[64:67], v[218:221], v[202:205], v[64:67]
	v_mfma_f32_16x16x32_bf16 v[116:119], v[214:217], v[148:151], v[116:119]
	v_mfma_f32_16x16x32_bf16 v[112:115], v[224:227], v[148:151], v[112:115]
	v_mfma_f32_16x16x32_bf16 v[100:103], v[214:217], v[184:187], v[100:103]
	v_mfma_f32_16x16x32_bf16 v[96:99], v[224:227], v[184:187], v[96:99]
	v_mfma_f32_16x16x32_bf16 v[84:87], v[214:217], v[198:201], v[84:87]
	v_mfma_f32_16x16x32_bf16 v[80:83], v[224:227], v[198:201], v[80:83]
	s_setprio 2
	s_barrier
	v_mfma_f32_16x16x32_bf16 v[68:71], v[214:217], v[206:209], v[68:71]
	v_mfma_f32_16x16x32_bf16 v[64:67], v[224:227], v[206:209], v[64:67]
	s_setprio 0
	s_mov_b32 m0, s49
	v_lshl_add_u64 v[230:231], s[14:15], 0, v[156:157]
	ds_read_b128 v[144:147], v183 offset:16384
	ds_read_b128 v[152:155], v183 offset:18432
	ds_read_b128 v[194:197], v183 offset:20480
	ds_read_b128 v[202:205], v183 offset:22528
	global_load_lds_dwordx4 v[230:231], off
	s_mov_b32 m0, s50
	v_lshl_add_u64 v[232:233], s[14:15], 0, v[160:161]
	global_load_lds_dwordx4 v[232:233], off
	s_setprio 1
	s_barrier
	ds_read_b128 v[148:151], v183 offset:17408
	ds_read_b128 v[184:187], v183 offset:19456
	ds_read_b128 v[198:201], v183 offset:21504
	ds_read_b128 v[206:209], v183 offset:23552
	s_waitcnt lgkmcnt(4)
	v_mfma_f32_16x16x32_bf16 v[60:63], v[128:131], v[144:147], v[60:63]
	v_mfma_f32_16x16x32_bf16 v[56:59], v[136:139], v[144:147], v[56:59]
	v_mfma_f32_16x16x32_bf16 v[44:47], v[128:131], v[152:155], v[44:47]
	v_mfma_f32_16x16x32_bf16 v[40:43], v[136:139], v[152:155], v[40:43]
	v_mfma_f32_16x16x32_bf16 v[28:31], v[128:131], v[194:197], v[28:31]
	v_mfma_f32_16x16x32_bf16 v[24:27], v[136:139], v[194:197], v[24:27]
	v_mfma_f32_16x16x32_bf16 v[12:15], v[128:131], v[202:205], v[12:15]
	v_mfma_f32_16x16x32_bf16 v[8:11], v[136:139], v[202:205], v[8:11]
	s_waitcnt lgkmcnt(3)
	v_mfma_f32_16x16x32_bf16 v[60:63], v[132:135], v[148:151], v[60:63]
	v_mfma_f32_16x16x32_bf16 v[56:59], v[140:143], v[148:151], v[56:59]
	s_waitcnt lgkmcnt(2)
	v_mfma_f32_16x16x32_bf16 v[44:47], v[132:135], v[184:187], v[44:47]
	v_mfma_f32_16x16x32_bf16 v[40:43], v[140:143], v[184:187], v[40:43]
	s_waitcnt lgkmcnt(1)
	v_mfma_f32_16x16x32_bf16 v[28:31], v[132:135], v[198:201], v[28:31]
	v_mfma_f32_16x16x32_bf16 v[24:27], v[140:143], v[198:201], v[24:27]
	s_waitcnt lgkmcnt(0)
	s_setprio 2
	s_barrier
; #define PG8_STAGE(bufoff, gbase, voff) do { _Pragma("unroll") for (int _i = 0; _i < 2; ++_i) \
;         __builtin_amdgcn_global_load_lds((const unsigned*)((const char*)(gbase) + (voff)[_i]), (LAS unsigned*)(lds + (bufoff) + ldsw + _i * 8192), 16, 0, 0); } while (0)
; #define PG8_LDA(dst, b, h) do { _Pragma("unroll") for (int m = 0; m < 4; ++m) _Pragma("unroll") for (int k = 0; k < 2; ++k) dst[m][k] = *(const LAS bf16x8*)(lds + PG8_SA(b, h) + aoff + m * 2048 + k * 1024); } while (0)
; #define PG8_LDB(dst, b, h) do { _Pragma("unroll") for (int n = 0; n < 2; ++n) _Pragma("unroll") for (int k = 0; k < 2; ++k) dst[n][k] = *(const LAS bf16x8*)(lds + PG8_SB(b, h) + boff + n * 2048 + k * 1024); } while (0)
; #define PG8_MMA(ai, bj, At, Bt) do { __builtin_amdgcn_s_setprio(1); _Pragma("unroll") for (int m = 0; m < 4; ++m) _Pragma("unroll") for (int n = 0; n < 2; ++n) _Pragma("unroll") for (int k = 0; k < 2; ++k) \
;         acc[ai][bj][m][n] = __builtin_amdgcn_mfma_f32_16x16x32_bf16(Bt[n][k], At[m][k], acc[ai][bj][m][n], 0, 0, 0); __builtin_amdgcn_s_setprio(0); } while (0)
; #define PG8_WAIT_V(n) asm volatile("s_waitcnt vmcnt(" #n ")" ::: "memory")
; #define PG8_WAIT_L(n) asm volatile("s_waitcnt lgkmcnt(" #n ")" ::: "memory")
; #define PG8_BAR __builtin_amdgcn_s_barrier()
; #define PG8_SCHED __builtin_amdgcn_sched_barrier(0)
; #define PG8_WAIT_V(n) asm volatile("s_waitcnt vmcnt(" #n ")" ::: "memory")
; #define PG8_WAIT_L(n) asm volatile("s_waitcnt lgkmcnt(" #n ")" ::: "memory")
; template <class Epi0, class Epi1>
; DI void gemm_phase_dual(LAS unsigned char* lds, const Gemm g, const Gemm g1, const StaticOrder S, const Epi0 E0, const Epi1 E1) {
;     ...
;             PG8_BAR; PG8_WAIT_L(0); PG8_MMA(1, 0, At, B0); PG8_BAR; PG8_SCHED;
;             PG8_STAGE(PG8_SB(0, 1), b2 + hstep, voffB);
;             PG8_WAIT_V(6); PG8_BAR; PG8_MMA(1, 1, At, B1); PG8_BAR;
;             PG8_LDB(B0, 1, 0); PG8_SCHED; PG8_LDA(At, 1, 0); PG8_STAGE(PG8_SA(0, 1), a2 + hstep, voffA);
;             PG8_WAIT_L(8); PG8_BAR; PG8_WAIT_L(0); PG8_MMA(0, 0, At, B0); PG8_BAR; PG8_SCHED;
;             PG8_LDB(B1, 1, 1); PG8_STAGE(PG8_SB(1, 0), b3, voffB);
;             PG8_BAR; PG8_WAIT_L(0); PG8_MMA(0, 1, At, B1); PG8_BAR;
;             PG8_LDA(At, 1, 1); PG8_STAGE(PG8_SA(1, 0), a3, voffA);
;             PG8_BAR; PG8_WAIT_L(0); PG8_MMA(1, 0, At, B0); PG8_BAR; PG8_SCHED;
	v_mfma_f32_16x16x32_bf16 v[12:15], v[132:135], v[206:209], v[12:15]
	v_mfma_f32_16x16x32_bf16 v[8:11], v[140:143], v[206:209], v[8:11]
	s_setprio 0
	s_add_u32 s90, s12, 0x40000
	s_addc_u32 s91, s13, 0
	s_add_i32 s41, s79, s48
	s_mov_b32 m0, s41
	v_lshl_add_u64 v[128:129], s[90:91], 0, v[158:159]
	global_load_lds_dwordx4 v[128:129], off
	s_add_i32 m0, s41, 0x2000
	v_lshl_add_u64 v[128:129], s[90:91], 0, v[162:163]
	global_load_lds_dwordx4 v[128:129], off
	s_waitcnt vmcnt(6)
	s_setprio 1
	s_barrier
	v_mfma_f32_16x16x32_bf16 v[52:55], v[210:213], v[144:147], v[52:55]
	v_mfma_f32_16x16x32_bf16 v[48:51], v[218:221], v[144:147], v[48:51]
	v_mfma_f32_16x16x32_bf16 v[36:39], v[210:213], v[152:155], v[36:39]
	v_mfma_f32_16x16x32_bf16 v[32:35], v[218:221], v[152:155], v[32:35]
	v_mfma_f32_16x16x32_bf16 v[20:23], v[210:213], v[194:197], v[20:23]
	v_mfma_f32_16x16x32_bf16 v[16:19], v[218:221], v[194:197], v[16:19]
	v_mfma_f32_16x16x32_bf16 v[4:7], v[210:213], v[202:205], v[4:7]
	v_mfma_f32_16x16x32_bf16 v[0:3], v[218:221], v[202:205], v[0:3]
	v_mfma_f32_16x16x32_bf16 v[52:55], v[214:217], v[148:151], v[52:55]
	v_mfma_f32_16x16x32_bf16 v[48:51], v[224:227], v[148:151], v[48:51]
	v_mfma_f32_16x16x32_bf16 v[36:39], v[214:217], v[184:187], v[36:39]
	v_mfma_f32_16x16x32_bf16 v[32:35], v[224:227], v[184:187], v[32:35]
	v_mfma_f32_16x16x32_bf16 v[20:23], v[214:217], v[198:201], v[20:23]
	v_mfma_f32_16x16x32_bf16 v[16:19], v[224:227], v[198:201], v[16:19]
	s_setprio 2
	s_barrier
	v_mfma_f32_16x16x32_bf16 v[4:7], v[214:217], v[206:209], v[4:7]
	v_mfma_f32_16x16x32_bf16 v[0:3], v[224:227], v[206:209], v[0:3]
	s_setprio 0
	s_add_i32 s41, 0, 0x18000
	v_add_u32_e32 v140, s41, v179
	ds_read_b128 v[128:131], v140
	ds_read_b128 v[132:135], v140 offset:1024
	ds_read_b128 v[136:139], v140 offset:2048
	ds_read_b128 v[140:143], v140 offset:3072
	s_add_u32 s14, s14, 0x40000
	s_addc_u32 s15, s15, 0
	s_mov_b32 m0, s51
	v_lshl_add_u64 v[210:211], s[14:15], 0, v[156:157]
	ds_read_b128 v[144:147], v183 offset:32768
	ds_read_b128 v[152:155], v183 offset:34816
	ds_read_b128 v[194:197], v183 offset:36864
	ds_read_b128 v[202:205], v183 offset:38912
	global_load_lds_dwordx4 v[210:211], off
	s_mov_b32 m0, s58
	v_lshl_add_u64 v[210:211], s[14:15], 0, v[160:161]
	global_load_lds_dwordx4 v[210:211], off
	s_waitcnt lgkmcnt(4)
	s_setprio 1
	s_barrier
	ds_read_b128 v[148:151], v183 offset:33792
	ds_read_b128 v[184:187], v183 offset:35840
	ds_read_b128 v[198:201], v183 offset:37888
	ds_read_b128 v[206:209], v183 offset:39936
	s_waitcnt lgkmcnt(4)
	v_mfma_f32_16x16x32_bf16 v[124:127], v[128:131], v[144:147], v[124:127]
	v_mfma_f32_16x16x32_bf16 v[120:123], v[136:139], v[144:147], v[120:123]
	v_mfma_f32_16x16x32_bf16 v[108:111], v[128:131], v[152:155], v[108:111]
	v_mfma_f32_16x16x32_bf16 v[104:107], v[136:139], v[152:155], v[104:107]
	v_mfma_f32_16x16x32_bf16 v[92:95], v[128:131], v[194:197], v[92:95]
	v_mfma_f32_16x16x32_bf16 v[88:91], v[136:139], v[194:197], v[88:91]
	v_mfma_f32_16x16x32_bf16 v[76:79], v[128:131], v[202:205], v[76:79]
	v_mfma_f32_16x16x32_bf16 v[72:75], v[136:139], v[202:205], v[72:75]
	s_waitcnt lgkmcnt(3)
	v_mfma_f32_16x16x32_bf16 v[124:127], v[132:135], v[148:151], v[124:127]
	v_mfma_f32_16x16x32_bf16 v[120:123], v[140:143], v[148:151], v[120:123]
	s_waitcnt lgkmcnt(2)
	v_mfma_f32_16x16x32_bf16 v[108:111], v[132:135], v[184:187], v[108:111]
	v_mfma_f32_16x16x32_bf16 v[104:107], v[140:143], v[184:187], v[104:107]
	s_waitcnt lgkmcnt(1)
	v_mfma_f32_16x16x32_bf16 v[92:95], v[132:135], v[198:201], v[92:95]
	v_mfma_f32_16x16x32_bf16 v[88:91], v[140:143], v[198:201], v[88:91]
	s_waitcnt lgkmcnt(0)
	s_setprio 2
	s_barrier
	v_mfma_f32_16x16x32_bf16 v[76:79], v[132:135], v[206:209], v[76:79]
	v_mfma_f32_16x16x32_bf16 v[72:75], v[140:143], v[206:209], v[72:75]
	s_setprio 0
	s_add_i32 s14, 0, 0x1c000
	s_add_i32 s15, s41, s48
	v_add_u32_e32 v176, s14, v179
	v_lshl_add_u64 v[190:191], v[190:191], 0, s[22:23]
	s_mov_b32 m0, s15
	ds_read_b128 v[210:213], v176
	ds_read_b128 v[214:217], v176 offset:1024
	ds_read_b128 v[218:221], v176 offset:2048
	ds_read_b128 v[224:227], v176 offset:3072
	global_load_lds_dwordx4 v[190:191], off
	s_add_i32 m0, s15, 0x2000
	v_lshl_add_u64 v[190:191], v[228:229], 0, s[22:23]
	global_load_lds_dwordx4 v[190:191], off
	s_setprio 1
	s_barrier
	s_waitcnt lgkmcnt(0)
	v_mfma_f32_16x16x32_bf16 v[116:119], v[210:213], v[144:147], v[116:119]
	v_mfma_f32_16x16x32_bf16 v[112:115], v[218:221], v[144:147], v[112:115]
	v_mfma_f32_16x16x32_bf16 v[100:103], v[210:213], v[152:155], v[100:103]
	v_mfma_f32_16x16x32_bf16 v[96:99], v[218:221], v[152:155], v[96:99]
	v_mfma_f32_16x16x32_bf16 v[84:87], v[210:213], v[194:197], v[84:87]
	v_mfma_f32_16x16x32_bf16 v[80:83], v[218:221], v[194:197], v[80:83]
	v_mfma_f32_16x16x32_bf16 v[68:71], v[210:213], v[202:205], v[68:71]
	v_mfma_f32_16x16x32_bf16 v[64:67], v[218:221], v[202:205], v[64:67]
	v_mfma_f32_16x16x32_bf16 v[116:119], v[214:217], v[148:151], v[116:119]
	v_mfma_f32_16x16x32_bf16 v[112:115], v[224:227], v[148:151], v[112:115]
	v_mfma_f32_16x16x32_bf16 v[100:103], v[214:217], v[184:187], v[100:103]
	v_mfma_f32_16x16x32_bf16 v[96:99], v[224:227], v[184:187], v[96:99]
	v_mfma_f32_16x16x32_bf16 v[84:87], v[214:217], v[198:201], v[84:87]
	v_mfma_f32_16x16x32_bf16 v[80:83], v[224:227], v[198:201], v[80:83]
	s_setprio 2
	s_barrier
	v_mfma_f32_16x16x32_bf16 v[68:71], v[214:217], v[206:209], v[68:71]
	v_mfma_f32_16x16x32_bf16 v[64:67], v[224:227], v[206:209], v[64:67]
	s_setprio 0
	s_mov_b32 m0, s76
	v_lshl_add_u64 v[190:191], v[230:231], 0, s[22:23]
	ds_read_b128 v[144:147], v183 offset:49152
	ds_read_b128 v[152:155], v183 offset:51200
	ds_read_b128 v[194:197], v183 offset:53248
	ds_read_b128 v[202:205], v183 offset:55296
	global_load_lds_dwordx4 v[190:191], off
	s_mov_b32 m0, s77
	v_lshl_add_u64 v[190:191], v[232:233], 0, s[22:23]
	global_load_lds_dwordx4 v[190:191], off
	s_setprio 1
	s_barrier
; #define PG8_STAGE(bufoff, gbase, voff) do { _Pragma("unroll") for (int _i = 0; _i < 2; ++_i) \
;         __builtin_amdgcn_global_load_lds((const unsigned*)((const char*)(gbase) + (voff)[_i]), (LAS unsigned*)(lds + (bufoff) + ldsw + _i * 8192), 16, 0, 0); } while (0)
; #define PG8_MMA(ai, bj, At, Bt) do { __builtin_amdgcn_s_setprio(1); _Pragma("unroll") for (int m = 0; m < 4; ++m) _Pragma("unroll") for (int n = 0; n < 2; ++n) _Pragma("unroll") for (int k = 0; k < 2; ++k) \
;         acc[ai][bj][m][n] = __builtin_amdgcn_mfma_f32_16x16x32_bf16(Bt[n][k], At[m][k], acc[ai][bj][m][n], 0, 0, 0); __builtin_amdgcn_s_setprio(0); } while (0)
; #define PG8_WAIT_V(n) asm volatile("s_waitcnt vmcnt(" #n ")" ::: "memory")
; #define PG8_WAIT_L(n) asm volatile("s_waitcnt lgkmcnt(" #n ")" ::: "memory")
; #define PG8_BAR __builtin_amdgcn_s_barrier()
; #define PG8_SCHED __builtin_amdgcn_sched_barrier(0)
; #define PG8_STAGE(bufoff, gbase, voff) do { _Pragma("unroll") for (int _i = 0; _i < 2; ++_i) \
;         __builtin_amdgcn_global_load_lds((const unsigned*)((const char*)(gbase) + (voff)[_i]), (LAS unsigned*)(lds + (bufoff) + ldsw + _i * 8192), 16, 0, 0); } while (0)
; #define PG8_MMA(ai, bj, At, Bt) do { __builtin_amdgcn_s_setprio(1); _Pragma("unroll") for (int m = 0; m < 4; ++m) _Pragma("unroll") for (int n = 0; n < 2; ++n) _Pragma("unroll") for (int k = 0; k < 2; ++k) \
;         acc[ai][bj][m][n] = __builtin_amdgcn_mfma_f32_16x16x32_bf16(Bt[n][k], At[m][k], acc[ai][bj][m][n], 0, 0, 0); __builtin_amdgcn_s_setprio(0); } while (0)
; #define PG8_WAIT_V(n) asm volatile("s_waitcnt vmcnt(" #n ")" ::: "memory")
; DI RowScales load_rowscales(const float* ss, int row0) {
;     RowScales t;
; #pragma unroll
;     for (int ai = 0; ai < 2; ++ai)
; #pragma unroll
;         for (int m = 0; m < 4; ++m) t.r[ai][m] = ss[row0 + ai * 128 + m * 16];
; #pragma unroll
;     for (int ai = 0; ai < 2; ++ai)
; #pragma unroll
;         for (int m = 0; m < 4; ++m) t.r[ai][m] = rsqrtf(t.r[ai][m] * (1.0f / 1024.0f) + 1e-6f);
; template <class Epi0, class Epi1>
; DI void gemm_phase_dual(LAS unsigned char* lds, const Gemm g, const Gemm g1, const StaticOrder S, const Epi0 E0, const Epi1 E1) {
;     ...
;             PG8_BAR; PG8_WAIT_L(0); PG8_MMA(1, 0, At, B0); PG8_BAR; PG8_SCHED;
;             PG8_STAGE(PG8_SB(1, 1), b3 + hstep, voffB);
;             PG8_WAIT_V(6); PG8_BAR; PG8_MMA(1, 1, At, B1); PG8_BAR;
	ds_read_b128 v[148:151], v183 offset:50176
	ds_read_b128 v[184:187], v183 offset:52224
	ds_read_b128 v[198:201], v183 offset:54272
	ds_read_b128 v[206:209], v183 offset:56320
	s_waitcnt lgkmcnt(4)
	v_mfma_f32_16x16x32_bf16 v[60:63], v[128:131], v[144:147], v[60:63]
	v_mfma_f32_16x16x32_bf16 v[56:59], v[136:139], v[144:147], v[56:59]
	v_mfma_f32_16x16x32_bf16 v[44:47], v[128:131], v[152:155], v[44:47]
	v_mfma_f32_16x16x32_bf16 v[40:43], v[136:139], v[152:155], v[40:43]
	v_mfma_f32_16x16x32_bf16 v[28:31], v[128:131], v[194:197], v[28:31]
	v_mfma_f32_16x16x32_bf16 v[24:27], v[136:139], v[194:197], v[24:27]
	v_mfma_f32_16x16x32_bf16 v[12:15], v[128:131], v[202:205], v[12:15]
	v_mfma_f32_16x16x32_bf16 v[8:11], v[136:139], v[202:205], v[8:11]
	s_waitcnt lgkmcnt(3)
	v_mfma_f32_16x16x32_bf16 v[60:63], v[132:135], v[148:151], v[60:63]
	v_mfma_f32_16x16x32_bf16 v[56:59], v[140:143], v[148:151], v[56:59]
	s_waitcnt lgkmcnt(2)
	v_mfma_f32_16x16x32_bf16 v[44:47], v[132:135], v[184:187], v[44:47]
	v_mfma_f32_16x16x32_bf16 v[40:43], v[140:143], v[184:187], v[40:43]
	s_waitcnt lgkmcnt(1)
	v_mfma_f32_16x16x32_bf16 v[28:31], v[132:135], v[198:201], v[28:31]
	v_mfma_f32_16x16x32_bf16 v[24:27], v[140:143], v[198:201], v[24:27]
	s_waitcnt lgkmcnt(0)
	s_setprio 2
	s_barrier
	v_mfma_f32_16x16x32_bf16 v[12:15], v[132:135], v[206:209], v[12:15]
	v_mfma_f32_16x16x32_bf16 v[8:11], v[140:143], v[206:209], v[8:11]
	s_setprio 0
	s_add_u32 s12, s12, 0x40080
	s_addc_u32 s13, s13, 0
	s_add_i32 s14, s14, s48
	s_mov_b32 m0, s14
	v_lshl_add_u64 v[128:129], s[12:13], 0, v[158:159]
	global_load_lds_dwordx4 v[128:129], off
	s_add_i32 m0, s14, 0x2000
	v_lshl_add_u64 v[128:129], s[12:13], 0, v[162:163]
	global_load_lds_dwordx4 v[128:129], off
	s_waitcnt vmcnt(6)
	s_setprio 1
	s_barrier
	v_mfma_f32_16x16x32_bf16 v[52:55], v[210:213], v[144:147], v[52:55]
	v_mfma_f32_16x16x32_bf16 v[48:51], v[218:221], v[144:147], v[48:51]
	v_mfma_f32_16x16x32_bf16 v[36:39], v[210:213], v[152:155], v[36:39]
	v_mfma_f32_16x16x32_bf16 v[32:35], v[218:221], v[152:155], v[32:35]
	v_mfma_f32_16x16x32_bf16 v[20:23], v[210:213], v[194:197], v[20:23]
	v_mfma_f32_16x16x32_bf16 v[16:19], v[218:221], v[194:197], v[16:19]
	v_mfma_f32_16x16x32_bf16 v[4:7], v[210:213], v[202:205], v[4:7]
	v_mfma_f32_16x16x32_bf16 v[0:3], v[218:221], v[202:205], v[0:3]
	v_mfma_f32_16x16x32_bf16 v[52:55], v[214:217], v[148:151], v[52:55]
	v_mfma_f32_16x16x32_bf16 v[48:51], v[224:227], v[148:151], v[48:51]
	v_mfma_f32_16x16x32_bf16 v[36:39], v[214:217], v[184:187], v[36:39]
	v_mfma_f32_16x16x32_bf16 v[32:35], v[224:227], v[184:187], v[32:35]
	v_mfma_f32_16x16x32_bf16 v[20:23], v[214:217], v[198:201], v[20:23]
	v_mfma_f32_16x16x32_bf16 v[16:19], v[224:227], v[198:201], v[16:19]
	s_setprio 2
	s_barrier
	v_mfma_f32_16x16x32_bf16 v[4:7], v[214:217], v[206:209], v[4:7]
	v_mfma_f32_16x16x32_bf16 v[0:3], v[224:227], v[206:209], v[0:3]
	s_setprio 0
	s_add_i32 s19, s19, 2
	s_add_u32 s10, s10, 0x100
	s_addc_u32 s11, s11, 0
	s_add_u32 s17, s17, 0x100
	s_addc_u32 s18, s18, 0
	s_cmp_gt_u32 s19, 13
	s_cbranch_scc0 .LBB0_632
	v_lshl_add_u32 v128, s0, 8, v177
	s_mov_b64 s[6:7], -1
	s_and_b64 vcc, exec, s[8:9]
	v_ashrrev_i32_e32 v129, 31, v128
	s_cbranch_vccz .LBB0_635
	v_lshl_add_u64 v[130:131], v[128:129], 2, s[60:61]
	global_load_dword v132, v[130:131], off
	global_load_dword v133, v[130:131], off offset:64
	global_load_dword v134, v[130:131], off offset:128
	global_load_dword v135, v[130:131], off offset:192
	global_load_dword v136, v[130:131], off offset:512
	global_load_dword v137, v[130:131], off offset:576
	global_load_dword v138, v[130:131], off offset:640
	global_load_dword v139, v[130:131], off offset:704
	s_lshl_b32 s0, s0, 3
	s_add_i32 s0, s0, s87
	s_ashr_i32 s1, s0, 31
	s_lshl_b64 s[0:1], s[0:1], 17
	v_lshl_add_u64 v[130:131], v[166:167], 0, s[0:1]
	s_mov_b64 s[6:7], 0
	s_waitcnt vmcnt(0)
	v_fmamk_f32 v132, v132, 0x3a800000, v193
	v_mul_f32_e32 v140, 0x4b800000, v132
	v_cmp_gt_f32_e32 vcc, s80, v132
	v_fmamk_f32 v134, v134, 0x3a800000, v193
	v_fmamk_f32 v136, v136, 0x3a800000, v193
	v_fmamk_f32 v137, v137, 0x3a800000, v193
	v_fmamk_f32 v138, v138, 0x3a800000, v193
	v_fmamk_f32 v139, v139, 0x3a800000, v193
	v_mul_f32_e32 v144, 0x4b800000, v136
	v_mul_f32_e32 v145, 0x4b800000, v137
	v_cndmask_b32_e32 v132, v132, v140, vcc
	v_cmp_gt_f32_e64 s[12:13], s80, v136
	v_cmp_gt_f32_e64 s[14:15], s80, v137
	v_fmamk_f32 v133, v133, 0x3a800000, v193
	v_fmamk_f32 v135, v135, 0x3a800000, v193
	v_mul_f32_e32 v142, 0x4b800000, v134
	v_mul_f32_e32 v146, 0x4b800000, v138
	v_mul_f32_e32 v147, 0x4b800000, v139
	v_cmp_gt_f32_e64 s[8:9], s80, v134
	v_cndmask_b32_e64 v136, v136, v144, s[12:13]
	v_cndmask_b32_e64 v137, v137, v145, s[14:15]
	v_cmp_gt_f32_e64 s[16:17], s80, v138
	v_cmp_gt_f32_e64 s[18:19], s80, v139
	v_rsq_f32_e32 v132, v132
	v_mul_f32_e32 v141, 0x4b800000, v133
	v_mul_f32_e32 v143, 0x4b800000, v135
	v_cmp_gt_f32_e64 s[0:1], s80, v133
	v_cndmask_b32_e64 v134, v134, v142, s[8:9]
	v_cmp_gt_f32_e64 s[10:11], s80, v135
	v_cndmask_b32_e64 v138, v138, v146, s[16:17]
	v_cndmask_b32_e64 v139, v139, v147, s[18:19]
	v_rsq_f32_e32 v136, v136
	v_rsq_f32_e32 v137, v137
	v_cndmask_b32_e64 v133, v133, v141, s[0:1]
	v_cndmask_b32_e64 v135, v135, v143, s[10:11]
	v_rsq_f32_e32 v134, v134
	v_rsq_f32_e32 v141, v138
	v_rsq_f32_e32 v139, v139
	v_rsq_f32_e32 v133, v133
	v_rsq_f32_e32 v135, v135
	v_mul_f32_e32 v138, 0x45800000, v132
	v_mul_f32_e32 v144, 0x45800000, v136
	v_mul_f32_e32 v145, 0x45800000, v137
	v_cndmask_b32_e32 v148, v132, v138, vcc
	v_mul_f32_e32 v142, 0x45800000, v134
	v_mul_f32_e32 v146, 0x45800000, v141
	v_mul_f32_e32 v147, 0x45800000, v139
; DI unsigned pk_bf16(float lo, float hi) { f32x2 v = {lo, hi}; return __builtin_bit_cast(unsigned, __builtin_convertvector(v, bf16v2)); }
; DI float fast_sigmoid(float x) { return __builtin_amdgcn_rcpf(1.0f + __expf(-x)); }
;     DI void operator()(AccRef acc, const Unit& u, int wr, int wc, int fr, int fq) const {
;     ...
;                 for (int bj = 0; bj < 2; ++bj) {
;                     const float rs = rsc.r[ai][m];
;                     const f32x4 r0 = acc[ai][bj][m][0] * rs, r1 = acc[ai][bj][m][1] * rs;
;                     u32x4 w;
;                     w.x = pk_bf16(fast_sigmoid(r0[0]), fast_sigmoid(r0[1])); w.y = pk_bf16(fast_sigmoid(r0[2]), fast_sigmoid(r0[3]));
;                     w.z = pk_bf16(fast_sigmoid(r1[0]), fast_sigmoid(r1[1])); w.w = pk_bf16(fast_sigmoid(r1[2]), fast_sigmoid(r1[3]));
;                     *(u32x4*)(Gp + (ai * 128 + m * 16) * 256 + bj * 128) = w;
	v_cndmask_b32_e64 v138, v136, v144, s[12:13]
	v_cndmask_b32_e64 v136, v137, v145, s[14:15]
	v_pk_mul_f32 v[144:145], v[126:127], v[148:149] op_sel_hi:[1,0]
	v_pk_mul_f32 v[152:153], v[122:123], v[148:149] op_sel_hi:[1,0]
	v_mul_f32_e32 v140, 0x45800000, v133
	v_mul_f32_e32 v143, 0x45800000, v135
	v_cndmask_b32_e64 v142, v134, v142, s[8:9]
	v_cndmask_b32_e64 v134, v141, v146, s[16:17]
	v_cndmask_b32_e64 v132, v139, v147, s[18:19]
	v_pk_mul_f32 v[146:147], v[124:125], v[148:149] op_sel_hi:[1,0]
	v_pk_mul_f32 v[154:155], v[120:121], v[148:149] op_sel_hi:[1,0]
	v_mul_f32_e32 v137, 0xbfb8aa3b, v144
	v_mul_f32_e32 v144, 0xbfb8aa3b, v152
	v_cndmask_b32_e64 v150, v133, v140, s[0:1]
	v_cndmask_b32_e64 v140, v135, v143, s[10:11]
	v_mul_f32_e32 v133, 0xbfb8aa3b, v146
	v_mul_f32_e32 v135, 0xbfb8aa3b, v147
	v_mul_f32_e32 v139, 0xbfb8aa3b, v145
	v_mul_f32_e32 v141, 0xbfb8aa3b, v154
	v_mul_f32_e32 v143, 0xbfb8aa3b, v155
	v_exp_f32_e32 v144, v144
	v_mul_f32_e32 v145, 0xbfb8aa3b, v153
	v_exp_f32_e32 v133, v133
	v_exp_f32_e32 v135, v135
	v_exp_f32_e32 v137, v137
	v_exp_f32_e32 v139, v139
	v_exp_f32_e32 v141, v141
	v_exp_f32_e32 v143, v143
	v_exp_f32_e32 v145, v145
	v_add_f32_e32 v144, 1.0, v144
	v_add_f32_e32 v133, 1.0, v133
	v_add_f32_e32 v135, 1.0, v135
	v_add_f32_e32 v137, 1.0, v137
	v_add_f32_e32 v139, 1.0, v139
	v_add_f32_e32 v141, 1.0, v141
	v_add_f32_e32 v143, 1.0, v143
	v_rcp_f32_e32 v147, v144
	v_add_f32_e32 v144, 1.0, v145
	v_rcp_f32_e32 v133, v133
	v_rcp_f32_e32 v135, v135
	v_rcp_f32_e32 v137, v137
	v_rcp_f32_e32 v139, v139
	v_rcp_f32_e32 v141, v141
	v_rcp_f32_e32 v143, v143
	v_rcp_f32_e32 v149, v144
	v_cvt_pk_bf16_f32 v144, v133, v135
	v_cvt_pk_bf16_f32 v145, v137, v139
	v_cvt_pk_bf16_f32 v146, v141, v143
	v_cvt_pk_bf16_f32 v147, v147, v149
	global_store_dwordx4 v[130:131], v[144:147], off
	v_pk_mul_f32 v[152:153], v[114:115], v[148:149] op_sel_hi:[1,0]
	s_nop 0
	v_pk_mul_f32 v[144:145], v[118:119], v[148:149] op_sel_hi:[1,0]
	v_pk_mul_f32 v[146:147], v[116:117], v[148:149] op_sel_hi:[1,0]
	v_mul_f32_e32 v137, 0xbfb8aa3b, v144
	v_mul_f32_e32 v133, 0xbfb8aa3b, v146
	v_mul_f32_e32 v135, 0xbfb8aa3b, v147
	v_pk_mul_f32 v[146:147], v[112:113], v[148:149] op_sel_hi:[1,0]
	v_mul_f32_e32 v144, 0xbfb8aa3b, v152
	v_mul_f32_e32 v139, 0xbfb8aa3b, v145
	v_mul_f32_e32 v141, 0xbfb8aa3b, v146
	v_mul_f32_e32 v143, 0xbfb8aa3b, v147
	v_exp_f32_e32 v144, v144
	v_mul_f32_e32 v145, 0xbfb8aa3b, v153
	v_exp_f32_e32 v133, v133
	v_exp_f32_e32 v135, v135
	v_exp_f32_e32 v137, v137
	v_exp_f32_e32 v139, v139
	v_exp_f32_e32 v141, v141
	v_exp_f32_e32 v143, v143
	v_exp_f32_e32 v145, v145
	v_add_f32_e32 v144, 1.0, v144
	v_add_f32_e32 v133, 1.0, v133
	v_add_f32_e32 v135, 1.0, v135
	v_add_f32_e32 v137, 1.0, v137
	v_add_f32_e32 v139, 1.0, v139
	v_add_f32_e32 v141, 1.0, v141
	v_add_f32_e32 v143, 1.0, v143
	v_rcp_f32_e32 v147, v144
	v_add_f32_e32 v144, 1.0, v145
	v_rcp_f32_e32 v133, v133
	v_rcp_f32_e32 v135, v135
	v_rcp_f32_e32 v137, v137
	v_rcp_f32_e32 v139, v139
	v_rcp_f32_e32 v141, v141
	v_rcp_f32_e32 v143, v143
	v_rcp_f32_e32 v148, v144
	v_cvt_pk_bf16_f32 v144, v133, v135
	v_cvt_pk_bf16_f32 v145, v137, v139
	v_cvt_pk_bf16_f32 v146, v141, v143
	v_cvt_pk_bf16_f32 v147, v147, v148
	global_store_dwordx4 v[130:131], v[144:147], off offset:256
	v_pk_mul_f32 v[148:149], v[106:107], v[150:151] op_sel_hi:[1,0]
	v_pk_mul_f32 v[152:153], v[98:99], v[150:151] op_sel_hi:[1,0]
	v_pk_mul_f32 v[144:145], v[110:111], v[150:151] op_sel_hi:[1,0]
	v_pk_mul_f32 v[146:147], v[108:109], v[150:151] op_sel_hi:[1,0]
	v_mul_f32_e32 v137, 0xbfb8aa3b, v144
	v_mul_f32_e32 v144, 0xbfb8aa3b, v148
	v_mul_f32_e32 v133, 0xbfb8aa3b, v146
	v_mul_f32_e32 v135, 0xbfb8aa3b, v147
	v_pk_mul_f32 v[146:147], v[104:105], v[150:151] op_sel_hi:[1,0]
	v_mul_f32_e32 v139, 0xbfb8aa3b, v145
	v_exp_f32_e32 v144, v144
	v_mul_f32_e32 v145, 0xbfb8aa3b, v149
	v_mul_f32_e32 v141, 0xbfb8aa3b, v146
	v_mul_f32_e32 v143, 0xbfb8aa3b, v147
	v_exp_f32_e32 v145, v145
	v_exp_f32_e32 v133, v133
	v_exp_f32_e32 v135, v135
	v_exp_f32_e32 v137, v137
	v_exp_f32_e32 v139, v139
	v_exp_f32_e32 v141, v141
	v_exp_f32_e32 v143, v143
	v_add_f32_e32 v144, 1.0, v144
	v_rcp_f32_e32 v147, v144
	v_add_f32_e32 v144, 1.0, v145
	v_add_f32_e32 v133, 1.0, v133
	v_add_f32_e32 v135, 1.0, v135
	v_add_f32_e32 v137, 1.0, v137
	v_add_f32_e32 v139, 1.0, v139
	v_add_f32_e32 v141, 1.0, v141
	v_add_f32_e32 v143, 1.0, v143
	v_rcp_f32_e32 v148, v144
	v_rcp_f32_e32 v133, v133
	v_rcp_f32_e32 v135, v135
	v_rcp_f32_e32 v137, v137
	v_rcp_f32_e32 v139, v139
	v_rcp_f32_e32 v141, v141
	v_rcp_f32_e32 v143, v143
	v_cvt_pk_bf16_f32 v147, v147, v148
	v_add_co_u32_e32 v148, vcc, s59, v130
	v_cvt_pk_bf16_f32 v144, v133, v135
	v_cvt_pk_bf16_f32 v145, v137, v139
	v_cvt_pk_bf16_f32 v146, v141, v143
	v_addc_co_u32_e32 v149, vcc, 0, v131, vcc
	global_store_dwordx4 v[148:149], v[144:147], off
	s_nop 1
	v_pk_mul_f32 v[144:145], v[102:103], v[150:151] op_sel_hi:[1,0]
	v_pk_mul_f32 v[146:147], v[100:101], v[150:151] op_sel_hi:[1,0]
	v_mul_f32_e32 v137, 0xbfb8aa3b, v144
	v_mul_f32_e32 v133, 0xbfb8aa3b, v146
	v_mul_f32_e32 v135, 0xbfb8aa3b, v147
	v_pk_mul_f32 v[146:147], v[96:97], v[150:151] op_sel_hi:[1,0]
	v_mul_f32_e32 v144, 0xbfb8aa3b, v152
	v_mul_f32_e32 v139, 0xbfb8aa3b, v145
	v_mul_f32_e32 v141, 0xbfb8aa3b, v146
	v_mul_f32_e32 v143, 0xbfb8aa3b, v147
	v_exp_f32_e32 v144, v144
	v_mul_f32_e32 v145, 0xbfb8aa3b, v153
	v_exp_f32_e32 v133, v133
	v_exp_f32_e32 v135, v135
	v_exp_f32_e32 v137, v137
	v_exp_f32_e32 v139, v139
	v_exp_f32_e32 v141, v141
	v_exp_f32_e32 v143, v143
	v_exp_f32_e32 v145, v145
	v_add_f32_e32 v144, 1.0, v144
	v_add_f32_e32 v133, 1.0, v133
	v_add_f32_e32 v135, 1.0, v135
; DI unsigned pk_bf16(float lo, float hi) { f32x2 v = {lo, hi}; return __builtin_bit_cast(unsigned, __builtin_convertvector(v, bf16v2)); }
; DI float fast_sigmoid(float x) { return __builtin_amdgcn_rcpf(1.0f + __expf(-x)); }
;     DI void operator()(AccRef acc, const Unit& u, int wr, int wc, int fr, int fq) const {
;     ...
;                 for (int bj = 0; bj < 2; ++bj) {
;                     const float rs = rsc.r[ai][m];
;                     const f32x4 r0 = acc[ai][bj][m][0] * rs, r1 = acc[ai][bj][m][1] * rs;
;                     u32x4 w;
;                     w.x = pk_bf16(fast_sigmoid(r0[0]), fast_sigmoid(r0[1])); w.y = pk_bf16(fast_sigmoid(r0[2]), fast_sigmoid(r0[3]));
;                     w.z = pk_bf16(fast_sigmoid(r1[0]), fast_sigmoid(r1[1])); w.w = pk_bf16(fast_sigmoid(r1[2]), fast_sigmoid(r1[3]));
;                     *(u32x4*)(Gp + (ai * 128 + m * 16) * 256 + bj * 128) = w;
	v_add_f32_e32 v137, 1.0, v137
	v_add_f32_e32 v139, 1.0, v139
	v_add_f32_e32 v141, 1.0, v141
	v_add_f32_e32 v143, 1.0, v143
	v_rcp_f32_e32 v147, v144
	v_add_f32_e32 v144, 1.0, v145
	v_rcp_f32_e32 v133, v133
	v_rcp_f32_e32 v135, v135
	v_rcp_f32_e32 v137, v137
	v_rcp_f32_e32 v139, v139
	v_rcp_f32_e32 v141, v141
	v_rcp_f32_e32 v143, v143
	v_rcp_f32_e32 v150, v144
	v_cvt_pk_bf16_f32 v144, v133, v135
	v_cvt_pk_bf16_f32 v145, v137, v139
	v_cvt_pk_bf16_f32 v146, v141, v143
	v_cvt_pk_bf16_f32 v147, v147, v150
	global_store_dwordx4 v[148:149], v[144:147], off offset:256
	v_pk_mul_f32 v[148:149], v[90:91], v[142:143] op_sel_hi:[1,0]
	s_nop 0
	v_pk_mul_f32 v[144:145], v[94:95], v[142:143] op_sel_hi:[1,0]
	v_pk_mul_f32 v[146:147], v[92:93], v[142:143] op_sel_hi:[1,0]
	v_mul_f32_e32 v137, 0xbfb8aa3b, v144
	v_mul_f32_e32 v144, 0xbfb8aa3b, v148
	v_mul_f32_e32 v133, 0xbfb8aa3b, v146
	v_mul_f32_e32 v135, 0xbfb8aa3b, v147
	v_pk_mul_f32 v[146:147], v[88:89], v[142:143] op_sel_hi:[1,0]
	v_mul_f32_e32 v139, 0xbfb8aa3b, v145
	v_exp_f32_e32 v144, v144
	v_mul_f32_e32 v145, 0xbfb8aa3b, v149
	v_mul_f32_e32 v141, 0xbfb8aa3b, v146
	v_mul_f32_e32 v143, 0xbfb8aa3b, v147
	v_exp_f32_e32 v145, v145
	v_exp_f32_e32 v133, v133
	v_exp_f32_e32 v135, v135
	v_exp_f32_e32 v137, v137
	v_exp_f32_e32 v139, v139
	v_exp_f32_e32 v141, v141
	v_exp_f32_e32 v143, v143
	v_add_f32_e32 v144, 1.0, v144
	v_rcp_f32_e32 v147, v144
	v_add_f32_e32 v144, 1.0, v145
	v_add_f32_e32 v133, 1.0, v133
	v_add_f32_e32 v135, 1.0, v135
	v_add_f32_e32 v137, 1.0, v137
	v_add_f32_e32 v139, 1.0, v139
	v_add_f32_e32 v141, 1.0, v141
	v_add_f32_e32 v143, 1.0, v143
	v_rcp_f32_e32 v148, v144
	v_rcp_f32_e32 v133, v133
	v_rcp_f32_e32 v135, v135
	v_rcp_f32_e32 v137, v137
	v_rcp_f32_e32 v139, v139
	v_rcp_f32_e32 v141, v141
	v_rcp_f32_e32 v143, v143
	v_cvt_pk_bf16_f32 v147, v147, v148
	v_add_co_u32_e32 v148, vcc, s66, v130
	v_cvt_pk_bf16_f32 v144, v133, v135
	v_cvt_pk_bf16_f32 v145, v137, v139
	v_cvt_pk_bf16_f32 v146, v141, v143
	v_addc_co_u32_e32 v149, vcc, 0, v131, vcc
	global_store_dwordx4 v[148:149], v[144:147], off
	v_pk_mul_f32 v[150:151], v[82:83], v[142:143] op_sel_hi:[1,0]
	s_nop 0
	v_pk_mul_f32 v[144:145], v[86:87], v[142:143] op_sel_hi:[1,0]
	v_pk_mul_f32 v[146:147], v[84:85], v[142:143] op_sel_hi:[1,0]
	v_pk_mul_f32 v[142:143], v[80:81], v[142:143] op_sel_hi:[1,0]
	v_mul_f32_e32 v133, 0xbfb8aa3b, v146
	v_mul_f32_e32 v141, 0xbfb8aa3b, v142
	v_mul_f32_e32 v142, 0xbfb8aa3b, v143
	v_exp_f32_e32 v142, v142
	v_mul_f32_e32 v143, 0xbfb8aa3b, v150
	v_mul_f32_e32 v135, 0xbfb8aa3b, v147
	v_mul_f32_e32 v137, 0xbfb8aa3b, v144
	v_mul_f32_e32 v139, 0xbfb8aa3b, v145
	v_exp_f32_e32 v143, v143
	v_mul_f32_e32 v144, 0xbfb8aa3b, v151
	v_exp_f32_e32 v133, v133
	v_exp_f32_e32 v135, v135
	v_exp_f32_e32 v137, v137
	v_exp_f32_e32 v139, v139
	v_exp_f32_e32 v141, v141
	v_exp_f32_e32 v144, v144
	v_add_f32_e32 v142, 1.0, v142
	v_rcp_f32_e32 v145, v142
	v_add_f32_e32 v142, 1.0, v143
	v_add_f32_e32 v133, 1.0, v133
	v_add_f32_e32 v135, 1.0, v135
	v_add_f32_e32 v137, 1.0, v137
	v_add_f32_e32 v139, 1.0, v139
	v_add_f32_e32 v141, 1.0, v141
	v_rcp_f32_e32 v146, v142
	v_add_f32_e32 v142, 1.0, v144
	v_rcp_f32_e32 v133, v133
	v_rcp_f32_e32 v135, v135
	v_rcp_f32_e32 v137, v137
	v_rcp_f32_e32 v139, v139
	v_rcp_f32_e32 v141, v141
	v_rcp_f32_e32 v147, v142
	v_cvt_pk_bf16_f32 v142, v133, v135
	v_cvt_pk_bf16_f32 v143, v137, v139
	v_cvt_pk_bf16_f32 v144, v141, v145
	v_cvt_pk_bf16_f32 v145, v146, v147
	global_store_dwordx4 v[148:149], v[142:145], off offset:256
	v_pk_mul_f32 v[146:147], v[74:75], v[140:141] op_sel_hi:[1,0]
	s_nop 0
	v_pk_mul_f32 v[144:145], v[76:77], v[140:141] op_sel_hi:[1,0]
	v_pk_mul_f32 v[142:143], v[78:79], v[140:141] op_sel_hi:[1,0]
	v_mul_f32_e32 v133, 0xbfb8aa3b, v144
	v_mul_f32_e32 v135, 0xbfb8aa3b, v145
	v_pk_mul_f32 v[144:145], v[72:73], v[140:141] op_sel_hi:[1,0]
	v_mul_f32_e32 v137, 0xbfb8aa3b, v142
	v_mul_f32_e32 v142, 0xbfb8aa3b, v145
	v_mul_f32_e32 v139, 0xbfb8aa3b, v143
	v_exp_f32_e32 v142, v142
	v_mul_f32_e32 v143, 0xbfb8aa3b, v146
	v_mul_f32_e32 v141, 0xbfb8aa3b, v144
	v_exp_f32_e32 v143, v143
	v_mul_f32_e32 v144, 0xbfb8aa3b, v147
	v_exp_f32_e32 v141, v141
	v_exp_f32_e32 v144, v144
	v_exp_f32_e32 v133, v133
	v_exp_f32_e32 v135, v135
	v_exp_f32_e32 v137, v137
	v_exp_f32_e32 v139, v139
	v_add_f32_e32 v142, 1.0, v142
	v_rcp_f32_e32 v145, v142
	v_add_f32_e32 v142, 1.0, v143
	v_add_f32_e32 v141, 1.0, v141
	v_rcp_f32_e32 v146, v142
	v_add_f32_e32 v142, 1.0, v144
	v_add_f32_e32 v133, 1.0, v133
	v_add_f32_e32 v135, 1.0, v135
	v_add_f32_e32 v137, 1.0, v137
	v_add_f32_e32 v139, 1.0, v139
	v_rcp_f32_e32 v141, v141
	v_rcp_f32_e32 v147, v142
	v_rcp_f32_e32 v133, v133
	v_rcp_f32_e32 v135, v135
	v_rcp_f32_e32 v137, v137
	v_rcp_f32_e32 v139, v139
	v_cvt_pk_bf16_f32 v144, v141, v145
	v_cvt_pk_bf16_f32 v145, v146, v147
	v_add_co_u32_e32 v146, vcc, s67, v130
	v_cvt_pk_bf16_f32 v142, v133, v135
	v_cvt_pk_bf16_f32 v143, v137, v139
	v_addc_co_u32_e32 v147, vcc, 0, v131, vcc
	global_store_dwordx4 v[146:147], v[142:145], off
	v_pk_mul_f32 v[148:149], v[66:67], v[140:141] op_sel_hi:[1,0]
	s_nop 0
	v_pk_mul_f32 v[142:143], v[70:71], v[140:141] op_sel_hi:[1,0]
	v_pk_mul_f32 v[144:145], v[68:69], v[140:141] op_sel_hi:[1,0]
	v_pk_mul_f32 v[140:141], v[64:65], v[140:141] op_sel_hi:[1,0]
	v_mul_f32_e32 v137, 0xbfb8aa3b, v142
	v_mul_f32_e32 v140, 0xbfb8aa3b, v140
	v_exp_f32_e32 v140, v140
	v_mul_f32_e32 v141, 0xbfb8aa3b, v141
	v_exp_f32_e32 v141, v141
	v_mul_f32_e32 v133, 0xbfb8aa3b, v144
	v_add_f32_e32 v140, 1.0, v140
	v_rcp_f32_e32 v142, v140
	v_add_f32_e32 v140, 1.0, v141
	v_mul_f32_e32 v141, 0xbfb8aa3b, v148
	v_mul_f32_e32 v135, 0xbfb8aa3b, v145
; DI unsigned pk_bf16(float lo, float hi) { f32x2 v = {lo, hi}; return __builtin_bit_cast(unsigned, __builtin_convertvector(v, bf16v2)); }
; DI float fast_sigmoid(float x) { return __builtin_amdgcn_rcpf(1.0f + __expf(-x)); }
;     DI void operator()(AccRef acc, const Unit& u, int wr, int wc, int fr, int fq) const {
;     ...
;                 for (int bj = 0; bj < 2; ++bj) {
;                     const float rs = rsc.r[ai][m];
;                     const f32x4 r0 = acc[ai][bj][m][0] * rs, r1 = acc[ai][bj][m][1] * rs;
;                     u32x4 w;
;                     w.x = pk_bf16(fast_sigmoid(r0[0]), fast_sigmoid(r0[1])); w.y = pk_bf16(fast_sigmoid(r0[2]), fast_sigmoid(r0[3]));
;                     w.z = pk_bf16(fast_sigmoid(r1[0]), fast_sigmoid(r1[1])); w.w = pk_bf16(fast_sigmoid(r1[2]), fast_sigmoid(r1[3]));
;                     *(u32x4*)(Gp + (ai * 128 + m * 16) * 256 + bj * 128) = w;
	v_mul_f32_e32 v139, 0xbfb8aa3b, v143
	v_exp_f32_e32 v141, v141
	v_mul_f32_e32 v143, 0xbfb8aa3b, v149
	v_exp_f32_e32 v133, v133
	v_exp_f32_e32 v135, v135
	v_exp_f32_e32 v137, v137
	v_exp_f32_e32 v139, v139
	v_exp_f32_e32 v143, v143
	v_rcp_f32_e32 v144, v140
	v_add_f32_e32 v140, 1.0, v141
	v_add_f32_e32 v133, 1.0, v133
	v_add_f32_e32 v135, 1.0, v135
	v_add_f32_e32 v137, 1.0, v137
	v_add_f32_e32 v139, 1.0, v139
	v_rcp_f32_e32 v145, v140
	v_add_f32_e32 v140, 1.0, v143
	v_rcp_f32_e32 v133, v133
	v_rcp_f32_e32 v135, v135
	v_rcp_f32_e32 v137, v137
	v_rcp_f32_e32 v139, v139
	v_rcp_f32_e32 v143, v140
	v_cvt_pk_bf16_f32 v140, v133, v135
	v_cvt_pk_bf16_f32 v142, v142, v144
	v_cvt_pk_bf16_f32 v141, v137, v139
	v_cvt_pk_bf16_f32 v143, v145, v143
	global_store_dwordx4 v[146:147], v[140:143], off offset:256
	v_pk_mul_f32 v[144:145], v[58:59], v[138:139] op_sel_hi:[1,0]
	s_nop 0
	v_pk_mul_f32 v[142:143], v[60:61], v[138:139] op_sel_hi:[1,0]
	v_pk_mul_f32 v[140:141], v[62:63], v[138:139] op_sel_hi:[1,0]
	v_mul_f32_e32 v133, 0xbfb8aa3b, v142
	v_mul_f32_e32 v135, 0xbfb8aa3b, v143
	v_pk_mul_f32 v[142:143], v[56:57], v[138:139] op_sel_hi:[1,0]
	v_mul_f32_e32 v137, 0xbfb8aa3b, v140
	v_mul_f32_e32 v140, 0xbfb8aa3b, v142
	v_mul_f32_e32 v139, 0xbfb8aa3b, v141
	v_exp_f32_e32 v140, v140
	v_mul_f32_e32 v141, 0xbfb8aa3b, v143
	v_exp_f32_e32 v141, v141
	v_mul_f32_e32 v143, 0xbfb8aa3b, v145
	v_add_f32_e32 v140, 1.0, v140
	v_rcp_f32_e32 v142, v140
	v_add_f32_e32 v140, 1.0, v141
	v_mul_f32_e32 v141, 0xbfb8aa3b, v144
	v_exp_f32_e32 v141, v141
	v_exp_f32_e32 v133, v133
	v_exp_f32_e32 v135, v135
	v_exp_f32_e32 v137, v137
	v_exp_f32_e32 v139, v139
	v_exp_f32_e32 v143, v143
	v_rcp_f32_e32 v144, v140
	v_add_f32_e32 v140, 1.0, v141
	v_add_f32_e32 v133, 1.0, v133
	v_add_f32_e32 v135, 1.0, v135
	v_add_f32_e32 v137, 1.0, v137
	v_add_f32_e32 v139, 1.0, v139
	v_rcp_f32_e32 v145, v140
	v_add_f32_e32 v140, 1.0, v143
	v_rcp_f32_e32 v133, v133
	v_rcp_f32_e32 v135, v135
	v_rcp_f32_e32 v137, v137
	v_rcp_f32_e32 v139, v139
	v_rcp_f32_e32 v143, v140
	v_cvt_pk_bf16_f32 v142, v142, v144
	v_add_co_u32_e32 v144, vcc, s62, v130
	v_cvt_pk_bf16_f32 v140, v133, v135
	v_cvt_pk_bf16_f32 v141, v137, v139
	v_cvt_pk_bf16_f32 v143, v145, v143
	v_addc_co_u32_e32 v145, vcc, 0, v131, vcc
	global_store_dwordx4 v[144:145], v[140:143], off
	v_pk_mul_f32 v[146:147], v[50:51], v[138:139] op_sel_hi:[1,0]
	s_nop 0
	v_pk_mul_f32 v[140:141], v[54:55], v[138:139] op_sel_hi:[1,0]
	v_pk_mul_f32 v[142:143], v[52:53], v[138:139] op_sel_hi:[1,0]
	v_pk_mul_f32 v[138:139], v[48:49], v[138:139] op_sel_hi:[1,0]
	v_mul_f32_e32 v137, 0xbfb8aa3b, v140
	v_mul_f32_e32 v138, 0xbfb8aa3b, v138
	v_exp_f32_e32 v138, v138
	v_mul_f32_e32 v139, 0xbfb8aa3b, v139
	v_exp_f32_e32 v139, v139
	v_mul_f32_e32 v140, 0xbfb8aa3b, v141
	v_add_f32_e32 v138, 1.0, v138
	v_rcp_f32_e32 v141, v138
	v_add_f32_e32 v138, 1.0, v139
	v_mul_f32_e32 v139, 0xbfb8aa3b, v146
	v_mul_f32_e32 v133, 0xbfb8aa3b, v142
	v_mul_f32_e32 v135, 0xbfb8aa3b, v143
	v_exp_f32_e32 v139, v139
	v_mul_f32_e32 v142, 0xbfb8aa3b, v147
	v_exp_f32_e32 v133, v133
	v_exp_f32_e32 v135, v135
	v_exp_f32_e32 v137, v137
	v_exp_f32_e32 v140, v140
	v_exp_f32_e32 v142, v142
	v_rcp_f32_e32 v143, v138
	v_add_f32_e32 v138, 1.0, v139
	v_add_f32_e32 v133, 1.0, v133
	v_add_f32_e32 v135, 1.0, v135
	v_add_f32_e32 v137, 1.0, v137
	v_add_f32_e32 v140, 1.0, v140
	v_rcp_f32_e32 v146, v138
	v_add_f32_e32 v138, 1.0, v142
	v_rcp_f32_e32 v133, v133
	v_rcp_f32_e32 v135, v135
	v_rcp_f32_e32 v137, v137
	v_rcp_f32_e32 v140, v140
	v_rcp_f32_e32 v142, v138
	v_cvt_pk_bf16_f32 v138, v133, v135
	v_cvt_pk_bf16_f32 v139, v137, v140
	v_cvt_pk_bf16_f32 v140, v141, v143
	v_cvt_pk_bf16_f32 v141, v146, v142
	global_store_dwordx4 v[144:145], v[138:141], off offset:256
	v_pk_mul_f32 v[142:143], v[42:43], v[136:137] op_sel_hi:[1,0]
	s_nop 0
	v_pk_mul_f32 v[138:139], v[46:47], v[136:137] op_sel_hi:[1,0]
	v_pk_mul_f32 v[140:141], v[44:45], v[136:137] op_sel_hi:[1,0]
	s_nop 0
	v_mul_f32_e32 v133, 0xbfb8aa3b, v140
	v_mul_f32_e32 v135, 0xbfb8aa3b, v141
	v_pk_mul_f32 v[140:141], v[40:41], v[136:137] op_sel_hi:[1,0]
	v_mul_f32_e32 v137, 0xbfb8aa3b, v138
	v_mul_f32_e32 v138, 0xbfb8aa3b, v139
	v_exp_f32_e32 v138, v138
	v_mul_f32_e32 v139, 0xbfb8aa3b, v140
	v_exp_f32_e32 v139, v139
	v_mul_f32_e32 v140, 0xbfb8aa3b, v141
	v_exp_f32_e32 v140, v140
	v_add_f32_e32 v138, 1.0, v138
	v_rcp_f32_e32 v141, v138
	v_add_f32_e32 v138, 1.0, v139
	v_mul_f32_e32 v139, 0xbfb8aa3b, v142
	v_rcp_f32_e32 v144, v138
	v_add_f32_e32 v138, 1.0, v140
	v_exp_f32_e32 v139, v139
	v_mul_f32_e32 v140, 0xbfb8aa3b, v143
	v_exp_f32_e32 v133, v133
	v_exp_f32_e32 v135, v135
	v_exp_f32_e32 v137, v137
	v_exp_f32_e32 v140, v140
	v_rcp_f32_e32 v142, v138
	v_add_f32_e32 v138, 1.0, v139
	v_add_f32_e32 v133, 1.0, v133
	v_add_f32_e32 v135, 1.0, v135
	v_add_f32_e32 v137, 1.0, v137
	v_rcp_f32_e32 v143, v138
	v_add_f32_e32 v138, 1.0, v140
	v_rcp_f32_e32 v133, v133
	v_rcp_f32_e32 v135, v135
	v_rcp_f32_e32 v137, v137
	v_rcp_f32_e32 v145, v138
	v_cvt_pk_bf16_f32 v140, v144, v142
	v_add_co_u32_e32 v142, vcc, s63, v130
	v_cvt_pk_bf16_f32 v138, v133, v135
	v_cvt_pk_bf16_f32 v139, v137, v141
	v_cvt_pk_bf16_f32 v141, v143, v145
	v_addc_co_u32_e32 v143, vcc, 0, v131, vcc
	global_store_dwordx4 v[142:143], v[138:141], off
	v_pk_mul_f32 v[144:145], v[34:35], v[136:137] op_sel_hi:[1,0]
	s_nop 0
	v_pk_mul_f32 v[138:139], v[38:39], v[136:137] op_sel_hi:[1,0]
	v_pk_mul_f32 v[140:141], v[36:37], v[136:137] op_sel_hi:[1,0]
	v_pk_mul_f32 v[136:137], v[32:33], v[136:137] op_sel_hi:[1,0]
	v_mul_f32_e32 v133, 0xbfb8aa3b, v140
	v_mul_f32_e32 v136, 0xbfb8aa3b, v136
	v_exp_f32_e32 v136, v136
; DI unsigned pk_bf16(float lo, float hi) { f32x2 v = {lo, hi}; return __builtin_bit_cast(unsigned, __builtin_convertvector(v, bf16v2)); }
; DI float fast_sigmoid(float x) { return __builtin_amdgcn_rcpf(1.0f + __expf(-x)); }
;     DI void operator()(AccRef acc, const Unit& u, int wr, int wc, int fr, int fq) const {
;     ...
;                 for (int bj = 0; bj < 2; ++bj) {
;                     const float rs = rsc.r[ai][m];
;                     const f32x4 r0 = acc[ai][bj][m][0] * rs, r1 = acc[ai][bj][m][1] * rs;
;                     u32x4 w;
;                     w.x = pk_bf16(fast_sigmoid(r0[0]), fast_sigmoid(r0[1])); w.y = pk_bf16(fast_sigmoid(r0[2]), fast_sigmoid(r0[3]));
;                     w.z = pk_bf16(fast_sigmoid(r1[0]), fast_sigmoid(r1[1])); w.w = pk_bf16(fast_sigmoid(r1[2]), fast_sigmoid(r1[3]));
;                     *(u32x4*)(Gp + (ai * 128 + m * 16) * 256 + bj * 128) = w;
	v_mul_f32_e32 v137, 0xbfb8aa3b, v137
	v_exp_f32_e32 v137, v137
	v_mul_f32_e32 v135, 0xbfb8aa3b, v141
	v_add_f32_e32 v136, 1.0, v136
	v_rcp_f32_e32 v140, v136
	v_add_f32_e32 v136, 1.0, v137
	v_mul_f32_e32 v137, 0xbfb8aa3b, v144
	v_mul_f32_e32 v138, 0xbfb8aa3b, v138
	v_mul_f32_e32 v139, 0xbfb8aa3b, v139
	v_exp_f32_e32 v137, v137
	v_mul_f32_e32 v141, 0xbfb8aa3b, v145
	v_exp_f32_e32 v133, v133
	v_exp_f32_e32 v135, v135
	v_exp_f32_e32 v138, v138
	v_exp_f32_e32 v139, v139
	v_exp_f32_e32 v141, v141
	v_rcp_f32_e32 v144, v136
	v_add_f32_e32 v136, 1.0, v137
	v_add_f32_e32 v133, 1.0, v133
	v_add_f32_e32 v135, 1.0, v135
	v_add_f32_e32 v138, 1.0, v138
	v_add_f32_e32 v139, 1.0, v139
	v_rcp_f32_e32 v145, v136
	v_add_f32_e32 v136, 1.0, v141
	v_rcp_f32_e32 v133, v133
	v_rcp_f32_e32 v135, v135
	v_rcp_f32_e32 v138, v138
	v_rcp_f32_e32 v139, v139
	v_rcp_f32_e32 v141, v136
	v_cvt_pk_bf16_f32 v136, v133, v135
	v_cvt_pk_bf16_f32 v137, v138, v139
	v_cvt_pk_bf16_f32 v138, v140, v144
	v_cvt_pk_bf16_f32 v139, v145, v141
	global_store_dwordx4 v[142:143], v[136:139], off offset:256
	v_pk_mul_f32 v[140:141], v[26:27], v[134:135] op_sel_hi:[1,0]
	s_nop 0
	v_pk_mul_f32 v[136:137], v[30:31], v[134:135] op_sel_hi:[1,0]
	v_pk_mul_f32 v[138:139], v[28:29], v[134:135] op_sel_hi:[1,0]
	v_mul_f32_e32 v136, 0xbfb8aa3b, v136
	v_mul_f32_e32 v135, 0xbfb8aa3b, v139
	v_exp_f32_e32 v135, v135
	v_exp_f32_e32 v136, v136
	v_mul_f32_e32 v137, 0xbfb8aa3b, v137
	v_exp_f32_e32 v137, v137
	v_mul_f32_e32 v133, 0xbfb8aa3b, v138
	v_pk_mul_f32 v[138:139], v[24:25], v[134:135] op_sel_hi:[1,0]
	v_add_f32_e32 v136, 1.0, v136
	v_rcp_f32_e32 v142, v136
	v_add_f32_e32 v136, 1.0, v137
	v_mul_f32_e32 v137, 0xbfb8aa3b, v138
	v_exp_f32_e32 v137, v137
	v_mul_f32_e32 v138, 0xbfb8aa3b, v139
	v_exp_f32_e32 v138, v138
	v_rcp_f32_e32 v139, v136
	v_add_f32_e32 v136, 1.0, v137
	v_mul_f32_e32 v137, 0xbfb8aa3b, v140
	v_rcp_f32_e32 v143, v136
	v_add_f32_e32 v136, 1.0, v138
	v_exp_f32_e32 v137, v137
	v_mul_f32_e32 v138, 0xbfb8aa3b, v141
	v_exp_f32_e32 v133, v133
	v_exp_f32_e32 v138, v138
	v_rcp_f32_e32 v140, v136
	v_add_f32_e32 v136, 1.0, v137
	v_add_f32_e32 v133, 1.0, v133
	v_add_f32_e32 v135, 1.0, v135
	v_rcp_f32_e32 v141, v136
	v_add_f32_e32 v136, 1.0, v138
	v_rcp_f32_e32 v133, v133
	v_rcp_f32_e32 v135, v135
	v_rcp_f32_e32 v144, v136
	v_cvt_pk_bf16_f32 v138, v143, v140
	v_add_co_u32_e32 v140, vcc, s64, v130
	v_cvt_pk_bf16_f32 v136, v133, v135
	v_cvt_pk_bf16_f32 v137, v142, v139
	v_cvt_pk_bf16_f32 v139, v141, v144
	v_addc_co_u32_e32 v141, vcc, 0, v131, vcc
	global_store_dwordx4 v[140:141], v[136:139], off
	v_pk_mul_f32 v[142:143], v[18:19], v[134:135] op_sel_hi:[1,0]
	s_nop 0
	v_pk_mul_f32 v[138:139], v[20:21], v[134:135] op_sel_hi:[1,0]
	v_pk_mul_f32 v[136:137], v[22:23], v[134:135] op_sel_hi:[1,0]
	v_mul_f32_e32 v135, 0xbfb8aa3b, v139
	v_mul_f32_e32 v133, 0xbfb8aa3b, v138
	v_exp_f32_e32 v138, v135
	v_pk_mul_f32 v[134:135], v[16:17], v[134:135] op_sel_hi:[1,0]
	v_mul_f32_e32 v136, 0xbfb8aa3b, v136
	v_mul_f32_e32 v134, 0xbfb8aa3b, v134
	v_exp_f32_e32 v134, v134
	v_mul_f32_e32 v135, 0xbfb8aa3b, v135
	v_exp_f32_e32 v135, v135
	v_mul_f32_e32 v137, 0xbfb8aa3b, v137
	v_add_f32_e32 v134, 1.0, v134
	v_rcp_f32_e32 v139, v134
	v_add_f32_e32 v134, 1.0, v135
	v_mul_f32_e32 v135, 0xbfb8aa3b, v142
	v_exp_f32_e32 v135, v135
	v_mul_f32_e32 v142, 0xbfb8aa3b, v143
	v_exp_f32_e32 v133, v133
	v_exp_f32_e32 v136, v136
	v_exp_f32_e32 v137, v137
	v_exp_f32_e32 v142, v142
	v_rcp_f32_e32 v143, v134
	v_add_f32_e32 v134, 1.0, v135
	v_add_f32_e32 v133, 1.0, v133
	v_add_f32_e32 v138, 1.0, v138
	v_add_f32_e32 v136, 1.0, v136
	v_add_f32_e32 v137, 1.0, v137
	v_rcp_f32_e32 v144, v134
	v_add_f32_e32 v134, 1.0, v142
	v_rcp_f32_e32 v133, v133
	v_rcp_f32_e32 v138, v138
	v_rcp_f32_e32 v136, v136
	v_rcp_f32_e32 v137, v137
	v_rcp_f32_e32 v142, v134
	v_cvt_pk_bf16_f32 v134, v133, v138
	v_cvt_pk_bf16_f32 v135, v136, v137
	v_cvt_pk_bf16_f32 v136, v139, v143
	v_cvt_pk_bf16_f32 v137, v144, v142
	global_store_dwordx4 v[140:141], v[134:137], off offset:256
	v_pk_mul_f32 v[138:139], v[10:11], v[132:133] op_sel_hi:[1,0]
	s_nop 0
	v_pk_mul_f32 v[134:135], v[14:15], v[132:133] op_sel_hi:[1,0]
	v_pk_mul_f32 v[136:137], v[12:13], v[132:133] op_sel_hi:[1,0]
	v_mul_f32_e32 v134, 0xbfb8aa3b, v134
	v_mul_f32_e32 v133, 0xbfb8aa3b, v136
	v_exp_f32_e32 v133, v133
	v_exp_f32_e32 v134, v134
	v_mul_f32_e32 v135, 0xbfb8aa3b, v135
	v_exp_f32_e32 v135, v135
	v_mul_f32_e32 v136, 0xbfb8aa3b, v137
	v_exp_f32_e32 v140, v136
	v_pk_mul_f32 v[136:137], v[8:9], v[132:133] op_sel_hi:[1,0]
	v_add_f32_e32 v134, 1.0, v134
	v_rcp_f32_e32 v141, v134
	v_add_f32_e32 v134, 1.0, v135
	v_mul_f32_e32 v135, 0xbfb8aa3b, v136
	v_exp_f32_e32 v135, v135
	v_mul_f32_e32 v136, 0xbfb8aa3b, v137
	v_exp_f32_e32 v136, v136
	v_rcp_f32_e32 v137, v134
	v_add_f32_e32 v134, 1.0, v135
	v_mul_f32_e32 v135, 0xbfb8aa3b, v138
	v_rcp_f32_e32 v142, v134
	v_add_f32_e32 v134, 1.0, v136
	v_exp_f32_e32 v135, v135
	v_mul_f32_e32 v136, 0xbfb8aa3b, v139
	v_exp_f32_e32 v136, v136
	v_rcp_f32_e32 v138, v134
	v_add_f32_e32 v134, 1.0, v135
	v_add_f32_e32 v133, 1.0, v133
	v_rcp_f32_e32 v139, v134
	v_add_f32_e32 v134, 1.0, v136
	v_rcp_f32_e32 v133, v133
	v_rcp_f32_e32 v143, v134
	v_add_f32_e32 v140, 1.0, v140
	v_rcp_f32_e32 v140, v140
	v_cvt_pk_bf16_f32 v136, v142, v138
	v_add_co_u32_e32 v138, vcc, s65, v130
	v_cvt_pk_bf16_f32 v135, v141, v137
	v_cvt_pk_bf16_f32 v137, v139, v143
	v_addc_co_u32_e32 v139, vcc, 0, v131, vcc
	v_pk_mul_f32 v[130:131], v[6:7], v[132:133] op_sel_hi:[1,0]
	v_cvt_pk_bf16_f32 v134, v133, v140
	v_mul_f32_e32 v130, 0xbfb8aa3b, v130
	v_exp_f32_e32 v130, v130
	v_mul_f32_e32 v131, 0xbfb8aa3b, v131
	global_store_dwordx4 v[138:139], v[134:137], off
	v_exp_f32_e32 v131, v131
	v_add_f32_e32 v130, 1.0, v130
	v_pk_mul_f32 v[134:135], v[4:5], v[132:133] op_sel_hi:[1,0]
	v_pk_mul_f32 v[136:137], v[2:3], v[132:133] op_sel_hi:[1,0]
	v_mul_f32_e32 v133, 0xbfb8aa3b, v134
	v_exp_f32_e32 v134, v133
	v_mul_f32_e32 v133, 0xbfb8aa3b, v135
	v_exp_f32_e32 v135, v133
	v_pk_mul_f32 v[132:133], v[0:1], v[132:133] op_sel_hi:[1,0]
	v_rcp_f32_e32 v140, v130
	v_add_f32_e32 v130, 1.0, v131
	v_mul_f32_e32 v131, 0xbfb8aa3b, v132
	v_exp_f32_e32 v131, v131
	v_mul_f32_e32 v132, 0xbfb8aa3b, v133
	v_exp_f32_e32 v132, v132
	v_rcp_f32_e32 v133, v130
	v_add_f32_e32 v130, 1.0, v131
	v_mul_f32_e32 v131, 0xbfb8aa3b, v136
	v_rcp_f32_e32 v141, v130
	v_add_f32_e32 v130, 1.0, v132
	v_exp_f32_e32 v131, v131
	v_mul_f32_e32 v132, 0xbfb8aa3b, v137
	v_exp_f32_e32 v132, v132
	v_rcp_f32_e32 v136, v130
	v_add_f32_e32 v130, 1.0, v131
	v_add_f32_e32 v134, 1.0, v134
	v_add_f32_e32 v135, 1.0, v135
	v_rcp_f32_e32 v137, v130
	v_add_f32_e32 v130, 1.0, v132
	v_rcp_f32_e32 v134, v134
	v_rcp_f32_e32 v135, v135
	v_rcp_f32_e32 v142, v130
	v_cvt_pk_bf16_f32 v131, v140, v133
	v_cvt_pk_bf16_f32 v132, v141, v136
	v_cvt_pk_bf16_f32 v130, v134, v135
	v_cvt_pk_bf16_f32 v133, v137, v142
	global_store_dwordx4 v[138:139], v[130:133], off offset:256

; #define PG8_STAGE(bufoff, gbase, voff) do { _Pragma("unroll") for (int _i = 0; _i < 2; ++_i) \
;         __builtin_amdgcn_global_load_lds((const unsigned*)((const char*)(gbase) + (voff)[_i]), (LAS unsigned*)(lds + (bufoff) + ldsw + _i * 8192), 16, 0, 0); } while (0)
; #define PG8_LDA(dst, b, h) do { _Pragma("unroll") for (int m = 0; m < 4; ++m) _Pragma("unroll") for (int k = 0; k < 2; ++k) dst[m][k] = *(const LAS bf16x8*)(lds + PG8_SA(b, h) + aoff + m * 2048 + k * 1024); } while (0)
; #define PG8_LDB(dst, b, h) do { _Pragma("unroll") for (int n = 0; n < 2; ++n) _Pragma("unroll") for (int k = 0; k < 2; ++k) dst[n][k] = *(const LAS bf16x8*)(lds + PG8_SB(b, h) + boff + n * 2048 + k * 1024); } while (0)
; #define PG8_MMA(ai, bj, At, Bt) do { __builtin_amdgcn_s_setprio(1); _Pragma("unroll") for (int m = 0; m < 4; ++m) _Pragma("unroll") for (int n = 0; n < 2; ++n) _Pragma("unroll") for (int k = 0; k < 2; ++k) \
;         acc[ai][bj][m][n] = __builtin_amdgcn_mfma_f32_16x16x32_bf16(Bt[n][k], At[m][k], acc[ai][bj][m][n], 0, 0, 0); __builtin_amdgcn_s_setprio(0); } while (0)
; #define PG8_WAIT_V(n) asm volatile("s_waitcnt vmcnt(" #n ")" ::: "memory")
; #define PG8_WAIT_L(n) asm volatile("s_waitcnt lgkmcnt(" #n ")" ::: "memory")
; #define PG8_BAR __builtin_amdgcn_s_barrier()
; #define PG8_SCHED __builtin_amdgcn_sched_barrier(0)
; #define PG8_WAIT_V(n) asm volatile("s_waitcnt vmcnt(" #n ")" ::: "memory")
; template <class Epi>
; DI void gemm_phase(LAS unsigned char* lds, const Gemm g, const StaticOrder S, const Epi E) {
;     ...
;             PG8_LDB(B0, 0, 0); PG8_SCHED; PG8_LDA(At, 0, 0); PG8_STAGE(PG8_SA(1, 1), a1 + hstep, voffA);
;             PG8_WAIT_L(8); PG8_BAR; PG8_WAIT_L(0); PG8_MMA(0, 0, At, B0); PG8_BAR; PG8_SCHED;
;             PG8_LDB(B1, 0, 1); PG8_STAGE(PG8_SB(0, 0), b2, voffB);
;             PG8_BAR; PG8_WAIT_L(0); PG8_MMA(0, 1, At, B1); PG8_BAR;
;             PG8_LDA(At, 0, 1); PG8_STAGE(PG8_SA(0, 0), a2, voffA);
;             PG8_BAR; PG8_WAIT_L(0); PG8_MMA(1, 0, At, B0); PG8_BAR; PG8_SCHED;
;             PG8_STAGE(PG8_SB(0, 1), b2 + hstep, voffB);
;             PG8_WAIT_V(6); PG8_BAR; PG8_MMA(1, 1, At, B1); PG8_BAR;
;             PG8_LDB(B0, 1, 0); PG8_SCHED; PG8_LDA(At, 1, 0); PG8_STAGE(PG8_SA(0, 1), a2 + hstep, voffA);
;             PG8_WAIT_L(8); PG8_BAR; PG8_WAIT_L(0); PG8_MMA(0, 0, At, B0); PG8_BAR; PG8_SCHED;
.LBB0_708:
	ds_read_b128 v[156:159], v179
	ds_read_b128 v[160:163], v179 offset:1024
	ds_read_b128 v[164:167], v179 offset:2048
	ds_read_b128 v[168:171], v179 offset:3072
	s_add_u32 s40, s38, 0xfffc0080
	s_addc_u32 s41, s39, -1
	s_cmp_eq_u32 s69, 12
	s_cselect_b32 s43, s6, s41
	s_cselect_b32 s42, s7, s40
	s_cselect_b32 s41, s17, s68
	s_cselect_b32 s40, s19, s67
	v_lshl_add_u64 v[210:211], s[38:39], 0, v[148:149]
	s_add_i32 m0, s25, 0xc000
	ds_read_b128 v[172:175], v180
	ds_read_b128 v[186:189], v180 offset:2048
	ds_read_b128 v[194:197], v180 offset:4096
	ds_read_b128 v[202:205], v180 offset:6144
	global_load_lds_dwordx4 v[210:211], off
	s_add_i32 m0, s25, 0xe000
	v_lshl_add_u64 v[210:211], s[38:39], 0, v[150:151]
	global_load_lds_dwordx4 v[210:211], off
	s_waitcnt lgkmcnt(4)
	s_setprio 1
	s_barrier
	ds_read_b128 v[182:185], v180 offset:1024
	ds_read_b128 v[190:193], v180 offset:3072
	ds_read_b128 v[198:201], v180 offset:5120
	ds_read_b128 v[206:209], v180 offset:7168
	s_waitcnt lgkmcnt(4)
	v_mfma_f32_16x16x32_bf16 v[124:127], v[156:159], v[172:175], v[124:127]
	v_mfma_f32_16x16x32_bf16 v[120:123], v[164:167], v[172:175], v[120:123]
	v_mfma_f32_16x16x32_bf16 v[108:111], v[156:159], v[186:189], v[108:111]
	v_mfma_f32_16x16x32_bf16 v[104:107], v[164:167], v[186:189], v[104:107]
	v_mfma_f32_16x16x32_bf16 v[92:95], v[156:159], v[194:197], v[92:95]
	v_mfma_f32_16x16x32_bf16 v[88:91], v[164:167], v[194:197], v[88:91]
	v_mfma_f32_16x16x32_bf16 v[84:87], v[156:159], v[202:205], v[84:87]
	v_mfma_f32_16x16x32_bf16 v[80:83], v[164:167], v[202:205], v[80:83]
	s_waitcnt lgkmcnt(3)
	v_mfma_f32_16x16x32_bf16 v[124:127], v[160:163], v[182:185], v[124:127]
	v_mfma_f32_16x16x32_bf16 v[120:123], v[168:171], v[182:185], v[120:123]
	s_waitcnt lgkmcnt(2)
	v_mfma_f32_16x16x32_bf16 v[108:111], v[160:163], v[190:193], v[108:111]
	v_mfma_f32_16x16x32_bf16 v[104:107], v[168:171], v[190:193], v[104:107]
	s_waitcnt lgkmcnt(1)
	v_mfma_f32_16x16x32_bf16 v[92:95], v[160:163], v[198:201], v[92:95]
	v_mfma_f32_16x16x32_bf16 v[88:91], v[168:171], v[198:201], v[88:91]
	s_waitcnt lgkmcnt(0)
	s_setprio 2
	s_barrier
	v_mfma_f32_16x16x32_bf16 v[84:87], v[160:163], v[206:209], v[84:87]
	v_mfma_f32_16x16x32_bf16 v[80:83], v[168:171], v[206:209], v[80:83]
	s_setprio 0
	s_add_i32 s76, s52, s44
	v_lshl_add_u64 v[228:229], s[40:41], 0, v[130:131]
	s_mov_b32 m0, s76
	ds_read_b128 v[210:213], v181
	ds_read_b128 v[214:217], v181 offset:1024
	ds_read_b128 v[218:221], v181 offset:2048
	ds_read_b128 v[224:227], v181 offset:3072
	global_load_lds_dwordx4 v[228:229], off
	s_add_i32 m0, s76, 0x2000
	v_lshl_add_u64 v[230:231], s[40:41], 0, v[134:135]
	global_load_lds_dwordx4 v[230:231], off
	s_setprio 1
	s_barrier
	s_waitcnt lgkmcnt(0)
	v_mfma_f32_16x16x32_bf16 v[116:119], v[210:213], v[172:175], v[116:119]
	v_mfma_f32_16x16x32_bf16 v[112:115], v[218:221], v[172:175], v[112:115]
	v_mfma_f32_16x16x32_bf16 v[100:103], v[210:213], v[186:189], v[100:103]
	v_mfma_f32_16x16x32_bf16 v[96:99], v[218:221], v[186:189], v[96:99]
	v_mfma_f32_16x16x32_bf16 v[76:79], v[210:213], v[194:197], v[76:79]
	v_mfma_f32_16x16x32_bf16 v[72:75], v[218:221], v[194:197], v[72:75]
	v_mfma_f32_16x16x32_bf16 v[68:71], v[210:213], v[202:205], v[68:71]
	v_mfma_f32_16x16x32_bf16 v[64:67], v[218:221], v[202:205], v[64:67]
	v_mfma_f32_16x16x32_bf16 v[116:119], v[214:217], v[182:185], v[116:119]
	v_mfma_f32_16x16x32_bf16 v[112:115], v[224:227], v[182:185], v[112:115]
	v_mfma_f32_16x16x32_bf16 v[100:103], v[214:217], v[190:193], v[100:103]
	v_mfma_f32_16x16x32_bf16 v[96:99], v[224:227], v[190:193], v[96:99]
	v_mfma_f32_16x16x32_bf16 v[76:79], v[214:217], v[198:201], v[76:79]
	v_mfma_f32_16x16x32_bf16 v[72:75], v[224:227], v[198:201], v[72:75]
	s_setprio 2
	s_barrier
	v_mfma_f32_16x16x32_bf16 v[68:71], v[214:217], v[206:209], v[68:71]
	v_mfma_f32_16x16x32_bf16 v[64:67], v[224:227], v[206:209], v[64:67]
	s_setprio 0
	s_mov_b32 m0, s25
	v_lshl_add_u64 v[232:233], s[42:43], 0, v[128:129]
	ds_read_b128 v[172:175], v180 offset:16384
	ds_read_b128 v[186:189], v180 offset:18432
	ds_read_b128 v[194:197], v180 offset:20480
	ds_read_b128 v[202:205], v180 offset:22528
	global_load_lds_dwordx4 v[232:233], off
	s_mov_b32 m0, s45
	v_lshl_add_u64 v[234:235], s[42:43], 0, v[132:133]
	global_load_lds_dwordx4 v[234:235], off
	s_setprio 1
	s_barrier
	ds_read_b128 v[182:185], v180 offset:17408
	ds_read_b128 v[190:193], v180 offset:19456
	ds_read_b128 v[198:201], v180 offset:21504
	ds_read_b128 v[206:209], v180 offset:23552
	s_waitcnt lgkmcnt(4)
	v_mfma_f32_16x16x32_bf16 v[60:63], v[156:159], v[172:175], v[60:63]
	v_mfma_f32_16x16x32_bf16 v[56:59], v[164:167], v[172:175], v[56:59]
	v_mfma_f32_16x16x32_bf16 v[52:55], v[156:159], v[186:189], v[52:55]
	v_mfma_f32_16x16x32_bf16 v[48:51], v[164:167], v[186:189], v[48:51]
	v_mfma_f32_16x16x32_bf16 v[28:31], v[156:159], v[194:197], v[28:31]
	v_mfma_f32_16x16x32_bf16 v[24:27], v[164:167], v[194:197], v[24:27]
	v_mfma_f32_16x16x32_bf16 v[20:23], v[156:159], v[202:205], v[20:23]
	v_mfma_f32_16x16x32_bf16 v[16:19], v[164:167], v[202:205], v[16:19]
	s_waitcnt lgkmcnt(3)
	v_mfma_f32_16x16x32_bf16 v[60:63], v[160:163], v[182:185], v[60:63]
	v_mfma_f32_16x16x32_bf16 v[56:59], v[168:171], v[182:185], v[56:59]
	s_waitcnt lgkmcnt(2)
	v_mfma_f32_16x16x32_bf16 v[52:55], v[160:163], v[190:193], v[52:55]
	v_mfma_f32_16x16x32_bf16 v[48:51], v[168:171], v[190:193], v[48:51]
	s_waitcnt lgkmcnt(1)
	v_mfma_f32_16x16x32_bf16 v[28:31], v[160:163], v[198:201], v[28:31]
	v_mfma_f32_16x16x32_bf16 v[24:27], v[168:171], v[198:201], v[24:27]
	s_waitcnt lgkmcnt(0)
	s_setprio 2
	s_barrier
; #define PG8_STAGE(bufoff, gbase, voff) do { _Pragma("unroll") for (int _i = 0; _i < 2; ++_i) \
;         __builtin_amdgcn_global_load_lds((const unsigned*)((const char*)(gbase) + (voff)[_i]), (LAS unsigned*)(lds + (bufoff) + ldsw + _i * 8192), 16, 0, 0); } while (0)
; #define PG8_LDA(dst, b, h) do { _Pragma("unroll") for (int m = 0; m < 4; ++m) _Pragma("unroll") for (int k = 0; k < 2; ++k) dst[m][k] = *(const LAS bf16x8*)(lds + PG8_SA(b, h) + aoff + m * 2048 + k * 1024); } while (0)
; #define PG8_LDB(dst, b, h) do { _Pragma("unroll") for (int n = 0; n < 2; ++n) _Pragma("unroll") for (int k = 0; k < 2; ++k) dst[n][k] = *(const LAS bf16x8*)(lds + PG8_SB(b, h) + boff + n * 2048 + k * 1024); } while (0)
; #define PG8_MMA(ai, bj, At, Bt) do { __builtin_amdgcn_s_setprio(1); _Pragma("unroll") for (int m = 0; m < 4; ++m) _Pragma("unroll") for (int n = 0; n < 2; ++n) _Pragma("unroll") for (int k = 0; k < 2; ++k) \
;         acc[ai][bj][m][n] = __builtin_amdgcn_mfma_f32_16x16x32_bf16(Bt[n][k], At[m][k], acc[ai][bj][m][n], 0, 0, 0); __builtin_amdgcn_s_setprio(0); } while (0)
; #define PG8_WAIT_V(n) asm volatile("s_waitcnt vmcnt(" #n ")" ::: "memory")
; #define PG8_WAIT_L(n) asm volatile("s_waitcnt lgkmcnt(" #n ")" ::: "memory")
; #define PG8_BAR __builtin_amdgcn_s_barrier()
; #define PG8_SCHED __builtin_amdgcn_sched_barrier(0)
; #define PG8_LDA(dst, b, h) do { _Pragma("unroll") for (int m = 0; m < 4; ++m) _Pragma("unroll") for (int k = 0; k < 2; ++k) dst[m][k] = *(const LAS bf16x8*)(lds + PG8_SA(b, h) + aoff + m * 2048 + k * 1024); } while (0)
; template <class Epi>
; DI void gemm_phase(LAS unsigned char* lds, const Gemm g, const StaticOrder S, const Epi E) {
;     ...
;             PG8_BAR; PG8_WAIT_L(0); PG8_MMA(1, 0, At, B0); PG8_BAR; PG8_SCHED;
;             PG8_STAGE(PG8_SB(0, 1), b2 + hstep, voffB);
;             PG8_WAIT_V(6); PG8_BAR; PG8_MMA(1, 1, At, B1); PG8_BAR;
;             PG8_LDB(B0, 1, 0); PG8_SCHED; PG8_LDA(At, 1, 0); PG8_STAGE(PG8_SA(0, 1), a2 + hstep, voffA);
;             PG8_WAIT_L(8); PG8_BAR; PG8_WAIT_L(0); PG8_MMA(0, 0, At, B0); PG8_BAR; PG8_SCHED;
;             PG8_LDB(B1, 1, 1); PG8_STAGE(PG8_SB(1, 0), b3, voffB);
;             PG8_BAR; PG8_WAIT_L(0); PG8_MMA(0, 1, At, B1); PG8_BAR;
;             PG8_LDA(At, 1, 1); PG8_STAGE(PG8_SA(1, 0), a3, voffA);
;             PG8_BAR; PG8_WAIT_L(0); PG8_MMA(1, 0, At, B0); PG8_BAR; PG8_SCHED;
	v_mfma_f32_16x16x32_bf16 v[20:23], v[160:163], v[206:209], v[20:23]
	v_mfma_f32_16x16x32_bf16 v[16:19], v[168:171], v[206:209], v[16:19]
	s_setprio 0
	s_add_u32 s76, s40, 0x40000
	s_addc_u32 s77, s41, 0
	s_add_i32 s78, s53, s44
	s_mov_b32 m0, s78
	v_lshl_add_u64 v[156:157], s[76:77], 0, v[130:131]
	global_load_lds_dwordx4 v[156:157], off
	s_add_i32 m0, s78, 0x2000
	v_lshl_add_u64 v[156:157], s[76:77], 0, v[134:135]
	global_load_lds_dwordx4 v[156:157], off
	s_waitcnt vmcnt(6)
	s_setprio 1
	s_barrier
	v_mfma_f32_16x16x32_bf16 v[44:47], v[210:213], v[172:175], v[44:47]
	v_mfma_f32_16x16x32_bf16 v[40:43], v[218:221], v[172:175], v[40:43]
	v_mfma_f32_16x16x32_bf16 v[36:39], v[210:213], v[186:189], v[36:39]
	v_mfma_f32_16x16x32_bf16 v[32:35], v[218:221], v[186:189], v[32:35]
	v_mfma_f32_16x16x32_bf16 v[12:15], v[210:213], v[194:197], v[12:15]
	v_mfma_f32_16x16x32_bf16 v[8:11], v[218:221], v[194:197], v[8:11]
	v_mfma_f32_16x16x32_bf16 v[4:7], v[210:213], v[202:205], v[4:7]
	v_mfma_f32_16x16x32_bf16 v[0:3], v[218:221], v[202:205], v[0:3]
	v_mfma_f32_16x16x32_bf16 v[44:47], v[214:217], v[182:185], v[44:47]
	v_mfma_f32_16x16x32_bf16 v[40:43], v[224:227], v[182:185], v[40:43]
	v_mfma_f32_16x16x32_bf16 v[36:39], v[214:217], v[190:193], v[36:39]
	v_mfma_f32_16x16x32_bf16 v[32:35], v[224:227], v[190:193], v[32:35]
	v_mfma_f32_16x16x32_bf16 v[12:15], v[214:217], v[198:201], v[12:15]
	v_mfma_f32_16x16x32_bf16 v[8:11], v[224:227], v[198:201], v[8:11]
	s_setprio 2
	s_barrier
	v_mfma_f32_16x16x32_bf16 v[4:7], v[214:217], v[206:209], v[4:7]
	v_mfma_f32_16x16x32_bf16 v[0:3], v[224:227], v[206:209], v[0:3]
	s_setprio 0
	s_add_i32 s76, 0, 0x18000
	v_add_u32_e32 v168, s76, v177
	ds_read_b128 v[156:159], v168
	ds_read_b128 v[160:163], v168 offset:1024
	ds_read_b128 v[164:167], v168 offset:2048
	ds_read_b128 v[168:171], v168 offset:3072
	s_add_u32 s42, s42, 0x40000
	s_addc_u32 s43, s43, 0
	s_mov_b32 m0, s46
	v_lshl_add_u64 v[210:211], s[42:43], 0, v[128:129]
	ds_read_b128 v[172:175], v180 offset:32768
	ds_read_b128 v[186:189], v180 offset:34816
	ds_read_b128 v[194:197], v180 offset:36864
	ds_read_b128 v[202:205], v180 offset:38912
	global_load_lds_dwordx4 v[210:211], off
	s_mov_b32 m0, s47
	v_lshl_add_u64 v[210:211], s[42:43], 0, v[132:133]
	global_load_lds_dwordx4 v[210:211], off
	s_waitcnt lgkmcnt(4)
	s_setprio 1
	s_barrier
	ds_read_b128 v[182:185], v180 offset:33792
	ds_read_b128 v[190:193], v180 offset:35840
	ds_read_b128 v[198:201], v180 offset:37888
	ds_read_b128 v[206:209], v180 offset:39936
	s_waitcnt lgkmcnt(4)
	v_mfma_f32_16x16x32_bf16 v[124:127], v[156:159], v[172:175], v[124:127]
	v_mfma_f32_16x16x32_bf16 v[120:123], v[164:167], v[172:175], v[120:123]
	v_mfma_f32_16x16x32_bf16 v[108:111], v[156:159], v[186:189], v[108:111]
	v_mfma_f32_16x16x32_bf16 v[104:107], v[164:167], v[186:189], v[104:107]
	v_mfma_f32_16x16x32_bf16 v[92:95], v[156:159], v[194:197], v[92:95]
	v_mfma_f32_16x16x32_bf16 v[88:91], v[164:167], v[194:197], v[88:91]
	v_mfma_f32_16x16x32_bf16 v[84:87], v[156:159], v[202:205], v[84:87]
	v_mfma_f32_16x16x32_bf16 v[80:83], v[164:167], v[202:205], v[80:83]
	s_waitcnt lgkmcnt(3)
	v_mfma_f32_16x16x32_bf16 v[124:127], v[160:163], v[182:185], v[124:127]
	v_mfma_f32_16x16x32_bf16 v[120:123], v[168:171], v[182:185], v[120:123]
	s_waitcnt lgkmcnt(2)
	v_mfma_f32_16x16x32_bf16 v[108:111], v[160:163], v[190:193], v[108:111]
	v_mfma_f32_16x16x32_bf16 v[104:107], v[168:171], v[190:193], v[104:107]
	s_waitcnt lgkmcnt(1)
	v_mfma_f32_16x16x32_bf16 v[92:95], v[160:163], v[198:201], v[92:95]
	v_mfma_f32_16x16x32_bf16 v[88:91], v[168:171], v[198:201], v[88:91]
	s_waitcnt lgkmcnt(0)
	s_setprio 2
	s_barrier
	v_mfma_f32_16x16x32_bf16 v[84:87], v[160:163], v[206:209], v[84:87]
	v_mfma_f32_16x16x32_bf16 v[80:83], v[168:171], v[206:209], v[80:83]
	s_setprio 0
	s_add_i32 s42, 0, 0x1c000
	s_add_i32 s43, s76, s44
	v_add_u32_e32 v224, s42, v177
	v_lshl_add_u64 v[228:229], v[228:229], 0, s[8:9]
	s_mov_b32 m0, s43
	ds_read_b128 v[210:213], v224
	ds_read_b128 v[214:217], v224 offset:1024
	ds_read_b128 v[218:221], v224 offset:2048
	ds_read_b128 v[224:227], v224 offset:3072
	global_load_lds_dwordx4 v[228:229], off
	s_add_i32 m0, s43, 0x2000
	v_lshl_add_u64 v[228:229], v[230:231], 0, s[8:9]
	global_load_lds_dwordx4 v[228:229], off
	s_setprio 1
	s_barrier
	s_waitcnt lgkmcnt(0)
	v_mfma_f32_16x16x32_bf16 v[116:119], v[210:213], v[172:175], v[116:119]
	v_mfma_f32_16x16x32_bf16 v[112:115], v[218:221], v[172:175], v[112:115]
	v_mfma_f32_16x16x32_bf16 v[100:103], v[210:213], v[186:189], v[100:103]
	v_mfma_f32_16x16x32_bf16 v[96:99], v[218:221], v[186:189], v[96:99]
	v_mfma_f32_16x16x32_bf16 v[76:79], v[210:213], v[194:197], v[76:79]
	v_mfma_f32_16x16x32_bf16 v[72:75], v[218:221], v[194:197], v[72:75]
	v_mfma_f32_16x16x32_bf16 v[68:71], v[210:213], v[202:205], v[68:71]
	v_mfma_f32_16x16x32_bf16 v[64:67], v[218:221], v[202:205], v[64:67]
	v_mfma_f32_16x16x32_bf16 v[116:119], v[214:217], v[182:185], v[116:119]
	v_mfma_f32_16x16x32_bf16 v[112:115], v[224:227], v[182:185], v[112:115]
	v_mfma_f32_16x16x32_bf16 v[100:103], v[214:217], v[190:193], v[100:103]
	v_mfma_f32_16x16x32_bf16 v[96:99], v[224:227], v[190:193], v[96:99]
	v_mfma_f32_16x16x32_bf16 v[76:79], v[214:217], v[198:201], v[76:79]
	v_mfma_f32_16x16x32_bf16 v[72:75], v[224:227], v[198:201], v[72:75]
	s_setprio 2
	s_barrier
	v_mfma_f32_16x16x32_bf16 v[68:71], v[214:217], v[206:209], v[68:71]
	v_mfma_f32_16x16x32_bf16 v[64:67], v[224:227], v[206:209], v[64:67]
	s_setprio 0
	s_mov_b32 m0, s59
	v_lshl_add_u64 v[228:229], v[232:233], 0, s[8:9]
	ds_read_b128 v[172:175], v180 offset:49152
	ds_read_b128 v[186:189], v180 offset:51200
	ds_read_b128 v[194:197], v180 offset:53248
	ds_read_b128 v[202:205], v180 offset:55296
	global_load_lds_dwordx4 v[228:229], off
	s_mov_b32 m0, s60
	v_lshl_add_u64 v[228:229], v[234:235], 0, s[8:9]
	global_load_lds_dwordx4 v[228:229], off
	s_setprio 1
	s_barrier
; #define PG8_STAGE(bufoff, gbase, voff) do { _Pragma("unroll") for (int _i = 0; _i < 2; ++_i) \
;         __builtin_amdgcn_global_load_lds((const unsigned*)((const char*)(gbase) + (voff)[_i]), (LAS unsigned*)(lds + (bufoff) + ldsw + _i * 8192), 16, 0, 0); } while (0)
; #define PG8_LDA(dst, b, h) do { _Pragma("unroll") for (int m = 0; m < 4; ++m) _Pragma("unroll") for (int k = 0; k < 2; ++k) dst[m][k] = *(const LAS bf16x8*)(lds + PG8_SA(b, h) + aoff + m * 2048 + k * 1024); } while (0)
; #define PG8_LDB(dst, b, h) do { _Pragma("unroll") for (int n = 0; n < 2; ++n) _Pragma("unroll") for (int k = 0; k < 2; ++k) dst[n][k] = *(const LAS bf16x8*)(lds + PG8_SB(b, h) + boff + n * 2048 + k * 1024); } while (0)
; #define PG8_WAIT_V(n) asm volatile("s_waitcnt vmcnt(" #n ")" ::: "memory")
; template <class Epi0, class Epi1>
; DI void gemm_phase_dual(LAS unsigned char* lds, const Gemm g, const Gemm g1, const StaticOrder S, const Epi0 E0, const Epi1 E1) {
;     ...
;             PG8_LDB(B1, 1, 1); PG8_STAGE(PG8_SB(1, 0), b3, voffB);
;             PG8_BAR; PG8_WAIT_L(0); PG8_MMA(0, 1, At, B1); PG8_BAR;
;             PG8_LDA(At, 1, 1); PG8_STAGE(PG8_SA(1, 0), a3, voffA);
;             PG8_BAR; PG8_WAIT_L(0); PG8_MMA(1, 0, At, B0); PG8_BAR; PG8_SCHED;
;             PG8_STAGE(PG8_SB(1, 1), b3 + hstep, voffB);
;             PG8_WAIT_V(6); PG8_BAR; PG8_MMA(1, 1, At, B1); PG8_BAR;
;         }
;         if (ui & 1) E1(acc, cur, wr, wc, fr, fq); else E0(acc, cur, wr, wc, fr, fq);
;     DI void operator()(AccRef acc, const Unit& u, int wr, int wc, int fr, int fq) const {
;         const int row0 = u.pm * 256 + wr * 64 + fr, col0 = u.pn * 256 + wc * 32 + 8 * fq;
; #pragma unroll
;         for (int ai = 0; ai < 2; ++ai)
; #pragma unroll
;             for (int mh = 0; mh < 2; ++mh) {
;                 u32x4 gv[2][2], mv[2][2];
; #pragma unroll
;                 for (int mm = 0; mm < 2; ++mm)
; #pragma unroll
;                     for (int bj = 0; bj < 2; ++bj) {
;                         const size_t row = (size_t)(row0 + ai * 128 + (mh * 2 + mm) * 16); const int col = col0 + bj * 128;
;                         gv[mm][bj] = *(const u32x4*)(gab + (size_t)(u.pm * 8 + SECOND * 4 + u.pn) * 65536 + (wr * 64 + fr + ai * 128 + (mh * 2 + mm) * 16) * 256 + wc * 32 + 8 * fq + bj * 128);
;                         if (SECOND) mv[mm][bj] = *(const u32x4*)(mrg + row * 1024 + col);
;                     }
	ds_read_b128 v[182:185], v180 offset:50176
	ds_read_b128 v[190:193], v180 offset:52224
	ds_read_b128 v[198:201], v180 offset:54272
	ds_read_b128 v[206:209], v180 offset:56320
	s_waitcnt lgkmcnt(4)
	v_mfma_f32_16x16x32_bf16 v[60:63], v[156:159], v[172:175], v[60:63]
	v_mfma_f32_16x16x32_bf16 v[56:59], v[164:167], v[172:175], v[56:59]
	v_mfma_f32_16x16x32_bf16 v[52:55], v[156:159], v[186:189], v[52:55]
	v_mfma_f32_16x16x32_bf16 v[48:51], v[164:167], v[186:189], v[48:51]
	v_mfma_f32_16x16x32_bf16 v[28:31], v[156:159], v[194:197], v[28:31]
	v_mfma_f32_16x16x32_bf16 v[24:27], v[164:167], v[194:197], v[24:27]
	v_mfma_f32_16x16x32_bf16 v[20:23], v[156:159], v[202:205], v[20:23]
	v_mfma_f32_16x16x32_bf16 v[16:19], v[164:167], v[202:205], v[16:19]
	s_waitcnt lgkmcnt(3)
	v_mfma_f32_16x16x32_bf16 v[60:63], v[160:163], v[182:185], v[60:63]
	v_mfma_f32_16x16x32_bf16 v[56:59], v[168:171], v[182:185], v[56:59]
	s_waitcnt lgkmcnt(2)
	v_mfma_f32_16x16x32_bf16 v[52:55], v[160:163], v[190:193], v[52:55]
	v_mfma_f32_16x16x32_bf16 v[48:51], v[168:171], v[190:193], v[48:51]
	s_waitcnt lgkmcnt(1)
	v_mfma_f32_16x16x32_bf16 v[28:31], v[160:163], v[198:201], v[28:31]
	v_mfma_f32_16x16x32_bf16 v[24:27], v[168:171], v[198:201], v[24:27]
	s_waitcnt lgkmcnt(0)
	s_setprio 2
	s_barrier
	v_mfma_f32_16x16x32_bf16 v[20:23], v[160:163], v[206:209], v[20:23]
	v_mfma_f32_16x16x32_bf16 v[16:19], v[168:171], v[206:209], v[16:19]
	s_setprio 0
	s_add_u32 s40, s40, 0x40080
	s_addc_u32 s41, s41, 0
	s_add_i32 s42, s42, s44
	s_mov_b32 m0, s42
	v_lshl_add_u64 v[156:157], s[40:41], 0, v[130:131]
	global_load_lds_dwordx4 v[156:157], off
	s_add_i32 m0, s42, 0x2000
	v_lshl_add_u64 v[156:157], s[40:41], 0, v[134:135]
	global_load_lds_dwordx4 v[156:157], off
	s_waitcnt vmcnt(6)
	s_setprio 1
	s_barrier
	v_mfma_f32_16x16x32_bf16 v[44:47], v[210:213], v[172:175], v[44:47]
	v_mfma_f32_16x16x32_bf16 v[40:43], v[218:221], v[172:175], v[40:43]
	v_mfma_f32_16x16x32_bf16 v[36:39], v[210:213], v[186:189], v[36:39]
	v_mfma_f32_16x16x32_bf16 v[32:35], v[218:221], v[186:189], v[32:35]
	v_mfma_f32_16x16x32_bf16 v[12:15], v[210:213], v[194:197], v[12:15]
	v_mfma_f32_16x16x32_bf16 v[8:11], v[218:221], v[194:197], v[8:11]
	v_mfma_f32_16x16x32_bf16 v[4:7], v[210:213], v[202:205], v[4:7]
	v_mfma_f32_16x16x32_bf16 v[0:3], v[218:221], v[202:205], v[0:3]
	v_mfma_f32_16x16x32_bf16 v[44:47], v[214:217], v[182:185], v[44:47]
	v_mfma_f32_16x16x32_bf16 v[40:43], v[224:227], v[182:185], v[40:43]
	v_mfma_f32_16x16x32_bf16 v[36:39], v[214:217], v[190:193], v[36:39]
	v_mfma_f32_16x16x32_bf16 v[32:35], v[224:227], v[190:193], v[32:35]
	v_mfma_f32_16x16x32_bf16 v[12:15], v[214:217], v[198:201], v[12:15]
	v_mfma_f32_16x16x32_bf16 v[8:11], v[224:227], v[198:201], v[8:11]
	s_setprio 2
	s_barrier
	v_mfma_f32_16x16x32_bf16 v[4:7], v[214:217], v[206:209], v[4:7]
	v_mfma_f32_16x16x32_bf16 v[0:3], v[224:227], v[206:209], v[0:3]
	s_setprio 0
	s_add_i32 s69, s69, 2
	s_add_u32 s38, s38, 0x100
	s_addc_u32 s39, s39, 0
	s_add_u32 s67, s67, 0x100
	s_addc_u32 s68, s68, 0
	s_cmp_gt_u32 s69, 13
	s_cbranch_scc0 .LBB0_708
	v_lshl_add_u32 v164, s24, 8, v176
	s_lshl_b32 s17, s66, 8
	v_or_b32_e32 v162, s17, v178
	v_or_b32_e32 v160, 16, v164
	s_mov_b64 s[6:7], -1
	s_and_b64 vcc, exec, s[28:29]
	v_ashrrev_i32_e32 v165, 31, v164
	v_ashrrev_i32_e32 v163, 31, v162
	v_ashrrev_i32_e32 v161, 31, v160
	v_or_b32_e32 v158, 32, v164
	v_or_b32_e32 v156, 48, v164
	s_cbranch_vccz .LBB0_711
	s_lshl_b32 s6, s24, 3
	s_add_i32 s6, s66, s6
	s_add_i32 s6, s6, 4
	v_lshlrev_b64 v[168:169], 11, v[160:161]
	s_ashr_i32 s7, s6, 31
	v_lshlrev_b64 v[166:167], 11, v[164:165]
	v_lshlrev_b64 v[170:171], 1, v[162:163]
	v_lshl_add_u64 v[168:169], s[36:37], 0, v[168:169]
	s_lshl_b64 s[6:7], s[6:7], 17
	v_lshl_add_u64 v[166:167], s[36:37], 0, v[166:167]
	v_lshl_add_u64 v[174:175], v[168:169], 0, v[170:171]
	v_lshl_add_u64 v[168:169], v[136:137], 0, s[6:7]
	v_lshl_add_u64 v[166:167], v[166:167], 0, v[170:171]
	v_lshl_add_u64 v[172:173], v[138:139], 1, v[168:169]
	global_load_dwordx4 v[182:185], v[166:167], off
	global_load_dwordx4 v[186:189], v[166:167], off offset:256
	global_load_dwordx4 v[190:193], v[174:175], off
	global_load_dwordx4 v[194:197], v[172:173], off
	global_load_dwordx4 v[198:201], v[172:173], off offset:256
	v_add_co_u32_e32 v206, vcc, s48, v172
	v_ashrrev_i32_e32 v159, 31, v158
	s_nop 0
	v_addc_co_u32_e32 v207, vcc, 0, v173, vcc
	global_load_dwordx4 v[202:205], v[206:207], off
	s_nop 0
	global_load_dwordx4 v[206:209], v[206:207], off offset:256
	s_nop 0
	global_load_dwordx4 v[210:213], v[174:175], off offset:256
	v_ashrrev_i32_e32 v157, 31, v156
	s_mov_b64 s[6:7], 0
	s_waitcnt vmcnt(0)
; DI unsigned pk_bf16(float lo, float hi) { f32x2 v = {lo, hi}; return __builtin_bit_cast(unsigned, __builtin_convertvector(v, bf16v2)); }
; DI float bf_lo(unsigned w) { return __uint_as_float(w << 16); }
; DI float bf_hi(unsigned w) { return __uint_as_float(w & 0xffff0000u); }
;     DI void operator()(AccRef acc, const Unit& u, int wr, int wc, int fr, int fq) const {
;     ...
;                 for (int mm = 0; mm < 2; ++mm)
; #pragma unroll
;                     for (int bj = 0; bj < 2; ++bj) {
;                         const size_t row = (size_t)(row0 + ai * 128 + (mh * 2 + mm) * 16); const int col = col0 + bj * 128;
;                         gv[mm][bj] = *(const u32x4*)(gab + (size_t)(u.pm * 8 + SECOND * 4 + u.pn) * 65536 + (wr * 64 + fr + ai * 128 + (mh * 2 + mm) * 16) * 256 + wc * 32 + 8 * fq + bj * 128);
;                         if (SECOND) mv[mm][bj] = *(const u32x4*)(mrg + row * 1024 + col);
;                     }
; #pragma unroll
;                 for (int mm = 0; mm < 2; ++mm)
; #pragma unroll
;                     for (int bj = 0; bj < 2; ++bj) {
;                         const int m = mh * 2 + mm;
;                         const size_t row = (size_t)(row0 + ai * 128 + m * 16); const int col = col0 + bj * 128;
;                         const u32x4 gt = gv[mm][bj];
;                         const f32x4 r0 = acc[ai][bj][m][0], r1 = acc[ai][bj][m][1];
;                         float v[8] = {bf_lo(gt.x) * r0[0], bf_hi(gt.x) * r0[1], bf_lo(gt.y) * r0[2], bf_hi(gt.y) * r0[3], bf_lo(gt.z) * r1[0], bf_hi(gt.z) * r1[1], bf_lo(gt.w) * r1[2], bf_hi(gt.w) * r1[3]};
;                         if (SECOND) { const u32x4 o = mv[mm][bj]; v[0] += bf_lo(o.x); v[1] += bf_hi(o.x); v[2] += bf_lo(o.y); v[3] += bf_hi(o.y); v[4] += bf_lo(o.z); v[5] += bf_hi(o.z); v[6] += bf_lo(o.w); v[7] += bf_hi(o.w); }
;                         u32x4 w; w.x = pk_bf16(v[0], v[1]); w.y = pk_bf16(v[2], v[3]); w.z = pk_bf16(v[4], v[5]); w.w = pk_bf16(v[6], v[7]);
;                         *(u32x4*)(mrg + row * 1024 + col) = w;
	v_lshlrev_b32_e32 v214, 16, v182
	v_and_b32_e32 v215, 0xffff0000, v182
	v_lshlrev_b32_e32 v182, 16, v183
	v_and_b32_e32 v183, 0xffff0000, v183
	v_lshlrev_b32_e32 v216, 16, v184
	v_and_b32_e32 v217, 0xffff0000, v184
	v_lshlrev_b32_e32 v184, 16, v185
	v_and_b32_e32 v185, 0xffff0000, v185
	v_lshlrev_b32_e32 v228, 16, v194
	v_and_b32_e32 v229, 0xffff0000, v194
	v_lshlrev_b32_e32 v194, 16, v195
	v_and_b32_e32 v195, 0xffff0000, v195
	v_lshlrev_b32_e32 v230, 16, v196
	v_and_b32_e32 v231, 0xffff0000, v196
	v_lshlrev_b32_e32 v196, 16, v197
	v_and_b32_e32 v197, 0xffff0000, v197
	v_lshlrev_b32_e32 v218, 16, v186
	v_and_b32_e32 v219, 0xffff0000, v186
	v_lshlrev_b32_e32 v186, 16, v187
	v_and_b32_e32 v187, 0xffff0000, v187
	v_lshlrev_b32_e32 v220, 16, v188
	v_and_b32_e32 v221, 0xffff0000, v188
	v_lshlrev_b32_e32 v188, 16, v189
	v_and_b32_e32 v189, 0xffff0000, v189
	v_lshlrev_b32_e32 v232, 16, v198
	v_and_b32_e32 v233, 0xffff0000, v198
	v_lshlrev_b32_e32 v198, 16, v199
	v_and_b32_e32 v199, 0xffff0000, v199
	v_lshlrev_b32_e32 v234, 16, v200
	v_and_b32_e32 v235, 0xffff0000, v200
	v_lshlrev_b32_e32 v200, 16, v201
	v_and_b32_e32 v201, 0xffff0000, v201
	v_pk_fma_f32 v[214:215], v[124:125], v[228:229], v[214:215]
	v_pk_fma_f32 v[194:195], v[126:127], v[194:195], v[182:183]
	v_pk_fma_f32 v[216:217], v[120:121], v[230:231], v[216:217]
	v_pk_fma_f32 v[196:197], v[122:123], v[196:197], v[184:185]
	v_pk_fma_f32 v[218:219], v[116:117], v[232:233], v[218:219]
	v_pk_fma_f32 v[198:199], v[118:119], v[198:199], v[186:187]
	v_pk_fma_f32 v[220:221], v[112:113], v[234:235], v[220:221]
	v_pk_fma_f32 v[200:201], v[114:115], v[200:201], v[188:189]
	v_cvt_pk_bf16_f32 v182, v214, v215
	v_cvt_pk_bf16_f32 v183, v194, v195
	v_cvt_pk_bf16_f32 v184, v216, v217
	v_cvt_pk_bf16_f32 v185, v196, v197
	v_lshlrev_b32_e32 v224, 16, v190
	v_and_b32_e32 v225, 0xffff0000, v190
	v_lshlrev_b32_e32 v190, 16, v191
	v_and_b32_e32 v191, 0xffff0000, v191
	v_lshlrev_b32_e32 v226, 16, v192
	v_and_b32_e32 v227, 0xffff0000, v192
	v_lshlrev_b32_e32 v228, 16, v202
	v_and_b32_e32 v229, 0xffff0000, v202
	v_lshlrev_b32_e32 v202, 16, v203
	v_and_b32_e32 v203, 0xffff0000, v203
	v_lshlrev_b32_e32 v230, 16, v204
	v_and_b32_e32 v231, 0xffff0000, v204
	v_cvt_pk_bf16_f32 v186, v218, v219
	v_cvt_pk_bf16_f32 v187, v198, v199
	v_cvt_pk_bf16_f32 v188, v220, v221
	v_cvt_pk_bf16_f32 v189, v200, v201
	global_store_dwordx4 v[166:167], v[182:185], off
	global_store_dwordx4 v[166:167], v[186:189], off offset:256
	v_pk_fma_f32 v[194:195], v[108:109], v[228:229], v[224:225]
	v_lshlrev_b32_e32 v182, 16, v205
	v_and_b32_e32 v183, 0xffff0000, v205
	v_lshlrev_b32_e32 v184, 16, v193
	v_and_b32_e32 v185, 0xffff0000, v193
	v_pk_fma_f32 v[190:191], v[110:111], v[202:203], v[190:191]
	v_pk_fma_f32 v[196:197], v[104:105], v[230:231], v[226:227]
	v_pk_fma_f32 v[186:187], v[106:107], v[182:183], v[184:185]
	v_cvt_pk_bf16_f32 v182, v194, v195
	v_cvt_pk_bf16_f32 v183, v190, v191
	v_cvt_pk_bf16_f32 v184, v196, v197
	v_cvt_pk_bf16_f32 v185, v186, v187
	global_store_dwordx4 v[174:175], v[182:185], off
	v_lshlrev_b32_e32 v186, 16, v211
	v_and_b32_e32 v187, 0xffff0000, v211
	v_lshlrev_b32_e32 v182, 16, v206
	v_and_b32_e32 v183, 0xffff0000, v206
	v_lshlrev_b32_e32 v184, 16, v210
	v_and_b32_e32 v185, 0xffff0000, v210
	v_pk_fma_f32 v[182:183], v[100:101], v[182:183], v[184:185]
	v_lshlrev_b32_e32 v184, 16, v207
	v_and_b32_e32 v185, 0xffff0000, v207
	v_pk_fma_f32 v[184:185], v[102:103], v[184:185], v[186:187]
	v_lshlrev_b32_e32 v186, 16, v208
	v_and_b32_e32 v187, 0xffff0000, v208
	v_lshlrev_b32_e32 v188, 16, v212
	v_and_b32_e32 v189, 0xffff0000, v212
	v_pk_fma_f32 v[190:191], v[96:97], v[186:187], v[188:189]
	v_lshlrev_b32_e32 v186, 16, v209
	v_and_b32_e32 v187, 0xffff0000, v209
	v_lshlrev_b32_e32 v188, 16, v213
	v_and_b32_e32 v189, 0xffff0000, v213
	v_cvt_pk_bf16_f32 v182, v182, v183
	v_cvt_pk_bf16_f32 v183, v184, v185
	v_lshlrev_b64 v[184:185], 11, v[158:159]
	v_pk_fma_f32 v[192:193], v[98:99], v[186:187], v[188:189]
	v_lshl_add_u64 v[184:185], s[36:37], 0, v[184:185]
	v_lshl_add_u64 v[210:211], v[184:185], 0, v[170:171]
	v_cvt_pk_bf16_f32 v184, v190, v191
	v_cvt_pk_bf16_f32 v185, v192, v193
	global_load_dwordx4 v[186:189], v[210:211], off
	s_waitcnt vmcnt(0)
	v_lshlrev_b32_e32 v214, 16, v188
	global_store_dwordx4 v[174:175], v[182:185], off offset:256
	v_add_co_u32_e32 v174, vcc, s49, v172
	v_and_b32_e32 v215, 0xffff0000, v188
	s_nop 0
	v_addc_co_u32_e32 v175, vcc, 0, v173, vcc
	global_load_dwordx4 v[182:185], v[174:175], off
	global_load_dwordx4 v[190:193], v[174:175], off offset:256
	global_load_dwordx4 v[194:197], v[210:211], off offset:256
	v_add_co_u32_e32 v202, vcc, s50, v172
	v_lshlrev_b64 v[174:175], 11, v[156:157]
	s_nop 0
	v_addc_co_u32_e32 v203, vcc, 0, v173, vcc
	v_lshl_add_u64 v[198:199], s[36:37], 0, v[174:175]
	global_load_dwordx4 v[172:175], v[202:203], off
	v_lshl_add_u64 v[212:213], v[198:199], 0, v[170:171]
	global_load_dwordx4 v[198:201], v[212:213], off
	s_nop 0
	global_load_dwordx4 v[202:205], v[202:203], off offset:256
	s_nop 0
	global_load_dwordx4 v[206:209], v[212:213], off offset:256
	v_lshlrev_b32_e32 v170, 16, v186
	v_and_b32_e32 v171, 0xffff0000, v186
	v_lshlrev_b32_e32 v186, 16, v187
	v_and_b32_e32 v187, 0xffff0000, v187
	v_lshlrev_b32_e32 v188, 16, v189
	v_and_b32_e32 v189, 0xffff0000, v189
	s_waitcnt vmcnt(0)
; DI unsigned pk_bf16(float lo, float hi) { f32x2 v = {lo, hi}; return __builtin_bit_cast(unsigned, __builtin_convertvector(v, bf16v2)); }
; DI float bf_lo(unsigned w) { return __uint_as_float(w << 16); }
; DI float bf_hi(unsigned w) { return __uint_as_float(w & 0xffff0000u); }
;     DI void operator()(AccRef acc, const Unit& u, int wr, int wc, int fr, int fq) const {
;     ...
;                 for (int mm = 0; mm < 2; ++mm)
; #pragma unroll
;                     for (int bj = 0; bj < 2; ++bj) {
;                         const size_t row = (size_t)(row0 + ai * 128 + (mh * 2 + mm) * 16); const int col = col0 + bj * 128;
;                         gv[mm][bj] = *(const u32x4*)(gab + (size_t)(u.pm * 8 + SECOND * 4 + u.pn) * 65536 + (wr * 64 + fr + ai * 128 + (mh * 2 + mm) * 16) * 256 + wc * 32 + 8 * fq + bj * 128);
;                         if (SECOND) mv[mm][bj] = *(const u32x4*)(mrg + row * 1024 + col);
;                     }
; #pragma unroll
;                 for (int mm = 0; mm < 2; ++mm)
; #pragma unroll
;                     for (int bj = 0; bj < 2; ++bj) {
;                         const int m = mh * 2 + mm;
;                         const size_t row = (size_t)(row0 + ai * 128 + m * 16); const int col = col0 + bj * 128;
;                         const u32x4 gt = gv[mm][bj];
;                         const f32x4 r0 = acc[ai][bj][m][0], r1 = acc[ai][bj][m][1];
;                         float v[8] = {bf_lo(gt.x) * r0[0], bf_hi(gt.x) * r0[1], bf_lo(gt.y) * r0[2], bf_hi(gt.y) * r0[3], bf_lo(gt.z) * r1[0], bf_hi(gt.z) * r1[1], bf_lo(gt.w) * r1[2], bf_hi(gt.w) * r1[3]};
;                         if (SECOND) { const u32x4 o = mv[mm][bj]; v[0] += bf_lo(o.x); v[1] += bf_hi(o.x); v[2] += bf_lo(o.y); v[3] += bf_hi(o.y); v[4] += bf_lo(o.z); v[5] += bf_hi(o.z); v[6] += bf_lo(o.w); v[7] += bf_hi(o.w); }
;                         u32x4 w; w.x = pk_bf16(v[0], v[1]); w.y = pk_bf16(v[2], v[3]); w.z = pk_bf16(v[4], v[5]); w.w = pk_bf16(v[6], v[7]);
;                         *(u32x4*)(mrg + row * 1024 + col) = w;
	v_lshlrev_b32_e32 v216, 16, v182
	v_and_b32_e32 v217, 0xffff0000, v182
	v_lshlrev_b32_e32 v182, 16, v183
	v_and_b32_e32 v183, 0xffff0000, v183
	v_lshlrev_b32_e32 v218, 16, v184
	v_and_b32_e32 v219, 0xffff0000, v184
	v_lshlrev_b32_e32 v184, 16, v185
	v_and_b32_e32 v185, 0xffff0000, v185
	v_pk_fma_f32 v[170:171], v[92:93], v[216:217], v[170:171]
	v_pk_fma_f32 v[186:187], v[94:95], v[182:183], v[186:187]
	v_pk_fma_f32 v[214:215], v[88:89], v[218:219], v[214:215]
	v_pk_fma_f32 v[188:189], v[90:91], v[184:185], v[188:189]
	v_cvt_pk_bf16_f32 v182, v170, v171
	v_cvt_pk_bf16_f32 v183, v186, v187
	v_cvt_pk_bf16_f32 v184, v214, v215
	v_cvt_pk_bf16_f32 v185, v188, v189
	global_store_dwordx4 v[210:211], v[182:185], off
	v_lshlrev_b32_e32 v186, 16, v196
	v_and_b32_e32 v187, 0xffff0000, v196
	v_lshlrev_b32_e32 v182, 16, v191
	v_and_b32_e32 v183, 0xffff0000, v191
	v_lshlrev_b32_e32 v184, 16, v195
	v_and_b32_e32 v185, 0xffff0000, v195
	v_pk_fma_f32 v[184:185], v[78:79], v[182:183], v[184:185]
	v_lshlrev_b32_e32 v182, 16, v192
	v_and_b32_e32 v183, 0xffff0000, v192
	v_lshlrev_b32_e32 v220, 16, v190
	v_and_b32_e32 v221, 0xffff0000, v190
	v_lshlrev_b32_e32 v170, 16, v194
	v_and_b32_e32 v171, 0xffff0000, v194
	v_pk_fma_f32 v[186:187], v[72:73], v[182:183], v[186:187]
	v_lshlrev_b32_e32 v182, 16, v193
	v_and_b32_e32 v183, 0xffff0000, v193
	v_lshlrev_b32_e32 v188, 16, v197
	v_and_b32_e32 v189, 0xffff0000, v197
	v_pk_fma_f32 v[170:171], v[76:77], v[220:221], v[170:171]
	v_pk_fma_f32 v[188:189], v[74:75], v[182:183], v[188:189]
	v_cvt_pk_bf16_f32 v182, v170, v171
	v_cvt_pk_bf16_f32 v183, v184, v185
	v_cvt_pk_bf16_f32 v184, v186, v187
	v_cvt_pk_bf16_f32 v185, v188, v189
	global_store_dwordx4 v[210:211], v[182:185], off offset:256
	v_lshlrev_b32_e32 v170, 16, v172
	v_and_b32_e32 v171, 0xffff0000, v172
	v_lshlrev_b32_e32 v182, 16, v198
	v_and_b32_e32 v183, 0xffff0000, v198
	v_pk_fma_f32 v[170:171], v[84:85], v[170:171], v[182:183]
	v_lshlrev_b32_e32 v172, 16, v173
	v_and_b32_e32 v173, 0xffff0000, v173
	v_lshlrev_b32_e32 v182, 16, v199
	v_and_b32_e32 v183, 0xffff0000, v199
	v_pk_fma_f32 v[172:173], v[86:87], v[172:173], v[182:183]
	v_lshlrev_b32_e32 v182, 16, v174
	v_and_b32_e32 v183, 0xffff0000, v174
	v_lshlrev_b32_e32 v184, 16, v200
	v_and_b32_e32 v185, 0xffff0000, v200
	v_pk_fma_f32 v[182:183], v[80:81], v[182:183], v[184:185]
	v_lshlrev_b32_e32 v174, 16, v175
	v_and_b32_e32 v175, 0xffff0000, v175
	v_lshlrev_b32_e32 v184, 16, v201
	v_and_b32_e32 v185, 0xffff0000, v201
	v_pk_fma_f32 v[174:175], v[82:83], v[174:175], v[184:185]
	v_cvt_pk_bf16_f32 v170, v170, v171
	v_cvt_pk_bf16_f32 v171, v172, v173
	v_cvt_pk_bf16_f32 v172, v182, v183
	v_cvt_pk_bf16_f32 v173, v174, v175
	global_store_dwordx4 v[212:213], v[170:173], off
	v_lshlrev_b32_e32 v174, 16, v207
	v_and_b32_e32 v175, 0xffff0000, v207
	v_lshlrev_b32_e32 v170, 16, v202
	v_and_b32_e32 v171, 0xffff0000, v202
	v_lshlrev_b32_e32 v172, 16, v206
	v_and_b32_e32 v173, 0xffff0000, v206
	v_pk_fma_f32 v[170:171], v[68:69], v[170:171], v[172:173]
	v_lshlrev_b32_e32 v172, 16, v203
	v_and_b32_e32 v173, 0xffff0000, v203
	v_pk_fma_f32 v[172:173], v[70:71], v[172:173], v[174:175]
	v_lshlrev_b32_e32 v174, 16, v204
	v_and_b32_e32 v175, 0xffff0000, v204
	v_lshlrev_b32_e32 v182, 16, v208
	v_and_b32_e32 v183, 0xffff0000, v208
	v_pk_fma_f32 v[174:175], v[64:65], v[174:175], v[182:183]
	v_lshlrev_b32_e32 v182, 16, v205
	v_and_b32_e32 v183, 0xffff0000, v205
	v_lshlrev_b32_e32 v184, 16, v209
	v_and_b32_e32 v185, 0xffff0000, v209
	v_pk_fma_f32 v[182:183], v[66:67], v[182:183], v[184:185]
	v_cvt_pk_bf16_f32 v170, v170, v171
	v_cvt_pk_bf16_f32 v171, v172, v173
	v_cvt_pk_bf16_f32 v172, v174, v175
	v_cvt_pk_bf16_f32 v173, v182, v183
	global_store_dwordx4 v[212:213], v[170:173], off offset:256
	v_lshl_add_u64 v[174:175], v[140:141], 1, v[168:169]
	v_add_co_u32_e32 v210, vcc, s61, v166
	global_load_dwordx4 v[170:173], v[174:175], off
	s_nop 0
	v_addc_co_u32_e32 v211, vcc, 0, v167, vcc
	global_load_dwordx4 v[182:185], v[210:211], off
	global_load_dwordx4 v[186:189], v[174:175], off offset:256
	v_lshl_add_u64 v[174:175], v[166:167], 0, s[0:1]
	global_load_dwordx4 v[190:193], v[174:175], off offset:256
	v_lshl_add_u64 v[202:203], v[142:143], 1, v[168:169]
	v_add_co_u32_e32 v212, vcc, s62, v166
	global_load_dwordx4 v[194:197], v[202:203], off
	s_nop 0
	v_addc_co_u32_e32 v213, vcc, 0, v167, vcc
	global_load_dwordx4 v[198:201], v[212:213], off
	s_nop 0
	global_load_dwordx4 v[202:205], v[202:203], off offset:256
	v_lshl_add_u64 v[214:215], v[166:167], 0, s[10:11]
	global_load_dwordx4 v[206:209], v[214:215], off offset:256
	s_waitcnt vmcnt(0)
; DI unsigned pk_bf16(float lo, float hi) { f32x2 v = {lo, hi}; return __builtin_bit_cast(unsigned, __builtin_convertvector(v, bf16v2)); }
; DI float bf_lo(unsigned w) { return __uint_as_float(w << 16); }
; DI float bf_hi(unsigned w) { return __uint_as_float(w & 0xffff0000u); }
;     DI void operator()(AccRef acc, const Unit& u, int wr, int wc, int fr, int fq) const {
;     ...
;                 for (int mm = 0; mm < 2; ++mm)
; #pragma unroll
;                     for (int bj = 0; bj < 2; ++bj) {
;                         const size_t row = (size_t)(row0 + ai * 128 + (mh * 2 + mm) * 16); const int col = col0 + bj * 128;
;                         gv[mm][bj] = *(const u32x4*)(gab + (size_t)(u.pm * 8 + SECOND * 4 + u.pn) * 65536 + (wr * 64 + fr + ai * 128 + (mh * 2 + mm) * 16) * 256 + wc * 32 + 8 * fq + bj * 128);
;                         if (SECOND) mv[mm][bj] = *(const u32x4*)(mrg + row * 1024 + col);
;                     }
; #pragma unroll
;                 for (int mm = 0; mm < 2; ++mm)
; #pragma unroll
;                     for (int bj = 0; bj < 2; ++bj) {
;                         const int m = mh * 2 + mm;
;                         const size_t row = (size_t)(row0 + ai * 128 + m * 16); const int col = col0 + bj * 128;
;                         const u32x4 gt = gv[mm][bj];
;                         const f32x4 r0 = acc[ai][bj][m][0], r1 = acc[ai][bj][m][1];
;                         float v[8] = {bf_lo(gt.x) * r0[0], bf_hi(gt.x) * r0[1], bf_lo(gt.y) * r0[2], bf_hi(gt.y) * r0[3], bf_lo(gt.z) * r1[0], bf_hi(gt.z) * r1[1], bf_lo(gt.w) * r1[2], bf_hi(gt.w) * r1[3]};
;                         if (SECOND) { const u32x4 o = mv[mm][bj]; v[0] += bf_lo(o.x); v[1] += bf_hi(o.x); v[2] += bf_lo(o.y); v[3] += bf_hi(o.y); v[4] += bf_lo(o.z); v[5] += bf_hi(o.z); v[6] += bf_lo(o.w); v[7] += bf_hi(o.w); }
;                         u32x4 w; w.x = pk_bf16(v[0], v[1]); w.y = pk_bf16(v[2], v[3]); w.z = pk_bf16(v[4], v[5]); w.w = pk_bf16(v[6], v[7]);
;                         *(u32x4*)(mrg + row * 1024 + col) = w;
	v_lshlrev_b32_e32 v216, 16, v170
	v_and_b32_e32 v217, 0xffff0000, v170
	v_lshlrev_b32_e32 v218, 16, v182
	v_and_b32_e32 v219, 0xffff0000, v182
	v_lshlrev_b32_e32 v170, 16, v171
	v_and_b32_e32 v171, 0xffff0000, v171
	v_lshlrev_b32_e32 v182, 16, v183
	v_and_b32_e32 v183, 0xffff0000, v183
	v_pk_fma_f32 v[216:217], v[60:61], v[216:217], v[218:219]
	v_pk_fma_f32 v[182:183], v[62:63], v[170:171], v[182:183]
	v_lshlrev_b32_e32 v170, 16, v172
	v_and_b32_e32 v171, 0xffff0000, v172
	v_lshlrev_b32_e32 v218, 16, v184
	v_and_b32_e32 v219, 0xffff0000, v184
	v_pk_fma_f32 v[218:219], v[56:57], v[170:171], v[218:219]
	v_lshlrev_b32_e32 v170, 16, v173
	v_and_b32_e32 v171, 0xffff0000, v173
	v_lshlrev_b32_e32 v172, 16, v185
	v_and_b32_e32 v173, 0xffff0000, v185
	v_pk_fma_f32 v[184:185], v[58:59], v[170:171], v[172:173]
	v_cvt_pk_bf16_f32 v170, v216, v217
	v_cvt_pk_bf16_f32 v171, v182, v183
	v_cvt_pk_bf16_f32 v172, v218, v219
	v_cvt_pk_bf16_f32 v173, v184, v185
	global_store_dwordx4 v[210:211], v[170:173], off
	v_lshlrev_b32_e32 v182, 16, v191
	v_and_b32_e32 v183, 0xffff0000, v191
	v_lshlrev_b32_e32 v170, 16, v186
	v_and_b32_e32 v171, 0xffff0000, v186
	v_lshlrev_b32_e32 v172, 16, v190
	v_and_b32_e32 v173, 0xffff0000, v190
	v_pk_fma_f32 v[170:171], v[44:45], v[170:171], v[172:173]
	v_lshlrev_b32_e32 v172, 16, v187
	v_and_b32_e32 v173, 0xffff0000, v187
	v_pk_fma_f32 v[172:173], v[46:47], v[172:173], v[182:183]
	v_lshlrev_b32_e32 v182, 16, v188
	v_and_b32_e32 v183, 0xffff0000, v188
	v_lshlrev_b32_e32 v184, 16, v192
	v_and_b32_e32 v185, 0xffff0000, v192
	v_pk_fma_f32 v[182:183], v[40:41], v[182:183], v[184:185]
	v_lshlrev_b32_e32 v184, 16, v189
	v_and_b32_e32 v185, 0xffff0000, v189
	v_lshlrev_b32_e32 v186, 16, v193
	v_and_b32_e32 v187, 0xffff0000, v193
	v_pk_fma_f32 v[184:185], v[42:43], v[184:185], v[186:187]
	v_cvt_pk_bf16_f32 v170, v170, v171
	v_cvt_pk_bf16_f32 v171, v172, v173
	v_cvt_pk_bf16_f32 v172, v182, v183
	v_cvt_pk_bf16_f32 v173, v184, v185
	global_store_dwordx4 v[174:175], v[170:173], off offset:256
	v_lshlrev_b32_e32 v174, 16, v199
	v_and_b32_e32 v175, 0xffff0000, v199
	v_lshlrev_b32_e32 v170, 16, v194
	v_and_b32_e32 v171, 0xffff0000, v194
	v_lshlrev_b32_e32 v172, 16, v198
	v_and_b32_e32 v173, 0xffff0000, v198
	v_pk_fma_f32 v[170:171], v[52:53], v[170:171], v[172:173]
	v_lshlrev_b32_e32 v172, 16, v195
	v_and_b32_e32 v173, 0xffff0000, v195
	v_pk_fma_f32 v[172:173], v[54:55], v[172:173], v[174:175]
	v_lshlrev_b32_e32 v174, 16, v196
	v_and_b32_e32 v175, 0xffff0000, v196
	v_lshlrev_b32_e32 v182, 16, v200
	v_and_b32_e32 v183, 0xffff0000, v200
	v_pk_fma_f32 v[174:175], v[48:49], v[174:175], v[182:183]
	v_lshlrev_b32_e32 v182, 16, v197
	v_and_b32_e32 v183, 0xffff0000, v197
	v_lshlrev_b32_e32 v184, 16, v201
	v_and_b32_e32 v185, 0xffff0000, v201
	v_pk_fma_f32 v[182:183], v[50:51], v[182:183], v[184:185]
	v_cvt_pk_bf16_f32 v170, v170, v171
	v_cvt_pk_bf16_f32 v171, v172, v173
	v_cvt_pk_bf16_f32 v172, v174, v175
	v_cvt_pk_bf16_f32 v173, v182, v183
	global_store_dwordx4 v[212:213], v[170:173], off
	v_lshlrev_b32_e32 v174, 16, v207
	v_and_b32_e32 v175, 0xffff0000, v207
	v_lshlrev_b32_e32 v170, 16, v202
	v_and_b32_e32 v171, 0xffff0000, v202
	v_lshlrev_b32_e32 v172, 16, v206
	v_and_b32_e32 v173, 0xffff0000, v206
	v_pk_fma_f32 v[170:171], v[36:37], v[170:171], v[172:173]
	v_lshlrev_b32_e32 v172, 16, v203
	v_and_b32_e32 v173, 0xffff0000, v203
	v_pk_fma_f32 v[172:173], v[38:39], v[172:173], v[174:175]
	v_lshlrev_b32_e32 v174, 16, v204
	v_and_b32_e32 v175, 0xffff0000, v204
	v_lshlrev_b32_e32 v182, 16, v208
	v_and_b32_e32 v183, 0xffff0000, v208
	v_pk_fma_f32 v[174:175], v[32:33], v[174:175], v[182:183]
	v_lshlrev_b32_e32 v182, 16, v205
	v_and_b32_e32 v183, 0xffff0000, v205
	v_lshlrev_b32_e32 v184, 16, v209
	v_and_b32_e32 v185, 0xffff0000, v209
	v_pk_fma_f32 v[182:183], v[34:35], v[182:183], v[184:185]
	v_cvt_pk_bf16_f32 v170, v170, v171
	v_cvt_pk_bf16_f32 v171, v172, v173
	v_cvt_pk_bf16_f32 v172, v174, v175
	v_cvt_pk_bf16_f32 v173, v182, v183
	global_store_dwordx4 v[214:215], v[170:173], off offset:256
	v_lshl_add_u64 v[174:175], v[144:145], 1, v[168:169]
	v_add_co_u32_e32 v206, vcc, s63, v166
	global_load_dwordx4 v[170:173], v[174:175], off
	s_nop 0
	v_addc_co_u32_e32 v207, vcc, 0, v167, vcc
	global_load_dwordx4 v[182:185], v[206:207], off
	global_load_dwordx4 v[186:189], v[174:175], off offset:256
	v_lshl_add_u64 v[174:175], v[166:167], 0, s[12:13]
	global_load_dwordx4 v[190:193], v[174:175], off offset:256
	v_lshl_add_u64 v[168:169], v[146:147], 1, v[168:169]
	v_add_co_u32_e32 v208, vcc, s64, v166
	global_load_dwordx4 v[194:197], v[168:169], off
	s_nop 0
	v_addc_co_u32_e32 v209, vcc, 0, v167, vcc
	global_load_dwordx4 v[198:201], v[208:209], off
	global_load_dwordx4 v[202:205], v[168:169], off offset:256
	v_lshl_add_u64 v[210:211], v[166:167], 0, s[14:15]
	global_load_dwordx4 v[166:169], v[210:211], off offset:256
	s_waitcnt vmcnt(0)
; DI unsigned pk_bf16(float lo, float hi) { f32x2 v = {lo, hi}; return __builtin_bit_cast(unsigned, __builtin_convertvector(v, bf16v2)); }
; DI float bf_lo(unsigned w) { return __uint_as_float(w << 16); }
; DI float bf_hi(unsigned w) { return __uint_as_float(w & 0xffff0000u); }
;     DI void operator()(AccRef acc, const Unit& u, int wr, int wc, int fr, int fq) const {
;     ...
;                 for (int mm = 0; mm < 2; ++mm)
; #pragma unroll
;                     for (int bj = 0; bj < 2; ++bj) {
;                         const size_t row = (size_t)(row0 + ai * 128 + (mh * 2 + mm) * 16); const int col = col0 + bj * 128;
;                         gv[mm][bj] = *(const u32x4*)(gab + (size_t)(u.pm * 8 + SECOND * 4 + u.pn) * 65536 + (wr * 64 + fr + ai * 128 + (mh * 2 + mm) * 16) * 256 + wc * 32 + 8 * fq + bj * 128);
;                         if (SECOND) mv[mm][bj] = *(const u32x4*)(mrg + row * 1024 + col);
;                     }
; #pragma unroll
;                 for (int mm = 0; mm < 2; ++mm)
; #pragma unroll
;                     for (int bj = 0; bj < 2; ++bj) {
;                         const int m = mh * 2 + mm;
;                         const size_t row = (size_t)(row0 + ai * 128 + m * 16); const int col = col0 + bj * 128;
;                         const u32x4 gt = gv[mm][bj];
;                         const f32x4 r0 = acc[ai][bj][m][0], r1 = acc[ai][bj][m][1];
;                         float v[8] = {bf_lo(gt.x) * r0[0], bf_hi(gt.x) * r0[1], bf_lo(gt.y) * r0[2], bf_hi(gt.y) * r0[3], bf_lo(gt.z) * r1[0], bf_hi(gt.z) * r1[1], bf_lo(gt.w) * r1[2], bf_hi(gt.w) * r1[3]};
;                         if (SECOND) { const u32x4 o = mv[mm][bj]; v[0] += bf_lo(o.x); v[1] += bf_hi(o.x); v[2] += bf_lo(o.y); v[3] += bf_hi(o.y); v[4] += bf_lo(o.z); v[5] += bf_hi(o.z); v[6] += bf_lo(o.w); v[7] += bf_hi(o.w); }
;                         u32x4 w; w.x = pk_bf16(v[0], v[1]); w.y = pk_bf16(v[2], v[3]); w.z = pk_bf16(v[4], v[5]); w.w = pk_bf16(v[6], v[7]);
;                         *(u32x4*)(mrg + row * 1024 + col) = w;
	v_lshlrev_b32_e32 v212, 16, v170
	v_and_b32_e32 v213, 0xffff0000, v170
	v_lshlrev_b32_e32 v214, 16, v182
	v_and_b32_e32 v215, 0xffff0000, v182
	v_lshlrev_b32_e32 v170, 16, v171
	v_and_b32_e32 v171, 0xffff0000, v171
	v_lshlrev_b32_e32 v182, 16, v183
	v_and_b32_e32 v183, 0xffff0000, v183
	v_pk_fma_f32 v[212:213], v[28:29], v[212:213], v[214:215]
	v_pk_fma_f32 v[182:183], v[30:31], v[170:171], v[182:183]
	v_lshlrev_b32_e32 v170, 16, v172
	v_and_b32_e32 v171, 0xffff0000, v172
	v_lshlrev_b32_e32 v214, 16, v184
	v_and_b32_e32 v215, 0xffff0000, v184
	v_pk_fma_f32 v[214:215], v[24:25], v[170:171], v[214:215]
	v_lshlrev_b32_e32 v170, 16, v173
	v_and_b32_e32 v171, 0xffff0000, v173
	v_lshlrev_b32_e32 v172, 16, v185
	v_and_b32_e32 v173, 0xffff0000, v185
	v_pk_fma_f32 v[184:185], v[26:27], v[170:171], v[172:173]
	v_cvt_pk_bf16_f32 v170, v212, v213
	v_cvt_pk_bf16_f32 v171, v182, v183
	v_cvt_pk_bf16_f32 v172, v214, v215
	v_cvt_pk_bf16_f32 v173, v184, v185
	global_store_dwordx4 v[206:207], v[170:173], off
	v_lshlrev_b32_e32 v182, 16, v191
	v_and_b32_e32 v183, 0xffff0000, v191
	v_lshlrev_b32_e32 v170, 16, v186
	v_and_b32_e32 v171, 0xffff0000, v186
	v_lshlrev_b32_e32 v172, 16, v190
	v_and_b32_e32 v173, 0xffff0000, v190
	v_pk_fma_f32 v[170:171], v[12:13], v[170:171], v[172:173]
	v_lshlrev_b32_e32 v172, 16, v187
	v_and_b32_e32 v173, 0xffff0000, v187
	v_pk_fma_f32 v[172:173], v[14:15], v[172:173], v[182:183]
	v_lshlrev_b32_e32 v182, 16, v188
	v_and_b32_e32 v183, 0xffff0000, v188
	v_lshlrev_b32_e32 v184, 16, v192
	v_and_b32_e32 v185, 0xffff0000, v192
	v_pk_fma_f32 v[182:183], v[8:9], v[182:183], v[184:185]
	v_lshlrev_b32_e32 v184, 16, v189
	v_and_b32_e32 v185, 0xffff0000, v189
	v_lshlrev_b32_e32 v186, 16, v193
	v_and_b32_e32 v187, 0xffff0000, v193
	v_pk_fma_f32 v[184:185], v[10:11], v[184:185], v[186:187]
	v_cvt_pk_bf16_f32 v170, v170, v171
	v_cvt_pk_bf16_f32 v171, v172, v173
	v_cvt_pk_bf16_f32 v172, v182, v183
	v_cvt_pk_bf16_f32 v173, v184, v185
	global_store_dwordx4 v[174:175], v[170:173], off offset:256
	v_lshlrev_b32_e32 v174, 16, v199
	v_and_b32_e32 v175, 0xffff0000, v199
	v_lshlrev_b32_e32 v170, 16, v194
	v_and_b32_e32 v171, 0xffff0000, v194
	v_lshlrev_b32_e32 v172, 16, v198
	v_and_b32_e32 v173, 0xffff0000, v198
	v_pk_fma_f32 v[170:171], v[20:21], v[170:171], v[172:173]
	v_lshlrev_b32_e32 v172, 16, v195
	v_and_b32_e32 v173, 0xffff0000, v195
	v_pk_fma_f32 v[172:173], v[22:23], v[172:173], v[174:175]
	v_lshlrev_b32_e32 v174, 16, v196
	v_and_b32_e32 v175, 0xffff0000, v196
	v_lshlrev_b32_e32 v182, 16, v200
	v_and_b32_e32 v183, 0xffff0000, v200
	v_pk_fma_f32 v[174:175], v[16:17], v[174:175], v[182:183]
	v_lshlrev_b32_e32 v182, 16, v197
	v_and_b32_e32 v183, 0xffff0000, v197
	v_lshlrev_b32_e32 v184, 16, v201
	v_and_b32_e32 v185, 0xffff0000, v201
	v_pk_fma_f32 v[182:183], v[18:19], v[182:183], v[184:185]
	v_cvt_pk_bf16_f32 v170, v170, v171
	v_cvt_pk_bf16_f32 v171, v172, v173
	v_cvt_pk_bf16_f32 v172, v174, v175
	v_cvt_pk_bf16_f32 v173, v182, v183
	global_store_dwordx4 v[208:209], v[170:173], off
	v_lshlrev_b32_e32 v174, 16, v168
	v_and_b32_e32 v175, 0xffff0000, v168
	v_lshlrev_b32_e32 v170, 16, v202
	v_and_b32_e32 v171, 0xffff0000, v202
	v_lshlrev_b32_e32 v172, 16, v166
	v_and_b32_e32 v173, 0xffff0000, v166
	v_pk_fma_f32 v[170:171], v[4:5], v[170:171], v[172:173]
	v_lshlrev_b32_e32 v172, 16, v203
	v_and_b32_e32 v173, 0xffff0000, v203
	v_lshlrev_b32_e32 v166, 16, v167
	v_and_b32_e32 v167, 0xffff0000, v167
	v_pk_fma_f32 v[172:173], v[6:7], v[172:173], v[166:167]
	v_lshlrev_b32_e32 v166, 16, v204
	v_and_b32_e32 v167, 0xffff0000, v204
	v_pk_fma_f32 v[174:175], v[0:1], v[166:167], v[174:175]
	v_lshlrev_b32_e32 v166, 16, v205
	v_and_b32_e32 v167, 0xffff0000, v205
	v_lshlrev_b32_e32 v168, 16, v169
	v_and_b32_e32 v169, 0xffff0000, v169
	v_pk_fma_f32 v[182:183], v[2:3], v[166:167], v[168:169]
	v_cvt_pk_bf16_f32 v166, v170, v171
	v_cvt_pk_bf16_f32 v167, v172, v173
	v_cvt_pk_bf16_f32 v168, v174, v175
	v_cvt_pk_bf16_f32 v169, v182, v183
	global_store_dwordx4 v[210:211], v[166:169], off offset:256

; #define PG8_STAGE(bufoff, gbase, voff) do { _Pragma("unroll") for (int _i = 0; _i < 2; ++_i) \
;         __builtin_amdgcn_global_load_lds((const unsigned*)((const char*)(gbase) + (voff)[_i]), (LAS unsigned*)(lds + (bufoff) + ldsw + _i * 8192), 16, 0, 0); } while (0)
; #define PG8_LDA(dst, b, h) do { _Pragma("unroll") for (int m = 0; m < 4; ++m) _Pragma("unroll") for (int k = 0; k < 2; ++k) dst[m][k] = *(const LAS bf16x8*)(lds + PG8_SA(b, h) + aoff + m * 2048 + k * 1024); } while (0)
; #define PG8_LDB(dst, b, h) do { _Pragma("unroll") for (int n = 0; n < 2; ++n) _Pragma("unroll") for (int k = 0; k < 2; ++k) dst[n][k] = *(const LAS bf16x8*)(lds + PG8_SB(b, h) + boff + n * 2048 + k * 1024); } while (0)
; #define PG8_MMA(ai, bj, At, Bt) do { __builtin_amdgcn_s_setprio(1); _Pragma("unroll") for (int m = 0; m < 4; ++m) _Pragma("unroll") for (int n = 0; n < 2; ++n) _Pragma("unroll") for (int k = 0; k < 2; ++k) \
;         acc[ai][bj][m][n] = __builtin_amdgcn_mfma_f32_16x16x32_bf16(Bt[n][k], At[m][k], acc[ai][bj][m][n], 0, 0, 0); __builtin_amdgcn_s_setprio(0); } while (0)
; #define PG8_WAIT_L(n) asm volatile("s_waitcnt lgkmcnt(" #n ")" ::: "memory")
; #define PG8_BAR __builtin_amdgcn_s_barrier()
; #define PG8_SCHED __builtin_amdgcn_sched_barrier(0)
; #define PG8_WAIT_L(n) asm volatile("s_waitcnt lgkmcnt(" #n ")" ::: "memory")
; #define PG8_BAR __builtin_amdgcn_s_barrier()
; #define PG8_SCHED __builtin_amdgcn_sched_barrier(0)
; template <class Epi>
; DI void gemm_phase(LAS unsigned char* lds, const Gemm g, const StaticOrder S, const Epi E) {
;     ...
;             const bool last = (t == nt - 2);
;             const char* a1 = cA + (size_t)(t + 1) * kstep;
;             const char* a2 = last ? nA : cA + (size_t)(t + 2) * kstep; const char* b2 = last ? nB : cB + (size_t)(t + 2) * kstep;
;             const char* a3 = a2 + kstep; const char* b3 = b2 + kstep;
;             PG8_LDB(B0, 0, 0); PG8_SCHED; PG8_LDA(At, 0, 0); PG8_STAGE(PG8_SA(1, 1), a1 + hstep, voffA);
;             PG8_WAIT_L(8); PG8_BAR; PG8_WAIT_L(0); PG8_MMA(0, 0, At, B0); PG8_BAR; PG8_SCHED;
;             PG8_LDB(B1, 0, 1); PG8_STAGE(PG8_SB(0, 0), b2, voffB);
;             PG8_BAR; PG8_WAIT_L(0); PG8_MMA(0, 1, At, B1); PG8_BAR;
;             PG8_LDA(At, 0, 1); PG8_STAGE(PG8_SA(0, 0), a2, voffA);
;             PG8_BAR; PG8_WAIT_L(0); PG8_MMA(1, 0, At, B0); PG8_BAR; PG8_SCHED;
.LBB0_786:
	ds_read_b128 v[128:131], v187
	ds_read_b128 v[132:135], v187 offset:1024
	ds_read_b128 v[136:139], v187 offset:2048
	ds_read_b128 v[140:143], v187 offset:3072
	s_add_u32 s28, s24, 0xfffc0080
	s_addc_u32 s29, s25, -1
	s_cmp_eq_u32 s52, 12
	s_cselect_b32 s39, s6, s29
	s_cselect_b32 s38, s7, s28
	s_cselect_b32 s29, s11, s51
	s_cselect_b32 s28, s13, s50
	v_lshl_add_u64 v[200:201], s[24:25], 0, v[160:161]
	s_add_i32 m0, s19, 0xc000
	ds_read_b128 v[144:147], v188
	ds_read_b128 v[168:171], v188 offset:2048
	ds_read_b128 v[176:179], v188 offset:4096
	ds_read_b128 v[192:195], v188 offset:6144
	global_load_lds_dwordx4 v[200:201], off
	s_add_i32 m0, s19, 0xe000
	v_lshl_add_u64 v[200:201], s[24:25], 0, v[162:163]
	global_load_lds_dwordx4 v[200:201], off
	s_waitcnt lgkmcnt(4)
	s_setprio 1
	s_barrier
	ds_read_b128 v[148:151], v188 offset:1024
	ds_read_b128 v[172:175], v188 offset:3072
	ds_read_b128 v[180:183], v188 offset:5120
	ds_read_b128 v[196:199], v188 offset:7168
	s_waitcnt lgkmcnt(4)
	v_mfma_f32_16x16x32_bf16 v[124:127], v[128:131], v[144:147], v[124:127]
	v_mfma_f32_16x16x32_bf16 v[120:123], v[136:139], v[144:147], v[120:123]
	v_mfma_f32_16x16x32_bf16 v[108:111], v[128:131], v[168:171], v[108:111]
	v_mfma_f32_16x16x32_bf16 v[104:107], v[136:139], v[168:171], v[104:107]
	v_mfma_f32_16x16x32_bf16 v[92:95], v[128:131], v[176:179], v[92:95]
	v_mfma_f32_16x16x32_bf16 v[88:91], v[136:139], v[176:179], v[88:91]
	v_mfma_f32_16x16x32_bf16 v[76:79], v[128:131], v[192:195], v[76:79]
	v_mfma_f32_16x16x32_bf16 v[72:75], v[136:139], v[192:195], v[72:75]
	s_waitcnt lgkmcnt(3)
	v_mfma_f32_16x16x32_bf16 v[124:127], v[132:135], v[148:151], v[124:127]
	v_mfma_f32_16x16x32_bf16 v[120:123], v[140:143], v[148:151], v[120:123]
	s_waitcnt lgkmcnt(2)
	v_mfma_f32_16x16x32_bf16 v[108:111], v[132:135], v[172:175], v[108:111]
	v_mfma_f32_16x16x32_bf16 v[104:107], v[140:143], v[172:175], v[104:107]
	s_waitcnt lgkmcnt(1)
	v_mfma_f32_16x16x32_bf16 v[92:95], v[132:135], v[180:183], v[92:95]
	v_mfma_f32_16x16x32_bf16 v[88:91], v[140:143], v[180:183], v[88:91]
	s_waitcnt lgkmcnt(0)
	s_setprio 2
	s_barrier
	v_mfma_f32_16x16x32_bf16 v[76:79], v[132:135], v[196:199], v[76:79]
	v_mfma_f32_16x16x32_bf16 v[72:75], v[140:143], v[196:199], v[72:75]
	s_setprio 0
	s_add_i32 s53, s48, s40
	v_lshl_add_u64 v[216:217], s[28:29], 0, v[154:155]
	s_mov_b32 m0, s53
	ds_read_b128 v[200:203], v189
	ds_read_b128 v[204:207], v189 offset:1024
	ds_read_b128 v[208:211], v189 offset:2048
	ds_read_b128 v[212:215], v189 offset:3072
	global_load_lds_dwordx4 v[216:217], off
	s_add_i32 m0, s53, 0x2000
	v_lshl_add_u64 v[218:219], s[28:29], 0, v[158:159]
	global_load_lds_dwordx4 v[218:219], off
	s_setprio 1
	s_barrier
	s_waitcnt lgkmcnt(0)
	v_mfma_f32_16x16x32_bf16 v[116:119], v[200:203], v[144:147], v[116:119]
	v_mfma_f32_16x16x32_bf16 v[112:115], v[208:211], v[144:147], v[112:115]
	v_mfma_f32_16x16x32_bf16 v[100:103], v[200:203], v[168:171], v[100:103]
	v_mfma_f32_16x16x32_bf16 v[96:99], v[208:211], v[168:171], v[96:99]
	v_mfma_f32_16x16x32_bf16 v[84:87], v[200:203], v[176:179], v[84:87]
	v_mfma_f32_16x16x32_bf16 v[80:83], v[208:211], v[176:179], v[80:83]
	v_mfma_f32_16x16x32_bf16 v[68:71], v[200:203], v[192:195], v[68:71]
	v_mfma_f32_16x16x32_bf16 v[64:67], v[208:211], v[192:195], v[64:67]
	v_mfma_f32_16x16x32_bf16 v[116:119], v[204:207], v[148:151], v[116:119]
	v_mfma_f32_16x16x32_bf16 v[112:115], v[212:215], v[148:151], v[112:115]
	v_mfma_f32_16x16x32_bf16 v[100:103], v[204:207], v[172:175], v[100:103]
	v_mfma_f32_16x16x32_bf16 v[96:99], v[212:215], v[172:175], v[96:99]
	v_mfma_f32_16x16x32_bf16 v[84:87], v[204:207], v[180:183], v[84:87]
	v_mfma_f32_16x16x32_bf16 v[80:83], v[212:215], v[180:183], v[80:83]
	s_setprio 2
	s_barrier
	v_mfma_f32_16x16x32_bf16 v[68:71], v[204:207], v[196:199], v[68:71]
	v_mfma_f32_16x16x32_bf16 v[64:67], v[212:215], v[196:199], v[64:67]
	s_setprio 0
	s_mov_b32 m0, s19
	v_lshl_add_u64 v[220:221], s[38:39], 0, v[152:153]
	ds_read_b128 v[144:147], v188 offset:16384
	ds_read_b128 v[168:171], v188 offset:18432
	ds_read_b128 v[176:179], v188 offset:20480
	ds_read_b128 v[192:195], v188 offset:22528
	global_load_lds_dwordx4 v[220:221], off
	s_mov_b32 m0, s23
	v_lshl_add_u64 v[224:225], s[38:39], 0, v[156:157]
	global_load_lds_dwordx4 v[224:225], off
	s_setprio 1
	s_barrier
	ds_read_b128 v[148:151], v188 offset:17408
	ds_read_b128 v[172:175], v188 offset:19456
	ds_read_b128 v[180:183], v188 offset:21504
	ds_read_b128 v[196:199], v188 offset:23552
	s_waitcnt lgkmcnt(4)
	v_mfma_f32_16x16x32_bf16 v[60:63], v[128:131], v[144:147], v[60:63]
	v_mfma_f32_16x16x32_bf16 v[56:59], v[136:139], v[144:147], v[56:59]
	v_mfma_f32_16x16x32_bf16 v[44:47], v[128:131], v[168:171], v[44:47]
	v_mfma_f32_16x16x32_bf16 v[40:43], v[136:139], v[168:171], v[40:43]
	v_mfma_f32_16x16x32_bf16 v[28:31], v[128:131], v[176:179], v[28:31]
	v_mfma_f32_16x16x32_bf16 v[24:27], v[136:139], v[176:179], v[24:27]
	v_mfma_f32_16x16x32_bf16 v[12:15], v[128:131], v[192:195], v[12:15]
	v_mfma_f32_16x16x32_bf16 v[8:11], v[136:139], v[192:195], v[8:11]
	s_waitcnt lgkmcnt(3)
	v_mfma_f32_16x16x32_bf16 v[60:63], v[132:135], v[148:151], v[60:63]
	v_mfma_f32_16x16x32_bf16 v[56:59], v[140:143], v[148:151], v[56:59]
	s_waitcnt lgkmcnt(2)
	v_mfma_f32_16x16x32_bf16 v[44:47], v[132:135], v[172:175], v[44:47]
	v_mfma_f32_16x16x32_bf16 v[40:43], v[140:143], v[172:175], v[40:43]
	s_waitcnt lgkmcnt(1)
	v_mfma_f32_16x16x32_bf16 v[28:31], v[132:135], v[180:183], v[28:31]
	v_mfma_f32_16x16x32_bf16 v[24:27], v[140:143], v[180:183], v[24:27]
	s_waitcnt lgkmcnt(0)
	s_setprio 2
	s_barrier
; #define PG8_STAGE(bufoff, gbase, voff) do { _Pragma("unroll") for (int _i = 0; _i < 2; ++_i) \
;         __builtin_amdgcn_global_load_lds((const unsigned*)((const char*)(gbase) + (voff)[_i]), (LAS unsigned*)(lds + (bufoff) + ldsw + _i * 8192), 16, 0, 0); } while (0)
; #define PG8_LDA(dst, b, h) do { _Pragma("unroll") for (int m = 0; m < 4; ++m) _Pragma("unroll") for (int k = 0; k < 2; ++k) dst[m][k] = *(const LAS bf16x8*)(lds + PG8_SA(b, h) + aoff + m * 2048 + k * 1024); } while (0)
; #define PG8_LDB(dst, b, h) do { _Pragma("unroll") for (int n = 0; n < 2; ++n) _Pragma("unroll") for (int k = 0; k < 2; ++k) dst[n][k] = *(const LAS bf16x8*)(lds + PG8_SB(b, h) + boff + n * 2048 + k * 1024); } while (0)
; #define PG8_MMA(ai, bj, At, Bt) do { __builtin_amdgcn_s_setprio(1); _Pragma("unroll") for (int m = 0; m < 4; ++m) _Pragma("unroll") for (int n = 0; n < 2; ++n) _Pragma("unroll") for (int k = 0; k < 2; ++k) \
;         acc[ai][bj][m][n] = __builtin_amdgcn_mfma_f32_16x16x32_bf16(Bt[n][k], At[m][k], acc[ai][bj][m][n], 0, 0, 0); __builtin_amdgcn_s_setprio(0); } while (0)
; #define PG8_WAIT_V(n) asm volatile("s_waitcnt vmcnt(" #n ")" ::: "memory")
; #define PG8_WAIT_L(n) asm volatile("s_waitcnt lgkmcnt(" #n ")" ::: "memory")
; #define PG8_BAR __builtin_amdgcn_s_barrier()
; #define PG8_SCHED __builtin_amdgcn_sched_barrier(0)
; #define PG8_LDA(dst, b, h) do { _Pragma("unroll") for (int m = 0; m < 4; ++m) _Pragma("unroll") for (int k = 0; k < 2; ++k) dst[m][k] = *(const LAS bf16x8*)(lds + PG8_SA(b, h) + aoff + m * 2048 + k * 1024); } while (0)
; template <class Epi>
; DI void gemm_phase(LAS unsigned char* lds, const Gemm g, const StaticOrder S, const Epi E) {
;     ...
;             PG8_BAR; PG8_WAIT_L(0); PG8_MMA(1, 0, At, B0); PG8_BAR; PG8_SCHED;
;             PG8_STAGE(PG8_SB(0, 1), b2 + hstep, voffB);
;             PG8_WAIT_V(6); PG8_BAR; PG8_MMA(1, 1, At, B1); PG8_BAR;
;             PG8_LDB(B0, 1, 0); PG8_SCHED; PG8_LDA(At, 1, 0); PG8_STAGE(PG8_SA(0, 1), a2 + hstep, voffA);
;             PG8_WAIT_L(8); PG8_BAR; PG8_WAIT_L(0); PG8_MMA(0, 0, At, B0); PG8_BAR; PG8_SCHED;
;             PG8_LDB(B1, 1, 1); PG8_STAGE(PG8_SB(1, 0), b3, voffB);
;             PG8_BAR; PG8_WAIT_L(0); PG8_MMA(0, 1, At, B1); PG8_BAR;
;             PG8_LDA(At, 1, 1); PG8_STAGE(PG8_SA(1, 0), a3, voffA);
;             PG8_BAR; PG8_WAIT_L(0); PG8_MMA(1, 0, At, B0); PG8_BAR; PG8_SCHED;
	v_mfma_f32_16x16x32_bf16 v[12:15], v[132:135], v[196:199], v[12:15]
	v_mfma_f32_16x16x32_bf16 v[8:11], v[140:143], v[196:199], v[8:11]
	s_setprio 0
	s_add_u32 s58, s28, 0x40000
	s_addc_u32 s59, s29, 0
	s_add_i32 s53, s49, s40
	s_mov_b32 m0, s53
	v_lshl_add_u64 v[128:129], s[58:59], 0, v[154:155]
	global_load_lds_dwordx4 v[128:129], off
	s_add_i32 m0, s53, 0x2000
	v_lshl_add_u64 v[128:129], s[58:59], 0, v[158:159]
	global_load_lds_dwordx4 v[128:129], off
	s_waitcnt vmcnt(6)
	s_setprio 1
	s_barrier
	v_mfma_f32_16x16x32_bf16 v[52:55], v[200:203], v[144:147], v[52:55]
	v_mfma_f32_16x16x32_bf16 v[48:51], v[208:211], v[144:147], v[48:51]
	v_mfma_f32_16x16x32_bf16 v[36:39], v[200:203], v[168:171], v[36:39]
	v_mfma_f32_16x16x32_bf16 v[32:35], v[208:211], v[168:171], v[32:35]
	v_mfma_f32_16x16x32_bf16 v[20:23], v[200:203], v[176:179], v[20:23]
	v_mfma_f32_16x16x32_bf16 v[16:19], v[208:211], v[176:179], v[16:19]
	v_mfma_f32_16x16x32_bf16 v[4:7], v[200:203], v[192:195], v[4:7]
	v_mfma_f32_16x16x32_bf16 v[0:3], v[208:211], v[192:195], v[0:3]
	v_mfma_f32_16x16x32_bf16 v[52:55], v[204:207], v[148:151], v[52:55]
	v_mfma_f32_16x16x32_bf16 v[48:51], v[212:215], v[148:151], v[48:51]
	v_mfma_f32_16x16x32_bf16 v[36:39], v[204:207], v[172:175], v[36:39]
	v_mfma_f32_16x16x32_bf16 v[32:35], v[212:215], v[172:175], v[32:35]
	v_mfma_f32_16x16x32_bf16 v[20:23], v[204:207], v[180:183], v[20:23]
	v_mfma_f32_16x16x32_bf16 v[16:19], v[212:215], v[180:183], v[16:19]
	s_setprio 2
	s_barrier
	v_mfma_f32_16x16x32_bf16 v[4:7], v[204:207], v[196:199], v[4:7]
	v_mfma_f32_16x16x32_bf16 v[0:3], v[212:215], v[196:199], v[0:3]
	s_setprio 0
	s_add_i32 s53, 0, 0x18000
	v_add_u32_e32 v140, s53, v185
	ds_read_b128 v[128:131], v140
	ds_read_b128 v[132:135], v140 offset:1024
	ds_read_b128 v[136:139], v140 offset:2048
	ds_read_b128 v[140:143], v140 offset:3072
	s_add_u32 s38, s38, 0x40000
	s_addc_u32 s39, s39, 0
	s_mov_b32 m0, s41
	v_lshl_add_u64 v[200:201], s[38:39], 0, v[152:153]
	ds_read_b128 v[144:147], v188 offset:32768
	ds_read_b128 v[168:171], v188 offset:34816
	ds_read_b128 v[176:179], v188 offset:36864
	ds_read_b128 v[192:195], v188 offset:38912
	global_load_lds_dwordx4 v[200:201], off
	s_mov_b32 m0, s42
	v_lshl_add_u64 v[200:201], s[38:39], 0, v[156:157]
	global_load_lds_dwordx4 v[200:201], off
	s_waitcnt lgkmcnt(4)
	s_setprio 1
	s_barrier
	ds_read_b128 v[148:151], v188 offset:33792
	ds_read_b128 v[172:175], v188 offset:35840
	ds_read_b128 v[180:183], v188 offset:37888
	ds_read_b128 v[196:199], v188 offset:39936
	s_waitcnt lgkmcnt(4)
	v_mfma_f32_16x16x32_bf16 v[124:127], v[128:131], v[144:147], v[124:127]
	v_mfma_f32_16x16x32_bf16 v[120:123], v[136:139], v[144:147], v[120:123]
	v_mfma_f32_16x16x32_bf16 v[108:111], v[128:131], v[168:171], v[108:111]
	v_mfma_f32_16x16x32_bf16 v[104:107], v[136:139], v[168:171], v[104:107]
	v_mfma_f32_16x16x32_bf16 v[92:95], v[128:131], v[176:179], v[92:95]
	v_mfma_f32_16x16x32_bf16 v[88:91], v[136:139], v[176:179], v[88:91]
	v_mfma_f32_16x16x32_bf16 v[76:79], v[128:131], v[192:195], v[76:79]
	v_mfma_f32_16x16x32_bf16 v[72:75], v[136:139], v[192:195], v[72:75]
	s_waitcnt lgkmcnt(3)
	v_mfma_f32_16x16x32_bf16 v[124:127], v[132:135], v[148:151], v[124:127]
	v_mfma_f32_16x16x32_bf16 v[120:123], v[140:143], v[148:151], v[120:123]
	s_waitcnt lgkmcnt(2)
	v_mfma_f32_16x16x32_bf16 v[108:111], v[132:135], v[172:175], v[108:111]
	v_mfma_f32_16x16x32_bf16 v[104:107], v[140:143], v[172:175], v[104:107]
	s_waitcnt lgkmcnt(1)
	v_mfma_f32_16x16x32_bf16 v[92:95], v[132:135], v[180:183], v[92:95]
	v_mfma_f32_16x16x32_bf16 v[88:91], v[140:143], v[180:183], v[88:91]
	s_waitcnt lgkmcnt(0)
	s_setprio 2
	s_barrier
	v_mfma_f32_16x16x32_bf16 v[76:79], v[132:135], v[196:199], v[76:79]
	v_mfma_f32_16x16x32_bf16 v[72:75], v[140:143], v[196:199], v[72:75]
	s_setprio 0
	s_add_i32 s38, 0, 0x1c000
	s_add_i32 s39, s53, s40
	v_add_u32_e32 v191, s38, v185
	v_lshl_add_u64 v[216:217], v[216:217], 0, s[8:9]
	s_mov_b32 m0, s39
	ds_read_b128 v[200:203], v191
	ds_read_b128 v[204:207], v191 offset:1024
	ds_read_b128 v[208:211], v191 offset:2048
	ds_read_b128 v[212:215], v191 offset:3072
	global_load_lds_dwordx4 v[216:217], off
	s_add_i32 m0, s39, 0x2000
	v_lshl_add_u64 v[216:217], v[218:219], 0, s[8:9]
	global_load_lds_dwordx4 v[216:217], off
	s_setprio 1
	s_barrier
	s_waitcnt lgkmcnt(0)
	v_mfma_f32_16x16x32_bf16 v[116:119], v[200:203], v[144:147], v[116:119]
	v_mfma_f32_16x16x32_bf16 v[112:115], v[208:211], v[144:147], v[112:115]
	v_mfma_f32_16x16x32_bf16 v[100:103], v[200:203], v[168:171], v[100:103]
	v_mfma_f32_16x16x32_bf16 v[96:99], v[208:211], v[168:171], v[96:99]
	v_mfma_f32_16x16x32_bf16 v[84:87], v[200:203], v[176:179], v[84:87]
	v_mfma_f32_16x16x32_bf16 v[80:83], v[208:211], v[176:179], v[80:83]
	v_mfma_f32_16x16x32_bf16 v[68:71], v[200:203], v[192:195], v[68:71]
	v_mfma_f32_16x16x32_bf16 v[64:67], v[208:211], v[192:195], v[64:67]
	v_mfma_f32_16x16x32_bf16 v[116:119], v[204:207], v[148:151], v[116:119]
	v_mfma_f32_16x16x32_bf16 v[112:115], v[212:215], v[148:151], v[112:115]
	v_mfma_f32_16x16x32_bf16 v[100:103], v[204:207], v[172:175], v[100:103]
	v_mfma_f32_16x16x32_bf16 v[96:99], v[212:215], v[172:175], v[96:99]
	v_mfma_f32_16x16x32_bf16 v[84:87], v[204:207], v[180:183], v[84:87]
	v_mfma_f32_16x16x32_bf16 v[80:83], v[212:215], v[180:183], v[80:83]
	s_setprio 2
	s_barrier
	v_mfma_f32_16x16x32_bf16 v[68:71], v[204:207], v[196:199], v[68:71]
	v_mfma_f32_16x16x32_bf16 v[64:67], v[212:215], v[196:199], v[64:67]
	s_setprio 0
	s_mov_b32 m0, s44
	v_lshl_add_u64 v[216:217], v[220:221], 0, s[8:9]
	ds_read_b128 v[144:147], v188 offset:49152
	ds_read_b128 v[168:171], v188 offset:51200
	ds_read_b128 v[176:179], v188 offset:53248
	ds_read_b128 v[192:195], v188 offset:55296
	global_load_lds_dwordx4 v[216:217], off
	s_mov_b32 m0, s45
	v_lshl_add_u64 v[216:217], v[224:225], 0, s[8:9]
	global_load_lds_dwordx4 v[216:217], off
	s_setprio 1
	s_barrier
; #define PG8_WAIT_V(n) asm volatile("s_waitcnt vmcnt(" #n ")" ::: "memory")
; template <class Epi>
; DI void gemm_phase(LAS unsigned char* lds, const Gemm g, const StaticOrder S, const Epi E) {
;     ...
;             PG8_LDB(B1, 1, 1); PG8_STAGE(PG8_SB(1, 0), b3, voffB);
;             PG8_BAR; PG8_WAIT_L(0); PG8_MMA(0, 1, At, B1); PG8_BAR;
;             PG8_LDA(At, 1, 1); PG8_STAGE(PG8_SA(1, 0), a3, voffA);
;             PG8_BAR; PG8_WAIT_L(0); PG8_MMA(1, 0, At, B0); PG8_BAR; PG8_SCHED;
;             PG8_STAGE(PG8_SB(1, 1), b3 + hstep, voffB);
;             PG8_WAIT_V(6); PG8_BAR; PG8_MMA(1, 1, At, B1); PG8_BAR;
;         }
;         E(acc, cur, wr, wc, fr, fq);
;     DI void operator()(AccRef acc, const Unit& u, int wr, int wc, int fr, int fq) const {
;     ...
;         const int row0 = u.pm * 256 + wr * 64 + fr, col0 = u.pn * 256 + wc * 32 + 8 * fq;
; #pragma unroll
;         for (int ai = 0; ai < 2; ++ai) {
;             f32x4 bv[4][2][2];
; #pragma unroll
;             for (int m = 0; m < 4; ++m)
; #pragma unroll
;                 for (int bj = 0; bj < 2; ++bj) {
;                     const size_t o = (size_t)(row0 + ai * 128 + m * 16) * DM + col0 + bj * 128;
;                     if (BASEF32) { bv[m][bj][0] = *(const f32x4*)(basef + o); bv[m][bj][1] = *(const f32x4*)(basef + o + 4); }
;                     else { const u32x4 h = *(const u32x4*)(xnb + o); bv[m][bj][0] = bf_lo4(h); bv[m][bj][1] = bf_hi4(h); }
;                 }
; #pragma unroll
;             for (int m = 0; m < 4; ++m) {
;                 const int row = row0 + ai * 128 + m * 16;
;                 float q = 0.f;
; #pragma unroll
;                 for (int bj = 0; bj < 2; ++bj) {
;                     const size_t o = (size_t)row * DM + col0 + bj * 128;
;                     const f32x4 r0 = bv[m][bj][0] + scale * acc[ai][bj][m][0], r1 = bv[m][bj][1] + scale * acc[ai][bj][m][1];
;                     u32x4 w; w.x = pk_bf16(r0[0], r0[1]); w.y = pk_bf16(r0[2], r0[3]); w.z = pk_bf16(r1[0], r1[1]); w.w = pk_bf16(r1[2], r1[3]);
;                     *(u32x4*)(xnb + o) = w;
;                     if (STATS) q += r0[0] * r0[0] + r0[1] * r0[1] + r0[2] * r0[2] + r0[3] * r0[3] + r1[0] * r1[0] + r1[1] * r1[1] + r1[2] * r1[2] + r1[3] * r1[3];
;                 }
;                 if (STATS) { q += __shfl_xor(q, 16); q += __shfl_xor(q, 32); if (fq == 0) atomicAdd(ss + row, q); }
	ds_read_b128 v[148:151], v188 offset:50176
	ds_read_b128 v[172:175], v188 offset:52224
	ds_read_b128 v[180:183], v188 offset:54272
	ds_read_b128 v[196:199], v188 offset:56320
	s_waitcnt lgkmcnt(4)
	v_mfma_f32_16x16x32_bf16 v[60:63], v[128:131], v[144:147], v[60:63]
	v_mfma_f32_16x16x32_bf16 v[56:59], v[136:139], v[144:147], v[56:59]
	v_mfma_f32_16x16x32_bf16 v[44:47], v[128:131], v[168:171], v[44:47]
	v_mfma_f32_16x16x32_bf16 v[40:43], v[136:139], v[168:171], v[40:43]
	v_mfma_f32_16x16x32_bf16 v[28:31], v[128:131], v[176:179], v[28:31]
	v_mfma_f32_16x16x32_bf16 v[24:27], v[136:139], v[176:179], v[24:27]
	v_mfma_f32_16x16x32_bf16 v[12:15], v[128:131], v[192:195], v[12:15]
	v_mfma_f32_16x16x32_bf16 v[8:11], v[136:139], v[192:195], v[8:11]
	s_waitcnt lgkmcnt(3)
	v_mfma_f32_16x16x32_bf16 v[60:63], v[132:135], v[148:151], v[60:63]
	v_mfma_f32_16x16x32_bf16 v[56:59], v[140:143], v[148:151], v[56:59]
	s_waitcnt lgkmcnt(2)
	v_mfma_f32_16x16x32_bf16 v[44:47], v[132:135], v[172:175], v[44:47]
	v_mfma_f32_16x16x32_bf16 v[40:43], v[140:143], v[172:175], v[40:43]
	s_waitcnt lgkmcnt(1)
	v_mfma_f32_16x16x32_bf16 v[28:31], v[132:135], v[180:183], v[28:31]
	v_mfma_f32_16x16x32_bf16 v[24:27], v[140:143], v[180:183], v[24:27]
	s_waitcnt lgkmcnt(0)
	s_setprio 2
	s_barrier
	v_mfma_f32_16x16x32_bf16 v[12:15], v[132:135], v[196:199], v[12:15]
	v_mfma_f32_16x16x32_bf16 v[8:11], v[140:143], v[196:199], v[8:11]
	s_setprio 0
	s_add_u32 s28, s28, 0x40080
	s_addc_u32 s29, s29, 0
	s_add_i32 s38, s38, s40
	s_mov_b32 m0, s38
	v_lshl_add_u64 v[128:129], s[28:29], 0, v[154:155]
	global_load_lds_dwordx4 v[128:129], off
	s_add_i32 m0, s38, 0x2000
	v_lshl_add_u64 v[128:129], s[28:29], 0, v[158:159]
	global_load_lds_dwordx4 v[128:129], off
	s_waitcnt vmcnt(6)
	s_setprio 1
	s_barrier
	v_mfma_f32_16x16x32_bf16 v[52:55], v[200:203], v[144:147], v[52:55]
	v_mfma_f32_16x16x32_bf16 v[48:51], v[208:211], v[144:147], v[48:51]
	v_mfma_f32_16x16x32_bf16 v[36:39], v[200:203], v[168:171], v[36:39]
	v_mfma_f32_16x16x32_bf16 v[32:35], v[208:211], v[168:171], v[32:35]
	v_mfma_f32_16x16x32_bf16 v[20:23], v[200:203], v[176:179], v[20:23]
	v_mfma_f32_16x16x32_bf16 v[16:19], v[208:211], v[176:179], v[16:19]
	v_mfma_f32_16x16x32_bf16 v[4:7], v[200:203], v[192:195], v[4:7]
	v_mfma_f32_16x16x32_bf16 v[0:3], v[208:211], v[192:195], v[0:3]
	v_mfma_f32_16x16x32_bf16 v[52:55], v[204:207], v[148:151], v[52:55]
	v_mfma_f32_16x16x32_bf16 v[48:51], v[212:215], v[148:151], v[48:51]
	v_mfma_f32_16x16x32_bf16 v[36:39], v[204:207], v[172:175], v[36:39]
	v_mfma_f32_16x16x32_bf16 v[32:35], v[212:215], v[172:175], v[32:35]
	v_mfma_f32_16x16x32_bf16 v[20:23], v[204:207], v[180:183], v[20:23]
	v_mfma_f32_16x16x32_bf16 v[16:19], v[212:215], v[180:183], v[16:19]
	s_setprio 2
	s_barrier
	v_mfma_f32_16x16x32_bf16 v[4:7], v[204:207], v[196:199], v[4:7]
	v_mfma_f32_16x16x32_bf16 v[0:3], v[212:215], v[196:199], v[0:3]
	s_setprio 0
	s_add_i32 s52, s52, 2
	s_add_u32 s24, s24, 0x100
	s_addc_u32 s25, s25, 0
	s_add_u32 s50, s50, 0x100
	s_addc_u32 s51, s51, 0
	s_cmp_gt_u32 s52, 13
	s_cbranch_scc0 .LBB0_786
	v_lshl_add_u32 v170, s18, 8, v184
	v_lshl_or_b32 v128, s22, 8, v186
	v_ashrrev_i32_e32 v129, 31, v128
	v_ashrrev_i32_e32 v171, 31, v170
	v_lshl_add_u64 v[168:169], v[128:129], 1, s[56:57]
	v_lshlrev_b64 v[128:129], 11, v[170:171]
	v_lshl_add_u64 v[202:203], v[168:169], 0, v[128:129]
	global_load_dwordx4 v[194:197], v[202:203], off
	global_load_dwordx4 v[198:201], v[202:203], off offset:256
	v_or_b32_e32 v180, 16, v170
	v_or_b32_e32 v176, 32, v170
	v_or_b32_e32 v172, 48, v170
	v_ashrrev_i32_e32 v181, 31, v180
	v_ashrrev_i32_e32 v177, 31, v176
	v_ashrrev_i32_e32 v173, 31, v172
	v_lshlrev_b64 v[128:129], 11, v[180:181]
	v_lshlrev_b64 v[130:131], 11, v[176:177]
	v_lshlrev_b64 v[132:133], 11, v[172:173]
	v_lshl_add_u64 v[182:183], v[168:169], 0, v[128:129]
	v_lshl_add_u64 v[178:179], v[168:169], 0, v[130:131]
	v_lshl_add_u64 v[174:175], v[168:169], 0, v[132:133]
	global_load_dwordx4 v[148:151], v[182:183], off
	global_load_dwordx4 v[144:147], v[182:183], off offset:256
	global_load_dwordx4 v[140:143], v[178:179], off
	global_load_dwordx4 v[136:139], v[178:179], off offset:256
	global_load_dwordx4 v[132:135], v[174:175], off
	global_load_dwordx4 v[128:131], v[174:175], off offset:256
	v_and_b32_e32 v192, 64, v190
	v_xor_b32_e32 v191, 16, v190
	v_add_u32_e32 v192, 64, v192
	v_cmp_lt_i32_e32 vcc, v191, v192
	v_xor_b32_e32 v193, 32, v190
	s_waitcnt vmcnt(0)
	v_lshlrev_b32_e32 v204, 16, v194
	v_and_b32_e32 v205, 0xffff0000, v194
	v_lshlrev_b32_e32 v208, 16, v198
	v_and_b32_e32 v209, 0xffff0000, v198
	v_lshlrev_b32_e32 v194, 16, v195
	v_and_b32_e32 v195, 0xffff0000, v195
	v_lshlrev_b32_e32 v210, 16, v200
	v_and_b32_e32 v211, 0xffff0000, v200
	v_lshlrev_b32_e32 v200, 16, v201
	v_and_b32_e32 v201, 0xffff0000, v201
	v_pk_add_f32 v[124:125], v[124:125], v[204:205]
	v_pk_add_f32 v[116:117], v[116:117], v[208:209]
	v_lshlrev_b32_e32 v198, 16, v199
	v_and_b32_e32 v199, 0xffff0000, v199
	v_pk_add_f32 v[126:127], v[126:127], v[194:195]
	v_pk_add_f32 v[194:195], v[114:115], v[200:201]
	v_mul_f32_e32 v114, v125, v125
	v_mul_f32_e32 v115, v117, v117
	v_pk_add_f32 v[118:119], v[118:119], v[198:199]
	v_fmac_f32_e32 v114, v124, v124
	v_fmac_f32_e32 v115, v116, v116
	v_lshlrev_b32_e32 v206, 16, v196
	v_and_b32_e32 v207, 0xffff0000, v196
	v_lshlrev_b32_e32 v196, 16, v197
	v_and_b32_e32 v197, 0xffff0000, v197
	v_fmac_f32_e32 v114, v126, v126
	v_fmac_f32_e32 v115, v118, v118
	v_pk_add_f32 v[122:123], v[122:123], v[196:197]
	v_pk_add_f32 v[120:121], v[120:121], v[206:207]
	v_pk_add_f32 v[196:197], v[112:113], v[210:211]
	v_fmac_f32_e32 v114, v127, v127
	v_fmac_f32_e32 v115, v119, v119
	v_fmac_f32_e32 v114, v120, v120
	v_fmac_f32_e32 v115, v196, v196
	v_fmac_f32_e32 v114, v121, v121
	v_fmac_f32_e32 v115, v197, v197
	v_fmac_f32_e32 v114, v122, v122
	v_fmac_f32_e32 v115, v194, v194
	v_cndmask_b32_e32 v191, v190, v191, vcc
	v_fmac_f32_e32 v114, v123, v123
	v_fmac_f32_e32 v115, v195, v195
	v_cmp_lt_i32_e32 vcc, v193, v192
	v_lshlrev_b32_e32 v192, 2, v191
	v_cvt_pk_bf16_f32 v112, v124, v125
	v_add_f32_e32 v124, v114, v115
	ds_bpermute_b32 v125, v192, v124
	v_cndmask_b32_e32 v193, v190, v193, vcc
	v_cvt_pk_bf16_f32 v113, v126, v127
	v_cvt_pk_bf16_f32 v114, v120, v121
	v_cvt_pk_bf16_f32 v115, v122, v123
	v_lshlrev_b32_e32 v191, 2, v193
	global_store_dwordx4 v[202:203], v[112:115], off
	s_waitcnt lgkmcnt(0)
	s_nop 0
	v_add_f32_e32 v112, v124, v125
	ds_bpermute_b32 v113, v191, v112
	v_cvt_pk_bf16_f32 v114, v116, v117
	v_cvt_pk_bf16_f32 v115, v118, v119
	v_cvt_pk_bf16_f32 v116, v196, v197
	v_cvt_pk_bf16_f32 v117, v194, v195
	global_store_dwordx4 v[202:203], v[114:117], off offset:256
	s_and_saveexec_b64 s[6:7], s[0:1]
	s_cbranch_execz .LBB0_789
	s_waitcnt lgkmcnt(0)
	v_add_f32_e32 v114, v112, v113
	v_lshl_add_u64 v[112:113], v[170:171], 2, s[20:21]
	global_atomic_add_f32 v[112:113], v114, off

; #define PG8_STAGE(bufoff, gbase, voff) do { _Pragma("unroll") for (int _i = 0; _i < 2; ++_i) \
;         __builtin_amdgcn_global_load_lds((const unsigned*)((const char*)(gbase) + (voff)[_i]), (LAS unsigned*)(lds + (bufoff) + ldsw + _i * 8192), 16, 0, 0); } while (0)
; #define PG8_LDA(dst, b, h) do { _Pragma("unroll") for (int m = 0; m < 4; ++m) _Pragma("unroll") for (int k = 0; k < 2; ++k) dst[m][k] = *(const LAS bf16x8*)(lds + PG8_SA(b, h) + aoff + m * 2048 + k * 1024); } while (0)
; #define PG8_LDB(dst, b, h) do { _Pragma("unroll") for (int n = 0; n < 2; ++n) _Pragma("unroll") for (int k = 0; k < 2; ++k) dst[n][k] = *(const LAS bf16x8*)(lds + PG8_SB(b, h) + boff + n * 2048 + k * 1024); } while (0)
; #define PG8_MMA(ai, bj, At, Bt) do { __builtin_amdgcn_s_setprio(1); _Pragma("unroll") for (int m = 0; m < 4; ++m) _Pragma("unroll") for (int n = 0; n < 2; ++n) _Pragma("unroll") for (int k = 0; k < 2; ++k) \
;         acc[ai][bj][m][n] = __builtin_amdgcn_mfma_f32_16x16x32_bf16(Bt[n][k], At[m][k], acc[ai][bj][m][n], 0, 0, 0); __builtin_amdgcn_s_setprio(0); } while (0)
; #define PG8_WAIT_L(n) asm volatile("s_waitcnt lgkmcnt(" #n ")" ::: "memory")
; #define PG8_BAR __builtin_amdgcn_s_barrier()
; #define PG8_SCHED __builtin_amdgcn_sched_barrier(0)
; #define PG8_WAIT_L(n) asm volatile("s_waitcnt lgkmcnt(" #n ")" ::: "memory")
; #define PG8_BAR __builtin_amdgcn_s_barrier()
; #define PG8_SCHED __builtin_amdgcn_sched_barrier(0)
; template <class Epi>
; DI void gemm_phase(LAS unsigned char* lds, const Gemm g, const StaticOrder S, const Epi E) {
;     ...
;             const bool last = (t == nt - 2);
;             const char* a1 = cA + (size_t)(t + 1) * kstep;
;             const char* a2 = last ? nA : cA + (size_t)(t + 2) * kstep; const char* b2 = last ? nB : cB + (size_t)(t + 2) * kstep;
;             const char* a3 = a2 + kstep; const char* b3 = b2 + kstep;
;             PG8_LDB(B0, 0, 0); PG8_SCHED; PG8_LDA(At, 0, 0); PG8_STAGE(PG8_SA(1, 1), a1 + hstep, voffA);
;             PG8_WAIT_L(8); PG8_BAR; PG8_WAIT_L(0); PG8_MMA(0, 0, At, B0); PG8_BAR; PG8_SCHED;
;             PG8_LDB(B1, 0, 1); PG8_STAGE(PG8_SB(0, 0), b2, voffB);
;             PG8_BAR; PG8_WAIT_L(0); PG8_MMA(0, 1, At, B1); PG8_BAR;
;             PG8_LDA(At, 0, 1); PG8_STAGE(PG8_SA(0, 0), a2, voffA);
;             PG8_BAR; PG8_WAIT_L(0); PG8_MMA(1, 0, At, B0); PG8_BAR; PG8_SCHED;
.LBB0_865:
	ds_read_b128 v[144:147], v155
	ds_read_b128 v[160:163], v155 offset:1024
	ds_read_b128 v[164:167], v155 offset:2048
	ds_read_b128 v[168:171], v155 offset:3072
	s_add_u32 s10, s8, 0xfffc0080
	s_addc_u32 s11, s9, -1
	s_cmp_eq_u32 s25, 12
	s_cselect_b32 s13, s14, s11
	s_cselect_b32 s12, s15, s10
	s_cselect_b32 s11, s16, s19
	s_cselect_b32 s10, s17, s18
	v_lshl_add_u64 v[204:205], s[8:9], 0, v[136:137]
	s_add_i32 m0, s40, 0xc000
	ds_read_b128 v[172:175], v157
	ds_read_b128 v[180:183], v157 offset:2048
	ds_read_b128 v[188:191], v157 offset:4096
	ds_read_b128 v[196:199], v157 offset:6144
	global_load_lds_dwordx4 v[204:205], off
	s_add_i32 m0, s40, 0xe000
	v_lshl_add_u64 v[204:205], s[8:9], 0, v[138:139]
	global_load_lds_dwordx4 v[204:205], off
	s_waitcnt lgkmcnt(4)
	s_setprio 1
	s_barrier
	ds_read_b128 v[176:179], v157 offset:1024
	ds_read_b128 v[184:187], v157 offset:3072
	ds_read_b128 v[192:195], v157 offset:5120
	ds_read_b128 v[200:203], v157 offset:7168
	s_waitcnt lgkmcnt(4)
	v_mfma_f32_16x16x32_bf16 v[124:127], v[144:147], v[172:175], v[124:127]
	v_mfma_f32_16x16x32_bf16 v[120:123], v[164:167], v[172:175], v[120:123]
	v_mfma_f32_16x16x32_bf16 v[108:111], v[144:147], v[180:183], v[108:111]
	v_mfma_f32_16x16x32_bf16 v[104:107], v[164:167], v[180:183], v[104:107]
	v_mfma_f32_16x16x32_bf16 v[92:95], v[144:147], v[188:191], v[92:95]
	v_mfma_f32_16x16x32_bf16 v[88:91], v[164:167], v[188:191], v[88:91]
	v_mfma_f32_16x16x32_bf16 v[76:79], v[144:147], v[196:199], v[76:79]
	v_mfma_f32_16x16x32_bf16 v[72:75], v[164:167], v[196:199], v[72:75]
	s_waitcnt lgkmcnt(3)
	v_mfma_f32_16x16x32_bf16 v[124:127], v[160:163], v[176:179], v[124:127]
	v_mfma_f32_16x16x32_bf16 v[120:123], v[168:171], v[176:179], v[120:123]
	s_waitcnt lgkmcnt(2)
	v_mfma_f32_16x16x32_bf16 v[108:111], v[160:163], v[184:187], v[108:111]
	v_mfma_f32_16x16x32_bf16 v[104:107], v[168:171], v[184:187], v[104:107]
	s_waitcnt lgkmcnt(1)
	v_mfma_f32_16x16x32_bf16 v[92:95], v[160:163], v[192:195], v[92:95]
	v_mfma_f32_16x16x32_bf16 v[88:91], v[168:171], v[192:195], v[88:91]
	s_waitcnt lgkmcnt(0)
	s_setprio 2
	s_barrier
	v_mfma_f32_16x16x32_bf16 v[76:79], v[160:163], v[200:203], v[76:79]
	v_mfma_f32_16x16x32_bf16 v[72:75], v[168:171], v[200:203], v[72:75]
	s_setprio 0
	s_add_i32 s29, s49, s34
	v_lshl_add_u64 v[220:221], s[10:11], 0, v[132:133]
	s_mov_b32 m0, s29
	ds_read_b128 v[204:207], v158
	ds_read_b128 v[208:211], v158 offset:1024
	ds_read_b128 v[212:215], v158 offset:2048
	ds_read_b128 v[216:219], v158 offset:3072
	global_load_lds_dwordx4 v[220:221], off
	s_add_i32 m0, s29, 0x2000
	v_lshl_add_u64 v[224:225], s[10:11], 0, v[128:129]
	global_load_lds_dwordx4 v[224:225], off
	s_setprio 1
	s_barrier
	s_waitcnt lgkmcnt(0)
	v_mfma_f32_16x16x32_bf16 v[116:119], v[204:207], v[172:175], v[116:119]
	v_mfma_f32_16x16x32_bf16 v[112:115], v[212:215], v[172:175], v[112:115]
	v_mfma_f32_16x16x32_bf16 v[100:103], v[204:207], v[180:183], v[100:103]
	v_mfma_f32_16x16x32_bf16 v[96:99], v[212:215], v[180:183], v[96:99]
	v_mfma_f32_16x16x32_bf16 v[84:87], v[204:207], v[188:191], v[84:87]
	v_mfma_f32_16x16x32_bf16 v[80:83], v[212:215], v[188:191], v[80:83]
	v_mfma_f32_16x16x32_bf16 v[68:71], v[204:207], v[196:199], v[68:71]
	v_mfma_f32_16x16x32_bf16 v[64:67], v[212:215], v[196:199], v[64:67]
	v_mfma_f32_16x16x32_bf16 v[116:119], v[208:211], v[176:179], v[116:119]
	v_mfma_f32_16x16x32_bf16 v[112:115], v[216:219], v[176:179], v[112:115]
	v_mfma_f32_16x16x32_bf16 v[100:103], v[208:211], v[184:187], v[100:103]
	v_mfma_f32_16x16x32_bf16 v[96:99], v[216:219], v[184:187], v[96:99]
	v_mfma_f32_16x16x32_bf16 v[84:87], v[208:211], v[192:195], v[84:87]
	v_mfma_f32_16x16x32_bf16 v[80:83], v[216:219], v[192:195], v[80:83]
	s_setprio 2
	s_barrier
	v_mfma_f32_16x16x32_bf16 v[68:71], v[208:211], v[200:203], v[68:71]
	v_mfma_f32_16x16x32_bf16 v[64:67], v[216:219], v[200:203], v[64:67]
	s_setprio 0
	s_mov_b32 m0, s40
	v_lshl_add_u64 v[226:227], s[12:13], 0, v[134:135]
	ds_read_b128 v[172:175], v157 offset:16384
	ds_read_b128 v[180:183], v157 offset:18432
	ds_read_b128 v[188:191], v157 offset:20480
	ds_read_b128 v[196:199], v157 offset:22528
	global_load_lds_dwordx4 v[226:227], off
	s_mov_b32 m0, s41
	v_lshl_add_u64 v[228:229], s[12:13], 0, v[130:131]
	global_load_lds_dwordx4 v[228:229], off
	s_setprio 1
	s_barrier
	ds_read_b128 v[176:179], v157 offset:17408
	ds_read_b128 v[184:187], v157 offset:19456
	ds_read_b128 v[192:195], v157 offset:21504
	ds_read_b128 v[200:203], v157 offset:23552
	s_waitcnt lgkmcnt(4)
	v_mfma_f32_16x16x32_bf16 v[60:63], v[144:147], v[172:175], v[60:63]
	v_mfma_f32_16x16x32_bf16 v[56:59], v[164:167], v[172:175], v[56:59]
	v_mfma_f32_16x16x32_bf16 v[44:47], v[144:147], v[180:183], v[44:47]
	v_mfma_f32_16x16x32_bf16 v[40:43], v[164:167], v[180:183], v[40:43]
	v_mfma_f32_16x16x32_bf16 v[28:31], v[144:147], v[188:191], v[28:31]
	v_mfma_f32_16x16x32_bf16 v[24:27], v[164:167], v[188:191], v[24:27]
	v_mfma_f32_16x16x32_bf16 v[12:15], v[144:147], v[196:199], v[12:15]
	v_mfma_f32_16x16x32_bf16 v[8:11], v[164:167], v[196:199], v[8:11]
	s_waitcnt lgkmcnt(3)
	v_mfma_f32_16x16x32_bf16 v[60:63], v[160:163], v[176:179], v[60:63]
	v_mfma_f32_16x16x32_bf16 v[56:59], v[168:171], v[176:179], v[56:59]
	s_waitcnt lgkmcnt(2)
	v_mfma_f32_16x16x32_bf16 v[44:47], v[160:163], v[184:187], v[44:47]
	v_mfma_f32_16x16x32_bf16 v[40:43], v[168:171], v[184:187], v[40:43]
	s_waitcnt lgkmcnt(1)
	v_mfma_f32_16x16x32_bf16 v[28:31], v[160:163], v[192:195], v[28:31]
	v_mfma_f32_16x16x32_bf16 v[24:27], v[168:171], v[192:195], v[24:27]
	s_waitcnt lgkmcnt(0)
	s_setprio 2
	s_barrier
; #define PG8_STAGE(bufoff, gbase, voff) do { _Pragma("unroll") for (int _i = 0; _i < 2; ++_i) \
;         __builtin_amdgcn_global_load_lds((const unsigned*)((const char*)(gbase) + (voff)[_i]), (LAS unsigned*)(lds + (bufoff) + ldsw + _i * 8192), 16, 0, 0); } while (0)
; #define PG8_LDA(dst, b, h) do { _Pragma("unroll") for (int m = 0; m < 4; ++m) _Pragma("unroll") for (int k = 0; k < 2; ++k) dst[m][k] = *(const LAS bf16x8*)(lds + PG8_SA(b, h) + aoff + m * 2048 + k * 1024); } while (0)
; #define PG8_LDB(dst, b, h) do { _Pragma("unroll") for (int n = 0; n < 2; ++n) _Pragma("unroll") for (int k = 0; k < 2; ++k) dst[n][k] = *(const LAS bf16x8*)(lds + PG8_SB(b, h) + boff + n * 2048 + k * 1024); } while (0)
; #define PG8_MMA(ai, bj, At, Bt) do { __builtin_amdgcn_s_setprio(1); _Pragma("unroll") for (int m = 0; m < 4; ++m) _Pragma("unroll") for (int n = 0; n < 2; ++n) _Pragma("unroll") for (int k = 0; k < 2; ++k) \
;         acc[ai][bj][m][n] = __builtin_amdgcn_mfma_f32_16x16x32_bf16(Bt[n][k], At[m][k], acc[ai][bj][m][n], 0, 0, 0); __builtin_amdgcn_s_setprio(0); } while (0)
; #define PG8_WAIT_V(n) asm volatile("s_waitcnt vmcnt(" #n ")" ::: "memory")
; #define PG8_WAIT_L(n) asm volatile("s_waitcnt lgkmcnt(" #n ")" ::: "memory")
; #define PG8_BAR __builtin_amdgcn_s_barrier()
; #define PG8_SCHED __builtin_amdgcn_sched_barrier(0)
; #define PG8_LDA(dst, b, h) do { _Pragma("unroll") for (int m = 0; m < 4; ++m) _Pragma("unroll") for (int k = 0; k < 2; ++k) dst[m][k] = *(const LAS bf16x8*)(lds + PG8_SA(b, h) + aoff + m * 2048 + k * 1024); } while (0)
; template <class Epi>
; DI void gemm_phase(LAS unsigned char* lds, const Gemm g, const StaticOrder S, const Epi E) {
;     ...
;             PG8_BAR; PG8_WAIT_L(0); PG8_MMA(1, 0, At, B0); PG8_BAR; PG8_SCHED;
;             PG8_STAGE(PG8_SB(0, 1), b2 + hstep, voffB);
;             PG8_WAIT_V(6); PG8_BAR; PG8_MMA(1, 1, At, B1); PG8_BAR;
;             PG8_LDB(B0, 1, 0); PG8_SCHED; PG8_LDA(At, 1, 0); PG8_STAGE(PG8_SA(0, 1), a2 + hstep, voffA);
;             PG8_WAIT_L(8); PG8_BAR; PG8_WAIT_L(0); PG8_MMA(0, 0, At, B0); PG8_BAR; PG8_SCHED;
;             PG8_LDB(B1, 1, 1); PG8_STAGE(PG8_SB(1, 0), b3, voffB);
;             PG8_BAR; PG8_WAIT_L(0); PG8_MMA(0, 1, At, B1); PG8_BAR;
;             PG8_LDA(At, 1, 1); PG8_STAGE(PG8_SA(1, 0), a3, voffA);
;             PG8_BAR; PG8_WAIT_L(0); PG8_MMA(1, 0, At, B0); PG8_BAR; PG8_SCHED;
	v_mfma_f32_16x16x32_bf16 v[12:15], v[160:163], v[200:203], v[12:15]
	v_mfma_f32_16x16x32_bf16 v[8:11], v[168:171], v[200:203], v[8:11]
	s_setprio 0
	s_add_u32 s58, s10, 0x40000
	s_addc_u32 s59, s11, 0
	s_add_i32 s29, s50, s34
	s_mov_b32 m0, s29
	v_lshl_add_u64 v[144:145], s[58:59], 0, v[132:133]
	global_load_lds_dwordx4 v[144:145], off
	s_add_i32 m0, s29, 0x2000
	v_lshl_add_u64 v[144:145], s[58:59], 0, v[128:129]
	global_load_lds_dwordx4 v[144:145], off
	s_waitcnt vmcnt(6)
	s_setprio 1
	s_barrier
	v_mfma_f32_16x16x32_bf16 v[52:55], v[204:207], v[172:175], v[52:55]
	v_mfma_f32_16x16x32_bf16 v[48:51], v[212:215], v[172:175], v[48:51]
	v_mfma_f32_16x16x32_bf16 v[36:39], v[204:207], v[180:183], v[36:39]
	v_mfma_f32_16x16x32_bf16 v[32:35], v[212:215], v[180:183], v[32:35]
	v_mfma_f32_16x16x32_bf16 v[20:23], v[204:207], v[188:191], v[20:23]
	v_mfma_f32_16x16x32_bf16 v[16:19], v[212:215], v[188:191], v[16:19]
	v_mfma_f32_16x16x32_bf16 v[4:7], v[204:207], v[196:199], v[4:7]
	v_mfma_f32_16x16x32_bf16 v[0:3], v[212:215], v[196:199], v[0:3]
	v_mfma_f32_16x16x32_bf16 v[52:55], v[208:211], v[176:179], v[52:55]
	v_mfma_f32_16x16x32_bf16 v[48:51], v[216:219], v[176:179], v[48:51]
	v_mfma_f32_16x16x32_bf16 v[36:39], v[208:211], v[184:187], v[36:39]
	v_mfma_f32_16x16x32_bf16 v[32:35], v[216:219], v[184:187], v[32:35]
	v_mfma_f32_16x16x32_bf16 v[20:23], v[208:211], v[192:195], v[20:23]
	v_mfma_f32_16x16x32_bf16 v[16:19], v[216:219], v[192:195], v[16:19]
	s_setprio 2
	s_barrier
	v_mfma_f32_16x16x32_bf16 v[4:7], v[208:211], v[200:203], v[4:7]
	v_mfma_f32_16x16x32_bf16 v[0:3], v[216:219], v[200:203], v[0:3]
	s_setprio 0
	s_add_i32 s29, 0, 0x18000
	v_add_u32_e32 v148, s29, v151
	ds_read_b128 v[144:147], v148
	ds_read_b128 v[160:163], v148 offset:1024
	ds_read_b128 v[164:167], v148 offset:2048
	ds_read_b128 v[168:171], v148 offset:3072
	s_add_u32 s12, s12, 0x40000
	s_addc_u32 s13, s13, 0
	s_mov_b32 m0, s42
	v_lshl_add_u64 v[204:205], s[12:13], 0, v[134:135]
	ds_read_b128 v[172:175], v157 offset:32768
	ds_read_b128 v[180:183], v157 offset:34816
	ds_read_b128 v[188:191], v157 offset:36864
	ds_read_b128 v[196:199], v157 offset:38912
	global_load_lds_dwordx4 v[204:205], off
	s_mov_b32 m0, s43
	v_lshl_add_u64 v[204:205], s[12:13], 0, v[130:131]
	global_load_lds_dwordx4 v[204:205], off
	s_waitcnt lgkmcnt(4)
	s_setprio 1
	s_barrier
	ds_read_b128 v[176:179], v157 offset:33792
	ds_read_b128 v[184:187], v157 offset:35840
	ds_read_b128 v[192:195], v157 offset:37888
	ds_read_b128 v[200:203], v157 offset:39936
	s_waitcnt lgkmcnt(4)
	v_mfma_f32_16x16x32_bf16 v[124:127], v[144:147], v[172:175], v[124:127]
	v_mfma_f32_16x16x32_bf16 v[120:123], v[164:167], v[172:175], v[120:123]
	v_mfma_f32_16x16x32_bf16 v[108:111], v[144:147], v[180:183], v[108:111]
	v_mfma_f32_16x16x32_bf16 v[104:107], v[164:167], v[180:183], v[104:107]
	v_mfma_f32_16x16x32_bf16 v[92:95], v[144:147], v[188:191], v[92:95]
	v_mfma_f32_16x16x32_bf16 v[88:91], v[164:167], v[188:191], v[88:91]
	v_mfma_f32_16x16x32_bf16 v[76:79], v[144:147], v[196:199], v[76:79]
	v_mfma_f32_16x16x32_bf16 v[72:75], v[164:167], v[196:199], v[72:75]
	s_waitcnt lgkmcnt(3)
	v_mfma_f32_16x16x32_bf16 v[124:127], v[160:163], v[176:179], v[124:127]
	v_mfma_f32_16x16x32_bf16 v[120:123], v[168:171], v[176:179], v[120:123]
	s_waitcnt lgkmcnt(2)
	v_mfma_f32_16x16x32_bf16 v[108:111], v[160:163], v[184:187], v[108:111]
	v_mfma_f32_16x16x32_bf16 v[104:107], v[168:171], v[184:187], v[104:107]
	s_waitcnt lgkmcnt(1)
	v_mfma_f32_16x16x32_bf16 v[92:95], v[160:163], v[192:195], v[92:95]
	v_mfma_f32_16x16x32_bf16 v[88:91], v[168:171], v[192:195], v[88:91]
	s_waitcnt lgkmcnt(0)
	s_setprio 2
	s_barrier
	v_mfma_f32_16x16x32_bf16 v[76:79], v[160:163], v[200:203], v[76:79]
	v_mfma_f32_16x16x32_bf16 v[72:75], v[168:171], v[200:203], v[72:75]
	s_setprio 0
	s_add_i32 s12, 0, 0x1c000
	s_add_i32 s13, s29, s34
	v_add_u32_e32 v148, s12, v151
	v_lshl_add_u64 v[220:221], v[220:221], 0, s[22:23]
	s_mov_b32 m0, s13
	ds_read_b128 v[204:207], v148
	ds_read_b128 v[208:211], v148 offset:1024
	ds_read_b128 v[212:215], v148 offset:2048
	ds_read_b128 v[216:219], v148 offset:3072
	global_load_lds_dwordx4 v[220:221], off
	s_add_i32 m0, s13, 0x2000
	v_lshl_add_u64 v[220:221], v[224:225], 0, s[22:23]
	global_load_lds_dwordx4 v[220:221], off
	s_setprio 1
	s_barrier
	s_waitcnt lgkmcnt(0)
	v_mfma_f32_16x16x32_bf16 v[116:119], v[204:207], v[172:175], v[116:119]
	v_mfma_f32_16x16x32_bf16 v[112:115], v[212:215], v[172:175], v[112:115]
	v_mfma_f32_16x16x32_bf16 v[100:103], v[204:207], v[180:183], v[100:103]
	v_mfma_f32_16x16x32_bf16 v[96:99], v[212:215], v[180:183], v[96:99]
	v_mfma_f32_16x16x32_bf16 v[84:87], v[204:207], v[188:191], v[84:87]
	v_mfma_f32_16x16x32_bf16 v[80:83], v[212:215], v[188:191], v[80:83]
	v_mfma_f32_16x16x32_bf16 v[68:71], v[204:207], v[196:199], v[68:71]
	v_mfma_f32_16x16x32_bf16 v[64:67], v[212:215], v[196:199], v[64:67]
	v_mfma_f32_16x16x32_bf16 v[116:119], v[208:211], v[176:179], v[116:119]
	v_mfma_f32_16x16x32_bf16 v[112:115], v[216:219], v[176:179], v[112:115]
	v_mfma_f32_16x16x32_bf16 v[100:103], v[208:211], v[184:187], v[100:103]
	v_mfma_f32_16x16x32_bf16 v[96:99], v[216:219], v[184:187], v[96:99]
	v_mfma_f32_16x16x32_bf16 v[84:87], v[208:211], v[192:195], v[84:87]
	v_mfma_f32_16x16x32_bf16 v[80:83], v[216:219], v[192:195], v[80:83]
	s_setprio 2
	s_barrier
	v_mfma_f32_16x16x32_bf16 v[68:71], v[208:211], v[200:203], v[68:71]
	v_mfma_f32_16x16x32_bf16 v[64:67], v[216:219], v[200:203], v[64:67]
	s_setprio 0
	s_mov_b32 m0, s45
	v_lshl_add_u64 v[220:221], v[226:227], 0, s[22:23]
	ds_read_b128 v[172:175], v157 offset:49152
	ds_read_b128 v[180:183], v157 offset:51200
	ds_read_b128 v[188:191], v157 offset:53248
	ds_read_b128 v[196:199], v157 offset:55296
	global_load_lds_dwordx4 v[220:221], off
	s_mov_b32 m0, s46
	v_lshl_add_u64 v[220:221], v[228:229], 0, s[22:23]
	global_load_lds_dwordx4 v[220:221], off
	s_setprio 1
	s_barrier
; #define PG8_STAGE(bufoff, gbase, voff) do { _Pragma("unroll") for (int _i = 0; _i < 2; ++_i) \
;         __builtin_amdgcn_global_load_lds((const unsigned*)((const char*)(gbase) + (voff)[_i]), (LAS unsigned*)(lds + (bufoff) + ldsw + _i * 8192), 16, 0, 0); } while (0)
; #define PG8_LDA(dst, b, h) do { _Pragma("unroll") for (int m = 0; m < 4; ++m) _Pragma("unroll") for (int k = 0; k < 2; ++k) dst[m][k] = *(const LAS bf16x8*)(lds + PG8_SA(b, h) + aoff + m * 2048 + k * 1024); } while (0)
; #define PG8_LDB(dst, b, h) do { _Pragma("unroll") for (int n = 0; n < 2; ++n) _Pragma("unroll") for (int k = 0; k < 2; ++k) dst[n][k] = *(const LAS bf16x8*)(lds + PG8_SB(b, h) + boff + n * 2048 + k * 1024); } while (0)
; #define PG8_MMA(ai, bj, At, Bt) do { __builtin_amdgcn_s_setprio(1); _Pragma("unroll") for (int m = 0; m < 4; ++m) _Pragma("unroll") for (int n = 0; n < 2; ++n) _Pragma("unroll") for (int k = 0; k < 2; ++k) \
;         acc[ai][bj][m][n] = __builtin_amdgcn_mfma_f32_16x16x32_bf16(Bt[n][k], At[m][k], acc[ai][bj][m][n], 0, 0, 0); __builtin_amdgcn_s_setprio(0); } while (0)
; #define PG8_WAIT_V(n) asm volatile("s_waitcnt vmcnt(" #n ")" ::: "memory")
; #define PG8_WAIT_L(n) asm volatile("s_waitcnt lgkmcnt(" #n ")" ::: "memory")
; #define PG8_BAR __builtin_amdgcn_s_barrier()
; #define PG8_SCHED __builtin_amdgcn_sched_barrier(0)
; #define PG8_BAR __builtin_amdgcn_s_barrier()
; DI RowScales load_rowscales(const float* ss, int row0) {
;     RowScales t;
; #pragma unroll
;     for (int ai = 0; ai < 2; ++ai)
; #pragma unroll
;         for (int m = 0; m < 4; ++m) t.r[ai][m] = ss[row0 + ai * 128 + m * 16];
; #pragma unroll
;     for (int ai = 0; ai < 2; ++ai)
; #pragma unroll
;         for (int m = 0; m < 4; ++m) t.r[ai][m] = rsqrtf(t.r[ai][m] * (1.0f / 1024.0f) + 1e-6f);
; template <class Epi>
; DI void gemm_phase(LAS unsigned char* lds, const Gemm g, const StaticOrder S, const Epi E) {
;     ...
;             PG8_LDB(B1, 1, 1); PG8_STAGE(PG8_SB(1, 0), b3, voffB);
;             PG8_BAR; PG8_WAIT_L(0); PG8_MMA(0, 1, At, B1); PG8_BAR;
;             PG8_LDA(At, 1, 1); PG8_STAGE(PG8_SA(1, 0), a3, voffA);
;             PG8_BAR; PG8_WAIT_L(0); PG8_MMA(1, 0, At, B0); PG8_BAR; PG8_SCHED;
;             PG8_STAGE(PG8_SB(1, 1), b3 + hstep, voffB);
;             PG8_WAIT_V(6); PG8_BAR; PG8_MMA(1, 1, At, B1); PG8_BAR;
;         }
;         E(acc, cur, wr, wc, fr, fq);
	ds_read_b128 v[176:179], v157 offset:50176
	ds_read_b128 v[184:187], v157 offset:52224
	ds_read_b128 v[192:195], v157 offset:54272
	ds_read_b128 v[200:203], v157 offset:56320
	s_waitcnt lgkmcnt(4)
	v_mfma_f32_16x16x32_bf16 v[60:63], v[144:147], v[172:175], v[60:63]
	v_mfma_f32_16x16x32_bf16 v[56:59], v[164:167], v[172:175], v[56:59]
	v_mfma_f32_16x16x32_bf16 v[44:47], v[144:147], v[180:183], v[44:47]
	v_mfma_f32_16x16x32_bf16 v[40:43], v[164:167], v[180:183], v[40:43]
	v_mfma_f32_16x16x32_bf16 v[28:31], v[144:147], v[188:191], v[28:31]
	v_mfma_f32_16x16x32_bf16 v[24:27], v[164:167], v[188:191], v[24:27]
	v_mfma_f32_16x16x32_bf16 v[12:15], v[144:147], v[196:199], v[12:15]
	v_mfma_f32_16x16x32_bf16 v[8:11], v[164:167], v[196:199], v[8:11]
	s_waitcnt lgkmcnt(3)
	v_mfma_f32_16x16x32_bf16 v[60:63], v[160:163], v[176:179], v[60:63]
	v_mfma_f32_16x16x32_bf16 v[56:59], v[168:171], v[176:179], v[56:59]
	s_waitcnt lgkmcnt(2)
	v_mfma_f32_16x16x32_bf16 v[44:47], v[160:163], v[184:187], v[44:47]
	v_mfma_f32_16x16x32_bf16 v[40:43], v[168:171], v[184:187], v[40:43]
	s_waitcnt lgkmcnt(1)
	v_mfma_f32_16x16x32_bf16 v[28:31], v[160:163], v[192:195], v[28:31]
	v_mfma_f32_16x16x32_bf16 v[24:27], v[168:171], v[192:195], v[24:27]
	s_waitcnt lgkmcnt(0)
	s_setprio 2
	s_barrier
	v_mfma_f32_16x16x32_bf16 v[12:15], v[160:163], v[200:203], v[12:15]
	v_mfma_f32_16x16x32_bf16 v[8:11], v[168:171], v[200:203], v[8:11]
	s_setprio 0
	s_add_u32 s10, s10, 0x40080
	s_addc_u32 s11, s11, 0
	s_add_i32 s12, s12, s34
	s_mov_b32 m0, s12
	v_lshl_add_u64 v[144:145], s[10:11], 0, v[132:133]
	global_load_lds_dwordx4 v[144:145], off
	s_add_i32 m0, s12, 0x2000
	v_lshl_add_u64 v[144:145], s[10:11], 0, v[128:129]
	global_load_lds_dwordx4 v[144:145], off
	s_waitcnt vmcnt(6)
	s_setprio 1
	s_barrier
	v_mfma_f32_16x16x32_bf16 v[52:55], v[204:207], v[172:175], v[52:55]
	v_mfma_f32_16x16x32_bf16 v[48:51], v[212:215], v[172:175], v[48:51]
	v_mfma_f32_16x16x32_bf16 v[36:39], v[204:207], v[180:183], v[36:39]
	v_mfma_f32_16x16x32_bf16 v[32:35], v[212:215], v[180:183], v[32:35]
	v_mfma_f32_16x16x32_bf16 v[20:23], v[204:207], v[188:191], v[20:23]
	v_mfma_f32_16x16x32_bf16 v[16:19], v[212:215], v[188:191], v[16:19]
	v_mfma_f32_16x16x32_bf16 v[4:7], v[204:207], v[196:199], v[4:7]
	v_mfma_f32_16x16x32_bf16 v[0:3], v[212:215], v[196:199], v[0:3]
	v_mfma_f32_16x16x32_bf16 v[52:55], v[208:211], v[176:179], v[52:55]
	v_mfma_f32_16x16x32_bf16 v[48:51], v[216:219], v[176:179], v[48:51]
	v_mfma_f32_16x16x32_bf16 v[36:39], v[208:211], v[184:187], v[36:39]
	v_mfma_f32_16x16x32_bf16 v[32:35], v[216:219], v[184:187], v[32:35]
	v_mfma_f32_16x16x32_bf16 v[20:23], v[208:211], v[192:195], v[20:23]
	v_mfma_f32_16x16x32_bf16 v[16:19], v[216:219], v[192:195], v[16:19]
	s_setprio 2
	s_barrier
	v_mfma_f32_16x16x32_bf16 v[4:7], v[208:211], v[200:203], v[4:7]
	v_mfma_f32_16x16x32_bf16 v[0:3], v[216:219], v[200:203], v[0:3]
	s_setprio 0
	s_add_i32 s25, s25, 2
	s_add_u32 s8, s8, 0x100
	s_addc_u32 s9, s9, 0
	s_add_u32 s18, s18, 0x100
	s_addc_u32 s19, s19, 0
	s_cmp_gt_u32 s25, 13
	s_cbranch_scc0 .LBB0_865
	v_lshl_add_u32 v146, s4, 8, v149
	v_ashrrev_i32_e32 v147, 31, v146
	v_lshl_add_u64 v[144:145], v[146:147], 2, s[20:21]
	global_load_dword v147, v[144:145], off
	global_load_dword v148, v[144:145], off offset:64
	global_load_dword v150, v[144:145], off offset:128
	global_load_dword v152, v[144:145], off offset:192
	global_load_dword v154, v[144:145], off offset:512
	global_load_dword v156, v[144:145], off offset:576
	global_load_dword v160, v[144:145], off offset:640
	global_load_dword v161, v[144:145], off offset:704
	v_lshl_or_b32 v144, s5, 7, v153
	v_ashrrev_i32_e32 v145, 31, v144
	v_lshl_add_u64 v[144:145], v[144:145], 1, s[54:55]
	s_waitcnt vmcnt(0)
	v_fmamk_f32 v147, v147, 0x3a800000, v159
	v_mul_f32_e32 v162, 0x4b800000, v147
	v_cmp_gt_f32_e32 vcc, s51, v147
	v_fmamk_f32 v152, v152, 0x3a800000, v159
	v_fmamk_f32 v154, v154, 0x3a800000, v159
	v_cndmask_b32_e32 v147, v147, v162, vcc
	v_mul_f32_e32 v165, 0x4b800000, v152
	v_fmamk_f32 v161, v161, 0x3a800000, v159
	v_mul_f32_e32 v166, 0x4b800000, v154
	v_mul_f32_e32 v169, 0x4b800000, v161
	v_cmp_gt_f32_e64 s[10:11], s51, v152
	v_cmp_gt_f32_e64 s[12:13], s51, v154
	v_cmp_gt_f32_e64 s[18:19], s51, v161
	v_rsq_f32_e32 v147, v147
	v_fmamk_f32 v156, v156, 0x3a800000, v159
	v_cndmask_b32_e64 v152, v152, v165, s[10:11]
	v_cndmask_b32_e64 v154, v154, v166, s[12:13]
	v_cndmask_b32_e64 v161, v161, v169, s[18:19]
	v_fmamk_f32 v148, v148, 0x3a800000, v159
	v_fmamk_f32 v160, v160, 0x3a800000, v159
	v_mul_f32_e32 v167, 0x4b800000, v156
	v_cmp_gt_f32_e64 s[14:15], s51, v156
	v_rsq_f32_e32 v152, v152
	v_rsq_f32_e32 v154, v154
	v_rsq_f32_e32 v161, v161
	v_mul_f32_e32 v163, 0x4b800000, v148
	v_mul_f32_e32 v168, 0x4b800000, v160
	v_cmp_gt_f32_e64 s[4:5], s51, v148
	v_cndmask_b32_e64 v156, v156, v167, s[14:15]
	v_cmp_gt_f32_e64 s[16:17], s51, v160
	v_fmamk_f32 v150, v150, 0x3a800000, v159
	v_cndmask_b32_e64 v148, v148, v163, s[4:5]
	v_cndmask_b32_e64 v160, v160, v168, s[16:17]
	v_rsq_f32_e32 v163, v156
	v_mul_f32_e32 v156, 0x45800000, v147
	v_mul_f32_e32 v164, 0x4b800000, v150
	v_cmp_gt_f32_e64 s[8:9], s51, v150
	v_rsq_f32_e32 v165, v160
	v_cndmask_b32_e32 v160, v147, v156, vcc
	v_cndmask_b32_e64 v150, v150, v164, s[8:9]
	v_rsq_f32_e32 v148, v148
	v_mul_f32_e32 v166, 0x45800000, v152
	v_mul_f32_e32 v167, 0x45800000, v154
	v_pk_mul_f32 v[126:127], v[126:127], v[160:161] op_sel_hi:[1,0]
	v_pk_mul_f32 v[124:125], v[124:125], v[160:161] op_sel_hi:[1,0]
	v_rsq_f32_e32 v150, v150
	v_cndmask_b32_e64 v156, v152, v166, s[10:11]
	v_cndmask_b32_e64 v154, v154, v167, s[12:13]
; DI unsigned pk_bf16(float lo, float hi) { f32x2 v = {lo, hi}; return __builtin_bit_cast(unsigned, __builtin_convertvector(v, bf16v2)); }
; DI float fast_sigmoid(float x) { return __builtin_amdgcn_rcpf(1.0f + __expf(-x)); }
; DI float fast_silu(float x) { return x * fast_sigmoid(x); }
;     DI void operator()(AccRef acc, const Unit& u, int wr, int wc, int fr, int fq) const {
;     ...
; #pragma unroll
;         for (int ai = 0; ai < 2; ++ai)
; #pragma unroll
;             for (int m = 0; m < 4; ++m) {
;                 const int row = row0 + ai * 128 + m * 16;
;                 const float r = RS ? rsc.r[ai][m] : 1.0f;
;                 const f32x4 a0 = acc[ai][0][m][0] * r, a1 = acc[ai][0][m][1] * r, b0 = acc[ai][1][m][0] * r, b1 = acc[ai][1][m][1] * r;
;                 u32x4 w;
;                 w.x = pk_bf16(fast_silu(a0[0]) * b0[0], fast_silu(a0[1]) * b0[1]); w.y = pk_bf16(fast_silu(a0[2]) * b0[2], fast_silu(a0[3]) * b0[3]);
;                 w.z = pk_bf16(fast_silu(a1[0]) * b1[0], fast_silu(a1[1]) * b1[1]); w.w = pk_bf16(fast_silu(a1[2]) * b1[2], fast_silu(a1[3]) * b1[3]);
;                 *(u32x4*)(G + (size_t)row * DFF + col) = w;
	v_pk_mul_f32 v[122:123], v[122:123], v[160:161] op_sel_hi:[1,0]
	v_pk_mul_f32 v[120:121], v[120:121], v[160:161] op_sel_hi:[1,0]
	v_pk_mul_f32 v[118:119], v[118:119], v[160:161] op_sel_hi:[1,0]
	v_pk_mul_f32 v[116:117], v[116:117], v[160:161] op_sel_hi:[1,0]
	v_pk_mul_f32 v[166:167], v[114:115], v[160:161] op_sel_hi:[1,0]
	v_pk_mul_f32 v[114:115], v[112:113], v[160:161] op_sel_hi:[1,0]
	v_mul_f32_e32 v112, 0xbfb8aa3b, v124
	v_mul_f32_e32 v113, 0xbfb8aa3b, v125
	v_mul_f32_e32 v147, 0xbfb8aa3b, v126
	v_mul_f32_e32 v160, 0xbfb8aa3b, v127
	v_exp_f32_e32 v112, v112
	v_exp_f32_e32 v113, v113
	v_exp_f32_e32 v147, v147
	v_exp_f32_e32 v160, v160
	v_mul_f32_e32 v162, 0x45800000, v148
	v_mul_f32_e32 v170, 0x45800000, v161
	v_mul_f32_e32 v164, 0x45800000, v150
	v_mul_f32_e32 v169, 0x45800000, v165
	v_cndmask_b32_e64 v162, v148, v162, s[4:5]
	v_cndmask_b32_e64 v148, v161, v170, s[18:19]
	v_mul_f32_e32 v161, 0xbfb8aa3b, v120
	v_cndmask_b32_e64 v164, v150, v164, s[8:9]
	v_cndmask_b32_e64 v150, v165, v169, s[16:17]
	v_exp_f32_e32 v165, v161
	v_add_f32_e32 v112, 1.0, v112
	v_add_f32_e32 v113, 1.0, v113
	v_add_f32_e32 v147, 1.0, v147
	v_add_f32_e32 v161, 1.0, v160
	v_rcp_f32_e32 v112, v112
	v_rcp_f32_e32 v113, v113
	v_rcp_f32_e32 v160, v147
	v_rcp_f32_e32 v161, v161
	v_mul_f32_e32 v168, 0x45800000, v163
	v_pk_mul_f32 v[112:113], v[124:125], v[112:113]
	v_cndmask_b32_e64 v152, v163, v168, s[14:15]
	v_pk_mul_f32 v[124:125], v[126:127], v[160:161]
	v_mul_f32_e32 v163, 0xbfb8aa3b, v121
	v_pk_mul_f32 v[112:113], v[116:117], v[112:113]
	v_pk_mul_f32 v[116:117], v[118:119], v[124:125]
	v_exp_f32_e32 v163, v163
	v_cvt_pk_bf16_f32 v112, v112, v113
	v_cvt_pk_bf16_f32 v113, v116, v117
	v_mul_f32_e32 v117, 0xbfb8aa3b, v122
	v_mul_f32_e32 v118, 0xbfb8aa3b, v123
	v_exp_f32_e32 v117, v117
	v_exp_f32_e32 v118, v118
	v_add_f32_e32 v116, 1.0, v163
	v_add_f32_e32 v147, 1.0, v165
	v_rcp_f32_e32 v169, v116
	v_add_f32_e32 v116, 1.0, v117
	v_add_f32_e32 v117, 1.0, v118
	v_rcp_f32_e32 v168, v147
	v_rcp_f32_e32 v116, v116
	v_rcp_f32_e32 v117, v117
	v_pk_mul_f32 v[108:109], v[108:109], v[162:163] op_sel_hi:[1,0]
	v_pk_mul_f32 v[118:119], v[120:121], v[168:169]
	v_pk_mul_f32 v[110:111], v[110:111], v[162:163] op_sel_hi:[1,0]
	v_pk_mul_f32 v[116:117], v[122:123], v[116:117]
	v_pk_mul_f32 v[114:115], v[114:115], v[118:119]
	v_pk_mul_f32 v[116:117], v[166:167], v[116:117]
	v_cvt_pk_bf16_f32 v114, v114, v115
	v_cvt_pk_bf16_f32 v115, v116, v117
	v_mad_i64_i32 v[116:117], s[4:5], v146, s52, v[144:145]
	global_store_dwordx4 v[116:117], v[112:115], off
	v_pk_mul_f32 v[100:101], v[100:101], v[162:163] op_sel_hi:[1,0]
	v_pk_mul_f32 v[104:105], v[104:105], v[162:163] op_sel_hi:[1,0]
	v_pk_mul_f32 v[112:113], v[98:99], v[162:163] op_sel_hi:[1,0]
	v_mul_f32_e32 v98, 0xbfb8aa3b, v108
	v_exp_f32_e32 v114, v98
	v_mul_f32_e32 v98, 0xbfb8aa3b, v109
	v_exp_f32_e32 v115, v98
	v_pk_mul_f32 v[98:99], v[96:97], v[162:163] op_sel_hi:[1,0]
	v_add_f32_e32 v96, 1.0, v114
	v_mul_f32_e32 v114, 0xbfb8aa3b, v110
	v_add_f32_e32 v97, 1.0, v115
	v_mul_f32_e32 v115, 0xbfb8aa3b, v111
	v_exp_f32_e32 v114, v114
	v_exp_f32_e32 v115, v115
	v_rcp_f32_e32 v96, v96
	v_rcp_f32_e32 v97, v97
	v_add_f32_e32 v114, 1.0, v114
	v_add_f32_e32 v115, 1.0, v115
	v_rcp_f32_e32 v114, v114
	v_rcp_f32_e32 v115, v115
	v_pk_mul_f32 v[96:97], v[108:109], v[96:97]
	v_pk_mul_f32 v[102:103], v[102:103], v[162:163] op_sel_hi:[1,0]
	v_pk_mul_f32 v[96:97], v[100:101], v[96:97]
	v_pk_mul_f32 v[100:101], v[110:111], v[114:115]
	v_cvt_pk_bf16_f32 v96, v96, v97
	v_mul_f32_e32 v97, 0xbfb8aa3b, v104
	v_pk_mul_f32 v[100:101], v[102:103], v[100:101]
	v_exp_f32_e32 v102, v97
	v_mul_f32_e32 v97, 0xbfb8aa3b, v105
	v_exp_f32_e32 v103, v97
	v_pk_mul_f32 v[106:107], v[106:107], v[162:163] op_sel_hi:[1,0]
	v_cvt_pk_bf16_f32 v97, v100, v101
	v_add_f32_e32 v100, 1.0, v102
	v_add_f32_e32 v101, 1.0, v103
	v_mul_f32_e32 v102, 0xbfb8aa3b, v106
	v_mul_f32_e32 v103, 0xbfb8aa3b, v107
	v_exp_f32_e32 v102, v102
	v_exp_f32_e32 v103, v103
	v_rcp_f32_e32 v100, v100
	v_rcp_f32_e32 v101, v101
	v_add_f32_e32 v102, 1.0, v102
	v_add_f32_e32 v103, 1.0, v103
	v_rcp_f32_e32 v102, v102
	v_rcp_f32_e32 v103, v103
	v_pk_mul_f32 v[100:101], v[104:105], v[100:101]
	v_or_b32_e32 v116, 16, v146
	v_pk_mul_f32 v[98:99], v[98:99], v[100:101]
	v_pk_mul_f32 v[100:101], v[106:107], v[102:103]
	v_cvt_pk_bf16_f32 v98, v98, v99
	v_pk_mul_f32 v[100:101], v[112:113], v[100:101]
	v_pk_mul_f32 v[92:93], v[92:93], v[164:165] op_sel_hi:[1,0]
	v_cvt_pk_bf16_f32 v99, v100, v101
	v_mad_i64_i32 v[100:101], s[4:5], v116, s52, v[144:145]
	global_store_dwordx4 v[100:101], v[96:99], off
	v_pk_mul_f32 v[94:95], v[94:95], v[164:165] op_sel_hi:[1,0]
	v_pk_mul_f32 v[84:85], v[84:85], v[164:165] op_sel_hi:[1,0]
	v_pk_mul_f32 v[96:97], v[82:83], v[164:165] op_sel_hi:[1,0]
	v_mul_f32_e32 v82, 0xbfb8aa3b, v92
	v_exp_f32_e32 v98, v82
	v_mul_f32_e32 v82, 0xbfb8aa3b, v93
	v_exp_f32_e32 v99, v82
	v_pk_mul_f32 v[82:83], v[80:81], v[164:165] op_sel_hi:[1,0]
	v_add_f32_e32 v80, 1.0, v98
	v_mul_f32_e32 v98, 0xbfb8aa3b, v94
	v_add_f32_e32 v81, 1.0, v99
	v_mul_f32_e32 v99, 0xbfb8aa3b, v95
	v_exp_f32_e32 v98, v98
	v_exp_f32_e32 v99, v99
	v_rcp_f32_e32 v80, v80
	v_rcp_f32_e32 v81, v81
	v_add_f32_e32 v98, 1.0, v98
	v_add_f32_e32 v99, 1.0, v99
	v_rcp_f32_e32 v98, v98
	v_rcp_f32_e32 v99, v99
	v_pk_mul_f32 v[80:81], v[92:93], v[80:81]
	v_pk_mul_f32 v[88:89], v[88:89], v[164:165] op_sel_hi:[1,0]
	v_pk_mul_f32 v[80:81], v[84:85], v[80:81]
	v_pk_mul_f32 v[86:87], v[86:87], v[164:165] op_sel_hi:[1,0]
	v_cvt_pk_bf16_f32 v80, v80, v81
	v_pk_mul_f32 v[84:85], v[94:95], v[98:99]
	v_mul_f32_e32 v81, 0xbfb8aa3b, v88
	v_pk_mul_f32 v[84:85], v[86:87], v[84:85]
; DI unsigned pk_bf16(float lo, float hi) { f32x2 v = {lo, hi}; return __builtin_bit_cast(unsigned, __builtin_convertvector(v, bf16v2)); }
; DI float fast_sigmoid(float x) { return __builtin_amdgcn_rcpf(1.0f + __expf(-x)); }
; DI float fast_silu(float x) { return x * fast_sigmoid(x); }
;     DI void operator()(AccRef acc, const Unit& u, int wr, int wc, int fr, int fq) const {
;     ...
; #pragma unroll
;         for (int ai = 0; ai < 2; ++ai)
; #pragma unroll
;             for (int m = 0; m < 4; ++m) {
;                 const int row = row0 + ai * 128 + m * 16;
;                 const float r = RS ? rsc.r[ai][m] : 1.0f;
;                 const f32x4 a0 = acc[ai][0][m][0] * r, a1 = acc[ai][0][m][1] * r, b0 = acc[ai][1][m][0] * r, b1 = acc[ai][1][m][1] * r;
;                 u32x4 w;
;                 w.x = pk_bf16(fast_silu(a0[0]) * b0[0], fast_silu(a0[1]) * b0[1]); w.y = pk_bf16(fast_silu(a0[2]) * b0[2], fast_silu(a0[3]) * b0[3]);
;                 w.z = pk_bf16(fast_silu(a1[0]) * b1[0], fast_silu(a1[1]) * b1[1]); w.w = pk_bf16(fast_silu(a1[2]) * b1[2], fast_silu(a1[3]) * b1[3]);
;                 *(u32x4*)(G + (size_t)row * DFF + col) = w;
	v_exp_f32_e32 v86, v81
	v_mul_f32_e32 v81, 0xbfb8aa3b, v89
	v_exp_f32_e32 v87, v81
	v_pk_mul_f32 v[90:91], v[90:91], v[164:165] op_sel_hi:[1,0]
	v_cvt_pk_bf16_f32 v81, v84, v85
	v_add_f32_e32 v84, 1.0, v86
	v_add_f32_e32 v85, 1.0, v87
	v_mul_f32_e32 v86, 0xbfb8aa3b, v90
	v_mul_f32_e32 v87, 0xbfb8aa3b, v91
	v_exp_f32_e32 v86, v86
	v_exp_f32_e32 v87, v87
	v_rcp_f32_e32 v84, v84
	v_rcp_f32_e32 v85, v85
	v_add_f32_e32 v86, 1.0, v86
	v_add_f32_e32 v87, 1.0, v87
	v_rcp_f32_e32 v86, v86
	v_rcp_f32_e32 v87, v87
	v_pk_mul_f32 v[84:85], v[88:89], v[84:85]
	v_or_b32_e32 v100, 32, v146
	v_pk_mul_f32 v[82:83], v[82:83], v[84:85]
	v_pk_mul_f32 v[84:85], v[90:91], v[86:87]
	v_cvt_pk_bf16_f32 v82, v82, v83
	v_pk_mul_f32 v[84:85], v[96:97], v[84:85]
	v_pk_mul_f32 v[76:77], v[76:77], v[156:157] op_sel_hi:[1,0]
	v_cvt_pk_bf16_f32 v83, v84, v85
	v_mad_i64_i32 v[84:85], s[4:5], v100, s52, v[144:145]
	global_store_dwordx4 v[84:85], v[80:83], off
	v_pk_mul_f32 v[78:79], v[78:79], v[156:157] op_sel_hi:[1,0]
	v_pk_mul_f32 v[68:69], v[68:69], v[156:157] op_sel_hi:[1,0]
	v_pk_mul_f32 v[80:81], v[66:67], v[156:157] op_sel_hi:[1,0]
	v_mul_f32_e32 v66, 0xbfb8aa3b, v76
	v_exp_f32_e32 v82, v66
	v_mul_f32_e32 v66, 0xbfb8aa3b, v77
	v_exp_f32_e32 v83, v66
	v_pk_mul_f32 v[66:67], v[64:65], v[156:157] op_sel_hi:[1,0]
	v_add_f32_e32 v64, 1.0, v82
	v_mul_f32_e32 v82, 0xbfb8aa3b, v78
	v_add_f32_e32 v65, 1.0, v83
	v_mul_f32_e32 v83, 0xbfb8aa3b, v79
	v_exp_f32_e32 v82, v82
	v_exp_f32_e32 v83, v83
	v_rcp_f32_e32 v64, v64
	v_rcp_f32_e32 v65, v65
	v_add_f32_e32 v82, 1.0, v82
	v_add_f32_e32 v83, 1.0, v83
	v_rcp_f32_e32 v82, v82
	v_rcp_f32_e32 v83, v83
	v_pk_mul_f32 v[64:65], v[76:77], v[64:65]
	v_pk_mul_f32 v[72:73], v[72:73], v[156:157] op_sel_hi:[1,0]
	v_pk_mul_f32 v[64:65], v[68:69], v[64:65]
	v_pk_mul_f32 v[70:71], v[70:71], v[156:157] op_sel_hi:[1,0]
	v_cvt_pk_bf16_f32 v64, v64, v65
	v_pk_mul_f32 v[68:69], v[78:79], v[82:83]
	v_mul_f32_e32 v65, 0xbfb8aa3b, v72
	v_pk_mul_f32 v[68:69], v[70:71], v[68:69]
	v_exp_f32_e32 v70, v65
	v_mul_f32_e32 v65, 0xbfb8aa3b, v73
	v_exp_f32_e32 v71, v65
	v_pk_mul_f32 v[74:75], v[74:75], v[156:157] op_sel_hi:[1,0]
	v_cvt_pk_bf16_f32 v65, v68, v69
	v_add_f32_e32 v68, 1.0, v70
	v_add_f32_e32 v69, 1.0, v71
	v_mul_f32_e32 v70, 0xbfb8aa3b, v74
	v_mul_f32_e32 v71, 0xbfb8aa3b, v75
	v_exp_f32_e32 v70, v70
	v_exp_f32_e32 v71, v71
	v_rcp_f32_e32 v68, v68
	v_rcp_f32_e32 v69, v69
	v_add_f32_e32 v70, 1.0, v70
	v_add_f32_e32 v71, 1.0, v71
	v_rcp_f32_e32 v70, v70
	v_rcp_f32_e32 v71, v71
	v_pk_mul_f32 v[68:69], v[72:73], v[68:69]
	v_or_b32_e32 v84, 48, v146
	v_pk_mul_f32 v[66:67], v[66:67], v[68:69]
	v_pk_mul_f32 v[68:69], v[74:75], v[70:71]
	v_cvt_pk_bf16_f32 v66, v66, v67
	v_pk_mul_f32 v[68:69], v[80:81], v[68:69]
	v_pk_mul_f32 v[60:61], v[60:61], v[154:155] op_sel_hi:[1,0]
	v_cvt_pk_bf16_f32 v67, v68, v69
	v_mad_i64_i32 v[68:69], s[4:5], v84, s52, v[144:145]
	global_store_dwordx4 v[68:69], v[64:67], off
	v_pk_mul_f32 v[62:63], v[62:63], v[154:155] op_sel_hi:[1,0]
	v_pk_mul_f32 v[52:53], v[52:53], v[154:155] op_sel_hi:[1,0]
	v_pk_mul_f32 v[64:65], v[50:51], v[154:155] op_sel_hi:[1,0]
	v_mul_f32_e32 v50, 0xbfb8aa3b, v60
	v_exp_f32_e32 v66, v50
	v_mul_f32_e32 v50, 0xbfb8aa3b, v61
	v_exp_f32_e32 v67, v50
	v_pk_mul_f32 v[50:51], v[48:49], v[154:155] op_sel_hi:[1,0]
	v_add_f32_e32 v48, 1.0, v66
	v_mul_f32_e32 v66, 0xbfb8aa3b, v62
	v_add_f32_e32 v49, 1.0, v67
	v_mul_f32_e32 v67, 0xbfb8aa3b, v63
	v_exp_f32_e32 v66, v66
	v_exp_f32_e32 v67, v67
	v_rcp_f32_e32 v48, v48
	v_rcp_f32_e32 v49, v49
	v_add_f32_e32 v66, 1.0, v66
	v_add_f32_e32 v67, 1.0, v67
	v_rcp_f32_e32 v66, v66
	v_rcp_f32_e32 v67, v67
	v_pk_mul_f32 v[48:49], v[60:61], v[48:49]
	v_pk_mul_f32 v[56:57], v[56:57], v[154:155] op_sel_hi:[1,0]
	v_pk_mul_f32 v[48:49], v[52:53], v[48:49]
	v_pk_mul_f32 v[54:55], v[54:55], v[154:155] op_sel_hi:[1,0]
	v_cvt_pk_bf16_f32 v48, v48, v49
	v_pk_mul_f32 v[52:53], v[62:63], v[66:67]
	v_mul_f32_e32 v49, 0xbfb8aa3b, v56
	v_pk_mul_f32 v[52:53], v[54:55], v[52:53]
	v_exp_f32_e32 v54, v49
	v_mul_f32_e32 v49, 0xbfb8aa3b, v57
	v_exp_f32_e32 v55, v49
	v_pk_mul_f32 v[58:59], v[58:59], v[154:155] op_sel_hi:[1,0]
	v_cvt_pk_bf16_f32 v49, v52, v53
	v_add_f32_e32 v52, 1.0, v54
	v_add_f32_e32 v53, 1.0, v55
	v_mul_f32_e32 v54, 0xbfb8aa3b, v58
	v_mul_f32_e32 v55, 0xbfb8aa3b, v59
	v_exp_f32_e32 v54, v54
	v_exp_f32_e32 v55, v55
	v_rcp_f32_e32 v52, v52
	v_rcp_f32_e32 v53, v53
	v_add_f32_e32 v54, 1.0, v54
	v_add_f32_e32 v55, 1.0, v55
	v_rcp_f32_e32 v54, v54
	v_rcp_f32_e32 v55, v55
	v_pk_mul_f32 v[52:53], v[56:57], v[52:53]
	v_add_u32_e32 v68, 0x80, v146
	v_pk_mul_f32 v[50:51], v[50:51], v[52:53]
	v_pk_mul_f32 v[52:53], v[58:59], v[54:55]
	v_cvt_pk_bf16_f32 v50, v50, v51
	v_pk_mul_f32 v[52:53], v[64:65], v[52:53]
	v_pk_mul_f32 v[44:45], v[44:45], v[152:153] op_sel_hi:[1,0]
	v_cvt_pk_bf16_f32 v51, v52, v53
	v_mad_i64_i32 v[52:53], s[4:5], v68, s52, v[144:145]
	global_store_dwordx4 v[52:53], v[48:51], off
	v_pk_mul_f32 v[46:47], v[46:47], v[152:153] op_sel_hi:[1,0]
	v_pk_mul_f32 v[36:37], v[36:37], v[152:153] op_sel_hi:[1,0]
	v_pk_mul_f32 v[48:49], v[34:35], v[152:153] op_sel_hi:[1,0]
	v_mul_f32_e32 v34, 0xbfb8aa3b, v44
	v_exp_f32_e32 v50, v34
	v_mul_f32_e32 v34, 0xbfb8aa3b, v45
	v_exp_f32_e32 v51, v34
	v_pk_mul_f32 v[34:35], v[32:33], v[152:153] op_sel_hi:[1,0]
	v_add_f32_e32 v32, 1.0, v50
	v_mul_f32_e32 v50, 0xbfb8aa3b, v46
	v_add_f32_e32 v33, 1.0, v51
	v_mul_f32_e32 v51, 0xbfb8aa3b, v47
	v_exp_f32_e32 v50, v50
	v_exp_f32_e32 v51, v51
	v_rcp_f32_e32 v32, v32
; DI unsigned pk_bf16(float lo, float hi) { f32x2 v = {lo, hi}; return __builtin_bit_cast(unsigned, __builtin_convertvector(v, bf16v2)); }
; DI float fast_silu(float x) { return x * fast_sigmoid(x); }
; #define PG8_WAIT_V(n) asm volatile("s_waitcnt vmcnt(" #n ")" ::: "memory")
; #define PG8_BAR __builtin_amdgcn_s_barrier()
; #define PG8_WAIT_V(n) asm volatile("s_waitcnt vmcnt(" #n ")" ::: "memory")
; #define PG8_BAR __builtin_amdgcn_s_barrier()
; template <class Epi>
; DI void gemm_phase(LAS unsigned char* lds, const Gemm g, const StaticOrder S, const Epi E) {
;     ...
;         cur = nxt; cA = nA; cB = nB; ++ui;
;     }
;     PG8_WAIT_V(0);
;     if (wr == 0) PG8_BAR;
;     PG8_BAR;
;     DI void operator()(AccRef acc, const Unit& u, int wr, int wc, int fr, int fq) const {
;     ...
; #pragma unroll
;         for (int ai = 0; ai < 2; ++ai)
; #pragma unroll
;             for (int m = 0; m < 4; ++m) {
;                 const int row = row0 + ai * 128 + m * 16;
;                 const float r = RS ? rsc.r[ai][m] : 1.0f;
;                 const f32x4 a0 = acc[ai][0][m][0] * r, a1 = acc[ai][0][m][1] * r, b0 = acc[ai][1][m][0] * r, b1 = acc[ai][1][m][1] * r;
;                 u32x4 w;
;                 w.x = pk_bf16(fast_silu(a0[0]) * b0[0], fast_silu(a0[1]) * b0[1]); w.y = pk_bf16(fast_silu(a0[2]) * b0[2], fast_silu(a0[3]) * b0[3]);
;                 w.z = pk_bf16(fast_silu(a1[0]) * b1[0], fast_silu(a1[1]) * b1[1]); w.w = pk_bf16(fast_silu(a1[2]) * b1[2], fast_silu(a1[3]) * b1[3]);
;                 *(u32x4*)(G + (size_t)row * DFF + col) = w;
	v_rcp_f32_e32 v33, v33
	v_add_f32_e32 v50, 1.0, v50
	v_add_f32_e32 v51, 1.0, v51
	v_rcp_f32_e32 v50, v50
	v_rcp_f32_e32 v51, v51
	v_pk_mul_f32 v[32:33], v[44:45], v[32:33]
	v_pk_mul_f32 v[40:41], v[40:41], v[152:153] op_sel_hi:[1,0]
	v_pk_mul_f32 v[32:33], v[36:37], v[32:33]
	v_pk_mul_f32 v[38:39], v[38:39], v[152:153] op_sel_hi:[1,0]
	v_cvt_pk_bf16_f32 v32, v32, v33
	v_pk_mul_f32 v[36:37], v[46:47], v[50:51]
	v_mul_f32_e32 v33, 0xbfb8aa3b, v40
	v_pk_mul_f32 v[36:37], v[38:39], v[36:37]
	v_exp_f32_e32 v38, v33
	v_mul_f32_e32 v33, 0xbfb8aa3b, v41
	v_exp_f32_e32 v39, v33
	v_pk_mul_f32 v[42:43], v[42:43], v[152:153] op_sel_hi:[1,0]
	v_cvt_pk_bf16_f32 v33, v36, v37
	v_add_f32_e32 v36, 1.0, v38
	v_add_f32_e32 v37, 1.0, v39
	v_mul_f32_e32 v38, 0xbfb8aa3b, v42
	v_mul_f32_e32 v39, 0xbfb8aa3b, v43
	v_exp_f32_e32 v38, v38
	v_exp_f32_e32 v39, v39
	v_rcp_f32_e32 v36, v36
	v_rcp_f32_e32 v37, v37
	v_add_f32_e32 v38, 1.0, v38
	v_add_f32_e32 v39, 1.0, v39
	v_rcp_f32_e32 v38, v38
	v_rcp_f32_e32 v39, v39
	v_pk_mul_f32 v[36:37], v[40:41], v[36:37]
	v_add_u32_e32 v52, 0x90, v146
	v_pk_mul_f32 v[34:35], v[34:35], v[36:37]
	v_pk_mul_f32 v[36:37], v[42:43], v[38:39]
	v_cvt_pk_bf16_f32 v34, v34, v35
	v_pk_mul_f32 v[36:37], v[48:49], v[36:37]
	v_pk_mul_f32 v[28:29], v[28:29], v[150:151] op_sel_hi:[1,0]
	v_cvt_pk_bf16_f32 v35, v36, v37
	v_mad_i64_i32 v[36:37], s[4:5], v52, s52, v[144:145]
	global_store_dwordx4 v[36:37], v[32:35], off
	v_pk_mul_f32 v[30:31], v[30:31], v[150:151] op_sel_hi:[1,0]
	v_pk_mul_f32 v[20:21], v[20:21], v[150:151] op_sel_hi:[1,0]
	v_pk_mul_f32 v[32:33], v[18:19], v[150:151] op_sel_hi:[1,0]
	v_mul_f32_e32 v18, 0xbfb8aa3b, v28
	v_exp_f32_e32 v34, v18
	v_mul_f32_e32 v18, 0xbfb8aa3b, v29
	v_exp_f32_e32 v35, v18
	v_pk_mul_f32 v[18:19], v[16:17], v[150:151] op_sel_hi:[1,0]
	v_add_f32_e32 v16, 1.0, v34
	v_mul_f32_e32 v34, 0xbfb8aa3b, v30
	v_add_f32_e32 v17, 1.0, v35
	v_mul_f32_e32 v35, 0xbfb8aa3b, v31
	v_exp_f32_e32 v34, v34
	v_exp_f32_e32 v35, v35
	v_rcp_f32_e32 v16, v16
	v_rcp_f32_e32 v17, v17
	v_add_f32_e32 v34, 1.0, v34
	v_add_f32_e32 v35, 1.0, v35
	v_rcp_f32_e32 v34, v34
	v_rcp_f32_e32 v35, v35
	v_pk_mul_f32 v[16:17], v[28:29], v[16:17]
	v_pk_mul_f32 v[24:25], v[24:25], v[150:151] op_sel_hi:[1,0]
	v_pk_mul_f32 v[16:17], v[20:21], v[16:17]
	v_pk_mul_f32 v[22:23], v[22:23], v[150:151] op_sel_hi:[1,0]
	v_cvt_pk_bf16_f32 v16, v16, v17
	v_pk_mul_f32 v[20:21], v[30:31], v[34:35]
	v_mul_f32_e32 v17, 0xbfb8aa3b, v24
	v_pk_mul_f32 v[20:21], v[22:23], v[20:21]
	v_exp_f32_e32 v22, v17
	v_mul_f32_e32 v17, 0xbfb8aa3b, v25
	v_exp_f32_e32 v23, v17
	v_pk_mul_f32 v[26:27], v[26:27], v[150:151] op_sel_hi:[1,0]
	v_cvt_pk_bf16_f32 v17, v20, v21
	v_add_f32_e32 v20, 1.0, v22
	v_add_f32_e32 v21, 1.0, v23
	v_mul_f32_e32 v22, 0xbfb8aa3b, v26
	v_mul_f32_e32 v23, 0xbfb8aa3b, v27
	v_exp_f32_e32 v22, v22
	v_exp_f32_e32 v23, v23
	v_rcp_f32_e32 v20, v20
	v_rcp_f32_e32 v21, v21
	v_add_f32_e32 v22, 1.0, v22
	v_add_f32_e32 v23, 1.0, v23
	v_rcp_f32_e32 v22, v22
	v_rcp_f32_e32 v23, v23
	v_pk_mul_f32 v[20:21], v[24:25], v[20:21]
	v_add_u32_e32 v36, 0xa0, v146
	v_pk_mul_f32 v[18:19], v[18:19], v[20:21]
	v_pk_mul_f32 v[20:21], v[26:27], v[22:23]
	v_cvt_pk_bf16_f32 v18, v18, v19
	v_pk_mul_f32 v[20:21], v[32:33], v[20:21]
	v_pk_mul_f32 v[12:13], v[12:13], v[148:149] op_sel_hi:[1,0]
	v_cvt_pk_bf16_f32 v19, v20, v21
	v_mad_i64_i32 v[20:21], s[4:5], v36, s52, v[144:145]
	global_store_dwordx4 v[20:21], v[16:19], off
	v_pk_mul_f32 v[14:15], v[14:15], v[148:149] op_sel_hi:[1,0]
	v_pk_mul_f32 v[4:5], v[4:5], v[148:149] op_sel_hi:[1,0]
	v_pk_mul_f32 v[16:17], v[2:3], v[148:149] op_sel_hi:[1,0]
	v_mul_f32_e32 v2, 0xbfb8aa3b, v12
	v_exp_f32_e32 v18, v2
	v_mul_f32_e32 v2, 0xbfb8aa3b, v13
	v_exp_f32_e32 v19, v2
	v_pk_mul_f32 v[2:3], v[0:1], v[148:149] op_sel_hi:[1,0]
	v_add_f32_e32 v0, 1.0, v18
	v_mul_f32_e32 v18, 0xbfb8aa3b, v14
	v_add_f32_e32 v1, 1.0, v19
	v_mul_f32_e32 v19, 0xbfb8aa3b, v15
	v_exp_f32_e32 v18, v18
	v_exp_f32_e32 v19, v19
	v_rcp_f32_e32 v0, v0
	v_rcp_f32_e32 v1, v1
	v_add_f32_e32 v18, 1.0, v18
	v_add_f32_e32 v19, 1.0, v19
	v_rcp_f32_e32 v18, v18
	v_rcp_f32_e32 v19, v19
	v_pk_mul_f32 v[0:1], v[12:13], v[0:1]
	v_pk_mul_f32 v[8:9], v[8:9], v[148:149] op_sel_hi:[1,0]
	v_pk_mul_f32 v[0:1], v[4:5], v[0:1]
	v_pk_mul_f32 v[6:7], v[6:7], v[148:149] op_sel_hi:[1,0]
	v_cvt_pk_bf16_f32 v0, v0, v1
	v_pk_mul_f32 v[4:5], v[14:15], v[18:19]
	v_mul_f32_e32 v1, 0xbfb8aa3b, v8
	v_pk_mul_f32 v[4:5], v[6:7], v[4:5]
	v_exp_f32_e32 v6, v1
	v_mul_f32_e32 v1, 0xbfb8aa3b, v9
	v_exp_f32_e32 v7, v1
	v_pk_mul_f32 v[10:11], v[10:11], v[148:149] op_sel_hi:[1,0]
	v_cvt_pk_bf16_f32 v1, v4, v5
	v_add_f32_e32 v4, 1.0, v6
	v_add_f32_e32 v5, 1.0, v7
	v_mul_f32_e32 v6, 0xbfb8aa3b, v10
	v_mul_f32_e32 v7, 0xbfb8aa3b, v11
	v_exp_f32_e32 v6, v6
	v_exp_f32_e32 v7, v7
	v_rcp_f32_e32 v4, v4
	v_rcp_f32_e32 v5, v5
	v_add_f32_e32 v6, 1.0, v6
	v_add_f32_e32 v7, 1.0, v7
	v_rcp_f32_e32 v6, v6
	v_rcp_f32_e32 v7, v7
	v_pk_mul_f32 v[4:5], v[8:9], v[4:5]
	v_add_u32_e32 v20, 0xb0, v146
	v_pk_mul_f32 v[2:3], v[2:3], v[4:5]
	v_pk_mul_f32 v[4:5], v[10:11], v[6:7]
	v_cvt_pk_bf16_f32 v2, v2, v3
	v_pk_mul_f32 v[4:5], v[16:17], v[4:5]
	s_and_b64 vcc, exec, s[0:1]
	v_cvt_pk_bf16_f32 v3, v4, v5
	v_mad_i64_i32 v[4:5], s[4:5], v20, s52, v[144:145]
	s_mov_b32 s5, s24
	s_mov_b32 s4, s28
	s_mov_b64 s[10:11], s[38:39]
	s_mov_b64 s[8:9], s[36:37]
	global_store_dwordx4 v[4:5], v[0:3], off
	s_cbranch_vccz .LBB0_862
	s_waitcnt vmcnt(0)
	s_cmpk_gt_u32 s6, 0xff
	s_cbranch_scc1 .LBB0_869
	s_barrier

; #define PG8_STAGE(bufoff, gbase, voff) do { _Pragma("unroll") for (int _i = 0; _i < 2; ++_i) \
;         __builtin_amdgcn_global_load_lds((const unsigned*)((const char*)(gbase) + (voff)[_i]), (LAS unsigned*)(lds + (bufoff) + ldsw + _i * 8192), 16, 0, 0); } while (0)
; #define PG8_LDA(dst, b, h) do { _Pragma("unroll") for (int m = 0; m < 4; ++m) _Pragma("unroll") for (int k = 0; k < 2; ++k) dst[m][k] = *(const LAS bf16x8*)(lds + PG8_SA(b, h) + aoff + m * 2048 + k * 1024); } while (0)
; #define PG8_LDB(dst, b, h) do { _Pragma("unroll") for (int n = 0; n < 2; ++n) _Pragma("unroll") for (int k = 0; k < 2; ++k) dst[n][k] = *(const LAS bf16x8*)(lds + PG8_SB(b, h) + boff + n * 2048 + k * 1024); } while (0)
; #define PG8_MMA(ai, bj, At, Bt) do { __builtin_amdgcn_s_setprio(1); _Pragma("unroll") for (int m = 0; m < 4; ++m) _Pragma("unroll") for (int n = 0; n < 2; ++n) _Pragma("unroll") for (int k = 0; k < 2; ++k) \
;         acc[ai][bj][m][n] = __builtin_amdgcn_mfma_f32_16x16x32_bf16(Bt[n][k], At[m][k], acc[ai][bj][m][n], 0, 0, 0); __builtin_amdgcn_s_setprio(0); } while (0)
; #define PG8_WAIT_L(n) asm volatile("s_waitcnt lgkmcnt(" #n ")" ::: "memory")
; #define PG8_BAR __builtin_amdgcn_s_barrier()
; #define PG8_SCHED __builtin_amdgcn_sched_barrier(0)
; #define PG8_WAIT_L(n) asm volatile("s_waitcnt lgkmcnt(" #n ")" ::: "memory")
; #define PG8_BAR __builtin_amdgcn_s_barrier()
; #define PG8_SCHED __builtin_amdgcn_sched_barrier(0)
; template <class Epi>
; DI void gemm_phase(LAS unsigned char* lds, const Gemm g, const StaticOrder S, const Epi E) {
;     ...
;             const bool last = (t == nt - 2);
;             const char* a1 = cA + (size_t)(t + 1) * kstep;
;             const char* a2 = last ? nA : cA + (size_t)(t + 2) * kstep; const char* b2 = last ? nB : cB + (size_t)(t + 2) * kstep;
;             const char* a3 = a2 + kstep; const char* b3 = b2 + kstep;
;             PG8_LDB(B0, 0, 0); PG8_SCHED; PG8_LDA(At, 0, 0); PG8_STAGE(PG8_SA(1, 1), a1 + hstep, voffA);
;             PG8_WAIT_L(8); PG8_BAR; PG8_WAIT_L(0); PG8_MMA(0, 0, At, B0); PG8_BAR; PG8_SCHED;
;             PG8_LDB(B1, 0, 1); PG8_STAGE(PG8_SB(0, 0), b2, voffB);
;             PG8_BAR; PG8_WAIT_L(0); PG8_MMA(0, 1, At, B1); PG8_BAR;
;             PG8_LDA(At, 0, 1); PG8_STAGE(PG8_SA(0, 0), a2, voffA);
;             PG8_BAR; PG8_WAIT_L(0); PG8_MMA(1, 0, At, B0); PG8_BAR; PG8_SCHED;
.LBB0_941:
	ds_read_b128 v[144:147], v199
	ds_read_b128 v[148:151], v199 offset:1024
	ds_read_b128 v[152:155], v199 offset:2048
	ds_read_b128 v[156:159], v199 offset:3072
	s_add_u32 s22, s20, 0x100
	s_addc_u32 s23, s21, 0
	s_cmp_eq_u32 s58, 40
	s_cselect_b32 s27, s9, s23
	s_cselect_b32 s26, s8, s22
	s_cselect_b32 s25, s5, s53
	s_cselect_b32 s24, s4, s52
	v_lshl_add_u64 v[192:193], s[20:21], 0, v[136:137]
	s_add_i32 m0, s33, 0xc000
	ds_read_b128 v[160:163], v200
	ds_read_b128 v[168:171], v200 offset:2048
	ds_read_b128 v[176:179], v200 offset:4096
	ds_read_b128 v[184:187], v200 offset:6144
	global_load_lds_dwordx4 v[192:193], off
	s_add_i32 m0, s33, 0xe000
	v_lshl_add_u64 v[192:193], s[20:21], 0, v[138:139]
	global_load_lds_dwordx4 v[192:193], off
	s_waitcnt lgkmcnt(4)
	s_setprio 1
	s_barrier
	ds_read_b128 v[164:167], v200 offset:1024
	ds_read_b128 v[172:175], v200 offset:3072
	ds_read_b128 v[180:183], v200 offset:5120
	ds_read_b128 v[188:191], v200 offset:7168
	s_waitcnt lgkmcnt(4)
	v_mfma_f32_16x16x32_bf16 v[124:127], v[144:147], v[160:163], v[124:127]
	v_mfma_f32_16x16x32_bf16 v[120:123], v[152:155], v[160:163], v[120:123]
	v_mfma_f32_16x16x32_bf16 v[108:111], v[144:147], v[168:171], v[108:111]
	v_mfma_f32_16x16x32_bf16 v[104:107], v[152:155], v[168:171], v[104:107]
	v_mfma_f32_16x16x32_bf16 v[92:95], v[144:147], v[176:179], v[92:95]
	v_mfma_f32_16x16x32_bf16 v[88:91], v[152:155], v[176:179], v[88:91]
	v_mfma_f32_16x16x32_bf16 v[84:87], v[144:147], v[184:187], v[84:87]
	v_mfma_f32_16x16x32_bf16 v[76:79], v[152:155], v[184:187], v[76:79]
	s_waitcnt lgkmcnt(3)
	v_mfma_f32_16x16x32_bf16 v[124:127], v[148:151], v[164:167], v[124:127]
	v_mfma_f32_16x16x32_bf16 v[120:123], v[156:159], v[164:167], v[120:123]
	s_waitcnt lgkmcnt(2)
	v_mfma_f32_16x16x32_bf16 v[108:111], v[148:151], v[172:175], v[108:111]
	v_mfma_f32_16x16x32_bf16 v[104:107], v[156:159], v[172:175], v[104:107]
	s_waitcnt lgkmcnt(1)
	v_mfma_f32_16x16x32_bf16 v[92:95], v[148:151], v[180:183], v[92:95]
	v_mfma_f32_16x16x32_bf16 v[88:91], v[156:159], v[180:183], v[88:91]
	s_waitcnt lgkmcnt(0)
	s_setprio 2
	s_barrier
	v_mfma_f32_16x16x32_bf16 v[84:87], v[148:151], v[188:191], v[84:87]
	v_mfma_f32_16x16x32_bf16 v[76:79], v[156:159], v[188:191], v[76:79]
	s_setprio 0
	s_add_i32 s20, s42, s29
	v_lshl_add_u64 v[214:215], s[24:25], 0, v[130:131]
	s_mov_b32 m0, s20
	ds_read_b128 v[192:195], v201
	ds_read_b128 v[202:205], v201 offset:1024
	ds_read_b128 v[206:209], v201 offset:2048
	ds_read_b128 v[210:213], v201 offset:3072
	global_load_lds_dwordx4 v[214:215], off
	s_add_i32 m0, s20, 0x2000
	v_lshl_add_u64 v[216:217], s[24:25], 0, v[134:135]
	global_load_lds_dwordx4 v[216:217], off
	s_setprio 1
	s_barrier
	s_waitcnt lgkmcnt(0)
	v_mfma_f32_16x16x32_bf16 v[116:119], v[192:195], v[160:163], v[116:119]
	v_mfma_f32_16x16x32_bf16 v[112:115], v[206:209], v[160:163], v[112:115]
	v_mfma_f32_16x16x32_bf16 v[100:103], v[192:195], v[168:171], v[100:103]
	v_mfma_f32_16x16x32_bf16 v[96:99], v[206:209], v[168:171], v[96:99]
	v_mfma_f32_16x16x32_bf16 v[80:83], v[192:195], v[176:179], v[80:83]
	v_mfma_f32_16x16x32_bf16 v[72:75], v[206:209], v[176:179], v[72:75]
	v_mfma_f32_16x16x32_bf16 v[68:71], v[192:195], v[184:187], v[68:71]
	v_mfma_f32_16x16x32_bf16 v[64:67], v[206:209], v[184:187], v[64:67]
	v_mfma_f32_16x16x32_bf16 v[116:119], v[202:205], v[164:167], v[116:119]
	v_mfma_f32_16x16x32_bf16 v[112:115], v[210:213], v[164:167], v[112:115]
	v_mfma_f32_16x16x32_bf16 v[100:103], v[202:205], v[172:175], v[100:103]
	v_mfma_f32_16x16x32_bf16 v[96:99], v[210:213], v[172:175], v[96:99]
	v_mfma_f32_16x16x32_bf16 v[80:83], v[202:205], v[180:183], v[80:83]
	v_mfma_f32_16x16x32_bf16 v[72:75], v[210:213], v[180:183], v[72:75]
	s_setprio 2
	s_barrier
	v_mfma_f32_16x16x32_bf16 v[68:71], v[202:205], v[188:191], v[68:71]
	v_mfma_f32_16x16x32_bf16 v[64:67], v[210:213], v[188:191], v[64:67]
	s_setprio 0
	s_mov_b32 m0, s33
	v_lshl_add_u64 v[218:219], s[26:27], 0, v[128:129]
	ds_read_b128 v[160:163], v200 offset:16384
	ds_read_b128 v[168:171], v200 offset:18432
	ds_read_b128 v[176:179], v200 offset:20480
	ds_read_b128 v[184:187], v200 offset:22528
	global_load_lds_dwordx4 v[218:219], off
	s_mov_b32 m0, s34
	v_lshl_add_u64 v[220:221], s[26:27], 0, v[132:133]
	global_load_lds_dwordx4 v[220:221], off
	s_setprio 1
	s_barrier
	ds_read_b128 v[164:167], v200 offset:17408
	ds_read_b128 v[172:175], v200 offset:19456
	ds_read_b128 v[180:183], v200 offset:21504
	ds_read_b128 v[188:191], v200 offset:23552
	s_waitcnt lgkmcnt(4)
	v_mfma_f32_16x16x32_bf16 v[60:63], v[144:147], v[160:163], v[60:63]
	v_mfma_f32_16x16x32_bf16 v[56:59], v[152:155], v[160:163], v[56:59]
	v_mfma_f32_16x16x32_bf16 v[48:51], v[144:147], v[168:171], v[48:51]
	v_mfma_f32_16x16x32_bf16 v[40:43], v[152:155], v[168:171], v[40:43]
	v_mfma_f32_16x16x32_bf16 v[32:35], v[144:147], v[176:179], v[32:35]
	v_mfma_f32_16x16x32_bf16 v[24:27], v[152:155], v[176:179], v[24:27]
	v_mfma_f32_16x16x32_bf16 v[16:19], v[144:147], v[184:187], v[16:19]
	v_mfma_f32_16x16x32_bf16 v[8:11], v[152:155], v[184:187], v[8:11]
	s_waitcnt lgkmcnt(3)
	v_mfma_f32_16x16x32_bf16 v[60:63], v[148:151], v[164:167], v[60:63]
	v_mfma_f32_16x16x32_bf16 v[56:59], v[156:159], v[164:167], v[56:59]
	s_waitcnt lgkmcnt(2)
	v_mfma_f32_16x16x32_bf16 v[48:51], v[148:151], v[172:175], v[48:51]
	v_mfma_f32_16x16x32_bf16 v[40:43], v[156:159], v[172:175], v[40:43]
	s_waitcnt lgkmcnt(1)
	v_mfma_f32_16x16x32_bf16 v[32:35], v[148:151], v[180:183], v[32:35]
	v_mfma_f32_16x16x32_bf16 v[24:27], v[156:159], v[180:183], v[24:27]
	s_waitcnt lgkmcnt(0)
	s_setprio 2
	s_barrier
; #define PG8_STAGE(bufoff, gbase, voff) do { _Pragma("unroll") for (int _i = 0; _i < 2; ++_i) \
;         __builtin_amdgcn_global_load_lds((const unsigned*)((const char*)(gbase) + (voff)[_i]), (LAS unsigned*)(lds + (bufoff) + ldsw + _i * 8192), 16, 0, 0); } while (0)
; #define PG8_LDA(dst, b, h) do { _Pragma("unroll") for (int m = 0; m < 4; ++m) _Pragma("unroll") for (int k = 0; k < 2; ++k) dst[m][k] = *(const LAS bf16x8*)(lds + PG8_SA(b, h) + aoff + m * 2048 + k * 1024); } while (0)
; #define PG8_LDB(dst, b, h) do { _Pragma("unroll") for (int n = 0; n < 2; ++n) _Pragma("unroll") for (int k = 0; k < 2; ++k) dst[n][k] = *(const LAS bf16x8*)(lds + PG8_SB(b, h) + boff + n * 2048 + k * 1024); } while (0)
; #define PG8_MMA(ai, bj, At, Bt) do { __builtin_amdgcn_s_setprio(1); _Pragma("unroll") for (int m = 0; m < 4; ++m) _Pragma("unroll") for (int n = 0; n < 2; ++n) _Pragma("unroll") for (int k = 0; k < 2; ++k) \
;         acc[ai][bj][m][n] = __builtin_amdgcn_mfma_f32_16x16x32_bf16(Bt[n][k], At[m][k], acc[ai][bj][m][n], 0, 0, 0); __builtin_amdgcn_s_setprio(0); } while (0)
; #define PG8_WAIT_V(n) asm volatile("s_waitcnt vmcnt(" #n ")" ::: "memory")
; #define PG8_WAIT_L(n) asm volatile("s_waitcnt lgkmcnt(" #n ")" ::: "memory")
; #define PG8_BAR __builtin_amdgcn_s_barrier()
; #define PG8_SCHED __builtin_amdgcn_sched_barrier(0)
; #define PG8_LDA(dst, b, h) do { _Pragma("unroll") for (int m = 0; m < 4; ++m) _Pragma("unroll") for (int k = 0; k < 2; ++k) dst[m][k] = *(const LAS bf16x8*)(lds + PG8_SA(b, h) + aoff + m * 2048 + k * 1024); } while (0)
; template <class Epi>
; DI void gemm_phase(LAS unsigned char* lds, const Gemm g, const StaticOrder S, const Epi E) {
;     ...
;             PG8_BAR; PG8_WAIT_L(0); PG8_MMA(1, 0, At, B0); PG8_BAR; PG8_SCHED;
;             PG8_STAGE(PG8_SB(0, 1), b2 + hstep, voffB);
;             PG8_WAIT_V(6); PG8_BAR; PG8_MMA(1, 1, At, B1); PG8_BAR;
;             PG8_LDB(B0, 1, 0); PG8_SCHED; PG8_LDA(At, 1, 0); PG8_STAGE(PG8_SA(0, 1), a2 + hstep, voffA);
;             PG8_WAIT_L(8); PG8_BAR; PG8_WAIT_L(0); PG8_MMA(0, 0, At, B0); PG8_BAR; PG8_SCHED;
;             PG8_LDB(B1, 1, 1); PG8_STAGE(PG8_SB(1, 0), b3, voffB);
;             PG8_BAR; PG8_WAIT_L(0); PG8_MMA(0, 1, At, B1); PG8_BAR;
;             PG8_LDA(At, 1, 1); PG8_STAGE(PG8_SA(1, 0), a3, voffA);
;             PG8_BAR; PG8_WAIT_L(0); PG8_MMA(1, 0, At, B0); PG8_BAR; PG8_SCHED;
	v_mfma_f32_16x16x32_bf16 v[16:19], v[148:151], v[188:191], v[16:19]
	v_mfma_f32_16x16x32_bf16 v[8:11], v[156:159], v[188:191], v[8:11]
	s_setprio 0
	s_add_u32 s20, s24, 0xb0000
	s_addc_u32 s21, s25, 0
	s_add_i32 s59, s43, s29
	s_mov_b32 m0, s59
	v_lshl_add_u64 v[144:145], s[20:21], 0, v[130:131]
	global_load_lds_dwordx4 v[144:145], off
	s_add_i32 m0, s59, 0x2000
	v_lshl_add_u64 v[144:145], s[20:21], 0, v[134:135]
	global_load_lds_dwordx4 v[144:145], off
	s_waitcnt vmcnt(6)
	s_setprio 1
	s_barrier
	v_mfma_f32_16x16x32_bf16 v[52:55], v[192:195], v[160:163], v[52:55]
	v_mfma_f32_16x16x32_bf16 v[44:47], v[206:209], v[160:163], v[44:47]
	v_mfma_f32_16x16x32_bf16 v[36:39], v[192:195], v[168:171], v[36:39]
	v_mfma_f32_16x16x32_bf16 v[28:31], v[206:209], v[168:171], v[28:31]
	v_mfma_f32_16x16x32_bf16 v[20:23], v[192:195], v[176:179], v[20:23]
	v_mfma_f32_16x16x32_bf16 v[12:15], v[206:209], v[176:179], v[12:15]
	v_mfma_f32_16x16x32_bf16 v[4:7], v[192:195], v[184:187], v[4:7]
	v_mfma_f32_16x16x32_bf16 v[0:3], v[206:209], v[184:187], v[0:3]
	v_mfma_f32_16x16x32_bf16 v[52:55], v[202:205], v[164:167], v[52:55]
	v_mfma_f32_16x16x32_bf16 v[44:47], v[210:213], v[164:167], v[44:47]
	v_mfma_f32_16x16x32_bf16 v[36:39], v[202:205], v[172:175], v[36:39]
	v_mfma_f32_16x16x32_bf16 v[28:31], v[210:213], v[172:175], v[28:31]
	v_mfma_f32_16x16x32_bf16 v[20:23], v[202:205], v[180:183], v[20:23]
	v_mfma_f32_16x16x32_bf16 v[12:15], v[210:213], v[180:183], v[12:15]
	s_setprio 2
	s_barrier
	v_mfma_f32_16x16x32_bf16 v[4:7], v[202:205], v[188:191], v[4:7]
	v_mfma_f32_16x16x32_bf16 v[0:3], v[210:213], v[188:191], v[0:3]
	s_setprio 0
	s_add_i32 s59, 0, 0x18000
	v_add_u32_e32 v156, s59, v197
	ds_read_b128 v[144:147], v156
	ds_read_b128 v[148:151], v156 offset:1024
	ds_read_b128 v[152:155], v156 offset:2048
	ds_read_b128 v[156:159], v156 offset:3072
	s_add_u32 s20, s26, 0xb0000
	s_addc_u32 s21, s27, 0
	s_mov_b32 m0, s35
	v_lshl_add_u64 v[192:193], s[20:21], 0, v[128:129]
	ds_read_b128 v[160:163], v200 offset:32768
	ds_read_b128 v[168:171], v200 offset:34816
	ds_read_b128 v[176:179], v200 offset:36864
	ds_read_b128 v[184:187], v200 offset:38912
	global_load_lds_dwordx4 v[192:193], off
	s_mov_b32 m0, s36
	v_lshl_add_u64 v[192:193], s[20:21], 0, v[132:133]
	global_load_lds_dwordx4 v[192:193], off
	s_waitcnt lgkmcnt(4)
	s_setprio 1
	s_barrier
	ds_read_b128 v[164:167], v200 offset:33792
	ds_read_b128 v[172:175], v200 offset:35840
	ds_read_b128 v[180:183], v200 offset:37888
	ds_read_b128 v[188:191], v200 offset:39936
	s_waitcnt lgkmcnt(4)
	v_mfma_f32_16x16x32_bf16 v[124:127], v[144:147], v[160:163], v[124:127]
	v_mfma_f32_16x16x32_bf16 v[120:123], v[152:155], v[160:163], v[120:123]
	v_mfma_f32_16x16x32_bf16 v[108:111], v[144:147], v[168:171], v[108:111]
	v_mfma_f32_16x16x32_bf16 v[104:107], v[152:155], v[168:171], v[104:107]
	v_mfma_f32_16x16x32_bf16 v[92:95], v[144:147], v[176:179], v[92:95]
	v_mfma_f32_16x16x32_bf16 v[88:91], v[152:155], v[176:179], v[88:91]
	v_mfma_f32_16x16x32_bf16 v[84:87], v[144:147], v[184:187], v[84:87]
	v_mfma_f32_16x16x32_bf16 v[76:79], v[152:155], v[184:187], v[76:79]
	s_waitcnt lgkmcnt(3)
	v_mfma_f32_16x16x32_bf16 v[124:127], v[148:151], v[164:167], v[124:127]
	v_mfma_f32_16x16x32_bf16 v[120:123], v[156:159], v[164:167], v[120:123]
	s_waitcnt lgkmcnt(2)
	v_mfma_f32_16x16x32_bf16 v[108:111], v[148:151], v[172:175], v[108:111]
	v_mfma_f32_16x16x32_bf16 v[104:107], v[156:159], v[172:175], v[104:107]
	s_waitcnt lgkmcnt(1)
	v_mfma_f32_16x16x32_bf16 v[92:95], v[148:151], v[180:183], v[92:95]
	v_mfma_f32_16x16x32_bf16 v[88:91], v[156:159], v[180:183], v[88:91]
	s_waitcnt lgkmcnt(0)
	s_setprio 2
	s_barrier
	v_mfma_f32_16x16x32_bf16 v[84:87], v[148:151], v[188:191], v[84:87]
	v_mfma_f32_16x16x32_bf16 v[76:79], v[156:159], v[188:191], v[76:79]
	s_setprio 0
	s_add_i32 s26, 0, 0x1c000
	s_add_i32 s20, s59, s29
	v_add_u32_e32 v210, s26, v197
	v_lshl_add_u64 v[214:215], v[214:215], 0, s[10:11]
	s_mov_b32 m0, s20
	ds_read_b128 v[192:195], v210
	ds_read_b128 v[202:205], v210 offset:1024
	ds_read_b128 v[206:209], v210 offset:2048
	ds_read_b128 v[210:213], v210 offset:3072
	global_load_lds_dwordx4 v[214:215], off
	s_add_i32 m0, s20, 0x2000
	v_lshl_add_u64 v[214:215], v[216:217], 0, s[10:11]
	global_load_lds_dwordx4 v[214:215], off
	s_setprio 1
	s_barrier
	s_waitcnt lgkmcnt(0)
	v_mfma_f32_16x16x32_bf16 v[116:119], v[192:195], v[160:163], v[116:119]
	v_mfma_f32_16x16x32_bf16 v[112:115], v[206:209], v[160:163], v[112:115]
	v_mfma_f32_16x16x32_bf16 v[100:103], v[192:195], v[168:171], v[100:103]
	v_mfma_f32_16x16x32_bf16 v[96:99], v[206:209], v[168:171], v[96:99]
	v_mfma_f32_16x16x32_bf16 v[80:83], v[192:195], v[176:179], v[80:83]
	v_mfma_f32_16x16x32_bf16 v[72:75], v[206:209], v[176:179], v[72:75]
	v_mfma_f32_16x16x32_bf16 v[68:71], v[192:195], v[184:187], v[68:71]
	v_mfma_f32_16x16x32_bf16 v[64:67], v[206:209], v[184:187], v[64:67]
	v_mfma_f32_16x16x32_bf16 v[116:119], v[202:205], v[164:167], v[116:119]
	v_mfma_f32_16x16x32_bf16 v[112:115], v[210:213], v[164:167], v[112:115]
	v_mfma_f32_16x16x32_bf16 v[100:103], v[202:205], v[172:175], v[100:103]
	v_mfma_f32_16x16x32_bf16 v[96:99], v[210:213], v[172:175], v[96:99]
	v_mfma_f32_16x16x32_bf16 v[80:83], v[202:205], v[180:183], v[80:83]
	v_mfma_f32_16x16x32_bf16 v[72:75], v[210:213], v[180:183], v[72:75]
	s_setprio 2
	s_barrier
	v_mfma_f32_16x16x32_bf16 v[68:71], v[202:205], v[188:191], v[68:71]
	v_mfma_f32_16x16x32_bf16 v[64:67], v[210:213], v[188:191], v[64:67]
	s_setprio 0
	s_mov_b32 m0, s38
	v_lshl_add_u64 v[214:215], v[218:219], 0, s[10:11]
	ds_read_b128 v[160:163], v200 offset:49152
	ds_read_b128 v[168:171], v200 offset:51200
	ds_read_b128 v[176:179], v200 offset:53248
	ds_read_b128 v[184:187], v200 offset:55296
	global_load_lds_dwordx4 v[214:215], off
	s_mov_b32 m0, s39
	v_lshl_add_u64 v[214:215], v[220:221], 0, s[10:11]
	global_load_lds_dwordx4 v[214:215], off
	s_setprio 1
	s_barrier
; DI f32x4 bf_lo4(u32x4 w) { f32x4 r; r[0] = bf_lo(w.x); r[1] = bf_hi(w.x); r[2] = bf_lo(w.y); r[3] = bf_hi(w.y); return r; }
; DI f32x4 bf_hi4(u32x4 w) { f32x4 r; r[0] = bf_lo(w.z); r[1] = bf_hi(w.z); r[2] = bf_lo(w.w); r[3] = bf_hi(w.w); return r; }
; #define PG8_STAGE(bufoff, gbase, voff) do { _Pragma("unroll") for (int _i = 0; _i < 2; ++_i) \
;         __builtin_amdgcn_global_load_lds((const unsigned*)((const char*)(gbase) + (voff)[_i]), (LAS unsigned*)(lds + (bufoff) + ldsw + _i * 8192), 16, 0, 0); } while (0)
; #define PG8_LDA(dst, b, h) do { _Pragma("unroll") for (int m = 0; m < 4; ++m) _Pragma("unroll") for (int k = 0; k < 2; ++k) dst[m][k] = *(const LAS bf16x8*)(lds + PG8_SA(b, h) + aoff + m * 2048 + k * 1024); } while (0)
; #define PG8_LDB(dst, b, h) do { _Pragma("unroll") for (int n = 0; n < 2; ++n) _Pragma("unroll") for (int k = 0; k < 2; ++k) dst[n][k] = *(const LAS bf16x8*)(lds + PG8_SB(b, h) + boff + n * 2048 + k * 1024); } while (0)
; #define PG8_BAR __builtin_amdgcn_s_barrier()
; template <class Epi>
; DI void gemm_phase(LAS unsigned char* lds, const Gemm g, const StaticOrder S, const Epi E) {
;     ...
;             PG8_LDB(B1, 1, 1); PG8_STAGE(PG8_SB(1, 0), b3, voffB);
;             PG8_BAR; PG8_WAIT_L(0); PG8_MMA(0, 1, At, B1); PG8_BAR;
;             PG8_LDA(At, 1, 1); PG8_STAGE(PG8_SA(1, 0), a3, voffA);
;             PG8_BAR; PG8_WAIT_L(0); PG8_MMA(1, 0, At, B0); PG8_BAR; PG8_SCHED;
;             PG8_STAGE(PG8_SB(1, 1), b3 + hstep, voffB);
;             PG8_WAIT_V(6); PG8_BAR; PG8_MMA(1, 1, At, B1); PG8_BAR;
;         }
;         E(acc, cur, wr, wc, fr, fq);
;     DI void operator()(AccRef acc, const Unit& u, int wr, int wc, int fr, int fq) const {
;     ...
;         const int row0 = u.pm * 256 + wr * 64 + fr, col0 = u.pn * 256 + wc * 32 + 8 * fq;
; #pragma unroll
;         for (int ai = 0; ai < 2; ++ai) {
;             f32x4 bv[4][2][2];
; #pragma unroll
;             for (int m = 0; m < 4; ++m)
; #pragma unroll
;                 for (int bj = 0; bj < 2; ++bj) {
;                     const size_t o = (size_t)(row0 + ai * 128 + m * 16) * DM + col0 + bj * 128;
;                     if (BASEF32) { bv[m][bj][0] = *(const f32x4*)(basef + o); bv[m][bj][1] = *(const f32x4*)(basef + o + 4); }
;                     else { const u32x4 h = *(const u32x4*)(xnb + o); bv[m][bj][0] = bf_lo4(h); bv[m][bj][1] = bf_hi4(h); }
;                 }
	ds_read_b128 v[164:167], v200 offset:50176
	ds_read_b128 v[172:175], v200 offset:52224
	ds_read_b128 v[180:183], v200 offset:54272
	ds_read_b128 v[188:191], v200 offset:56320
	s_waitcnt lgkmcnt(4)
	v_mfma_f32_16x16x32_bf16 v[60:63], v[144:147], v[160:163], v[60:63]
	v_mfma_f32_16x16x32_bf16 v[56:59], v[152:155], v[160:163], v[56:59]
	v_mfma_f32_16x16x32_bf16 v[48:51], v[144:147], v[168:171], v[48:51]
	v_mfma_f32_16x16x32_bf16 v[40:43], v[152:155], v[168:171], v[40:43]
	v_mfma_f32_16x16x32_bf16 v[32:35], v[144:147], v[176:179], v[32:35]
	v_mfma_f32_16x16x32_bf16 v[24:27], v[152:155], v[176:179], v[24:27]
	v_mfma_f32_16x16x32_bf16 v[16:19], v[144:147], v[184:187], v[16:19]
	v_mfma_f32_16x16x32_bf16 v[8:11], v[152:155], v[184:187], v[8:11]
	s_waitcnt lgkmcnt(3)
	v_mfma_f32_16x16x32_bf16 v[60:63], v[148:151], v[164:167], v[60:63]
	v_mfma_f32_16x16x32_bf16 v[56:59], v[156:159], v[164:167], v[56:59]
	s_waitcnt lgkmcnt(2)
	v_mfma_f32_16x16x32_bf16 v[48:51], v[148:151], v[172:175], v[48:51]
	v_mfma_f32_16x16x32_bf16 v[40:43], v[156:159], v[172:175], v[40:43]
	s_waitcnt lgkmcnt(1)
	v_mfma_f32_16x16x32_bf16 v[32:35], v[148:151], v[180:183], v[32:35]
	v_mfma_f32_16x16x32_bf16 v[24:27], v[156:159], v[180:183], v[24:27]
	s_waitcnt lgkmcnt(0)
	s_setprio 2
	s_barrier
	v_mfma_f32_16x16x32_bf16 v[16:19], v[148:151], v[188:191], v[16:19]
	v_mfma_f32_16x16x32_bf16 v[8:11], v[156:159], v[188:191], v[8:11]
	s_setprio 0
	s_add_u32 s20, s24, 0xb0080
	s_addc_u32 s21, s25, 0
	s_add_i32 s24, s26, s29
	s_mov_b32 m0, s24
	v_lshl_add_u64 v[144:145], s[20:21], 0, v[130:131]
	global_load_lds_dwordx4 v[144:145], off
	s_add_i32 m0, s24, 0x2000
	v_lshl_add_u64 v[144:145], s[20:21], 0, v[134:135]
	global_load_lds_dwordx4 v[144:145], off
	s_waitcnt vmcnt(6)
	s_setprio 1
	s_barrier
	v_mfma_f32_16x16x32_bf16 v[52:55], v[192:195], v[160:163], v[52:55]
	v_mfma_f32_16x16x32_bf16 v[44:47], v[206:209], v[160:163], v[44:47]
	v_mfma_f32_16x16x32_bf16 v[36:39], v[192:195], v[168:171], v[36:39]
	v_mfma_f32_16x16x32_bf16 v[28:31], v[206:209], v[168:171], v[28:31]
	v_mfma_f32_16x16x32_bf16 v[20:23], v[192:195], v[176:179], v[20:23]
	v_mfma_f32_16x16x32_bf16 v[12:15], v[206:209], v[176:179], v[12:15]
	v_mfma_f32_16x16x32_bf16 v[4:7], v[192:195], v[184:187], v[4:7]
	v_mfma_f32_16x16x32_bf16 v[0:3], v[206:209], v[184:187], v[0:3]
	v_mfma_f32_16x16x32_bf16 v[52:55], v[202:205], v[164:167], v[52:55]
	v_mfma_f32_16x16x32_bf16 v[44:47], v[210:213], v[164:167], v[44:47]
	v_mfma_f32_16x16x32_bf16 v[36:39], v[202:205], v[172:175], v[36:39]
	v_mfma_f32_16x16x32_bf16 v[28:31], v[210:213], v[172:175], v[28:31]
	v_mfma_f32_16x16x32_bf16 v[20:23], v[202:205], v[180:183], v[20:23]
	v_mfma_f32_16x16x32_bf16 v[12:15], v[210:213], v[180:183], v[12:15]
	s_setprio 2
	s_barrier
	v_mfma_f32_16x16x32_bf16 v[4:7], v[202:205], v[188:191], v[4:7]
	v_mfma_f32_16x16x32_bf16 v[0:3], v[210:213], v[188:191], v[0:3]
	s_setprio 0
	s_add_i32 s58, s58, 2
	s_add_u32 s52, s52, 0x100
	s_addc_u32 s53, s53, 0
	s_cmp_gt_u32 s58, 41
	s_mov_b64 s[20:21], s[22:23]
	s_cbranch_scc0 .LBB0_941
	v_lshl_add_u32 v148, s50, 8, v196
	v_lshl_or_b32 v144, s51, 8, v198
	v_or_b32_e32 v146, 16, v148
	v_ashrrev_i32_e32 v145, 31, v144
	v_ashrrev_i32_e32 v147, 31, v146
	v_lshl_add_u64 v[176:177], v[144:145], 1, s[56:57]
	v_ashrrev_i32_e32 v149, 31, v148
	v_lshlrev_b64 v[146:147], 11, v[146:147]
	v_lshlrev_b64 v[144:145], 11, v[148:149]
	v_lshl_add_u64 v[150:151], v[176:177], 0, v[146:147]
	v_or_b32_e32 v146, 32, v148
	v_or_b32_e32 v148, 48, v148
	v_ashrrev_i32_e32 v147, 31, v146
	v_ashrrev_i32_e32 v149, 31, v148
	v_lshl_add_u64 v[144:145], v[176:177], 0, v[144:145]
	v_lshlrev_b64 v[146:147], 11, v[146:147]
	v_lshlrev_b64 v[148:149], 11, v[148:149]
	global_load_dwordx4 v[152:155], v[144:145], off
	global_load_dwordx4 v[156:159], v[144:145], off offset:256
	v_lshl_add_u64 v[146:147], v[176:177], 0, v[146:147]
	v_lshl_add_u64 v[148:149], v[176:177], 0, v[148:149]
	global_load_dwordx4 v[160:163], v[150:151], off
	global_load_dwordx4 v[164:167], v[150:151], off offset:256
	global_load_dwordx4 v[168:171], v[146:147], off
	global_load_dwordx4 v[172:175], v[146:147], off offset:256
	global_load_dwordx4 v[202:205], v[148:149], off
	global_load_dwordx4 v[206:209], v[148:149], off offset:256
	s_mov_b32 s51, s48
	s_mov_b32 s50, s49
	s_mov_b64 s[22:23], s[4:5]
	s_mov_b64 s[20:21], s[8:9]
	s_waitcnt vmcnt(0)
; DI unsigned pk_bf16(float lo, float hi) { f32x2 v = {lo, hi}; return __builtin_bit_cast(unsigned, __builtin_convertvector(v, bf16v2)); }
; DI f32x4 bf_lo4(u32x4 w) { f32x4 r; r[0] = bf_lo(w.x); r[1] = bf_hi(w.x); r[2] = bf_lo(w.y); r[3] = bf_hi(w.y); return r; }
; DI f32x4 bf_hi4(u32x4 w) { f32x4 r; r[0] = bf_lo(w.z); r[1] = bf_hi(w.z); r[2] = bf_lo(w.w); r[3] = bf_hi(w.w); return r; }
;     DI void operator()(AccRef acc, const Unit& u, int wr, int wc, int fr, int fq) const {
;     ...
;         const int row0 = u.pm * 256 + wr * 64 + fr, col0 = u.pn * 256 + wc * 32 + 8 * fq;
; #pragma unroll
;         for (int ai = 0; ai < 2; ++ai) {
;             f32x4 bv[4][2][2];
; #pragma unroll
;             for (int m = 0; m < 4; ++m)
; #pragma unroll
;                 for (int bj = 0; bj < 2; ++bj) {
;                     const size_t o = (size_t)(row0 + ai * 128 + m * 16) * DM + col0 + bj * 128;
;                     if (BASEF32) { bv[m][bj][0] = *(const f32x4*)(basef + o); bv[m][bj][1] = *(const f32x4*)(basef + o + 4); }
;                     else { const u32x4 h = *(const u32x4*)(xnb + o); bv[m][bj][0] = bf_lo4(h); bv[m][bj][1] = bf_hi4(h); }
;                 }
; #pragma unroll
;             for (int m = 0; m < 4; ++m) {
;                 const int row = row0 + ai * 128 + m * 16;
;                 float q = 0.f;
; #pragma unroll
;                 for (int bj = 0; bj < 2; ++bj) {
;                     const size_t o = (size_t)row * DM + col0 + bj * 128;
;                     const f32x4 r0 = bv[m][bj][0] + scale * acc[ai][bj][m][0], r1 = bv[m][bj][1] + scale * acc[ai][bj][m][1];
;                     u32x4 w; w.x = pk_bf16(r0[0], r0[1]); w.y = pk_bf16(r0[2], r0[3]); w.z = pk_bf16(r1[0], r1[1]); w.w = pk_bf16(r1[2], r1[3]);
;                     *(u32x4*)(xnb + o) = w;
	v_lshlrev_b32_e32 v214, 16, v154
	v_and_b32_e32 v215, 0xffff0000, v154
	v_lshlrev_b32_e32 v216, 16, v155
	v_and_b32_e32 v217, 0xffff0000, v155
	v_lshlrev_b32_e32 v210, 16, v152
	v_and_b32_e32 v211, 0xffff0000, v152
	v_lshlrev_b32_e32 v212, 16, v153
	v_and_b32_e32 v213, 0xffff0000, v153
	v_lshlrev_b32_e32 v194, 16, v162
	v_and_b32_e32 v195, 0xffff0000, v162
	v_lshlrev_b32_e32 v230, 16, v163
	v_and_b32_e32 v231, 0xffff0000, v163
	v_lshlrev_b32_e32 v154, 16, v202
	v_and_b32_e32 v155, 0xffff0000, v202
	v_lshlrev_b32_e32 v162, 16, v203
	v_and_b32_e32 v163, 0xffff0000, v203
	v_pk_fma_f32 v[202:203], v[122:123], 0.5, v[216:217] op_sel_hi:[1,0,1]
	v_pk_fma_f32 v[122:123], v[120:121], 0.5, v[214:215] op_sel_hi:[1,0,1]
	v_lshlrev_b32_e32 v218, 16, v156
	v_and_b32_e32 v219, 0xffff0000, v156
	v_lshlrev_b32_e32 v220, 16, v157
	v_and_b32_e32 v221, 0xffff0000, v157
	v_pk_fma_f32 v[126:127], v[126:127], 0.5, v[212:213] op_sel_hi:[1,0,1]
	v_pk_fma_f32 v[124:125], v[124:125], 0.5, v[210:211] op_sel_hi:[1,0,1]
	v_cvt_pk_bf16_f32 v122, v122, v123
	v_cvt_pk_bf16_f32 v123, v202, v203
	v_add_co_u32_e32 v202, vcc, s44, v144
	v_lshlrev_b32_e32 v224, 16, v158
	v_and_b32_e32 v225, 0xffff0000, v158
	v_lshlrev_b32_e32 v226, 16, v159
	v_and_b32_e32 v227, 0xffff0000, v159
	v_cvt_pk_bf16_f32 v120, v124, v125
	v_cvt_pk_bf16_f32 v121, v126, v127
	v_pk_fma_f32 v[118:119], v[118:119], 0.5, v[220:221] op_sel_hi:[1,0,1]
	v_pk_fma_f32 v[116:117], v[116:117], 0.5, v[218:219] op_sel_hi:[1,0,1]
	v_addc_co_u32_e32 v203, vcc, 0, v145, vcc
	v_lshlrev_b32_e32 v192, 16, v160
	v_and_b32_e32 v193, 0xffff0000, v160
	global_store_dwordx4 v[144:145], v[120:123], off
	v_pk_fma_f32 v[108:109], v[108:109], 0.5, v[192:193] op_sel_hi:[1,0,1]
	v_lshl_add_u64 v[192:193], v[144:145], 0, s[12:13]
	v_pk_fma_f32 v[120:121], v[114:115], 0.5, v[226:227] op_sel_hi:[1,0,1]
	v_pk_fma_f32 v[114:115], v[112:113], 0.5, v[224:225] op_sel_hi:[1,0,1]
	v_cvt_pk_bf16_f32 v112, v116, v117
	v_cvt_pk_bf16_f32 v113, v118, v119
	global_load_dwordx4 v[116:119], v[202:203], off
	v_cvt_pk_bf16_f32 v114, v114, v115
	v_cvt_pk_bf16_f32 v115, v120, v121
	v_lshlrev_b32_e32 v228, 16, v161
	v_and_b32_e32 v229, 0xffff0000, v161
	global_store_dwordx4 v[144:145], v[112:115], off offset:256
	v_pk_fma_f32 v[120:121], v[106:107], 0.5, v[230:231] op_sel_hi:[1,0,1]
	v_pk_fma_f32 v[110:111], v[110:111], 0.5, v[228:229] op_sel_hi:[1,0,1]
	v_pk_fma_f32 v[112:113], v[104:105], 0.5, v[194:195] op_sel_hi:[1,0,1]
	global_load_dwordx4 v[104:107], v[192:193], off offset:256
	v_add_co_u32_e32 v194, vcc, s45, v144
	v_lshlrev_b32_e32 v184, 16, v164
	s_nop 0
	v_addc_co_u32_e32 v195, vcc, 0, v145, vcc
	v_and_b32_e32 v185, 0xffff0000, v164
	v_lshlrev_b32_e32 v188, 16, v165
	v_and_b32_e32 v189, 0xffff0000, v165
	v_lshlrev_b32_e32 v186, 16, v166
	v_and_b32_e32 v187, 0xffff0000, v166
	v_lshlrev_b32_e32 v190, 16, v167
	v_and_b32_e32 v191, 0xffff0000, v167
	v_cvt_pk_bf16_f32 v108, v108, v109
	v_cvt_pk_bf16_f32 v109, v110, v111
	v_cvt_pk_bf16_f32 v110, v112, v113
	global_load_dwordx4 v[112:115], v[194:195], off
	v_cvt_pk_bf16_f32 v111, v120, v121
	global_store_dwordx4 v[150:151], v[108:111], off
	v_pk_fma_f32 v[124:125], v[98:99], 0.5, v[190:191] op_sel_hi:[1,0,1]
	v_pk_fma_f32 v[96:97], v[96:97], 0.5, v[186:187] op_sel_hi:[1,0,1]
	v_pk_fma_f32 v[110:111], v[102:103], 0.5, v[188:189] op_sel_hi:[1,0,1]
	v_pk_fma_f32 v[108:109], v[100:101], 0.5, v[184:185] op_sel_hi:[1,0,1]
	v_lshl_add_u64 v[98:99], v[144:145], 0, s[14:15]
	global_load_dwordx4 v[100:103], v[98:99], off offset:256
	v_cvt_pk_bf16_f32 v108, v108, v109
	v_cvt_pk_bf16_f32 v109, v110, v111
	v_cvt_pk_bf16_f32 v110, v96, v97
	v_add_co_u32_e32 v96, vcc, s46, v144
	v_lshlrev_b32_e32 v176, 16, v168
	s_nop 0
	v_addc_co_u32_e32 v97, vcc, 0, v145, vcc
	v_and_b32_e32 v177, 0xffff0000, v168
	v_lshlrev_b32_e32 v180, 16, v169
	v_and_b32_e32 v181, 0xffff0000, v169
	v_lshlrev_b32_e32 v178, 16, v170
	v_and_b32_e32 v179, 0xffff0000, v170
	v_lshlrev_b32_e32 v182, 16, v171
	v_and_b32_e32 v183, 0xffff0000, v171
	global_load_dwordx4 v[120:123], v[96:97], off
	v_cvt_pk_bf16_f32 v111, v124, v125
	global_store_dwordx4 v[150:151], v[108:111], off offset:256
	v_pk_fma_f32 v[150:151], v[90:91], 0.5, v[182:183] op_sel_hi:[1,0,1]
	v_pk_fma_f32 v[88:89], v[88:89], 0.5, v[178:179] op_sel_hi:[1,0,1]
	v_pk_fma_f32 v[110:111], v[94:95], 0.5, v[180:181] op_sel_hi:[1,0,1]
	v_pk_fma_f32 v[108:109], v[92:93], 0.5, v[176:177] op_sel_hi:[1,0,1]
	v_lshl_add_u64 v[90:91], v[144:145], 0, s[16:17]
	global_load_dwordx4 v[92:95], v[90:91], off offset:256
	v_cvt_pk_bf16_f32 v108, v108, v109
	v_cvt_pk_bf16_f32 v109, v110, v111
	v_cvt_pk_bf16_f32 v110, v88, v89
	v_add_co_u32_e32 v88, vcc, s47, v144
	v_lshlrev_b32_e32 v170, 16, v174
	s_nop 0
	v_addc_co_u32_e32 v89, vcc, 0, v145, vcc
	v_and_b32_e32 v171, 0xffff0000, v174
	global_load_dwordx4 v[124:127], v[88:89], off
	v_lshlrev_b32_e32 v168, 16, v172
	v_and_b32_e32 v169, 0xffff0000, v172
	v_lshlrev_b32_e32 v172, 16, v173
	v_and_b32_e32 v173, 0xffff0000, v173
	v_cvt_pk_bf16_f32 v111, v150, v151
	v_pk_fma_f32 v[150:151], v[72:73], 0.5, v[170:171] op_sel_hi:[1,0,1]
	v_lshl_add_u64 v[72:73], v[144:145], 0, s[18:19]
	global_store_dwordx4 v[146:147], v[108:111], off
	v_lshlrev_b32_e32 v174, 16, v175
	v_and_b32_e32 v175, 0xffff0000, v175
	v_pk_fma_f32 v[110:111], v[82:83], 0.5, v[172:173] op_sel_hi:[1,0,1]
	v_pk_fma_f32 v[108:109], v[80:81], 0.5, v[168:169] op_sel_hi:[1,0,1]
	global_load_dwordx4 v[80:83], v[72:73], off offset:256
	v_lshlrev_b32_e32 v160, 16, v204
	v_and_b32_e32 v161, 0xffff0000, v204
	v_lshlrev_b32_e32 v166, 16, v205
	v_and_b32_e32 v167, 0xffff0000, v205
	v_pk_fma_f32 v[74:75], v[74:75], 0.5, v[174:175] op_sel_hi:[1,0,1]
	v_cvt_pk_bf16_f32 v108, v108, v109
	v_cvt_pk_bf16_f32 v109, v110, v111
	v_cvt_pk_bf16_f32 v111, v74, v75
	v_pk_fma_f32 v[86:87], v[86:87], 0.5, v[162:163] op_sel_hi:[1,0,1]
	v_pk_fma_f32 v[74:75], v[84:85], 0.5, v[154:155] op_sel_hi:[1,0,1]
	v_pk_fma_f32 v[78:79], v[78:79], 0.5, v[166:167] op_sel_hi:[1,0,1]
	v_pk_fma_f32 v[76:77], v[76:77], 0.5, v[160:161] op_sel_hi:[1,0,1]
	v_lshlrev_b32_e32 v152, 16, v206
	v_and_b32_e32 v153, 0xffff0000, v206
	v_lshlrev_b32_e32 v158, 16, v207
	v_and_b32_e32 v159, 0xffff0000, v207
	v_lshlrev_b32_e32 v156, 16, v208
	v_and_b32_e32 v157, 0xffff0000, v208
	v_lshlrev_b32_e32 v164, 16, v209
	v_and_b32_e32 v165, 0xffff0000, v209
	v_cvt_pk_bf16_f32 v74, v74, v75
	v_cvt_pk_bf16_f32 v75, v86, v87
	v_cvt_pk_bf16_f32 v76, v76, v77
	v_cvt_pk_bf16_f32 v77, v78, v79
	global_store_dwordx4 v[148:149], v[74:77], off
	v_pk_fma_f32 v[70:71], v[70:71], 0.5, v[158:159] op_sel_hi:[1,0,1]
	v_pk_fma_f32 v[68:69], v[68:69], 0.5, v[152:153] op_sel_hi:[1,0,1]
	v_pk_fma_f32 v[74:75], v[66:67], 0.5, v[164:165] op_sel_hi:[1,0,1]
	v_pk_fma_f32 v[66:67], v[64:65], 0.5, v[156:157] op_sel_hi:[1,0,1]
	v_cvt_pk_bf16_f32 v64, v68, v69
	v_cvt_pk_bf16_f32 v65, v70, v71
	v_cvt_pk_bf16_f32 v66, v66, v67
	v_cvt_pk_bf16_f32 v67, v74, v75
	global_store_dwordx4 v[148:149], v[64:67], off offset:256
	s_waitcnt vmcnt(0)
; DI unsigned pk_bf16(float lo, float hi) { f32x2 v = {lo, hi}; return __builtin_bit_cast(unsigned, __builtin_convertvector(v, bf16v2)); }
; #define PG8_WAIT_V(n) asm volatile("s_waitcnt vmcnt(" #n ")" ::: "memory")
; #define PG8_BAR __builtin_amdgcn_s_barrier()
; #define PG8_WAIT_V(n) asm volatile("s_waitcnt vmcnt(" #n ")" ::: "memory")
; #define PG8_BAR __builtin_amdgcn_s_barrier()
; template <class Epi>
; DI void gemm_phase(LAS unsigned char* lds, const Gemm g, const StaticOrder S, const Epi E) {
;     ...
;         cur = nxt; cA = nA; cB = nB; ++ui;
;     }
;     PG8_WAIT_V(0);
;     if (wr == 0) PG8_BAR;
;     PG8_BAR;
;     DI void operator()(AccRef acc, const Unit& u, int wr, int wc, int fr, int fq) const {
;     ...
;             for (int m = 0; m < 4; ++m) {
;                 const int row = row0 + ai * 128 + m * 16;
;                 float q = 0.f;
; #pragma unroll
;                 for (int bj = 0; bj < 2; ++bj) {
;                     const size_t o = (size_t)row * DM + col0 + bj * 128;
;                     const f32x4 r0 = bv[m][bj][0] + scale * acc[ai][bj][m][0], r1 = bv[m][bj][1] + scale * acc[ai][bj][m][1];
;                     u32x4 w; w.x = pk_bf16(r0[0], r0[1]); w.y = pk_bf16(r0[2], r0[3]); w.z = pk_bf16(r1[0], r1[1]); w.w = pk_bf16(r1[2], r1[3]);
;                     *(u32x4*)(xnb + o) = w;
	v_lshlrev_b32_e32 v68, 16, v118
	v_and_b32_e32 v69, 0xffff0000, v118
	v_lshlrev_b32_e32 v64, 16, v116
	v_and_b32_e32 v65, 0xffff0000, v116
	v_lshlrev_b32_e32 v66, 16, v117
	v_and_b32_e32 v67, 0xffff0000, v117
	v_lshlrev_b32_e32 v70, 16, v119
	v_and_b32_e32 v71, 0xffff0000, v119
	v_pk_fma_f32 v[62:63], v[62:63], 0.5, v[66:67] op_sel_hi:[1,0,1]
	v_pk_fma_f32 v[60:61], v[60:61], 0.5, v[64:65] op_sel_hi:[1,0,1]
	v_pk_fma_f32 v[64:65], v[58:59], 0.5, v[70:71] op_sel_hi:[1,0,1]
	v_pk_fma_f32 v[58:59], v[56:57], 0.5, v[68:69] op_sel_hi:[1,0,1]
	v_lshlrev_b32_e32 v74, 16, v104
	v_and_b32_e32 v75, 0xffff0000, v104
	v_lshlrev_b32_e32 v76, 16, v105
	v_and_b32_e32 v77, 0xffff0000, v105
	v_lshlrev_b32_e32 v78, 16, v106
	v_and_b32_e32 v79, 0xffff0000, v106
	v_lshlrev_b32_e32 v84, 16, v107
	v_and_b32_e32 v85, 0xffff0000, v107
	v_cvt_pk_bf16_f32 v56, v60, v61
	v_cvt_pk_bf16_f32 v57, v62, v63
	v_cvt_pk_bf16_f32 v58, v58, v59
	v_cvt_pk_bf16_f32 v59, v64, v65
	v_cvt_pk_bf16_f32 v110, v150, v151
	global_store_dwordx4 v[202:203], v[56:59], off
	v_pk_fma_f32 v[54:55], v[54:55], 0.5, v[76:77] op_sel_hi:[1,0,1]
	v_pk_fma_f32 v[52:53], v[52:53], 0.5, v[74:75] op_sel_hi:[1,0,1]
	v_pk_fma_f32 v[56:57], v[46:47], 0.5, v[84:85] op_sel_hi:[1,0,1]
	v_pk_fma_f32 v[46:47], v[44:45], 0.5, v[78:79] op_sel_hi:[1,0,1]
	global_store_dwordx4 v[146:147], v[108:111], off offset:256
	v_lshlrev_b32_e32 v86, 16, v112
	v_and_b32_e32 v87, 0xffff0000, v112
	v_lshlrev_b32_e32 v104, 16, v113
	v_and_b32_e32 v105, 0xffff0000, v113
	v_lshlrev_b32_e32 v106, 16, v114
	v_and_b32_e32 v107, 0xffff0000, v114
	v_lshlrev_b32_e32 v108, 16, v115
	v_and_b32_e32 v109, 0xffff0000, v115
	v_cvt_pk_bf16_f32 v44, v52, v53
	v_cvt_pk_bf16_f32 v45, v54, v55
	v_cvt_pk_bf16_f32 v46, v46, v47
	v_cvt_pk_bf16_f32 v47, v56, v57
	global_store_dwordx4 v[192:193], v[44:47], off offset:256
	v_lshlrev_b32_e32 v110, 16, v100
	v_and_b32_e32 v111, 0xffff0000, v100
	v_pk_fma_f32 v[44:45], v[50:51], 0.5, v[104:105] op_sel_hi:[1,0,1]
	v_pk_fma_f32 v[46:47], v[48:49], 0.5, v[86:87] op_sel_hi:[1,0,1]
	v_pk_fma_f32 v[48:49], v[42:43], 0.5, v[108:109] op_sel_hi:[1,0,1]
	v_pk_fma_f32 v[42:43], v[40:41], 0.5, v[106:107] op_sel_hi:[1,0,1]
	v_lshlrev_b32_e32 v100, 16, v101
	v_and_b32_e32 v101, 0xffff0000, v101
	v_lshlrev_b32_e32 v112, 16, v102
	v_and_b32_e32 v113, 0xffff0000, v102
	v_lshlrev_b32_e32 v102, 16, v103
	v_and_b32_e32 v103, 0xffff0000, v103
	v_cvt_pk_bf16_f32 v40, v46, v47
	v_cvt_pk_bf16_f32 v41, v44, v45
	v_cvt_pk_bf16_f32 v42, v42, v43
	v_cvt_pk_bf16_f32 v43, v48, v49
	global_store_dwordx4 v[194:195], v[40:43], off
	v_pk_fma_f32 v[38:39], v[38:39], 0.5, v[100:101] op_sel_hi:[1,0,1]
	v_pk_fma_f32 v[36:37], v[36:37], 0.5, v[110:111] op_sel_hi:[1,0,1]
	v_pk_fma_f32 v[40:41], v[30:31], 0.5, v[102:103] op_sel_hi:[1,0,1]
	v_pk_fma_f32 v[30:31], v[28:29], 0.5, v[112:113] op_sel_hi:[1,0,1]
	v_lshlrev_b32_e32 v114, 16, v120
	v_and_b32_e32 v115, 0xffff0000, v120
	v_lshlrev_b32_e32 v116, 16, v121
	v_and_b32_e32 v117, 0xffff0000, v121
	v_lshlrev_b32_e32 v118, 16, v122
	v_and_b32_e32 v119, 0xffff0000, v122
	v_lshlrev_b32_e32 v120, 16, v123
	v_and_b32_e32 v121, 0xffff0000, v123
	v_cvt_pk_bf16_f32 v28, v36, v37
	v_cvt_pk_bf16_f32 v29, v38, v39
	v_cvt_pk_bf16_f32 v30, v30, v31
	v_cvt_pk_bf16_f32 v31, v40, v41
	global_store_dwordx4 v[98:99], v[28:31], off offset:256
	v_lshlrev_b32_e32 v122, 16, v92
	v_and_b32_e32 v123, 0xffff0000, v92
	v_pk_fma_f32 v[28:29], v[34:35], 0.5, v[116:117] op_sel_hi:[1,0,1]
	v_pk_fma_f32 v[30:31], v[32:33], 0.5, v[114:115] op_sel_hi:[1,0,1]
	v_pk_fma_f32 v[32:33], v[26:27], 0.5, v[120:121] op_sel_hi:[1,0,1]
	v_pk_fma_f32 v[26:27], v[24:25], 0.5, v[118:119] op_sel_hi:[1,0,1]
	v_lshlrev_b32_e32 v92, 16, v93
	v_and_b32_e32 v93, 0xffff0000, v93
	v_lshlrev_b32_e32 v144, 16, v94
	v_and_b32_e32 v145, 0xffff0000, v94
	v_lshlrev_b32_e32 v94, 16, v95
	v_and_b32_e32 v95, 0xffff0000, v95
	v_cvt_pk_bf16_f32 v24, v30, v31
	v_cvt_pk_bf16_f32 v25, v28, v29
	v_cvt_pk_bf16_f32 v26, v26, v27
	v_cvt_pk_bf16_f32 v27, v32, v33
	global_store_dwordx4 v[96:97], v[24:27], off
	v_pk_fma_f32 v[22:23], v[22:23], 0.5, v[92:93] op_sel_hi:[1,0,1]
	v_pk_fma_f32 v[20:21], v[20:21], 0.5, v[122:123] op_sel_hi:[1,0,1]
	v_pk_fma_f32 v[24:25], v[14:15], 0.5, v[94:95] op_sel_hi:[1,0,1]
	v_pk_fma_f32 v[14:15], v[12:13], 0.5, v[144:145] op_sel_hi:[1,0,1]
	v_lshlrev_b32_e32 v146, 16, v124
	v_and_b32_e32 v147, 0xffff0000, v124
	v_lshlrev_b32_e32 v124, 16, v125
	v_and_b32_e32 v125, 0xffff0000, v125
	v_lshlrev_b32_e32 v148, 16, v126
	v_and_b32_e32 v149, 0xffff0000, v126
	v_lshlrev_b32_e32 v126, 16, v127
	v_and_b32_e32 v127, 0xffff0000, v127
	v_cvt_pk_bf16_f32 v12, v20, v21
	v_cvt_pk_bf16_f32 v13, v22, v23
	v_cvt_pk_bf16_f32 v14, v14, v15
	v_cvt_pk_bf16_f32 v15, v24, v25
	global_store_dwordx4 v[90:91], v[12:15], off offset:256
	v_lshlrev_b32_e32 v150, 16, v80
	v_and_b32_e32 v151, 0xffff0000, v80
	v_pk_fma_f32 v[12:13], v[18:19], 0.5, v[124:125] op_sel_hi:[1,0,1]
	v_pk_fma_f32 v[14:15], v[16:17], 0.5, v[146:147] op_sel_hi:[1,0,1]
	v_pk_fma_f32 v[16:17], v[10:11], 0.5, v[126:127] op_sel_hi:[1,0,1]
	v_pk_fma_f32 v[10:11], v[8:9], 0.5, v[148:149] op_sel_hi:[1,0,1]
	v_lshlrev_b32_e32 v80, 16, v81
	v_and_b32_e32 v81, 0xffff0000, v81
	v_lshlrev_b32_e32 v152, 16, v82
	v_and_b32_e32 v153, 0xffff0000, v82
	v_lshlrev_b32_e32 v82, 16, v83
	v_and_b32_e32 v83, 0xffff0000, v83
	v_cvt_pk_bf16_f32 v8, v14, v15
	v_cvt_pk_bf16_f32 v9, v12, v13
	v_cvt_pk_bf16_f32 v10, v10, v11
	v_cvt_pk_bf16_f32 v11, v16, v17
	global_store_dwordx4 v[88:89], v[8:11], off
	v_pk_fma_f32 v[6:7], v[6:7], 0.5, v[80:81] op_sel_hi:[1,0,1]
	v_pk_fma_f32 v[4:5], v[4:5], 0.5, v[150:151] op_sel_hi:[1,0,1]
	v_pk_fma_f32 v[8:9], v[2:3], 0.5, v[82:83] op_sel_hi:[1,0,1]
	v_pk_fma_f32 v[2:3], v[0:1], 0.5, v[152:153] op_sel_hi:[1,0,1]
	v_cvt_pk_bf16_f32 v0, v4, v5
	v_cvt_pk_bf16_f32 v1, v6, v7
	v_cvt_pk_bf16_f32 v2, v2, v3
	v_cvt_pk_bf16_f32 v3, v8, v9
	s_and_b64 vcc, exec, s[0:1]
	global_store_dwordx4 v[72:73], v[0:3], off offset:256
	s_cbranch_vccz .LBB0_930
	s_waitcnt vmcnt(0)
	s_cmpk_gt_u32 s6, 0xff
	s_cbranch_scc1 .LBB0_945
	s_barrier
